# attention: clamp via v_med3_i32 (158 chains), self-max canonicalizations removed, hazard nops re-derived
# speedup vs baseline: 1.2122x; 1.0013x over previous
.LBB0_246:
	s_lshl_b32 s1, s71, 2
	s_and_b32 s22, s1, 0xffffff00
	s_lshr_b32 s0, s71, 3
	s_bfe_u32 s56, s71, 0x30003
	s_or_b32 s24, s22, s72
	s_cmp_lt_i32 s24, 0x8000
	s_movk_i32 s22, 0xfff
	s_cselect_b32 s75, s22, 0x1fff
	s_bfe_u32 s0, s0, 0x10002
	s_andn2_b32 s74, s1, s75
	s_mul_i32 s0, s0, 0x1800000
	s_add_u32 s0, s96, s0
	s_addc_u32 s1, s97, 0
	s_lshl_b32 s22, s71, 4
	s_and_b32 s22, s22, 0x180
	s_add_u32 s22, s0, s22
	v_or_b32_e32 v162, s24, v167
	s_addc_u32 s23, s1, 0
	v_ashrrev_i32_e32 v163, 31, v162
	v_lshl_add_u64 v[12:13], s[22:23], 0, v[158:159]
	v_lshlrev_b64 v[0:1], 9, v[162:163]
	v_lshl_add_u64 v[8:9], v[12:13], 0, v[0:1]
	global_load_dwordx4 v[0:3], v[8:9], off
	v_or_b32_e32 v160, 8, v162
	v_ashrrev_i32_e32 v161, 31, v160
	s_add_u32 s68, s22, 0x3000000
	s_addc_u32 s69, s23, 0
	s_sub_i32 s76, s24, s74
	s_sub_i32 s0, s76, 64
	s_waitcnt vmcnt(7)
	v_add_u32_e32 v20, s0, v172
	v_min_i32_e32 v21, s75, v20
	s_waitcnt vmcnt(6)
	v_add_u32_e32 v24, s0, v173
	v_min_i32_e32 v25, s75, v24
	s_waitcnt vmcnt(5)
	v_add_u32_e32 v28, s0, v182
	v_min_i32_e32 v29, s75, v28
	s_waitcnt vmcnt(2)
	v_add_u32_e32 v40, s0, v166
	v_min_i32_e32 v32, s75, v40
	v_add_u32_e32 v41, 16, v40
	s_movk_i32 s1, 0xffef
	v_min_i32_e32 v41, s75, v41
	v_or_b32_e32 v128, 32, v166
	v_add_u32_e32 v56, s0, v128
	v_add_u32_e32 v149, s76, v155
	v_add_u32_e32 v150, s76, v172
	v_add_u32_e32 v151, s76, v173
	v_add_u32_e32 v252, s76, v182
	v_or_b32_e32 v251, s76, v167
	v_subrev_u32_e32 v250, s76, v251
	v_or_b32_e32 v144, 8, v251
	v_subrev_u32_e32 v249, s76, v144
	v_add_u32_e32 v196, 0x60, v155
	v_add_u32_e32 v168, 0x60, v172
	v_add_u32_e32 v193, 0x60, v173
	v_add_u32_e32 v194, 0x60, v182
	v_add_u32_e32 v186, s76, v206
	s_waitcnt vmcnt(0)
	v_lshlrev_b32_e32 v4, 16, v0
	v_and_b32_e32 v5, 0xffff0000, v0
	v_lshlrev_b32_e32 v0, 16, v1
	v_and_b32_e32 v1, 0xffff0000, v1
	v_pk_mul_f32 v[4:5], v[4:5], s[58:59] op_sel_hi:[1,0]
	v_pk_mul_f32 v[0:1], v[0:1], s[58:59] op_sel_hi:[1,0]
	v_cvt_pk_bf16_f32 v4, v4, v5
	v_cvt_pk_bf16_f32 v5, v0, v1
	v_lshlrev_b32_e32 v0, 16, v2
	v_and_b32_e32 v1, 0xffff0000, v2
	v_pk_mul_f32 v[0:1], v[0:1], s[58:59] op_sel_hi:[1,0]
	s_nop 0
	v_cvt_pk_bf16_f32 v6, v0, v1
	v_lshlrev_b32_e32 v0, 16, v3
	v_and_b32_e32 v1, 0xffff0000, v3
	v_pk_mul_f32 v[0:1], v[0:1], s[58:59] op_sel_hi:[1,0]
	s_nop 0
	v_cvt_pk_bf16_f32 v7, v0, v1
	global_load_dwordx4 v[0:3], v[8:9], off offset:64
	s_waitcnt vmcnt(0)
	v_lshlrev_b32_e32 v8, 16, v0
	v_and_b32_e32 v9, 0xffff0000, v0
	v_lshlrev_b32_e32 v0, 16, v1
	v_and_b32_e32 v1, 0xffff0000, v1
	v_pk_mul_f32 v[8:9], v[8:9], s[58:59] op_sel_hi:[1,0]
	v_pk_mul_f32 v[0:1], v[0:1], s[58:59] op_sel_hi:[1,0]
	v_cvt_pk_bf16_f32 v8, v8, v9
	v_cvt_pk_bf16_f32 v9, v0, v1
	v_lshlrev_b32_e32 v0, 16, v2
	v_and_b32_e32 v1, 0xffff0000, v2
	v_pk_mul_f32 v[0:1], v[0:1], s[58:59] op_sel_hi:[1,0]
	s_nop 0
	v_cvt_pk_bf16_f32 v10, v0, v1
	v_lshlrev_b32_e32 v0, 16, v3
	v_and_b32_e32 v1, 0xffff0000, v3
	v_pk_mul_f32 v[0:1], v[0:1], s[58:59] op_sel_hi:[1,0]
	s_nop 0
	v_cvt_pk_bf16_f32 v11, v0, v1
	v_lshlrev_b64 v[0:1], 9, v[160:161]
	v_lshl_add_u64 v[16:17], v[12:13], 0, v[0:1]
	global_load_dwordx4 v[0:3], v[16:17], off
	s_waitcnt vmcnt(0)
	v_lshlrev_b32_e32 v12, 16, v0
	v_and_b32_e32 v13, 0xffff0000, v0
	v_lshlrev_b32_e32 v0, 16, v1
	v_and_b32_e32 v1, 0xffff0000, v1
	v_pk_mul_f32 v[12:13], v[12:13], s[58:59] op_sel_hi:[1,0]
	v_pk_mul_f32 v[0:1], v[0:1], s[58:59] op_sel_hi:[1,0]
	v_cvt_pk_bf16_f32 v12, v12, v13
	v_cvt_pk_bf16_f32 v13, v0, v1
	v_lshlrev_b32_e32 v0, 16, v2
	v_and_b32_e32 v1, 0xffff0000, v2
	v_pk_mul_f32 v[0:1], v[0:1], s[58:59] op_sel_hi:[1,0]
	s_nop 0
	v_cvt_pk_bf16_f32 v14, v0, v1
	v_lshlrev_b32_e32 v0, 16, v3
	v_and_b32_e32 v1, 0xffff0000, v3
	v_pk_mul_f32 v[0:1], v[0:1], s[58:59] op_sel_hi:[1,0]
	s_nop 0
	v_cvt_pk_bf16_f32 v15, v0, v1
	global_load_dwordx4 v[0:3], v[16:17], off offset:64
	s_waitcnt vmcnt(0)
	v_lshlrev_b32_e32 v16, 16, v0
	v_and_b32_e32 v17, 0xffff0000, v0
	v_pk_mul_f32 v[16:17], v[16:17], s[58:59] op_sel_hi:[1,0]
	s_nop 0
	v_cvt_pk_bf16_f32 v0, v16, v17
	v_lshlrev_b32_e32 v16, 16, v1
	v_and_b32_e32 v17, 0xffff0000, v1
	v_pk_mul_f32 v[16:17], v[16:17], s[58:59] op_sel_hi:[1,0]
	s_nop 0
	v_cvt_pk_bf16_f32 v1, v16, v17
	v_lshlrev_b32_e32 v16, 16, v2
	v_and_b32_e32 v17, 0xffff0000, v2
	v_pk_mul_f32 v[16:17], v[16:17], s[58:59] op_sel_hi:[1,0]
	s_nop 0
	v_cvt_pk_bf16_f32 v2, v16, v17
	v_lshlrev_b32_e32 v16, 16, v3
	v_and_b32_e32 v17, 0xffff0000, v3
	v_pk_mul_f32 v[16:17], v[16:17], s[58:59] op_sel_hi:[1,0]
	s_nop 0
	v_cvt_pk_bf16_f32 v3, v16, v17
	v_lshl_add_u64 v[16:17], s[22:23], 0, v[152:153]
	s_mov_b64 s[22:23], 0x6000000
	v_lshl_add_u64 v[164:165], v[16:17], 0, s[22:23]
	v_add_u32_e32 v16, s0, v155
	s_sub_i32 s22, 0x80, s76
	s_nop 0
	v_med3_i32 v16, v16, 0, s75
	v_cmp_lt_i32_e32 vcc, -1, v20
	v_add_u32_e32 v16, s74, v16
	v_ashrrev_i32_e32 v17, 31, v16
	v_cndmask_b32_e32 v20, 0, v21, vcc
	v_cmp_lt_i32_e32 vcc, -1, v24
	v_add_u32_e32 v20, s74, v20
	v_lshlrev_b64 v[16:17], 9, v[16:17]
	v_cndmask_b32_e32 v24, 0, v25, vcc
	v_cmp_lt_i32_e32 vcc, -1, v28
	v_ashrrev_i32_e32 v21, 31, v20
	v_add_u32_e32 v24, s74, v24
	v_cndmask_b32_e32 v28, 0, v29, vcc
	v_lshl_add_u64 v[16:17], v[164:165], 0, v[16:17]
	v_lshlrev_b64 v[20:21], 9, v[20:21]
	v_ashrrev_i32_e32 v25, 31, v24
	v_add_u32_e32 v28, s74, v28
	global_load_dwordx4 v[16:19], v[16:17], off
	v_lshl_add_u64 v[20:21], v[164:165], 0, v[20:21]
	v_lshlrev_b64 v[24:25], 9, v[24:25]
	v_ashrrev_i32_e32 v29, 31, v28
	v_cmp_lt_i32_e32 vcc, -1, v40
	global_load_dwordx4 v[20:23], v[20:21], off
	v_lshl_add_u64 v[24:25], v[164:165], 0, v[24:25]
	v_lshlrev_b64 v[28:29], 9, v[28:29]
	v_cndmask_b32_e32 v32, 0, v32, vcc
	v_cmp_lt_i32_e32 vcc, s1, v40
	global_load_dwordx4 v[24:27], v[24:25], off
	v_lshl_add_u64 v[28:29], v[164:165], 0, v[28:29]
	v_cndmask_b32_e32 v40, 0, v41, vcc
	global_load_dwordx4 v[28:31], v[28:29], off
	v_add_u32_e32 v32, s74, v32
	v_add_u32_e32 v40, s74, v40
	v_ashrrev_i32_e32 v33, 31, v32
	v_ashrrev_i32_e32 v41, 31, v40
	v_lshlrev_b64 v[32:33], 9, v[32:33]
	v_lshlrev_b64 v[40:41], 9, v[40:41]
	v_lshl_add_u64 v[32:33], s[68:69], 0, v[32:33]
	v_lshl_add_u64 v[40:41], s[68:69], 0, v[40:41]
	v_lshl_add_u64 v[36:37], v[32:33], 0, v[158:159]
	v_lshl_add_u64 v[40:41], v[40:41], 0, v[158:159]
	s_sub_i32 s1, s76, 32
	global_load_dwordx4 v[32:35], v[36:37], off
	s_nop 0
	global_load_dwordx4 v[36:39], v[36:37], off offset:64
	s_nop 0
	global_load_dwordx4 v[48:51], v[40:41], off
	global_load_dwordx4 v[52:55], v[40:41], off offset:64
	v_add_u32_e32 v40, s1, v155
	v_med3_i32 v40, v40, 0, s75
	v_add_u32_e32 v40, s74, v40
	v_ashrrev_i32_e32 v41, 31, v40
	v_lshlrev_b64 v[40:41], 9, v[40:41]
	v_lshl_add_u64 v[40:41], v[164:165], 0, v[40:41]
	global_load_dwordx4 v[76:79], v[40:41], off
	v_add_u32_e32 v40, s1, v172
	v_med3_i32 v40, v40, 0, s75
	v_add_u32_e32 v40, s74, v40
	v_ashrrev_i32_e32 v41, 31, v40
	v_lshlrev_b64 v[40:41], 9, v[40:41]
	v_lshl_add_u64 v[40:41], v[164:165], 0, v[40:41]
	global_load_dwordx4 v[84:87], v[40:41], off
	v_add_u32_e32 v40, s1, v173
	v_med3_i32 v40, v40, 0, s75
	v_add_u32_e32 v40, s74, v40
	v_ashrrev_i32_e32 v41, 31, v40
	v_lshlrev_b64 v[40:41], 9, v[40:41]
	v_lshl_add_u64 v[40:41], v[164:165], 0, v[40:41]
	global_load_dwordx4 v[88:91], v[40:41], off
	v_add_u32_e32 v40, s1, v182
	s_min_i32 s1, s0, 0
	s_sub_i32 s1, 0, s1
	v_med3_i32 v40, v40, 0, s75
	v_add_u32_e32 v40, s74, v40
	v_ashrrev_i32_e32 v41, 31, v40
	v_lshlrev_b64 v[40:41], 9, v[40:41]
	v_lshl_add_u64 v[40:41], v[164:165], 0, v[40:41]
	global_load_dwordx4 v[92:95], v[40:41], off
	v_min_i32_e32 v40, s75, v56
	v_cmp_lt_i32_e32 vcc, -1, v56
	v_add_u32_e32 v56, 16, v56
	s_nop 0
	v_cndmask_b32_e32 v40, 0, v40, vcc
	v_add_u32_e32 v40, s74, v40
	v_ashrrev_i32_e32 v41, 31, v40
	v_med3_i32 v56, v56, 0, s75
	v_add_u32_e32 v56, s74, v56
	v_ashrrev_i32_e32 v57, 31, v56
	v_lshlrev_b64 v[40:41], 9, v[40:41]
	v_lshlrev_b64 v[56:57], 9, v[56:57]
	v_lshl_add_u64 v[40:41], s[68:69], 0, v[40:41]
	v_lshl_add_u64 v[56:57], s[68:69], 0, v[56:57]
	v_lshl_add_u64 v[44:45], v[40:41], 0, v[158:159]
	v_lshl_add_u64 v[60:61], v[56:57], 0, v[158:159]
	global_load_dwordx4 v[40:43], v[44:45], off
	s_nop 0
	global_load_dwordx4 v[44:47], v[44:45], off offset:64
	s_nop 0
	global_load_dwordx4 v[56:59], v[60:61], off
	s_nop 0
	global_load_dwordx4 v[60:63], v[60:61], off offset:64
	s_waitcnt vmcnt(15)
	ds_write_b128 v241, v[16:19]
	s_waitcnt vmcnt(14)
	ds_write_b128 v242, v[20:23]
	s_waitcnt vmcnt(13)
	ds_write_b128 v243, v[24:27]
	s_waitcnt vmcnt(12)
	ds_write_b128 v244, v[28:31]
	v_or_b32_e32 v24, 16, v166
	v_add_u32_e32 v24, s76, v24
	v_med3_i32 v16, v149, 0, s75
	v_add_u32_e32 v16, s74, v16
	v_ashrrev_i32_e32 v17, 31, v16
	v_lshlrev_b64 v[16:17], 9, v[16:17]
	v_lshl_add_u64 v[16:17], v[164:165], 0, v[16:17]
	global_load_dwordx4 v[64:67], v[16:17], off
	s_sub_i32 s0, s75, s0
	v_med3_i32 v16, v150, 0, s75
	v_add_u32_e32 v16, s74, v16
	v_ashrrev_i32_e32 v17, 31, v16
	v_lshlrev_b64 v[16:17], 9, v[16:17]
	v_lshl_add_u64 v[16:17], v[164:165], 0, v[16:17]
	global_load_dwordx4 v[68:71], v[16:17], off
	v_max_i32_e32 v147, s1, v250
	v_max_i32_e32 v148, s1, v249
	v_med3_i32 v16, v151, 0, s75
	v_add_u32_e32 v16, s74, v16
	v_ashrrev_i32_e32 v17, 31, v16
	v_lshlrev_b64 v[16:17], 9, v[16:17]
	v_lshl_add_u64 v[16:17], v[164:165], 0, v[16:17]
	global_load_dwordx4 v[72:75], v[16:17], off
	v_med3_i32 v16, v252, 0, s75
	v_add_u32_e32 v16, s74, v16
	v_ashrrev_i32_e32 v17, 31, v16
	v_lshlrev_b64 v[16:17], 9, v[16:17]
	v_lshl_add_u64 v[16:17], v[164:165], 0, v[16:17]
	global_load_dwordx4 v[80:83], v[16:17], off
	v_add_u32_e32 v16, s76, v166
	v_med3_i32 v16, v16, 0, s75
	v_add_u32_e32 v16, s74, v16
	v_ashrrev_i32_e32 v17, 31, v16
	v_med3_i32 v24, v24, 0, s75
	v_add_u32_e32 v24, s74, v24
	v_ashrrev_i32_e32 v25, 31, v24
	v_lshlrev_b64 v[16:17], 9, v[16:17]
	v_lshlrev_b64 v[24:25], 9, v[24:25]
	v_lshl_add_u64 v[16:17], s[68:69], 0, v[16:17]
	v_lshl_add_u64 v[24:25], s[68:69], 0, v[24:25]
	v_lshl_add_u64 v[20:21], v[16:17], 0, v[158:159]
	v_lshl_add_u64 v[28:29], v[24:25], 0, v[158:159]
	global_load_dwordx4 v[16:19], v[20:21], off
	s_nop 0
	global_load_dwordx4 v[20:23], v[20:21], off offset:64
	s_nop 0
	global_load_dwordx4 v[24:27], v[28:29], off
	s_nop 0
	global_load_dwordx4 v[28:31], v[28:29], off offset:64
	ds_read_b64_tr_b16 v[98:99], v169 offset:2304
	ds_read_b64_tr_b16 v[96:97], v169
	ds_read_b64_tr_b16 v[100:101], v169 offset:32
	ds_read_b64_tr_b16 v[102:103], v169 offset:2336
	ds_read_b64_tr_b16 v[116:117], v169 offset:64
	ds_read_b64_tr_b16 v[118:119], v169 offset:2368
	ds_read_b64_tr_b16 v[134:135], v169 offset:96
	ds_read_b64_tr_b16 v[136:137], v169 offset:2400
	s_waitcnt vmcnt(15)
	ds_write_b128 v241, v[76:79] offset:4608
	s_waitcnt vmcnt(14)
	ds_write_b128 v242, v[84:87] offset:4608
	s_waitcnt vmcnt(13)
	ds_write_b128 v243, v[88:91] offset:4608
	s_waitcnt vmcnt(12)
	ds_write_b128 v244, v[92:95] offset:4608
	v_mfma_f32_16x16x32_bf16 v[76:79], v[32:35], v[4:7], 0
	v_mfma_f32_16x16x32_bf16 v[32:35], v[32:35], v[12:15], 0
	v_mfma_f32_16x16x32_bf16 v[76:79], v[36:39], v[8:11], v[76:79]
	v_mfma_f32_16x16x32_bf16 v[84:87], v[48:51], v[4:7], 0
	v_mfma_f32_16x16x32_bf16 v[32:35], v[36:39], v[0:3], v[32:35]
	v_mfma_f32_16x16x32_bf16 v[36:39], v[48:51], v[12:15], 0
	v_add_u32_e32 v48, s22, v251
	v_min3_i32 v48, v48, s0, v245
	v_sub_u32_e32 v49, v154, v147
	v_sub_u32_e32 v146, v48, v147
	v_add_u32_e32 v48, s22, v144
	v_min3_i32 v48, v48, s0, v245
	v_add_u32_e32 v51, 1, v49
	v_sub_u32_e32 v145, v48, v148
	v_max_f32_e32 v48, v76, v76
	v_cmp_gt_u32_e64 s[0:1], v51, v146
	v_cmp_gt_u32_e32 vcc, v49, v146
	v_max_f32_e32 v48, 0xf149f2ca, v48
	v_cndmask_b32_e64 v51, v77, v246, s[0:1]
	v_cndmask_b32_e32 v48, v48, v246, vcc
	v_mfma_f32_16x16x32_bf16 v[84:87], v[52:55], v[8:11], v[84:87]
	v_max_f32_e32 v48, v48, v51
	v_add_u32_e32 v51, 2, v49
	v_cmp_gt_u32_e64 s[22:23], v51, v146
	v_mfma_f32_16x16x32_bf16 v[36:39], v[52:55], v[0:3], v[36:39]
	v_add_u32_e32 v52, 3, v49
	v_cmp_gt_u32_e64 s[24:25], v52, v146
	v_cndmask_b32_e64 v51, v78, v246, s[22:23]
	v_sub_u32_e32 v50, v154, v148
	v_cndmask_b32_e64 v52, v79, v246, s[24:25]
	v_max3_f32 v48, v48, v51, v52
	v_add_u32_e32 v51, 16, v49
	v_add_u32_e32 v52, 17, v49
	v_cmp_gt_u32_e64 s[26:27], v51, v146
	v_cmp_gt_u32_e64 s[28:29], v52, v146
	v_cmp_gt_u32_e64 s[38:39], v50, v145
	v_cndmask_b32_e64 v51, v84, v246, s[26:27]
	v_cndmask_b32_e64 v52, v85, v246, s[28:29]
	v_max3_f32 v48, v48, v51, v52
	v_add_u32_e32 v51, 18, v49
	v_add_u32_e32 v49, 19, v49
	v_cmp_gt_u32_e64 s[30:31], v51, v146
	v_cmp_gt_u32_e64 s[34:35], v49, v146
	v_add_u32_e32 v52, 3, v50
	v_cndmask_b32_e64 v51, v86, v246, s[30:31]
	v_cndmask_b32_e64 v49, v87, v246, s[34:35]
	v_max3_f32 v48, v48, v51, v49
	v_add_u32_e32 v51, 1, v50
	v_max_f32_e32 v49, v32, v32
	v_cmp_gt_u32_e64 s[40:41], v51, v145
	v_max_f32_e32 v49, 0xf149f2ca, v49
	v_cndmask_b32_e64 v49, v49, v246, s[38:39]
	v_cndmask_b32_e64 v51, v33, v246, s[40:41]
	v_max_f32_e32 v49, v49, v51
	v_add_u32_e32 v51, 2, v50
	v_cmp_gt_u32_e64 s[42:43], v51, v145
	v_cmp_gt_u32_e64 s[44:45], v52, v145
	s_nop 0
	v_cndmask_b32_e64 v51, v34, v246, s[42:43]
	v_cndmask_b32_e64 v52, v35, v246, s[44:45]
	v_max3_f32 v49, v49, v51, v52
	v_add_u32_e32 v51, 16, v50
	v_add_u32_e32 v52, 17, v50
	v_cmp_gt_u32_e64 s[46:47], v51, v145
	v_cmp_gt_u32_e64 s[48:49], v52, v145
	s_nop 0
	v_cndmask_b32_e64 v51, v36, v246, s[46:47]
	v_cndmask_b32_e64 v52, v37, v246, s[48:49]
	v_max3_f32 v49, v49, v51, v52
	v_add_u32_e32 v51, 18, v50
	v_add_u32_e32 v50, 19, v50
	v_cmp_gt_u32_e64 s[50:51], v51, v145
	v_cmp_gt_u32_e64 s[52:53], v50, v145
	s_nop 0
	v_cndmask_b32_e64 v51, v38, v246, s[50:51]
	v_cndmask_b32_e64 v50, v39, v246, s[52:53]
	v_max3_f32 v49, v49, v51, v50
	v_mov_b32_e32 v50, v48
	v_mov_b32_e32 v51, v48
	s_nop 1
	v_permlane32_swap_b32_e32 v50, v51
	v_max3_f32 v48, v48, v50, v51
	v_mov_b32_e32 v50, v49
	v_mov_b32_e32 v51, v49
	s_nop 1
	v_permlane32_swap_b32_e32 v50, v51
	v_max3_f32 v49, v49, v50, v51
	v_mov_b32_e32 v50, v48
	v_mov_b32_e32 v51, v48
	s_nop 1
	v_permlane16_swap_b32_e32 v50, v51
	v_max_f32_e32 v48, v48, v50
	v_mov_b32_e32 v50, v49
	v_mov_b32_e32 v88, v49
	s_nop 1
	v_permlane16_swap_b32_e32 v50, v88
	v_max3_f32 v129, v48, v51, s73
	v_sub_f32_e32 v48, 0xf149f2ca, v129
	v_max_f32_e32 v49, v49, v50
	v_exp_f32_e32 v50, v48
	v_sub_f32_e32 v48, v76, v129
	v_exp_f32_e32 v48, v48
	v_sub_f32_e32 v52, v77, v129
	v_max3_f32 v131, v49, v88, s73
	v_exp_f32_e32 v52, v52
	v_sub_f32_e32 v36, v36, v131
	v_sub_f32_e32 v53, v78, v129
	v_exp_f32_e32 v36, v36
	v_exp_f32_e32 v53, v53
	v_sub_f32_e32 v54, v79, v129
	v_cndmask_b32_e64 v51, v48, 0, vcc
	v_exp_f32_e32 v54, v54
	v_sub_f32_e32 v55, v84, v129
	v_add_f32_e32 v48, 0, v51
	v_cndmask_b32_e64 v52, v52, 0, s[0:1]
	v_exp_f32_e32 v55, v55
	v_sub_f32_e32 v76, v85, v129
	v_add_f32_e32 v48, v52, v48
	v_exp_f32_e32 v76, v76
	v_sub_f32_e32 v77, v86, v129
	v_cvt_pk_bf16_f32 v52, v51, v52
	v_cndmask_b32_e64 v51, v36, 0, s[46:47]
	v_sub_f32_e32 v36, v37, v131
	v_cndmask_b32_e64 v53, v53, 0, s[22:23]
	v_exp_f32_e32 v77, v77
	v_sub_f32_e32 v78, v87, v129
	v_exp_f32_e32 v36, v36
	v_add_f32_e32 v48, v53, v48
	v_cndmask_b32_e64 v54, v54, 0, s[24:25]
	v_exp_f32_e32 v78, v78
	v_add_f32_e32 v48, v54, v48
	v_cndmask_b32_e64 v55, v55, 0, s[26:27]
	v_sub_f32_e32 v32, v32, v131
	v_add_f32_e32 v48, v55, v48
	v_cndmask_b32_e64 v76, v76, 0, s[28:29]
	v_exp_f32_e32 v32, v32
	v_sub_f32_e32 v33, v33, v131
	v_add_f32_e32 v48, v76, v48
	v_cndmask_b32_e64 v77, v77, 0, s[30:31]
	v_cvt_pk_bf16_f32 v53, v53, v54
	v_cvt_pk_bf16_f32 v54, v55, v76
	v_exp_f32_e32 v33, v33
	v_sub_f32_e32 v34, v34, v131
	v_cndmask_b32_e64 v76, v36, 0, s[48:49]
	v_sub_f32_e32 v36, v38, v131
	v_add_f32_e32 v48, v77, v48
	v_cndmask_b32_e64 v78, v78, 0, s[34:35]
	v_exp_f32_e32 v34, v34
	v_sub_f32_e32 v35, v35, v131
	v_exp_f32_e32 v36, v36
	v_add_f32_e32 v130, v78, v48
	v_exp_f32_e32 v35, v35
	v_mul_f32_e32 v48, 0, v50
	v_fmac_f32_e32 v130, 0, v50
	v_cndmask_b32_e64 v50, v32, 0, s[38:39]
	v_add_f32_e32 v32, 0, v50
	v_cndmask_b32_e64 v33, v33, 0, s[40:41]
	v_cvt_pk_bf16_f32 v55, v77, v78
	v_add_f32_e32 v32, v33, v32
	v_cndmask_b32_e64 v34, v34, 0, s[42:43]
	v_cndmask_b32_e64 v77, v36, 0, s[50:51]
	v_sub_f32_e32 v36, v39, v131
	v_sub_f32_e32 v49, 0xf149f2ca, v131
	v_add_f32_e32 v32, v34, v32
	v_cndmask_b32_e64 v35, v35, 0, s[44:45]
	v_exp_f32_e32 v36, v36
	v_exp_f32_e32 v49, v49
	v_add_f32_e32 v32, v35, v32
	v_add_f32_e32 v32, v51, v32
	v_add_f32_e32 v32, v76, v32
	v_add_f32_e32 v32, v77, v32
	v_cndmask_b32_e64 v39, v36, 0, s[52:53]
	v_add_f32_e32 v132, v39, v32
	v_mul_f32_e32 v32, 0, v49
	v_fmac_f32_e32 v132, 0, v49
	v_cvt_pk_bf16_f32 v36, v50, v33
	v_cvt_pk_bf16_f32 v37, v34, v35
	v_cvt_pk_bf16_f32 v38, v51, v76
	v_cvt_pk_bf16_f32 v39, v77, v39
	v_mov_b32_e32 v49, v48
	v_mov_b32_e32 v50, v48
	v_mov_b32_e32 v51, v48
	v_mov_b32_e32 v33, v32
	v_mov_b32_e32 v34, v32
	v_mov_b32_e32 v35, v32
	s_waitcnt lgkmcnt(6)
	v_mfma_f32_16x16x32_bf16 v[112:115], v[116:119], v[52:55], v[48:51]
	v_mfma_f32_16x16x32_bf16 v[124:127], v[96:99], v[36:39], v[32:35]
	v_mfma_f32_16x16x32_bf16 v[108:111], v[100:103], v[36:39], v[32:35]
	v_mfma_f32_16x16x32_bf16 v[116:119], v[116:119], v[36:39], v[32:35]
	s_waitcnt lgkmcnt(4)
	v_mfma_f32_16x16x32_bf16 v[88:91], v[134:137], v[36:39], v[32:35]
	s_nop 2
	v_add_u32_e32 v32, 32, v155
	v_add_u32_e32 v32, s76, v32
	v_mfma_f32_16x16x32_bf16 v[120:123], v[96:99], v[52:55], v[48:51]
	s_nop 0
	v_med3_i32 v32, v32, 0, s75
	v_add_u32_e32 v32, s74, v32
	v_ashrrev_i32_e32 v33, 31, v32
	v_lshlrev_b64 v[32:33], 9, v[32:33]
	v_lshl_add_u64 v[32:33], v[164:165], 0, v[32:33]
	global_load_dwordx4 v[76:79], v[32:33], off
	v_add_u32_e32 v32, 32, v172
	v_add_u32_e32 v32, s76, v32
	v_mfma_f32_16x16x32_bf16 v[104:107], v[100:103], v[52:55], v[48:51]
	s_nop 0
	v_med3_i32 v32, v32, 0, s75
	v_add_u32_e32 v32, s74, v32
	v_ashrrev_i32_e32 v33, 31, v32
	v_lshlrev_b64 v[32:33], 9, v[32:33]
	v_lshl_add_u64 v[32:33], v[164:165], 0, v[32:33]
	global_load_dwordx4 v[84:87], v[32:33], off
	v_add_u32_e32 v32, 32, v173
	v_add_u32_e32 v32, s76, v32
	v_mfma_f32_16x16x32_bf16 v[96:99], v[134:137], v[52:55], v[48:51]
	s_nop 0
	v_med3_i32 v32, v32, 0, s75
	v_add_u32_e32 v32, s74, v32
	v_ashrrev_i32_e32 v33, 31, v32
	v_lshlrev_b64 v[32:33], 9, v[32:33]
	v_lshl_add_u64 v[32:33], v[164:165], 0, v[32:33]
	global_load_dwordx4 v[92:95], v[32:33], off
	v_add_u32_e32 v32, 32, v182
	v_add_u32_e32 v32, s76, v32
	v_or_b32_e32 v48, 48, v166
	v_add_u32_e32 v48, s76, v48
	v_med3_i32 v32, v32, 0, s75
	v_add_u32_e32 v32, s74, v32
	v_ashrrev_i32_e32 v33, 31, v32
	v_lshlrev_b64 v[32:33], 9, v[32:33]
	v_lshl_add_u64 v[32:33], v[164:165], 0, v[32:33]
	global_load_dwordx4 v[100:103], v[32:33], off
	v_add_u32_e32 v32, s76, v128
	s_nop 0
	v_med3_i32 v32, v32, 0, s75
	v_add_u32_e32 v32, s74, v32
	v_ashrrev_i32_e32 v33, 31, v32
	v_med3_i32 v48, v48, 0, s75
	v_add_u32_e32 v48, s74, v48
	v_ashrrev_i32_e32 v49, 31, v48
	v_lshlrev_b64 v[32:33], 9, v[32:33]
	v_lshlrev_b64 v[48:49], 9, v[48:49]
	v_lshl_add_u64 v[32:33], s[68:69], 0, v[32:33]
	v_lshl_add_u64 v[48:49], s[68:69], 0, v[48:49]
	v_lshl_add_u64 v[36:37], v[32:33], 0, v[158:159]
	v_lshl_add_u64 v[52:53], v[48:49], 0, v[158:159]
	global_load_dwordx4 v[32:35], v[36:37], off
	s_nop 0
	global_load_dwordx4 v[36:39], v[36:37], off offset:64
	s_nop 0
	global_load_dwordx4 v[48:51], v[52:53], off
	s_nop 0
	global_load_dwordx4 v[52:55], v[52:53], off offset:64
	ds_read_b64_tr_b16 v[136:137], v169 offset:6912
	ds_read_b64_tr_b16 v[134:135], v169 offset:4608
	ds_read_b64_tr_b16 v[138:139], v169 offset:4640
	ds_read_b64_tr_b16 v[140:141], v169 offset:6944
	ds_read_b64_tr_b16 v[176:177], v169 offset:4672
	ds_read_b64_tr_b16 v[178:179], v169 offset:6976
	ds_read_b64_tr_b16 v[188:189], v169 offset:4704
	ds_read_b64_tr_b16 v[190:191], v169 offset:7008
	s_waitcnt vmcnt(15)
	ds_write_b128 v241, v[64:67]
	s_waitcnt vmcnt(14)
	ds_write_b128 v242, v[68:71]
	s_waitcnt vmcnt(13)
	ds_write_b128 v243, v[72:75]
	s_waitcnt vmcnt(12)
	ds_write_b128 v244, v[80:83]
	v_mfma_f32_16x16x32_bf16 v[64:67], v[40:43], v[4:7], 0
	v_mfma_f32_16x16x32_bf16 v[40:43], v[40:43], v[12:15], 0
	v_mfma_f32_16x16x32_bf16 v[64:67], v[44:47], v[8:11], v[64:67]
	v_mfma_f32_16x16x32_bf16 v[68:71], v[56:59], v[4:7], 0
	v_mfma_f32_16x16x32_bf16 v[40:43], v[44:47], v[0:3], v[40:43]
	v_mfma_f32_16x16x32_bf16 v[44:47], v[56:59], v[12:15], 0
	v_sub_u32_e32 v56, v187, v147
	v_add_u32_e32 v59, 1, v56
	s_nop 2
	v_max_f32_e32 v58, v64, v64
	v_cmp_gt_u32_e64 s[0:1], v59, v146
	v_cmp_gt_u32_e32 vcc, v56, v146
	v_max_f32_e32 v58, 0xf149f2ca, v58
	v_cndmask_b32_e64 v59, v65, v246, s[0:1]
	v_cndmask_b32_e32 v58, v58, v246, vcc
	v_mfma_f32_16x16x32_bf16 v[68:71], v[60:63], v[8:11], v[68:71]
	v_max_f32_e32 v58, v58, v59
	v_add_u32_e32 v59, 2, v56
	v_cmp_gt_u32_e64 s[22:23], v59, v146
	v_mfma_f32_16x16x32_bf16 v[44:47], v[60:63], v[0:3], v[44:47]
	v_add_u32_e32 v60, 3, v56
	v_cmp_gt_u32_e64 s[24:25], v60, v146
	v_cndmask_b32_e64 v59, v66, v246, s[22:23]
	v_sub_u32_e32 v57, v187, v148
	v_cndmask_b32_e64 v60, v67, v246, s[24:25]
	v_max3_f32 v58, v58, v59, v60
	v_add_u32_e32 v59, 16, v56
	v_add_u32_e32 v60, 17, v56
	v_cmp_gt_u32_e64 s[26:27], v59, v146
	v_cmp_gt_u32_e64 s[28:29], v60, v146
	v_cmp_gt_u32_e64 s[38:39], v57, v145
	v_cndmask_b32_e64 v59, v68, v246, s[26:27]
	v_cndmask_b32_e64 v60, v69, v246, s[28:29]
	v_max3_f32 v58, v58, v59, v60
	v_add_u32_e32 v59, 18, v56
	v_add_u32_e32 v56, 19, v56
	v_cmp_gt_u32_e64 s[30:31], v59, v146
	v_cmp_gt_u32_e64 s[34:35], v56, v146
	v_add_u32_e32 v60, 3, v57
	v_cndmask_b32_e64 v59, v70, v246, s[30:31]
	v_cndmask_b32_e64 v56, v71, v246, s[34:35]
	v_max3_f32 v56, v58, v59, v56
	v_add_u32_e32 v59, 1, v57
	v_max_f32_e32 v58, v40, v40
	v_cmp_gt_u32_e64 s[40:41], v59, v145
	v_max_f32_e32 v58, 0xf149f2ca, v58
	v_cndmask_b32_e64 v58, v58, v246, s[38:39]
	v_cndmask_b32_e64 v59, v41, v246, s[40:41]
	v_max_f32_e32 v58, v58, v59
	v_add_u32_e32 v59, 2, v57
	v_cmp_gt_u32_e64 s[42:43], v59, v145
	v_cmp_gt_u32_e64 s[44:45], v60, v145
	s_nop 0
	v_cndmask_b32_e64 v59, v42, v246, s[42:43]
	v_cndmask_b32_e64 v60, v43, v246, s[44:45]
	v_max3_f32 v58, v58, v59, v60
	v_add_u32_e32 v59, 16, v57
	v_add_u32_e32 v60, 17, v57
	v_cmp_gt_u32_e64 s[46:47], v59, v145
	v_cmp_gt_u32_e64 s[48:49], v60, v145
	s_nop 0
	v_cndmask_b32_e64 v59, v44, v246, s[46:47]
	v_cndmask_b32_e64 v60, v45, v246, s[48:49]
	v_max3_f32 v58, v58, v59, v60
	v_add_u32_e32 v59, 18, v57
	v_add_u32_e32 v57, 19, v57
	v_cmp_gt_u32_e64 s[50:51], v59, v145
	v_cmp_gt_u32_e64 s[52:53], v57, v145
	s_nop 0
	v_cndmask_b32_e64 v59, v46, v246, s[50:51]
	v_cndmask_b32_e64 v57, v47, v246, s[52:53]
	v_max3_f32 v57, v58, v59, v57
	v_mov_b32_e32 v58, v56
	v_mov_b32_e32 v59, v56
	s_nop 1
	v_permlane32_swap_b32_e32 v58, v59
	v_max3_f32 v56, v56, v58, v59
	v_mov_b32_e32 v58, v57
	v_mov_b32_e32 v59, v57
	s_nop 1
	v_permlane32_swap_b32_e32 v58, v59
	v_max3_f32 v57, v57, v58, v59
	v_mov_b32_e32 v58, v56
	v_mov_b32_e32 v59, v56
	s_nop 1
	v_permlane16_swap_b32_e32 v58, v59
	v_max_f32_e32 v56, v56, v58
	v_mov_b32_e32 v58, v57
	v_mov_b32_e32 v61, v57
	v_max3_f32 v128, v129, v56, v59
	s_nop 0
	v_permlane16_swap_b32_e32 v58, v61
	v_sub_f32_e32 v56, v129, v128
	v_exp_f32_e32 v60, v56
	v_sub_f32_e32 v56, v64, v128
	v_max_f32_e32 v62, v57, v58
	v_exp_f32_e32 v56, v56
	v_sub_f32_e32 v58, v65, v128
	v_exp_f32_e32 v58, v58
	v_sub_f32_e32 v59, v66, v128
	v_exp_f32_e32 v59, v59
	v_sub_f32_e32 v63, v67, v128
	v_exp_f32_e32 v63, v63
	v_sub_f32_e32 v64, v68, v128
	v_cndmask_b32_e64 v56, v56, 0, vcc
	v_exp_f32_e32 v64, v64
	v_sub_f32_e32 v65, v69, v128
	v_add_f32_e32 v57, 0, v56
	v_cndmask_b32_e64 v58, v58, 0, s[0:1]
	v_exp_f32_e32 v65, v65
	v_sub_f32_e32 v66, v70, v128
	v_add_f32_e32 v57, v58, v57
	v_cndmask_b32_e64 v59, v59, 0, s[22:23]
	v_exp_f32_e32 v66, v66
	v_sub_f32_e32 v67, v71, v128
	v_add_f32_e32 v57, v59, v57
	v_cndmask_b32_e64 v63, v63, 0, s[24:25]
	v_exp_f32_e32 v67, v67
	v_add_f32_e32 v57, v63, v57
	v_cndmask_b32_e64 v64, v64, 0, s[26:27]
	v_add_f32_e32 v57, v64, v57
	v_cndmask_b32_e64 v65, v65, 0, s[28:29]
	v_add_f32_e32 v57, v65, v57
	v_cndmask_b32_e64 v66, v66, 0, s[30:31]
	v_add_f32_e32 v57, v66, v57
	v_cndmask_b32_e64 v67, v67, 0, s[34:35]
	v_add_f32_e32 v129, v67, v57
	v_fmac_f32_e32 v129, v130, v60
	v_max3_f32 v130, v131, v62, v61
	v_sub_f32_e32 v40, v40, v130
	v_exp_f32_e32 v40, v40
	v_sub_f32_e32 v41, v41, v130
	v_exp_f32_e32 v41, v41
	v_sub_f32_e32 v42, v42, v130
	v_exp_f32_e32 v42, v42
	v_sub_f32_e32 v43, v43, v130
	v_exp_f32_e32 v43, v43
	v_sub_f32_e32 v44, v44, v130
	v_sub_f32_e32 v61, v131, v130
	v_cndmask_b32_e64 v40, v40, 0, s[38:39]
	v_exp_f32_e32 v44, v44
	v_sub_f32_e32 v45, v45, v130
	v_exp_f32_e32 v62, v61
	v_add_f32_e32 v61, 0, v40
	v_cndmask_b32_e64 v41, v41, 0, s[40:41]
	v_exp_f32_e32 v45, v45
	v_sub_f32_e32 v46, v46, v130
	v_add_f32_e32 v61, v41, v61
	v_cndmask_b32_e64 v42, v42, 0, s[42:43]
	v_exp_f32_e32 v46, v46
	v_sub_f32_e32 v47, v47, v130
	v_add_f32_e32 v61, v42, v61
	v_cndmask_b32_e64 v43, v43, 0, s[44:45]
	v_exp_f32_e32 v47, v47
	v_add_f32_e32 v61, v43, v61
	v_cndmask_b32_e64 v44, v44, 0, s[46:47]
	v_add_f32_e32 v61, v44, v61
	v_cndmask_b32_e64 v45, v45, 0, s[48:49]
	v_add_f32_e32 v61, v45, v61
	v_cndmask_b32_e64 v46, v46, 0, s[50:51]
	v_add_f32_e32 v61, v46, v61
	v_cndmask_b32_e64 v47, v47, 0, s[52:53]
	v_cvt_pk_bf16_f32 v56, v56, v58
	v_cvt_pk_bf16_f32 v57, v59, v63
	v_cvt_pk_bf16_f32 v58, v64, v65
	v_cvt_pk_bf16_f32 v59, v66, v67
	v_add_f32_e32 v131, v47, v61
	v_cvt_pk_bf16_f32 v40, v40, v41
	v_cvt_pk_bf16_f32 v41, v42, v43
	v_cvt_pk_bf16_f32 v42, v44, v45
	v_cvt_pk_bf16_f32 v43, v46, v47
	v_pk_mul_f32 v[46:47], v[122:123], v[60:61] op_sel_hi:[1,0]
	v_pk_mul_f32 v[44:45], v[120:121], v[60:61] op_sel_hi:[1,0]
	v_fmac_f32_e32 v131, v132, v62
	s_waitcnt lgkmcnt(10)
	v_mfma_f32_16x16x32_bf16 v[64:67], v[134:137], v[56:59], v[44:47]
	s_nop 2
	v_mul_f32_e64 v46, v126, v62
	v_mul_f32_e64 v47, v127, v62
	v_pk_mul_f32 v[44:45], v[124:125], v[62:63] op_sel_hi:[1,0]
	s_nop 1
	v_mfma_f32_16x16x32_bf16 v[68:71], v[134:137], v[40:43], v[44:47]
	s_nop 2
	v_mul_f32_e64 v46, v106, v60
	v_mul_f32_e64 v47, v107, v60
	v_pk_mul_f32 v[44:45], v[104:105], v[60:61] op_sel_hi:[1,0]
	s_waitcnt lgkmcnt(8)
	s_nop 0
	v_mfma_f32_16x16x32_bf16 v[104:107], v[138:141], v[56:59], v[44:47]
	s_nop 2
	v_mul_f32_e64 v46, v110, v62
	v_mul_f32_e64 v47, v111, v62
	v_pk_mul_f32 v[44:45], v[108:109], v[62:63] op_sel_hi:[1,0]
	s_nop 1
	v_mfma_f32_16x16x32_bf16 v[108:111], v[138:141], v[40:43], v[44:47]
	s_nop 2
	v_mul_f32_e64 v46, v114, v60
	v_mul_f32_e64 v47, v115, v60
	v_pk_mul_f32 v[44:45], v[112:113], v[60:61] op_sel_hi:[1,0]
	s_waitcnt lgkmcnt(6)
	s_nop 0
	v_mfma_f32_16x16x32_bf16 v[112:115], v[176:179], v[56:59], v[44:47]
	s_nop 2
	v_mul_f32_e64 v46, v118, v62
	v_mul_f32_e64 v47, v119, v62
	v_pk_mul_f32 v[44:45], v[116:117], v[62:63] op_sel_hi:[1,0]
	s_nop 1
	v_mfma_f32_16x16x32_bf16 v[116:119], v[176:179], v[40:43], v[44:47]
	s_nop 2
	v_mul_f32_e64 v46, v98, v60
	v_mul_f32_e64 v47, v99, v60
	v_pk_mul_f32 v[44:45], v[96:97], v[60:61] op_sel_hi:[1,0]
	s_waitcnt lgkmcnt(4)
	s_nop 0
	v_mfma_f32_16x16x32_bf16 v[120:123], v[188:191], v[56:59], v[44:47]
	v_or_b32_e32 v56, 0x50, v166
	v_add_u32_e32 v56, s76, v56
	s_nop 0
	v_pk_mul_f32 v[46:47], v[90:91], v[62:63] op_sel_hi:[1,0]
	v_pk_mul_f32 v[44:45], v[88:89], v[62:63] op_sel_hi:[1,0]
	s_nop 1
	v_mfma_f32_16x16x32_bf16 v[124:127], v[188:191], v[40:43], v[44:47]
	v_add_u32_e32 v40, 64, v155
	v_add_u32_e32 v40, s76, v40
	v_med3_i32 v40, v40, 0, s75
	v_add_u32_e32 v40, s74, v40
	v_ashrrev_i32_e32 v41, 31, v40
	v_lshlrev_b64 v[40:41], 9, v[40:41]
	v_lshl_add_u64 v[40:41], v[164:165], 0, v[40:41]
	global_load_dwordx4 v[72:75], v[40:41], off
	v_add_u32_e32 v40, 64, v172
	v_add_u32_e32 v40, s76, v40
	v_med3_i32 v40, v40, 0, s75
	v_add_u32_e32 v40, s74, v40
	v_ashrrev_i32_e32 v41, 31, v40
	v_lshlrev_b64 v[40:41], 9, v[40:41]
	v_lshl_add_u64 v[40:41], v[164:165], 0, v[40:41]
	global_load_dwordx4 v[80:83], v[40:41], off
	v_add_u32_e32 v40, 64, v173
	v_add_u32_e32 v40, s76, v40
	v_med3_i32 v40, v40, 0, s75
	v_add_u32_e32 v40, s74, v40
	v_ashrrev_i32_e32 v41, 31, v40
	v_lshlrev_b64 v[40:41], 9, v[40:41]
	v_lshl_add_u64 v[40:41], v[164:165], 0, v[40:41]
	global_load_dwordx4 v[88:91], v[40:41], off
	v_add_u32_e32 v40, 64, v182
	v_add_u32_e32 v40, s76, v40
	v_med3_i32 v40, v40, 0, s75
	v_add_u32_e32 v40, s74, v40
	v_ashrrev_i32_e32 v41, 31, v40
	v_lshlrev_b64 v[40:41], 9, v[40:41]
	v_lshl_add_u64 v[40:41], v[164:165], 0, v[40:41]
	global_load_dwordx4 v[96:99], v[40:41], off
	v_or_b32_e32 v40, 64, v166
	v_add_u32_e32 v40, s76, v40
	v_med3_i32 v40, v40, 0, s75
	v_add_u32_e32 v40, s74, v40
	v_ashrrev_i32_e32 v41, 31, v40
	v_med3_i32 v56, v56, 0, s75
	v_add_u32_e32 v56, s74, v56
	v_ashrrev_i32_e32 v57, 31, v56
	v_lshlrev_b64 v[40:41], 9, v[40:41]
	v_lshlrev_b64 v[56:57], 9, v[56:57]
	v_lshl_add_u64 v[40:41], s[68:69], 0, v[40:41]
	v_lshl_add_u64 v[56:57], s[68:69], 0, v[56:57]
	v_lshl_add_u64 v[44:45], v[40:41], 0, v[158:159]
	v_lshl_add_u64 v[60:61], v[56:57], 0, v[158:159]
	global_load_dwordx4 v[40:43], v[44:45], off
	s_nop 0
	global_load_dwordx4 v[44:47], v[44:45], off offset:64
	s_nop 0
	global_load_dwordx4 v[56:59], v[60:61], off
	s_nop 0
	global_load_dwordx4 v[60:63], v[60:61], off offset:64
	ds_read_b64_tr_b16 v[136:137], v169 offset:2304
	ds_read_b64_tr_b16 v[134:135], v169
	ds_read_b64_tr_b16 v[138:139], v169 offset:32
	ds_read_b64_tr_b16 v[140:141], v169 offset:2336
	ds_read_b64_tr_b16 v[176:177], v169 offset:64
	ds_read_b64_tr_b16 v[178:179], v169 offset:2368
	ds_read_b64_tr_b16 v[188:189], v169 offset:96
	ds_read_b64_tr_b16 v[190:191], v169 offset:2400
	s_waitcnt vmcnt(15)
	ds_write_b128 v241, v[76:79] offset:4608
	s_waitcnt vmcnt(14)
	ds_write_b128 v242, v[84:87] offset:4608
	s_waitcnt vmcnt(13)
	ds_write_b128 v243, v[92:95] offset:4608
	s_waitcnt vmcnt(12)
	ds_write_b128 v244, v[100:103] offset:4608
	v_mfma_f32_16x16x32_bf16 v[76:79], v[16:19], v[4:7], 0
	v_mfma_f32_16x16x32_bf16 v[16:19], v[16:19], v[12:15], 0
	v_mfma_f32_16x16x32_bf16 v[76:79], v[20:23], v[8:11], v[76:79]
	v_mfma_f32_16x16x32_bf16 v[84:87], v[24:27], v[4:7], 0
	v_mfma_f32_16x16x32_bf16 v[16:19], v[20:23], v[0:3], v[16:19]
	v_mfma_f32_16x16x32_bf16 v[20:23], v[24:27], v[12:15], 0
	v_sub_u32_e32 v24, v192, v147
	v_add_u32_e32 v27, 1, v24
	s_nop 2
	v_max_f32_e32 v26, v76, v76
	v_cmp_gt_u32_e64 s[0:1], v27, v146
	v_cmp_gt_u32_e32 vcc, v24, v146
	v_max_f32_e32 v26, 0xf149f2ca, v26
	v_cndmask_b32_e64 v27, v77, v246, s[0:1]
	v_cndmask_b32_e32 v26, v26, v246, vcc
	v_mfma_f32_16x16x32_bf16 v[84:87], v[28:31], v[8:11], v[84:87]
	v_max_f32_e32 v26, v26, v27
	v_add_u32_e32 v27, 2, v24
	v_cmp_gt_u32_e64 s[22:23], v27, v146
	v_mfma_f32_16x16x32_bf16 v[20:23], v[28:31], v[0:3], v[20:23]
	v_add_u32_e32 v28, 3, v24
	v_cmp_gt_u32_e64 s[24:25], v28, v146
	v_cndmask_b32_e64 v27, v78, v246, s[22:23]
	v_sub_u32_e32 v25, v192, v148
	v_cndmask_b32_e64 v28, v79, v246, s[24:25]
	v_max3_f32 v26, v26, v27, v28
	v_add_u32_e32 v27, 16, v24
	v_add_u32_e32 v28, 17, v24
	v_cmp_gt_u32_e64 s[26:27], v27, v146
	v_cmp_gt_u32_e64 s[28:29], v28, v146
	v_cmp_gt_u32_e64 s[38:39], v25, v145
	v_cndmask_b32_e64 v27, v84, v246, s[26:27]
	v_cndmask_b32_e64 v28, v85, v246, s[28:29]
	v_max3_f32 v26, v26, v27, v28
	v_add_u32_e32 v27, 18, v24
	v_add_u32_e32 v24, 19, v24
	v_cmp_gt_u32_e64 s[30:31], v27, v146
	v_cmp_gt_u32_e64 s[34:35], v24, v146
	v_add_u32_e32 v28, 3, v25
	v_cndmask_b32_e64 v27, v86, v246, s[30:31]
	v_cndmask_b32_e64 v24, v87, v246, s[34:35]
	v_max3_f32 v24, v26, v27, v24
	v_add_u32_e32 v27, 1, v25
	v_max_f32_e32 v26, v16, v16
	v_cmp_gt_u32_e64 s[40:41], v27, v145
	v_max_f32_e32 v26, 0xf149f2ca, v26
	v_cndmask_b32_e64 v26, v26, v246, s[38:39]
	v_cndmask_b32_e64 v27, v17, v246, s[40:41]
	v_max_f32_e32 v26, v26, v27
	v_add_u32_e32 v27, 2, v25
	v_cmp_gt_u32_e64 s[42:43], v27, v145
	v_cmp_gt_u32_e64 s[44:45], v28, v145
	s_nop 0
	v_cndmask_b32_e64 v27, v18, v246, s[42:43]
	v_cndmask_b32_e64 v28, v19, v246, s[44:45]
	v_max3_f32 v26, v26, v27, v28
	v_add_u32_e32 v27, 16, v25
	v_add_u32_e32 v28, 17, v25
	v_cmp_gt_u32_e64 s[46:47], v27, v145
	v_cmp_gt_u32_e64 s[48:49], v28, v145
	s_nop 0
	v_cndmask_b32_e64 v27, v20, v246, s[46:47]
	v_cndmask_b32_e64 v28, v21, v246, s[48:49]
	v_max3_f32 v26, v26, v27, v28
	v_add_u32_e32 v27, 18, v25
	v_add_u32_e32 v25, 19, v25
	v_cmp_gt_u32_e64 s[50:51], v27, v145
	v_cmp_gt_u32_e64 s[52:53], v25, v145
	s_nop 0
	v_cndmask_b32_e64 v27, v22, v246, s[50:51]
	v_cndmask_b32_e64 v25, v23, v246, s[52:53]
	v_max3_f32 v25, v26, v27, v25
	v_mov_b32_e32 v26, v24
	v_mov_b32_e32 v27, v24
	s_nop 1
	v_permlane32_swap_b32_e32 v26, v27
	v_max3_f32 v24, v24, v26, v27
	v_mov_b32_e32 v26, v25
	v_mov_b32_e32 v27, v25
	s_nop 1
	v_permlane32_swap_b32_e32 v26, v27
	v_max3_f32 v25, v25, v26, v27
	v_mov_b32_e32 v26, v24
	v_mov_b32_e32 v27, v24
	s_nop 1
	v_permlane16_swap_b32_e32 v26, v27
	v_max_f32_e32 v24, v24, v26
	v_mov_b32_e32 v26, v25
	v_mov_b32_e32 v28, v25
	v_max3_f32 v132, v128, v24, v27
	s_nop 0
	v_permlane16_swap_b32_e32 v26, v28
	v_sub_f32_e32 v24, v128, v132
	v_exp_f32_e32 v92, v24
	v_sub_f32_e32 v24, v76, v132
	v_max_f32_e32 v29, v25, v26
	v_exp_f32_e32 v24, v24
	v_sub_f32_e32 v26, v77, v132
	v_exp_f32_e32 v26, v26
	v_sub_f32_e32 v27, v78, v132
	v_exp_f32_e32 v27, v27
	v_sub_f32_e32 v30, v79, v132
	v_exp_f32_e32 v30, v30
	v_sub_f32_e32 v31, v84, v132
	v_cndmask_b32_e64 v24, v24, 0, vcc
	v_exp_f32_e32 v31, v31
	v_sub_f32_e32 v76, v85, v132
	v_add_f32_e32 v25, 0, v24
	v_cndmask_b32_e64 v26, v26, 0, s[0:1]
	v_exp_f32_e32 v76, v76
	v_sub_f32_e32 v77, v86, v132
	v_add_f32_e32 v25, v26, v25
	v_cndmask_b32_e64 v27, v27, 0, s[22:23]
	v_exp_f32_e32 v77, v77
	v_sub_f32_e32 v78, v87, v132
	v_add_f32_e32 v25, v27, v25
	v_cndmask_b32_e64 v30, v30, 0, s[24:25]
	v_exp_f32_e32 v78, v78
	v_add_f32_e32 v25, v30, v25
	v_cndmask_b32_e64 v31, v31, 0, s[26:27]
	v_add_f32_e32 v25, v31, v25
	v_cndmask_b32_e64 v76, v76, 0, s[28:29]
	v_add_f32_e32 v25, v76, v25
	v_cndmask_b32_e64 v77, v77, 0, s[30:31]
	v_add_f32_e32 v25, v77, v25
	v_cndmask_b32_e64 v78, v78, 0, s[34:35]
	v_add_f32_e32 v128, v78, v25
	v_fmac_f32_e32 v128, v129, v92
	v_max3_f32 v129, v130, v29, v28
	v_sub_f32_e32 v16, v16, v129
	v_exp_f32_e32 v16, v16
	v_sub_f32_e32 v17, v17, v129
	v_exp_f32_e32 v17, v17
	v_sub_f32_e32 v18, v18, v129
	v_exp_f32_e32 v18, v18
	v_sub_f32_e32 v19, v19, v129
	v_exp_f32_e32 v19, v19
	v_sub_f32_e32 v20, v20, v129
	v_sub_f32_e32 v28, v130, v129
	v_cndmask_b32_e64 v16, v16, 0, s[38:39]
	v_exp_f32_e32 v20, v20
	v_sub_f32_e32 v21, v21, v129
	v_cvt_pk_bf16_f32 v24, v24, v26
	v_cvt_pk_bf16_f32 v26, v31, v76
	v_exp_f32_e32 v76, v28
	v_add_f32_e32 v28, 0, v16
	v_cndmask_b32_e64 v17, v17, 0, s[40:41]
	v_exp_f32_e32 v21, v21
	v_sub_f32_e32 v22, v22, v129
	v_add_f32_e32 v28, v17, v28
	v_cndmask_b32_e64 v18, v18, 0, s[42:43]
	v_exp_f32_e32 v22, v22
	v_sub_f32_e32 v23, v23, v129
	v_add_f32_e32 v28, v18, v28
	v_cndmask_b32_e64 v19, v19, 0, s[44:45]
	v_exp_f32_e32 v23, v23
	v_add_f32_e32 v28, v19, v28
	v_cndmask_b32_e64 v20, v20, 0, s[46:47]
	v_add_f32_e32 v28, v20, v28
	v_cndmask_b32_e64 v21, v21, 0, s[48:49]
	v_add_f32_e32 v28, v21, v28
	v_cndmask_b32_e64 v22, v22, 0, s[50:51]
	v_add_f32_e32 v28, v22, v28
	v_cndmask_b32_e64 v23, v23, 0, s[52:53]
	v_cvt_pk_bf16_f32 v25, v27, v30
	v_cvt_pk_bf16_f32 v27, v77, v78
	v_add_f32_e32 v130, v23, v28
	v_cvt_pk_bf16_f32 v28, v16, v17
	v_cvt_pk_bf16_f32 v29, v18, v19
	v_pk_mul_f32 v[18:19], v[66:67], v[92:93] op_sel_hi:[1,0]
	v_pk_mul_f32 v[16:17], v[64:65], v[92:93] op_sel_hi:[1,0]
	v_pk_mul_f32 v[66:67], v[106:107], v[92:93] op_sel_hi:[1,0]
	v_pk_mul_f32 v[64:65], v[104:105], v[92:93] op_sel_hi:[1,0]
	v_cvt_pk_bf16_f32 v30, v20, v21
	v_cvt_pk_bf16_f32 v31, v22, v23
	s_waitcnt lgkmcnt(8)
	v_mfma_f32_16x16x32_bf16 v[104:107], v[138:141], v[24:27], v[64:67]
	v_fmac_f32_e32 v130, v131, v76
	v_pk_mul_f32 v[22:23], v[70:71], v[76:77] op_sel_hi:[1,0]
	v_pk_mul_f32 v[20:21], v[68:69], v[76:77] op_sel_hi:[1,0]
	v_pk_mul_f32 v[66:67], v[110:111], v[76:77] op_sel_hi:[1,0]
	v_pk_mul_f32 v[64:65], v[108:109], v[76:77] op_sel_hi:[1,0]
	v_mfma_f32_16x16x32_bf16 v[16:19], v[134:137], v[24:27], v[16:19]
	s_nop 0
	v_mfma_f32_16x16x32_bf16 v[108:111], v[138:141], v[28:31], v[64:67]
	s_nop 2
	v_mul_f32_e64 v66, v114, v92
	v_mul_f32_e64 v67, v115, v92
	v_pk_mul_f32 v[64:65], v[112:113], v[92:93] op_sel_hi:[1,0]
	v_mfma_f32_16x16x32_bf16 v[20:23], v[134:137], v[28:31], v[20:23]
	s_waitcnt lgkmcnt(6)
	v_mfma_f32_16x16x32_bf16 v[112:115], v[176:179], v[24:27], v[64:67]
	s_nop 2
	v_mul_f32_e64 v66, v118, v76
	v_mul_f32_e64 v67, v119, v76
	v_pk_mul_f32 v[64:65], v[116:117], v[76:77] op_sel_hi:[1,0]
	s_nop 1
	v_mfma_f32_16x16x32_bf16 v[116:119], v[176:179], v[28:31], v[64:67]
	s_nop 2
	v_mul_f32_e64 v66, v122, v92
	v_mul_f32_e64 v67, v123, v92
	v_pk_mul_f32 v[64:65], v[120:121], v[92:93] op_sel_hi:[1,0]
	s_waitcnt lgkmcnt(4)
	s_nop 0
	v_mfma_f32_16x16x32_bf16 v[120:123], v[188:191], v[24:27], v[64:67]
	v_mul_f32_e64 v26, v126, v76
	v_mul_f32_e64 v27, v127, v76
	v_pk_mul_f32 v[24:25], v[124:125], v[76:77] op_sel_hi:[1,0]
	v_or_b32_e32 v64, 0x70, v166
	s_nop 0
	v_mfma_f32_16x16x32_bf16 v[124:127], v[188:191], v[28:31], v[24:27]
	v_add_u32_e32 v64, s76, v64
	s_nop 0
	s_nop 0
	v_add_u32_e32 v24, s76, v196
	v_med3_i32 v24, v24, 0, s75
	v_add_u32_e32 v24, s74, v24
	v_ashrrev_i32_e32 v25, 31, v24
	v_lshlrev_b64 v[24:25], 9, v[24:25]
	v_lshl_add_u64 v[24:25], v[164:165], 0, v[24:25]
	global_load_dwordx4 v[76:79], v[24:25], off
	v_add_u32_e32 v24, s76, v168
	v_med3_i32 v24, v24, 0, s75
	v_add_u32_e32 v24, s74, v24
	v_ashrrev_i32_e32 v25, 31, v24
	v_lshlrev_b64 v[24:25], 9, v[24:25]
	v_lshl_add_u64 v[24:25], v[164:165], 0, v[24:25]
	global_load_dwordx4 v[84:87], v[24:25], off
	v_add_u32_e32 v24, s76, v193
	v_med3_i32 v24, v24, 0, s75
	v_add_u32_e32 v24, s74, v24
	v_ashrrev_i32_e32 v25, 31, v24
	v_lshlrev_b64 v[24:25], 9, v[24:25]
	v_lshl_add_u64 v[24:25], v[164:165], 0, v[24:25]
	global_load_dwordx4 v[92:95], v[24:25], off
	v_add_u32_e32 v24, s76, v194
	v_med3_i32 v24, v24, 0, s75
	v_add_u32_e32 v24, s74, v24
	v_ashrrev_i32_e32 v25, 31, v24
	v_lshlrev_b64 v[24:25], 9, v[24:25]
	v_lshl_add_u64 v[24:25], v[164:165], 0, v[24:25]
	global_load_dwordx4 v[100:103], v[24:25], off
	v_or_b32_e32 v24, 0x60, v166
	v_add_u32_e32 v24, s76, v24
	v_med3_i32 v24, v24, 0, s75
	v_add_u32_e32 v24, s74, v24
	v_ashrrev_i32_e32 v25, 31, v24
	v_med3_i32 v64, v64, 0, s75
	v_add_u32_e32 v64, s74, v64
	v_ashrrev_i32_e32 v65, 31, v64
	v_lshlrev_b64 v[24:25], 9, v[24:25]
	v_lshlrev_b64 v[64:65], 9, v[64:65]
	v_lshl_add_u64 v[24:25], s[68:69], 0, v[24:25]
	v_lshl_add_u64 v[64:65], s[68:69], 0, v[64:65]
	v_lshl_add_u64 v[28:29], v[24:25], 0, v[158:159]
	v_lshl_add_u64 v[68:69], v[64:65], 0, v[158:159]
	global_load_dwordx4 v[24:27], v[28:29], off
	s_nop 0
	global_load_dwordx4 v[28:31], v[28:29], off offset:64
	s_nop 0
	global_load_dwordx4 v[64:67], v[68:69], off
	s_nop 0
	global_load_dwordx4 v[68:71], v[68:69], off offset:64
	ds_read_b64_tr_b16 v[136:137], v169 offset:6912
	ds_read_b64_tr_b16 v[134:135], v169 offset:4608
	ds_read_b64_tr_b16 v[138:139], v169 offset:4640
	ds_read_b64_tr_b16 v[140:141], v169 offset:6944
	ds_read_b64_tr_b16 v[176:177], v169 offset:4672
	ds_read_b64_tr_b16 v[178:179], v169 offset:6976
	ds_read_b64_tr_b16 v[188:189], v169 offset:4704
	ds_read_b64_tr_b16 v[190:191], v169 offset:7008
	s_waitcnt vmcnt(15)
	ds_write_b128 v241, v[72:75]
	s_waitcnt vmcnt(14)
	ds_write_b128 v242, v[80:83]
	s_waitcnt vmcnt(13)
	ds_write_b128 v243, v[88:91]
	s_waitcnt vmcnt(12)
	ds_write_b128 v244, v[96:99]
	v_mfma_f32_16x16x32_bf16 v[72:75], v[32:35], v[4:7], 0
	v_mfma_f32_16x16x32_bf16 v[32:35], v[32:35], v[12:15], 0
	v_mfma_f32_16x16x32_bf16 v[72:75], v[36:39], v[8:11], v[72:75]
	v_mfma_f32_16x16x32_bf16 v[80:83], v[48:51], v[4:7], 0
	v_mfma_f32_16x16x32_bf16 v[32:35], v[36:39], v[0:3], v[32:35]
	v_mfma_f32_16x16x32_bf16 v[36:39], v[48:51], v[12:15], 0
	v_sub_u32_e32 v48, v197, v147
	v_add_u32_e32 v51, 1, v48
	s_nop 2
	v_max_f32_e32 v50, v72, v72
	v_cmp_gt_u32_e64 s[0:1], v51, v146
	v_cmp_gt_u32_e32 vcc, v48, v146
	v_max_f32_e32 v50, 0xf149f2ca, v50
	v_cndmask_b32_e64 v51, v73, v246, s[0:1]
	v_cndmask_b32_e32 v50, v50, v246, vcc
	v_mfma_f32_16x16x32_bf16 v[80:83], v[52:55], v[8:11], v[80:83]
	v_max_f32_e32 v50, v50, v51
	v_add_u32_e32 v51, 2, v48
	v_cmp_gt_u32_e64 s[22:23], v51, v146
	v_mfma_f32_16x16x32_bf16 v[36:39], v[52:55], v[0:3], v[36:39]
	v_add_u32_e32 v52, 3, v48
	v_cmp_gt_u32_e64 s[24:25], v52, v146
	v_cndmask_b32_e64 v51, v74, v246, s[22:23]
	v_sub_u32_e32 v49, v197, v148
	v_cndmask_b32_e64 v52, v75, v246, s[24:25]
	v_max3_f32 v50, v50, v51, v52
	v_add_u32_e32 v51, 16, v48
	v_add_u32_e32 v52, 17, v48
	v_cmp_gt_u32_e64 s[26:27], v51, v146
	v_cmp_gt_u32_e64 s[28:29], v52, v146
	v_cmp_gt_u32_e64 s[38:39], v49, v145
	v_cndmask_b32_e64 v51, v80, v246, s[26:27]
	v_cndmask_b32_e64 v52, v81, v246, s[28:29]
	v_max3_f32 v50, v50, v51, v52
	v_add_u32_e32 v51, 18, v48
	v_add_u32_e32 v48, 19, v48
	v_cmp_gt_u32_e64 s[30:31], v51, v146
	v_cmp_gt_u32_e64 s[34:35], v48, v146
	v_add_u32_e32 v52, 3, v49
	v_cndmask_b32_e64 v51, v82, v246, s[30:31]
	v_cndmask_b32_e64 v48, v83, v246, s[34:35]
	v_max3_f32 v48, v50, v51, v48
	v_add_u32_e32 v51, 1, v49
	v_max_f32_e32 v50, v32, v32
	v_cmp_gt_u32_e64 s[40:41], v51, v145
	v_max_f32_e32 v50, 0xf149f2ca, v50
	v_cndmask_b32_e64 v50, v50, v246, s[38:39]
	v_cndmask_b32_e64 v51, v33, v246, s[40:41]
	v_max_f32_e32 v50, v50, v51
	v_add_u32_e32 v51, 2, v49
	v_cmp_gt_u32_e64 s[42:43], v51, v145
	v_cmp_gt_u32_e64 s[44:45], v52, v145
	s_nop 0
	v_cndmask_b32_e64 v51, v34, v246, s[42:43]
	v_cndmask_b32_e64 v52, v35, v246, s[44:45]
	v_max3_f32 v50, v50, v51, v52
	v_add_u32_e32 v51, 16, v49
	v_add_u32_e32 v52, 17, v49
	v_cmp_gt_u32_e64 s[46:47], v51, v145
	v_cmp_gt_u32_e64 s[48:49], v52, v145
	s_nop 0
	v_cndmask_b32_e64 v51, v36, v246, s[46:47]
	v_cndmask_b32_e64 v52, v37, v246, s[48:49]
	v_max3_f32 v50, v50, v51, v52
	v_add_u32_e32 v51, 18, v49
	v_add_u32_e32 v49, 19, v49
	v_cmp_gt_u32_e64 s[50:51], v51, v145
	v_cmp_gt_u32_e64 s[52:53], v49, v145
	s_nop 0
	v_cndmask_b32_e64 v51, v38, v246, s[50:51]
	v_cndmask_b32_e64 v49, v39, v246, s[52:53]
	v_max3_f32 v49, v50, v51, v49
	v_mov_b32_e32 v50, v48
	v_mov_b32_e32 v51, v48
	s_nop 1
	v_permlane32_swap_b32_e32 v50, v51
	v_max3_f32 v48, v48, v50, v51
	v_mov_b32_e32 v50, v49
	v_mov_b32_e32 v51, v49
	s_nop 1
	v_permlane32_swap_b32_e32 v50, v51
	v_max3_f32 v49, v49, v50, v51
	v_mov_b32_e32 v50, v48
	v_mov_b32_e32 v51, v48
	s_nop 1
	v_permlane16_swap_b32_e32 v50, v51
	v_max_f32_e32 v48, v48, v50
	v_mov_b32_e32 v50, v49
	v_mov_b32_e32 v53, v49
	v_max3_f32 v131, v132, v48, v51
	s_nop 0
	v_permlane16_swap_b32_e32 v50, v53
	v_sub_f32_e32 v48, v132, v131
	v_exp_f32_e32 v52, v48
	v_sub_f32_e32 v48, v72, v131
	v_max_f32_e32 v54, v49, v50
	v_exp_f32_e32 v48, v48
	v_sub_f32_e32 v50, v73, v131
	v_exp_f32_e32 v50, v50
	v_sub_f32_e32 v51, v74, v131
	v_exp_f32_e32 v51, v51
	v_sub_f32_e32 v55, v75, v131
	v_exp_f32_e32 v55, v55
	v_sub_f32_e32 v72, v80, v131
	v_cndmask_b32_e64 v48, v48, 0, vcc
	v_exp_f32_e32 v72, v72
	v_sub_f32_e32 v73, v81, v131
	v_add_f32_e32 v49, 0, v48
	v_cndmask_b32_e64 v50, v50, 0, s[0:1]
	v_exp_f32_e32 v73, v73
	v_sub_f32_e32 v74, v82, v131
	v_add_f32_e32 v49, v50, v49
	v_cndmask_b32_e64 v51, v51, 0, s[22:23]
	v_exp_f32_e32 v74, v74
	v_sub_f32_e32 v75, v83, v131
	v_add_f32_e32 v49, v51, v49
	v_cndmask_b32_e64 v55, v55, 0, s[24:25]
	v_exp_f32_e32 v75, v75
	v_add_f32_e32 v49, v55, v49
	v_cndmask_b32_e64 v72, v72, 0, s[26:27]
	v_add_f32_e32 v49, v72, v49
	v_cndmask_b32_e64 v73, v73, 0, s[28:29]
	v_add_f32_e32 v49, v73, v49
	v_cndmask_b32_e64 v74, v74, 0, s[30:31]
	v_add_f32_e32 v49, v74, v49
	v_cndmask_b32_e64 v75, v75, 0, s[34:35]
	v_add_f32_e32 v132, v75, v49
	v_fmac_f32_e32 v132, v128, v52
	v_max3_f32 v128, v129, v54, v53
	v_sub_f32_e32 v32, v32, v128
	v_exp_f32_e32 v32, v32
	v_sub_f32_e32 v33, v33, v128
	v_exp_f32_e32 v33, v33
	v_sub_f32_e32 v34, v34, v128
	v_exp_f32_e32 v34, v34
	v_sub_f32_e32 v35, v35, v128
	v_exp_f32_e32 v35, v35
	v_sub_f32_e32 v36, v36, v128
	v_sub_f32_e32 v53, v129, v128
	v_cndmask_b32_e64 v32, v32, 0, s[38:39]
	v_exp_f32_e32 v36, v36
	v_sub_f32_e32 v37, v37, v128
	v_exp_f32_e32 v54, v53
	v_add_f32_e32 v53, 0, v32
	v_cndmask_b32_e64 v33, v33, 0, s[40:41]
	v_exp_f32_e32 v37, v37
	v_add_f32_e32 v53, v33, v53
	v_cndmask_b32_e64 v34, v34, 0, s[42:43]
	v_add_f32_e32 v53, v34, v53
	v_cndmask_b32_e64 v35, v35, 0, s[44:45]
	v_cvt_pk_bf16_f32 v49, v51, v55
	v_add_f32_e32 v53, v35, v53
	v_cndmask_b32_e64 v55, v36, 0, s[46:47]
	v_add_f32_e32 v36, v55, v53
	v_cndmask_b32_e64 v53, v37, 0, s[48:49]
	v_sub_f32_e32 v37, v38, v128
	v_exp_f32_e32 v37, v37
	v_cvt_pk_bf16_f32 v48, v48, v50
	v_cvt_pk_bf16_f32 v50, v72, v73
	v_add_f32_e32 v36, v53, v36
	v_cndmask_b32_e64 v72, v37, 0, s[50:51]
	v_sub_f32_e32 v37, v39, v128
	v_exp_f32_e32 v37, v37
	v_cvt_pk_bf16_f32 v51, v74, v75
	v_add_f32_e32 v36, v72, v36
	v_pk_mul_f32 v[18:19], v[18:19], v[52:53] op_sel_hi:[1,0]
	v_cndmask_b32_e64 v39, v37, 0, s[52:53]
	v_pk_mul_f32 v[16:17], v[16:17], v[52:53] op_sel_hi:[1,0]
	v_add_f32_e32 v129, v39, v36
	v_cvt_pk_bf16_f32 v36, v32, v33
	v_cvt_pk_bf16_f32 v37, v34, v35
	v_cvt_pk_bf16_f32 v38, v55, v53
	v_cvt_pk_bf16_f32 v39, v72, v39
	s_waitcnt lgkmcnt(10)
	v_mfma_f32_16x16x32_bf16 v[32:35], v[134:137], v[48:51], v[16:19]
	v_fmac_f32_e32 v129, v130, v54
	s_nop 1
	v_pk_mul_f32 v[18:19], v[22:23], v[54:55] op_sel_hi:[1,0]
	v_pk_mul_f32 v[16:17], v[20:21], v[54:55] op_sel_hi:[1,0]
	s_nop 1
	v_mfma_f32_16x16x32_bf16 v[96:99], v[134:137], v[36:39], v[16:19]
	s_nop 2
	v_mul_f32_e64 v18, v106, v52
	v_mul_f32_e64 v19, v107, v52
	v_pk_mul_f32 v[16:17], v[104:105], v[52:53] op_sel_hi:[1,0]
	s_waitcnt lgkmcnt(8)
	s_nop 0
	v_mfma_f32_16x16x32_bf16 v[104:107], v[138:141], v[48:51], v[16:19]
	s_nop 2
	v_mul_f32_e64 v18, v110, v54
	v_mul_f32_e64 v19, v111, v54
	v_pk_mul_f32 v[16:17], v[108:109], v[54:55] op_sel_hi:[1,0]
	s_nop 1
	v_mfma_f32_16x16x32_bf16 v[108:111], v[138:141], v[36:39], v[16:19]
	s_nop 2
	v_mul_f32_e64 v18, v114, v52
	v_mul_f32_e64 v19, v115, v52
	v_pk_mul_f32 v[16:17], v[112:113], v[52:53] op_sel_hi:[1,0]
	s_waitcnt lgkmcnt(6)
	s_nop 0
	v_mfma_f32_16x16x32_bf16 v[112:115], v[176:179], v[48:51], v[16:19]
	s_nop 2
	v_mul_f32_e64 v18, v118, v54
	v_mul_f32_e64 v19, v119, v54
	v_pk_mul_f32 v[16:17], v[116:117], v[54:55] op_sel_hi:[1,0]
	s_nop 1
	v_mfma_f32_16x16x32_bf16 v[116:119], v[176:179], v[36:39], v[16:19]
	s_nop 2
	v_mul_f32_e64 v18, v122, v52
	v_mul_f32_e64 v19, v123, v52
	v_pk_mul_f32 v[16:17], v[120:121], v[52:53] op_sel_hi:[1,0]
	s_waitcnt lgkmcnt(4)
	s_nop 0
	v_mfma_f32_16x16x32_bf16 v[120:123], v[188:191], v[48:51], v[16:19]
	v_or_b32_e32 v48, 0x90, v166
	v_add_u32_e32 v48, s76, v48
	s_nop 0
	v_pk_mul_f32 v[18:19], v[126:127], v[54:55] op_sel_hi:[1,0]
	v_pk_mul_f32 v[16:17], v[124:125], v[54:55] op_sel_hi:[1,0]
	s_nop 1
	v_mfma_f32_16x16x32_bf16 v[124:127], v[188:191], v[36:39], v[16:19]
	s_nop 2
	v_add_u32_e32 v16, 0x80, v149
	v_med3_i32 v16, v16, 0, s75
	v_add_u32_e32 v16, s74, v16
	v_ashrrev_i32_e32 v17, 31, v16
	v_lshlrev_b64 v[16:17], 9, v[16:17]
	v_lshl_add_u64 v[16:17], v[164:165], 0, v[16:17]
	global_load_dwordx4 v[36:39], v[16:17], off
	v_add_u32_e32 v16, 0x80, v150
	v_med3_i32 v16, v16, 0, s75
	v_add_u32_e32 v16, s74, v16
	v_ashrrev_i32_e32 v17, 31, v16
	v_lshlrev_b64 v[16:17], 9, v[16:17]
	v_lshl_add_u64 v[16:17], v[164:165], 0, v[16:17]
	global_load_dwordx4 v[72:75], v[16:17], off
	v_add_u32_e32 v16, 0x80, v151
	v_med3_i32 v16, v16, 0, s75
	v_add_u32_e32 v16, s74, v16
	v_ashrrev_i32_e32 v17, 31, v16
	v_lshlrev_b64 v[16:17], 9, v[16:17]
	v_lshl_add_u64 v[16:17], v[164:165], 0, v[16:17]
	global_load_dwordx4 v[80:83], v[16:17], off
	v_add_u32_e32 v16, 0x80, v252
	v_med3_i32 v16, v16, 0, s75
	v_add_u32_e32 v16, s74, v16
	v_ashrrev_i32_e32 v17, 31, v16
	v_lshlrev_b64 v[16:17], 9, v[16:17]
	v_lshl_add_u64 v[16:17], v[164:165], 0, v[16:17]
	global_load_dwordx4 v[88:91], v[16:17], off
	v_or_b32_e32 v16, 0x80, v166
	v_add_u32_e32 v16, s76, v16
	v_med3_i32 v16, v16, 0, s75
	v_add_u32_e32 v16, s74, v16
	v_ashrrev_i32_e32 v17, 31, v16
	v_med3_i32 v48, v48, 0, s75
	v_add_u32_e32 v48, s74, v48
	v_ashrrev_i32_e32 v49, 31, v48
	v_lshlrev_b64 v[16:17], 9, v[16:17]
	v_lshlrev_b64 v[48:49], 9, v[48:49]
	v_lshl_add_u64 v[16:17], s[68:69], 0, v[16:17]
	v_lshl_add_u64 v[48:49], s[68:69], 0, v[48:49]
	v_lshl_add_u64 v[20:21], v[16:17], 0, v[158:159]
	v_lshl_add_u64 v[52:53], v[48:49], 0, v[158:159]
	global_load_dwordx4 v[16:19], v[20:21], off
	s_nop 0
	global_load_dwordx4 v[20:23], v[20:21], off offset:64
	s_nop 0
	global_load_dwordx4 v[48:51], v[52:53], off
	s_nop 0
	global_load_dwordx4 v[52:55], v[52:53], off offset:64
	ds_read_b64_tr_b16 v[136:137], v169 offset:2304
	ds_read_b64_tr_b16 v[134:135], v169
	ds_read_b64_tr_b16 v[138:139], v169 offset:32
	ds_read_b64_tr_b16 v[140:141], v169 offset:2336
	ds_read_b64_tr_b16 v[188:189], v169 offset:64
	ds_read_b64_tr_b16 v[190:191], v169 offset:2368
	ds_read_b64_tr_b16 v[200:201], v169 offset:96
	ds_read_b64_tr_b16 v[202:203], v169 offset:2400
	s_waitcnt vmcnt(15)
	ds_write_b128 v241, v[76:79] offset:4608
	s_waitcnt vmcnt(14)
	ds_write_b128 v242, v[84:87] offset:4608
	s_waitcnt vmcnt(13)
	ds_write_b128 v243, v[92:95] offset:4608
	s_waitcnt vmcnt(12)
	ds_write_b128 v244, v[100:103] offset:4608
	v_mfma_f32_16x16x32_bf16 v[76:79], v[40:43], v[4:7], 0
	v_mfma_f32_16x16x32_bf16 v[40:43], v[40:43], v[12:15], 0
	v_mfma_f32_16x16x32_bf16 v[76:79], v[44:47], v[8:11], v[76:79]
	v_mfma_f32_16x16x32_bf16 v[84:87], v[56:59], v[4:7], 0
	v_mfma_f32_16x16x32_bf16 v[40:43], v[44:47], v[0:3], v[40:43]
	v_mfma_f32_16x16x32_bf16 v[44:47], v[56:59], v[12:15], 0
	v_sub_u32_e32 v56, v198, v147
	v_add_u32_e32 v59, 1, v56
	s_nop 2
	v_max_f32_e32 v58, v76, v76
	v_cmp_gt_u32_e64 s[0:1], v59, v146
	v_cmp_gt_u32_e32 vcc, v56, v146
	v_max_f32_e32 v58, 0xf149f2ca, v58
	v_cndmask_b32_e64 v59, v77, v246, s[0:1]
	v_cndmask_b32_e32 v58, v58, v246, vcc
	v_mfma_f32_16x16x32_bf16 v[84:87], v[60:63], v[8:11], v[84:87]
	v_max_f32_e32 v58, v58, v59
	v_add_u32_e32 v59, 2, v56
	v_cmp_gt_u32_e64 s[22:23], v59, v146
	v_mfma_f32_16x16x32_bf16 v[44:47], v[60:63], v[0:3], v[44:47]
	v_add_u32_e32 v60, 3, v56
	v_cmp_gt_u32_e64 s[24:25], v60, v146
	v_cndmask_b32_e64 v59, v78, v246, s[22:23]
	v_sub_u32_e32 v57, v198, v148
	v_cndmask_b32_e64 v60, v79, v246, s[24:25]
	v_max3_f32 v58, v58, v59, v60
	v_add_u32_e32 v59, 16, v56
	v_add_u32_e32 v60, 17, v56
	v_cmp_gt_u32_e64 s[26:27], v59, v146
	v_cmp_gt_u32_e64 s[28:29], v60, v146
	v_cmp_gt_u32_e64 s[38:39], v57, v145
	v_cndmask_b32_e64 v59, v84, v246, s[26:27]
	v_cndmask_b32_e64 v60, v85, v246, s[28:29]
	v_max3_f32 v58, v58, v59, v60
	v_add_u32_e32 v59, 18, v56
	v_add_u32_e32 v56, 19, v56
	v_cmp_gt_u32_e64 s[30:31], v59, v146
	v_cmp_gt_u32_e64 s[34:35], v56, v146
	v_add_u32_e32 v60, 3, v57
	v_cndmask_b32_e64 v59, v86, v246, s[30:31]
	v_cndmask_b32_e64 v56, v87, v246, s[34:35]
	v_max3_f32 v56, v58, v59, v56
	v_add_u32_e32 v59, 1, v57
	v_max_f32_e32 v58, v40, v40
	v_cmp_gt_u32_e64 s[40:41], v59, v145
	v_max_f32_e32 v58, 0xf149f2ca, v58
	v_cndmask_b32_e64 v58, v58, v246, s[38:39]
	v_cndmask_b32_e64 v59, v41, v246, s[40:41]
	v_max_f32_e32 v58, v58, v59
	v_add_u32_e32 v59, 2, v57
	v_cmp_gt_u32_e64 s[42:43], v59, v145
	v_cmp_gt_u32_e64 s[44:45], v60, v145
	s_nop 0
	v_cndmask_b32_e64 v59, v42, v246, s[42:43]
	v_cndmask_b32_e64 v60, v43, v246, s[44:45]
	v_max3_f32 v58, v58, v59, v60
	v_add_u32_e32 v59, 16, v57
	v_add_u32_e32 v60, 17, v57
	v_cmp_gt_u32_e64 s[46:47], v59, v145
	v_cmp_gt_u32_e64 s[48:49], v60, v145
	s_nop 0
	v_cndmask_b32_e64 v59, v44, v246, s[46:47]
	v_cndmask_b32_e64 v60, v45, v246, s[48:49]
	v_max3_f32 v58, v58, v59, v60
	v_add_u32_e32 v59, 18, v57
	v_add_u32_e32 v57, 19, v57
	v_cmp_gt_u32_e64 s[50:51], v59, v145
	v_cmp_gt_u32_e64 s[52:53], v57, v145
	s_nop 0
	v_cndmask_b32_e64 v59, v46, v246, s[50:51]
	v_cndmask_b32_e64 v57, v47, v246, s[52:53]
	v_max3_f32 v57, v58, v59, v57
	v_mov_b32_e32 v58, v56
	v_mov_b32_e32 v59, v56
	s_nop 1
	v_permlane32_swap_b32_e32 v58, v59
	v_max3_f32 v56, v56, v58, v59
	v_mov_b32_e32 v58, v57
	v_mov_b32_e32 v59, v57
	s_nop 1
	v_permlane32_swap_b32_e32 v58, v59
	v_max3_f32 v57, v57, v58, v59
	v_mov_b32_e32 v58, v56
	v_mov_b32_e32 v59, v56
	s_nop 1
	v_permlane16_swap_b32_e32 v58, v59
	v_max_f32_e32 v56, v56, v58
	v_mov_b32_e32 v58, v57
	v_mov_b32_e32 v61, v57
	s_nop 1
	v_permlane16_swap_b32_e32 v58, v61
	v_max_f32_e32 v62, v57, v58
	v_max3_f32 v175, v131, v56, v59
	v_sub_f32_e32 v56, v131, v175
	v_max3_f32 v177, v128, v62, v61
	v_exp_f32_e32 v60, v56
	v_sub_f32_e32 v56, v76, v175
	v_sub_f32_e32 v40, v40, v177
	v_exp_f32_e32 v56, v56
	v_sub_f32_e32 v58, v77, v175
	v_exp_f32_e32 v40, v40
	v_sub_f32_e32 v41, v41, v177
	v_exp_f32_e32 v58, v58
	v_sub_f32_e32 v59, v78, v175
	v_exp_f32_e32 v41, v41
	v_sub_f32_e32 v42, v42, v177
	v_exp_f32_e32 v59, v59
	v_sub_f32_e32 v63, v79, v175
	v_exp_f32_e32 v42, v42
	v_sub_f32_e32 v43, v43, v177
	v_exp_f32_e32 v63, v63
	v_sub_f32_e32 v76, v84, v175
	v_exp_f32_e32 v43, v43
	v_sub_f32_e32 v44, v44, v177
	v_cndmask_b32_e64 v56, v56, 0, vcc
	v_exp_f32_e32 v76, v76
	v_sub_f32_e32 v77, v85, v175
	v_sub_f32_e32 v61, v128, v177
	v_cndmask_b32_e64 v40, v40, 0, s[38:39]
	v_exp_f32_e32 v44, v44
	v_sub_f32_e32 v45, v45, v177
	v_add_f32_e32 v57, 0, v56
	v_cndmask_b32_e64 v58, v58, 0, s[0:1]
	v_exp_f32_e32 v77, v77
	v_sub_f32_e32 v78, v86, v175
	v_exp_f32_e32 v62, v61
	v_add_f32_e32 v61, 0, v40
	v_cndmask_b32_e64 v41, v41, 0, s[40:41]
	v_exp_f32_e32 v45, v45
	v_sub_f32_e32 v46, v46, v177
	v_add_f32_e32 v57, v58, v57
	v_cndmask_b32_e64 v59, v59, 0, s[22:23]
	v_exp_f32_e32 v78, v78
	v_sub_f32_e32 v79, v87, v175
	v_add_f32_e32 v61, v41, v61
	v_cndmask_b32_e64 v42, v42, 0, s[42:43]
	v_exp_f32_e32 v46, v46
	v_add_f32_e32 v57, v59, v57
	v_cndmask_b32_e64 v63, v63, 0, s[24:25]
	v_exp_f32_e32 v79, v79
	v_add_f32_e32 v61, v42, v61
	v_cndmask_b32_e64 v43, v43, 0, s[44:45]
	v_sub_f32_e32 v47, v47, v177
	v_add_f32_e32 v57, v63, v57
	v_cndmask_b32_e64 v76, v76, 0, s[26:27]
	v_add_f32_e32 v61, v43, v61
	v_cndmask_b32_e64 v44, v44, 0, s[46:47]
	v_exp_f32_e32 v47, v47
	v_add_f32_e32 v57, v76, v57
	v_cndmask_b32_e64 v77, v77, 0, s[28:29]
	v_add_f32_e32 v61, v44, v61
	v_cndmask_b32_e64 v45, v45, 0, s[48:49]
	v_add_f32_e32 v57, v77, v57
	v_cndmask_b32_e64 v78, v78, 0, s[30:31]
	v_add_f32_e32 v61, v45, v61
	v_cndmask_b32_e64 v46, v46, 0, s[50:51]
	v_add_f32_e32 v57, v78, v57
	v_cndmask_b32_e64 v79, v79, 0, s[34:35]
	v_add_f32_e32 v61, v46, v61
	v_add_f32_e32 v176, v79, v57
	v_cvt_pk_bf16_f32 v56, v56, v58
	v_cvt_pk_bf16_f32 v57, v59, v63
	v_cvt_pk_bf16_f32 v58, v76, v77
	v_cvt_pk_bf16_f32 v59, v78, v79
	v_cndmask_b32_e64 v47, v47, 0, s[52:53]
	v_pk_mul_f32 v[34:35], v[34:35], v[60:61] op_sel_hi:[1,0]
	v_pk_mul_f32 v[32:33], v[32:33], v[60:61] op_sel_hi:[1,0]
	v_add_f32_e32 v178, v47, v61
	v_cvt_pk_bf16_f32 v40, v40, v41
	v_cvt_pk_bf16_f32 v41, v42, v43
	v_cvt_pk_bf16_f32 v42, v44, v45
	v_cvt_pk_bf16_f32 v43, v46, v47
	s_waitcnt lgkmcnt(10)
	v_mfma_f32_16x16x32_bf16 v[44:47], v[134:137], v[56:59], v[32:35]
	v_fmac_f32_e32 v176, v132, v60
	v_fmac_f32_e32 v178, v129, v62
	s_nop 0
	v_pk_mul_f32 v[34:35], v[98:99], v[62:63] op_sel_hi:[1,0]
	v_pk_mul_f32 v[32:33], v[96:97], v[62:63] op_sel_hi:[1,0]
	s_nop 1
	v_mfma_f32_16x16x32_bf16 v[100:103], v[134:137], v[40:43], v[32:35]
	s_nop 2
	v_mul_f32_e64 v34, v106, v60
	v_mul_f32_e64 v35, v107, v60
	v_pk_mul_f32 v[32:33], v[104:105], v[60:61] op_sel_hi:[1,0]
	s_waitcnt lgkmcnt(8)
	s_nop 0
	v_mfma_f32_16x16x32_bf16 v[104:107], v[138:141], v[56:59], v[32:35]
	s_nop 2
	v_mul_f32_e64 v34, v110, v62
	v_mul_f32_e64 v35, v111, v62
	v_pk_mul_f32 v[32:33], v[108:109], v[62:63] op_sel_hi:[1,0]
	s_nop 1
	v_mfma_f32_16x16x32_bf16 v[108:111], v[138:141], v[40:43], v[32:35]
	s_nop 2
	v_mul_f32_e64 v34, v114, v60
	v_mul_f32_e64 v35, v115, v60
	v_pk_mul_f32 v[32:33], v[112:113], v[60:61] op_sel_hi:[1,0]
	s_waitcnt lgkmcnt(6)
	s_nop 0
	v_mfma_f32_16x16x32_bf16 v[112:115], v[188:191], v[56:59], v[32:35]
	s_nop 2
	v_mul_f32_e64 v34, v118, v62
	v_mul_f32_e64 v35, v119, v62
	v_pk_mul_f32 v[32:33], v[116:117], v[62:63] op_sel_hi:[1,0]
	s_nop 1
	v_mfma_f32_16x16x32_bf16 v[116:119], v[188:191], v[40:43], v[32:35]
	v_add_u32_e32 v188, s76, v207
	s_nop 1
	v_pk_mul_f32 v[34:35], v[122:123], v[60:61] op_sel_hi:[1,0]
	v_pk_mul_f32 v[32:33], v[120:121], v[60:61] op_sel_hi:[1,0]
	s_waitcnt lgkmcnt(4)
	s_nop 0
	v_mfma_f32_16x16x32_bf16 v[120:123], v[200:203], v[56:59], v[32:35]
	v_or_b32_e32 v56, 0xb0, v166
	v_add_u32_e32 v56, s76, v56
	s_nop 0
	v_pk_mul_f32 v[34:35], v[126:127], v[62:63] op_sel_hi:[1,0]
	v_pk_mul_f32 v[32:33], v[124:125], v[62:63] op_sel_hi:[1,0]
	s_nop 1
	v_mfma_f32_16x16x32_bf16 v[124:127], v[200:203], v[40:43], v[32:35]
	s_nop 2
	v_add_u32_e32 v32, 0xa0, v149
	v_med3_i32 v32, v32, 0, s75
	v_add_u32_e32 v32, s74, v32
	v_ashrrev_i32_e32 v33, 31, v32
	v_lshlrev_b64 v[32:33], 9, v[32:33]
	v_lshl_add_u64 v[32:33], v[164:165], 0, v[32:33]
	global_load_dwordx4 v[76:79], v[32:33], off
	v_add_u32_e32 v32, 0xa0, v150
	v_med3_i32 v32, v32, 0, s75
	v_add_u32_e32 v32, s74, v32
	v_ashrrev_i32_e32 v33, 31, v32
	v_lshlrev_b64 v[32:33], 9, v[32:33]
	v_lshl_add_u64 v[32:33], v[164:165], 0, v[32:33]
	global_load_dwordx4 v[84:87], v[32:33], off
	v_add_u32_e32 v32, 0xa0, v151
	v_med3_i32 v32, v32, 0, s75
	v_add_u32_e32 v32, s74, v32
	v_ashrrev_i32_e32 v33, 31, v32
	v_lshlrev_b64 v[32:33], 9, v[32:33]
	v_lshl_add_u64 v[32:33], v[164:165], 0, v[32:33]
	global_load_dwordx4 v[92:95], v[32:33], off
	v_add_u32_e32 v32, 0xa0, v252
	v_med3_i32 v32, v32, 0, s75
	v_add_u32_e32 v32, s74, v32
	v_ashrrev_i32_e32 v33, 31, v32
	v_lshlrev_b64 v[32:33], 9, v[32:33]
	v_lshl_add_u64 v[32:33], v[164:165], 0, v[32:33]
	global_load_dwordx4 v[96:99], v[32:33], off
	v_or_b32_e32 v32, 0xa0, v166
	v_add_u32_e32 v32, s76, v32
	v_med3_i32 v32, v32, 0, s75
	v_add_u32_e32 v32, s74, v32
	v_ashrrev_i32_e32 v33, 31, v32
	v_med3_i32 v56, v56, 0, s75
	v_add_u32_e32 v56, s74, v56
	v_ashrrev_i32_e32 v57, 31, v56
	v_lshlrev_b64 v[32:33], 9, v[32:33]
	v_lshlrev_b64 v[56:57], 9, v[56:57]
	v_lshl_add_u64 v[32:33], s[68:69], 0, v[32:33]
	v_lshl_add_u64 v[56:57], s[68:69], 0, v[56:57]
	v_lshl_add_u64 v[40:41], v[32:33], 0, v[158:159]
	v_lshl_add_u64 v[60:61], v[56:57], 0, v[158:159]
	global_load_dwordx4 v[32:35], v[40:41], off
	s_nop 0
	global_load_dwordx4 v[40:43], v[40:41], off offset:64
	s_nop 0
	global_load_dwordx4 v[56:59], v[60:61], off
	s_nop 0
	global_load_dwordx4 v[60:63], v[60:61], off offset:64
	ds_read_b64_tr_b16 v[142:143], v169 offset:6912
	ds_read_b64_tr_b16 v[140:141], v169 offset:4608
	ds_read_b64_tr_b16 v[136:137], v169 offset:4640
	ds_read_b64_tr_b16 v[138:139], v169 offset:6944
	ds_read_b64_tr_b16 v[132:133], v169 offset:4672
	ds_read_b64_tr_b16 v[134:135], v169 offset:6976
	ds_read_b64_tr_b16 v[128:129], v169 offset:4704
	ds_read_b64_tr_b16 v[130:131], v169 offset:7008
	s_waitcnt vmcnt(15)
	ds_write_b128 v241, v[36:39]
	s_waitcnt vmcnt(14)
	ds_write_b128 v242, v[72:75]
	s_waitcnt vmcnt(13)
	ds_write_b128 v243, v[80:83]
	s_waitcnt vmcnt(12)
	ds_write_b128 v244, v[88:91]
	v_mfma_f32_16x16x32_bf16 v[36:39], v[24:27], v[4:7], 0
	v_mfma_f32_16x16x32_bf16 v[24:27], v[24:27], v[12:15], 0
	v_mfma_f32_16x16x32_bf16 v[36:39], v[28:31], v[8:11], v[36:39]
	v_mfma_f32_16x16x32_bf16 v[72:75], v[64:67], v[4:7], 0
	v_mfma_f32_16x16x32_bf16 v[24:27], v[28:31], v[0:3], v[24:27]
	v_mfma_f32_16x16x32_bf16 v[28:31], v[64:67], v[12:15], 0
	v_sub_u32_e32 v64, v199, v147
	v_add_u32_e32 v67, 1, v64
	s_nop 2
	v_max_f32_e32 v66, v36, v36
	v_cmp_gt_u32_e64 s[0:1], v67, v146
	v_cmp_gt_u32_e32 vcc, v64, v146
	v_max_f32_e32 v66, 0xf149f2ca, v66
	v_cndmask_b32_e64 v67, v37, v246, s[0:1]
	v_cndmask_b32_e32 v66, v66, v246, vcc
	v_mfma_f32_16x16x32_bf16 v[72:75], v[68:71], v[8:11], v[72:75]
	v_max_f32_e32 v66, v66, v67
	v_add_u32_e32 v67, 2, v64
	v_cmp_gt_u32_e64 s[22:23], v67, v146
	v_mfma_f32_16x16x32_bf16 v[28:31], v[68:71], v[0:3], v[28:31]
	v_add_u32_e32 v68, 3, v64
	v_cmp_gt_u32_e64 s[24:25], v68, v146
	v_cndmask_b32_e64 v67, v38, v246, s[22:23]
	v_sub_u32_e32 v65, v199, v148
	v_cndmask_b32_e64 v68, v39, v246, s[24:25]
	v_max3_f32 v66, v66, v67, v68
	v_add_u32_e32 v67, 16, v64
	v_add_u32_e32 v68, 17, v64
	v_cmp_gt_u32_e64 s[26:27], v67, v146
	v_cmp_gt_u32_e64 s[28:29], v68, v146
	v_cmp_gt_u32_e64 s[38:39], v65, v145
	v_cndmask_b32_e64 v67, v72, v246, s[26:27]
	v_cndmask_b32_e64 v68, v73, v246, s[28:29]
	v_max3_f32 v66, v66, v67, v68
	v_add_u32_e32 v67, 18, v64
	v_add_u32_e32 v64, 19, v64
	v_cmp_gt_u32_e64 s[30:31], v67, v146
	v_cmp_gt_u32_e64 s[34:35], v64, v146
	v_add_u32_e32 v68, 3, v65
	v_cndmask_b32_e64 v67, v74, v246, s[30:31]
	v_cndmask_b32_e64 v64, v75, v246, s[34:35]
	v_max3_f32 v64, v66, v67, v64
	v_add_u32_e32 v67, 1, v65
	v_max_f32_e32 v66, v24, v24
	v_cmp_gt_u32_e64 s[40:41], v67, v145
	v_max_f32_e32 v66, 0xf149f2ca, v66
	v_cndmask_b32_e64 v66, v66, v246, s[38:39]
	v_cndmask_b32_e64 v67, v25, v246, s[40:41]
	v_max_f32_e32 v66, v66, v67
	v_add_u32_e32 v67, 2, v65
	v_cmp_gt_u32_e64 s[42:43], v67, v145
	v_cmp_gt_u32_e64 s[44:45], v68, v145
	s_nop 0
	v_cndmask_b32_e64 v67, v26, v246, s[42:43]
	v_cndmask_b32_e64 v68, v27, v246, s[44:45]
	v_max3_f32 v66, v66, v67, v68
	v_add_u32_e32 v67, 16, v65
	v_add_u32_e32 v68, 17, v65
	v_cmp_gt_u32_e64 s[46:47], v67, v145
	v_cmp_gt_u32_e64 s[48:49], v68, v145
	s_nop 0
	v_cndmask_b32_e64 v67, v28, v246, s[46:47]
	v_cndmask_b32_e64 v68, v29, v246, s[48:49]
	v_max3_f32 v66, v66, v67, v68
	v_add_u32_e32 v67, 18, v65
	v_add_u32_e32 v65, 19, v65
	v_cmp_gt_u32_e64 s[50:51], v67, v145
	v_cmp_gt_u32_e64 s[52:53], v65, v145
	s_nop 0
	v_cndmask_b32_e64 v67, v30, v246, s[50:51]
	v_cndmask_b32_e64 v65, v31, v246, s[52:53]
	v_max3_f32 v65, v66, v67, v65
	v_mov_b32_e32 v66, v64
	v_mov_b32_e32 v67, v64
	s_nop 1
	v_permlane32_swap_b32_e32 v66, v67
	v_max3_f32 v64, v64, v66, v67
	v_mov_b32_e32 v66, v65
	v_mov_b32_e32 v67, v65
	s_nop 1
	v_permlane32_swap_b32_e32 v66, v67
	v_max3_f32 v65, v65, v66, v67
	v_mov_b32_e32 v66, v64
	v_mov_b32_e32 v67, v64
	s_nop 1
	v_permlane16_swap_b32_e32 v66, v67
	v_max_f32_e32 v64, v64, v66
	v_max3_f32 v179, v175, v64, v67
	v_sub_f32_e32 v36, v36, v179
	v_exp_f32_e32 v36, v36
	v_sub_f32_e32 v37, v37, v179
	v_mov_b32_e32 v66, v65
	v_mov_b32_e32 v68, v65
	v_exp_f32_e32 v37, v37
	v_sub_f32_e32 v38, v38, v179
	v_permlane16_swap_b32_e32 v66, v68
	v_exp_f32_e32 v38, v38
	v_sub_f32_e32 v39, v39, v179
	v_exp_f32_e32 v39, v39
	v_sub_f32_e32 v67, v72, v179
	v_max_f32_e32 v65, v65, v66
	v_cndmask_b32_e64 v36, v36, 0, vcc
	v_exp_f32_e32 v67, v67
	v_sub_f32_e32 v69, v73, v179
	v_add_f32_e32 v66, 0, v36
	v_cndmask_b32_e64 v37, v37, 0, s[0:1]
	v_exp_f32_e32 v69, v69
	v_sub_f32_e32 v70, v74, v179
	v_max3_f32 v181, v177, v65, v68
	v_add_f32_e32 v66, v37, v66
	v_cndmask_b32_e64 v38, v38, 0, s[22:23]
	v_exp_f32_e32 v70, v70
	v_sub_f32_e32 v71, v75, v179
	v_sub_f32_e32 v24, v24, v181
	v_add_f32_e32 v66, v38, v66
	v_cndmask_b32_e64 v39, v39, 0, s[24:25]
	v_exp_f32_e32 v71, v71
	v_exp_f32_e32 v24, v24
	v_sub_f32_e32 v25, v25, v181
	v_add_f32_e32 v66, v39, v66
	v_cndmask_b32_e64 v67, v67, 0, s[26:27]
	v_exp_f32_e32 v25, v25
	v_sub_f32_e32 v26, v26, v181
	v_add_f32_e32 v66, v67, v66
	v_cndmask_b32_e64 v69, v69, 0, s[28:29]
	v_exp_f32_e32 v26, v26
	v_sub_f32_e32 v27, v27, v181
	v_add_f32_e32 v66, v69, v66
	v_cndmask_b32_e64 v70, v70, 0, s[30:31]
	v_exp_f32_e32 v27, v27
	v_sub_f32_e32 v28, v28, v181
	v_add_f32_e32 v66, v70, v66
	v_cndmask_b32_e64 v71, v71, 0, s[34:35]
	v_sub_f32_e32 v65, v177, v181
	v_cndmask_b32_e64 v24, v24, 0, s[38:39]
	v_exp_f32_e32 v28, v28
	v_sub_f32_e32 v29, v29, v181
	v_add_f32_e32 v180, v71, v66
	v_exp_f32_e32 v66, v65
	v_add_f32_e32 v65, 0, v24
	v_cndmask_b32_e64 v25, v25, 0, s[40:41]
	v_exp_f32_e32 v29, v29
	v_sub_f32_e32 v30, v30, v181
	v_add_f32_e32 v65, v25, v65
	v_cndmask_b32_e64 v26, v26, 0, s[42:43]
	v_exp_f32_e32 v30, v30
	v_sub_f32_e32 v31, v31, v181
	v_sub_f32_e32 v64, v175, v179
	v_add_f32_e32 v65, v26, v65
	v_cndmask_b32_e64 v27, v27, 0, s[44:45]
	v_exp_f32_e32 v31, v31
	v_exp_f32_e32 v64, v64
	v_add_f32_e32 v65, v27, v65
	v_cndmask_b32_e64 v28, v28, 0, s[46:47]
	v_add_f32_e32 v65, v28, v65
	v_cndmask_b32_e64 v29, v29, 0, s[48:49]
	v_add_f32_e32 v65, v29, v65
	v_cndmask_b32_e64 v30, v30, 0, s[50:51]
	v_add_f32_e32 v65, v30, v65
	v_cndmask_b32_e64 v31, v31, 0, s[52:53]
	v_cvt_pk_bf16_f32 v36, v36, v37
	v_cvt_pk_bf16_f32 v37, v38, v39
	v_cvt_pk_bf16_f32 v38, v67, v69
	v_cvt_pk_bf16_f32 v39, v70, v71
	v_add_f32_e32 v183, v31, v65
	v_cvt_pk_bf16_f32 v24, v24, v25
	v_cvt_pk_bf16_f32 v25, v26, v27
	v_cvt_pk_bf16_f32 v26, v28, v29
	v_cvt_pk_bf16_f32 v27, v30, v31
	v_pk_mul_f32 v[30:31], v[46:47], v[64:65] op_sel_hi:[1,0]
	v_pk_mul_f32 v[28:29], v[44:45], v[64:65] op_sel_hi:[1,0]
	v_fmac_f32_e32 v180, v176, v64
	v_fmac_f32_e32 v183, v178, v66
	s_waitcnt lgkmcnt(10)
	v_mfma_f32_16x16x32_bf16 v[68:71], v[140:143], v[36:39], v[28:31]
	s_nop 2
	v_mul_f32_e64 v30, v102, v66
	v_mul_f32_e64 v31, v103, v66
	v_pk_mul_f32 v[28:29], v[100:101], v[66:67] op_sel_hi:[1,0]
	s_nop 1
	v_mfma_f32_16x16x32_bf16 v[72:75], v[140:143], v[24:27], v[28:31]
	s_nop 2
	v_mul_f32_e64 v30, v106, v64
	v_mul_f32_e64 v31, v107, v64
	v_pk_mul_f32 v[28:29], v[104:105], v[64:65] op_sel_hi:[1,0]
	s_waitcnt lgkmcnt(8)
	s_nop 0
	v_mfma_f32_16x16x32_bf16 v[80:83], v[136:139], v[36:39], v[28:31]
	s_nop 2
	v_mul_f32_e64 v30, v110, v66
	v_mul_f32_e64 v31, v111, v66
	v_pk_mul_f32 v[28:29], v[108:109], v[66:67] op_sel_hi:[1,0]
	s_nop 1
	v_mfma_f32_16x16x32_bf16 v[108:111], v[136:139], v[24:27], v[28:31]
	s_nop 2
	v_mul_f32_e64 v30, v114, v64
	v_mul_f32_e64 v31, v115, v64
	v_pk_mul_f32 v[28:29], v[112:113], v[64:65] op_sel_hi:[1,0]
	s_waitcnt lgkmcnt(6)
	s_nop 0
	v_mfma_f32_16x16x32_bf16 v[112:115], v[132:135], v[36:39], v[28:31]
	s_nop 2
	v_mul_f32_e64 v30, v118, v66
	v_mul_f32_e64 v31, v119, v66
	v_pk_mul_f32 v[28:29], v[116:117], v[66:67] op_sel_hi:[1,0]
	s_nop 1
	v_mfma_f32_16x16x32_bf16 v[116:119], v[132:135], v[24:27], v[28:31]
	s_nop 2
	v_mul_f32_e64 v30, v122, v64
	v_mul_f32_e64 v31, v123, v64
	v_pk_mul_f32 v[28:29], v[120:121], v[64:65] op_sel_hi:[1,0]
	s_waitcnt lgkmcnt(4)
	s_nop 0
	v_mfma_f32_16x16x32_bf16 v[120:123], v[128:131], v[36:39], v[28:31]
	s_nop 2
	v_mul_f32_e64 v30, v126, v66
	v_mul_f32_e64 v31, v127, v66
	v_pk_mul_f32 v[28:29], v[124:125], v[66:67] op_sel_hi:[1,0]
	s_nop 1
	v_mfma_f32_16x16x32_bf16 v[124:127], v[128:131], v[24:27], v[28:31]
	v_add_u32_e32 v24, 0xc0, v149
	v_med3_i32 v24, v24, 0, s75
	v_add_u32_e32 v24, s74, v24
	v_ashrrev_i32_e32 v25, 31, v24
	v_lshlrev_b64 v[24:25], 9, v[24:25]
	v_lshl_add_u64 v[24:25], v[164:165], 0, v[24:25]
	global_load_dwordx4 v[64:67], v[24:25], off
	v_add_u32_e32 v24, 0xc0, v150
	v_med3_i32 v24, v24, 0, s75
	v_add_u32_e32 v24, s74, v24
	v_ashrrev_i32_e32 v25, 31, v24
	v_lshlrev_b64 v[24:25], 9, v[24:25]
	v_lshl_add_u64 v[24:25], v[164:165], 0, v[24:25]
	global_load_dwordx4 v[88:91], v[24:25], off
	v_add_u32_e32 v24, 0xc0, v151
	v_med3_i32 v24, v24, 0, s75
	v_add_u32_e32 v24, s74, v24
	v_ashrrev_i32_e32 v25, 31, v24
	v_lshlrev_b64 v[24:25], 9, v[24:25]
	v_lshl_add_u64 v[24:25], v[164:165], 0, v[24:25]
	global_load_dwordx4 v[100:103], v[24:25], off
	v_add_u32_e32 v24, 0xc0, v252
	v_med3_i32 v24, v24, 0, s75
	v_add_u32_e32 v24, s74, v24
	v_ashrrev_i32_e32 v25, 31, v24
	v_lshlrev_b64 v[24:25], 9, v[24:25]
	v_lshl_add_u64 v[24:25], v[164:165], 0, v[24:25]
	global_load_dwordx4 v[104:107], v[24:25], off
	v_or_b32_e32 v24, 0xc0, v166
	v_add_u32_e32 v24, s76, v24
	v_med3_i32 v24, v24, 0, s75
	v_add_u32_e32 v24, s74, v24
	v_ashrrev_i32_e32 v25, 31, v24
	v_lshlrev_b64 v[24:25], 9, v[24:25]
	v_lshl_add_u64 v[24:25], s[68:69], 0, v[24:25]
	v_lshl_add_u64 v[24:25], v[24:25], 0, v[158:159]
	global_load_dwordx4 v[36:39], v[24:25], off
	global_load_dwordx4 v[44:47], v[24:25], off offset:64
	v_or_b32_e32 v24, 0xd0, v166
	v_add_u32_e32 v24, s76, v24
	v_med3_i32 v24, v24, 0, s75
	v_add_u32_e32 v24, s74, v24
	v_ashrrev_i32_e32 v25, 31, v24
	v_lshlrev_b64 v[24:25], 9, v[24:25]
	v_lshl_add_u64 v[24:25], s[68:69], 0, v[24:25]
	v_lshl_add_u64 v[28:29], v[24:25], 0, v[158:159]
	global_load_dwordx4 v[24:27], v[28:29], off
	s_nop 0
	global_load_dwordx4 v[28:31], v[28:29], off offset:64
	ds_read_b64_tr_b16 v[142:143], v169 offset:2304
	ds_read_b64_tr_b16 v[140:141], v169
	ds_read_b64_tr_b16 v[136:137], v169 offset:32
	ds_read_b64_tr_b16 v[138:139], v169 offset:2336
	ds_read_b64_tr_b16 v[132:133], v169 offset:64
	ds_read_b64_tr_b16 v[134:135], v169 offset:2368
	ds_read_b64_tr_b16 v[128:129], v169 offset:96
	ds_read_b64_tr_b16 v[130:131], v169 offset:2400
	s_waitcnt vmcnt(15)
	ds_write_b128 v241, v[76:79] offset:4608
	s_waitcnt vmcnt(14)
	ds_write_b128 v242, v[84:87] offset:4608
	s_waitcnt vmcnt(13)
	ds_write_b128 v243, v[92:95] offset:4608
	s_waitcnt vmcnt(12)
	ds_write_b128 v244, v[96:99] offset:4608
	v_mfma_f32_16x16x32_bf16 v[76:79], v[16:19], v[4:7], 0
	v_mfma_f32_16x16x32_bf16 v[16:19], v[16:19], v[12:15], 0
	v_mfma_f32_16x16x32_bf16 v[76:79], v[20:23], v[8:11], v[76:79]
	v_mfma_f32_16x16x32_bf16 v[84:87], v[48:51], v[4:7], 0
	v_mfma_f32_16x16x32_bf16 v[16:19], v[20:23], v[0:3], v[16:19]
	v_mfma_f32_16x16x32_bf16 v[20:23], v[48:51], v[12:15], 0
	v_add_u32_e32 v49, 0xc0, v154
	v_sub_u32_e32 v48, v49, v147
	v_add_u32_e32 v51, 1, v48
	s_nop 1
	v_max_f32_e32 v50, v76, v76
	v_cmp_gt_u32_e64 s[0:1], v51, v146
	v_cmp_gt_u32_e32 vcc, v48, v146
	v_max_f32_e32 v50, 0xf149f2ca, v50
	v_cndmask_b32_e64 v51, v77, v246, s[0:1]
	v_cndmask_b32_e32 v50, v50, v246, vcc
	v_mfma_f32_16x16x32_bf16 v[84:87], v[52:55], v[8:11], v[84:87]
	v_max_f32_e32 v50, v50, v51
	v_add_u32_e32 v51, 2, v48
	v_cmp_gt_u32_e64 s[22:23], v51, v146
	v_mfma_f32_16x16x32_bf16 v[20:23], v[52:55], v[0:3], v[20:23]
	v_add_u32_e32 v52, 3, v48
	v_cmp_gt_u32_e64 s[24:25], v52, v146
	v_cndmask_b32_e64 v51, v78, v246, s[22:23]
	v_sub_u32_e32 v49, v49, v148
	v_cndmask_b32_e64 v52, v79, v246, s[24:25]
	v_max3_f32 v50, v50, v51, v52
	v_add_u32_e32 v51, 16, v48
	v_add_u32_e32 v52, 17, v48
	v_cmp_gt_u32_e64 s[26:27], v51, v146
	v_cmp_gt_u32_e64 s[28:29], v52, v146
	v_cmp_gt_u32_e64 s[38:39], v49, v145
	v_cndmask_b32_e64 v51, v84, v246, s[26:27]
	v_cndmask_b32_e64 v52, v85, v246, s[28:29]
	v_max3_f32 v50, v50, v51, v52
	v_add_u32_e32 v51, 18, v48
	v_add_u32_e32 v48, 19, v48
	v_cmp_gt_u32_e64 s[30:31], v51, v146
	v_cmp_gt_u32_e64 s[34:35], v48, v146
	v_add_u32_e32 v52, 3, v49
	v_cndmask_b32_e64 v51, v86, v246, s[30:31]
	v_cndmask_b32_e64 v48, v87, v246, s[34:35]
	v_max3_f32 v48, v50, v51, v48
	v_add_u32_e32 v51, 1, v49
	v_max_f32_e32 v50, v16, v16
	v_cmp_gt_u32_e64 s[40:41], v51, v145
	v_max_f32_e32 v50, 0xf149f2ca, v50
	v_cndmask_b32_e64 v50, v50, v246, s[38:39]
	v_cndmask_b32_e64 v51, v17, v246, s[40:41]
	v_max_f32_e32 v50, v50, v51
	v_add_u32_e32 v51, 2, v49
	v_cmp_gt_u32_e64 s[42:43], v51, v145
	v_cmp_gt_u32_e64 s[44:45], v52, v145
	s_nop 0
	v_cndmask_b32_e64 v51, v18, v246, s[42:43]
	v_cndmask_b32_e64 v52, v19, v246, s[44:45]
	v_max3_f32 v50, v50, v51, v52
	v_add_u32_e32 v51, 16, v49
	v_add_u32_e32 v52, 17, v49
	v_cmp_gt_u32_e64 s[46:47], v51, v145
	v_cmp_gt_u32_e64 s[48:49], v52, v145
	s_nop 0
	v_cndmask_b32_e64 v51, v20, v246, s[46:47]
	v_cndmask_b32_e64 v52, v21, v246, s[48:49]
	v_max3_f32 v50, v50, v51, v52
	v_add_u32_e32 v51, 18, v49
	v_add_u32_e32 v49, 19, v49
	v_cmp_gt_u32_e64 s[50:51], v51, v145
	v_cmp_gt_u32_e64 s[52:53], v49, v145
	s_nop 0
	v_cndmask_b32_e64 v51, v22, v246, s[50:51]
	v_cndmask_b32_e64 v49, v23, v246, s[52:53]
	v_max3_f32 v49, v50, v51, v49
	v_mov_b32_e32 v50, v48
	v_mov_b32_e32 v51, v48
	s_nop 1
	v_permlane32_swap_b32_e32 v50, v51
	v_max3_f32 v48, v48, v50, v51
	v_mov_b32_e32 v50, v49
	v_mov_b32_e32 v51, v49
	s_nop 1
	v_permlane32_swap_b32_e32 v50, v51
	v_max3_f32 v49, v49, v50, v51
	v_mov_b32_e32 v50, v48
	v_mov_b32_e32 v51, v48
	s_nop 1
	v_permlane16_swap_b32_e32 v50, v51
	v_max_f32_e32 v48, v48, v50
	v_mov_b32_e32 v50, v49
	v_mov_b32_e32 v53, v49
	s_nop 1
	v_permlane16_swap_b32_e32 v50, v53
	v_max_f32_e32 v54, v49, v50
	v_max3_f32 v175, v179, v48, v51
	v_sub_f32_e32 v48, v179, v175
	v_max3_f32 v177, v181, v54, v53
	v_exp_f32_e32 v52, v48
	v_sub_f32_e32 v48, v76, v175
	v_sub_f32_e32 v16, v16, v177
	v_exp_f32_e32 v48, v48
	v_sub_f32_e32 v50, v77, v175
	v_exp_f32_e32 v16, v16
	v_sub_f32_e32 v17, v17, v177
	v_exp_f32_e32 v50, v50
	v_sub_f32_e32 v51, v78, v175
	v_exp_f32_e32 v17, v17
	v_sub_f32_e32 v18, v18, v177
	v_exp_f32_e32 v51, v51
	v_sub_f32_e32 v55, v79, v175
	v_exp_f32_e32 v18, v18
	v_sub_f32_e32 v19, v19, v177
	v_exp_f32_e32 v55, v55
	v_sub_f32_e32 v76, v84, v175
	v_exp_f32_e32 v19, v19
	v_sub_f32_e32 v20, v20, v177
	v_cndmask_b32_e64 v48, v48, 0, vcc
	v_exp_f32_e32 v76, v76
	v_sub_f32_e32 v77, v85, v175
	v_sub_f32_e32 v53, v181, v177
	v_cndmask_b32_e64 v16, v16, 0, s[38:39]
	v_exp_f32_e32 v20, v20
	v_sub_f32_e32 v21, v21, v177
	v_add_f32_e32 v49, 0, v48
	v_cndmask_b32_e64 v50, v50, 0, s[0:1]
	v_exp_f32_e32 v77, v77
	v_sub_f32_e32 v78, v86, v175
	v_exp_f32_e32 v54, v53
	v_add_f32_e32 v53, 0, v16
	v_cndmask_b32_e64 v17, v17, 0, s[40:41]
	v_exp_f32_e32 v21, v21
	v_sub_f32_e32 v22, v22, v177
	v_add_f32_e32 v49, v50, v49
	v_cndmask_b32_e64 v51, v51, 0, s[22:23]
	v_exp_f32_e32 v78, v78
	v_sub_f32_e32 v79, v87, v175
	v_add_f32_e32 v53, v17, v53
	v_cndmask_b32_e64 v18, v18, 0, s[42:43]
	v_exp_f32_e32 v22, v22
	v_sub_f32_e32 v23, v23, v177
	v_add_f32_e32 v49, v51, v49
	v_cndmask_b32_e64 v55, v55, 0, s[24:25]
	v_exp_f32_e32 v79, v79
	v_add_f32_e32 v53, v18, v53
	v_cndmask_b32_e64 v19, v19, 0, s[44:45]
	v_exp_f32_e32 v23, v23
	v_add_f32_e32 v49, v55, v49
	v_cndmask_b32_e64 v76, v76, 0, s[26:27]
	v_add_f32_e32 v53, v19, v53
	v_cndmask_b32_e64 v20, v20, 0, s[46:47]
	v_add_f32_e32 v49, v76, v49
	v_cndmask_b32_e64 v77, v77, 0, s[28:29]
	v_add_f32_e32 v53, v20, v53
	v_cndmask_b32_e64 v21, v21, 0, s[48:49]
	v_add_f32_e32 v49, v77, v49
	v_cndmask_b32_e64 v78, v78, 0, s[30:31]
	v_add_f32_e32 v53, v21, v53
	v_cndmask_b32_e64 v22, v22, 0, s[50:51]
	v_add_f32_e32 v49, v78, v49
	v_cndmask_b32_e64 v79, v79, 0, s[34:35]
	v_add_f32_e32 v53, v22, v53
	v_cndmask_b32_e64 v23, v23, 0, s[52:53]
	v_add_f32_e32 v176, v79, v49
	v_cvt_pk_bf16_f32 v48, v48, v50
	v_cvt_pk_bf16_f32 v49, v51, v55
	v_cvt_pk_bf16_f32 v50, v76, v77
	v_cvt_pk_bf16_f32 v51, v78, v79
	v_add_f32_e32 v178, v23, v53
	v_cvt_pk_bf16_f32 v16, v16, v17
	v_cvt_pk_bf16_f32 v17, v18, v19
	v_cvt_pk_bf16_f32 v18, v20, v21
	v_cvt_pk_bf16_f32 v19, v22, v23
	v_pk_mul_f32 v[22:23], v[70:71], v[52:53] op_sel_hi:[1,0]
	v_pk_mul_f32 v[20:21], v[68:69], v[52:53] op_sel_hi:[1,0]
	v_fmac_f32_e32 v176, v180, v52
	v_fmac_f32_e32 v178, v183, v54
	s_waitcnt lgkmcnt(10)
	v_mfma_f32_16x16x32_bf16 v[76:79], v[140:143], v[48:51], v[20:23]
	v_add_u32_e32 v180, 0x100, v149
	v_add_u32_e32 v179, 0x100, v150
	s_nop 0
	v_pk_mul_f32 v[22:23], v[74:75], v[54:55] op_sel_hi:[1,0]
	v_pk_mul_f32 v[20:21], v[72:73], v[54:55] op_sel_hi:[1,0]
	s_nop 1
	v_mfma_f32_16x16x32_bf16 v[92:95], v[140:143], v[16:19], v[20:23]
	s_nop 2
	v_mul_f32_e64 v22, v82, v52
	v_mul_f32_e64 v23, v83, v52
	v_pk_mul_f32 v[20:21], v[80:81], v[52:53] op_sel_hi:[1,0]
	s_waitcnt lgkmcnt(8)
	s_nop 0
	v_mfma_f32_16x16x32_bf16 v[96:99], v[136:139], v[48:51], v[20:23]
	s_nop 2
	v_mul_f32_e64 v22, v110, v54
	v_mul_f32_e64 v23, v111, v54
	v_pk_mul_f32 v[20:21], v[108:109], v[54:55] op_sel_hi:[1,0]
	s_nop 1
	v_mfma_f32_16x16x32_bf16 v[108:111], v[136:139], v[16:19], v[20:23]
	s_nop 2
	v_mul_f32_e64 v22, v114, v52
	v_mul_f32_e64 v23, v115, v52
	v_pk_mul_f32 v[20:21], v[112:113], v[52:53] op_sel_hi:[1,0]
	s_waitcnt lgkmcnt(6)
	s_nop 0
	v_mfma_f32_16x16x32_bf16 v[112:115], v[132:135], v[48:51], v[20:23]
	s_nop 2
	v_mul_f32_e64 v22, v118, v54
	v_mul_f32_e64 v23, v119, v54
	v_pk_mul_f32 v[20:21], v[116:117], v[54:55] op_sel_hi:[1,0]
	s_nop 1
	v_mfma_f32_16x16x32_bf16 v[116:119], v[132:135], v[16:19], v[20:23]
	s_nop 2
	v_mul_f32_e64 v22, v122, v52
	v_mul_f32_e64 v23, v123, v52
	v_pk_mul_f32 v[20:21], v[120:121], v[52:53] op_sel_hi:[1,0]
	s_waitcnt lgkmcnt(4)
	s_nop 0
	v_mfma_f32_16x16x32_bf16 v[120:123], v[128:131], v[48:51], v[20:23]
	s_nop 2
	v_mul_f32_e64 v22, v126, v54
	v_mul_f32_e64 v23, v127, v54
	v_pk_mul_f32 v[20:21], v[124:125], v[54:55] op_sel_hi:[1,0]
	s_nop 1
	v_mfma_f32_16x16x32_bf16 v[124:127], v[128:131], v[16:19], v[20:23]
	v_add_u32_e32 v16, 0xe0, v149
	v_med3_i32 v16, v16, 0, s75
	v_add_u32_e32 v16, s74, v16
	v_ashrrev_i32_e32 v17, 31, v16
	v_lshlrev_b64 v[16:17], 9, v[16:17]
	v_lshl_add_u64 v[16:17], v[164:165], 0, v[16:17]
	global_load_dwordx4 v[68:71], v[16:17], off
	v_add_u32_e32 v16, 0xe0, v150
	v_med3_i32 v16, v16, 0, s75
	v_add_u32_e32 v16, s74, v16
	v_ashrrev_i32_e32 v17, 31, v16
	v_lshlrev_b64 v[16:17], 9, v[16:17]
	v_lshl_add_u64 v[16:17], v[164:165], 0, v[16:17]
	global_load_dwordx4 v[72:75], v[16:17], off
	v_add_u32_e32 v16, 0xe0, v151
	v_med3_i32 v16, v16, 0, s75
	v_add_u32_e32 v16, s74, v16
	v_ashrrev_i32_e32 v17, 31, v16
	v_lshlrev_b64 v[16:17], 9, v[16:17]
	v_lshl_add_u64 v[16:17], v[164:165], 0, v[16:17]
	global_load_dwordx4 v[80:83], v[16:17], off
	v_add_u32_e32 v16, 0xe0, v252
	v_med3_i32 v16, v16, 0, s75
	v_add_u32_e32 v16, s74, v16
	v_ashrrev_i32_e32 v17, 31, v16
	v_lshlrev_b64 v[16:17], 9, v[16:17]
	v_lshl_add_u64 v[16:17], v[164:165], 0, v[16:17]
	global_load_dwordx4 v[84:87], v[16:17], off
	v_or_b32_e32 v16, 0xe0, v166
	v_add_u32_e32 v16, s76, v16
	v_med3_i32 v16, v16, 0, s75
	v_add_u32_e32 v16, s74, v16
	v_ashrrev_i32_e32 v17, 31, v16
	v_lshlrev_b64 v[16:17], 9, v[16:17]
	v_lshl_add_u64 v[16:17], s[68:69], 0, v[16:17]
	v_lshl_add_u64 v[16:17], v[16:17], 0, v[158:159]
	global_load_dwordx4 v[48:51], v[16:17], off
	global_load_dwordx4 v[52:55], v[16:17], off offset:64
	v_or_b32_e32 v16, 0xf0, v166
	v_add_u32_e32 v16, s76, v16
	v_med3_i32 v16, v16, 0, s75
	v_add_u32_e32 v16, s74, v16
	v_ashrrev_i32_e32 v17, 31, v16
	v_lshlrev_b64 v[16:17], 9, v[16:17]
	v_lshl_add_u64 v[16:17], s[68:69], 0, v[16:17]
	v_lshl_add_u64 v[20:21], v[16:17], 0, v[158:159]
	global_load_dwordx4 v[16:19], v[20:21], off
	s_nop 0
	global_load_dwordx4 v[20:23], v[20:21], off offset:64
	ds_read_b64_tr_b16 v[142:143], v169 offset:6912
	ds_read_b64_tr_b16 v[140:141], v169 offset:4608
	ds_read_b64_tr_b16 v[136:137], v169 offset:4640
	ds_read_b64_tr_b16 v[138:139], v169 offset:6944
	ds_read_b64_tr_b16 v[132:133], v169 offset:4672
	ds_read_b64_tr_b16 v[134:135], v169 offset:6976
	ds_read_b64_tr_b16 v[128:129], v169 offset:4704
	ds_read_b64_tr_b16 v[130:131], v169 offset:7008
	s_waitcnt vmcnt(15)
	ds_write_b128 v241, v[64:67]
	s_waitcnt vmcnt(14)
	ds_write_b128 v242, v[88:91]
	s_waitcnt vmcnt(13)
	ds_write_b128 v243, v[100:103]
	s_waitcnt vmcnt(12)
	ds_write_b128 v244, v[104:107]
	v_mfma_f32_16x16x32_bf16 v[64:67], v[32:35], v[4:7], 0
	v_mfma_f32_16x16x32_bf16 v[32:35], v[32:35], v[12:15], 0
	v_mfma_f32_16x16x32_bf16 v[64:67], v[40:43], v[8:11], v[64:67]
	v_mfma_f32_16x16x32_bf16 v[88:91], v[56:59], v[4:7], 0
	v_mfma_f32_16x16x32_bf16 v[32:35], v[40:43], v[0:3], v[32:35]
	v_mfma_f32_16x16x32_bf16 v[40:43], v[56:59], v[12:15], 0
	v_add_u32_e32 v57, 0xe0, v154
	v_sub_u32_e32 v56, v57, v147
	v_add_u32_e32 v59, 1, v56
	s_nop 1
	v_max_f32_e32 v58, v64, v64
	v_cmp_gt_u32_e64 s[0:1], v59, v146
	v_cmp_gt_u32_e32 vcc, v56, v146
	v_max_f32_e32 v58, 0xf149f2ca, v58
	v_cndmask_b32_e64 v59, v65, v246, s[0:1]
	v_cndmask_b32_e32 v58, v58, v246, vcc
	v_mfma_f32_16x16x32_bf16 v[88:91], v[60:63], v[8:11], v[88:91]
	v_max_f32_e32 v58, v58, v59
	v_add_u32_e32 v59, 2, v56
	v_cmp_gt_u32_e64 s[22:23], v59, v146
	v_mfma_f32_16x16x32_bf16 v[40:43], v[60:63], v[0:3], v[40:43]
	v_add_u32_e32 v60, 3, v56
	v_cmp_gt_u32_e64 s[24:25], v60, v146
	v_cndmask_b32_e64 v59, v66, v246, s[22:23]
	v_sub_u32_e32 v57, v57, v148
	v_cndmask_b32_e64 v60, v67, v246, s[24:25]
	v_max3_f32 v58, v58, v59, v60
	v_add_u32_e32 v59, 16, v56
	v_add_u32_e32 v60, 17, v56
	v_cmp_gt_u32_e64 s[26:27], v59, v146
	v_cmp_gt_u32_e64 s[28:29], v60, v146
	v_cmp_gt_u32_e64 s[38:39], v57, v145
	v_cndmask_b32_e64 v59, v88, v246, s[26:27]
	v_cndmask_b32_e64 v60, v89, v246, s[28:29]
	v_max3_f32 v58, v58, v59, v60
	v_add_u32_e32 v59, 18, v56
	v_add_u32_e32 v56, 19, v56
	v_cmp_gt_u32_e64 s[30:31], v59, v146
	v_cmp_gt_u32_e64 s[34:35], v56, v146
	v_add_u32_e32 v60, 3, v57
	v_cndmask_b32_e64 v59, v90, v246, s[30:31]
	v_cndmask_b32_e64 v56, v91, v246, s[34:35]
	v_max3_f32 v56, v58, v59, v56
	v_add_u32_e32 v59, 1, v57
	v_max_f32_e32 v58, v32, v32
	v_cmp_gt_u32_e64 s[40:41], v59, v145
	v_max_f32_e32 v58, 0xf149f2ca, v58
	v_cndmask_b32_e64 v58, v58, v246, s[38:39]
	v_cndmask_b32_e64 v59, v33, v246, s[40:41]
	v_max_f32_e32 v58, v58, v59
	v_add_u32_e32 v59, 2, v57
	v_cmp_gt_u32_e64 s[42:43], v59, v145
	v_cmp_gt_u32_e64 s[44:45], v60, v145
	s_nop 0
	v_cndmask_b32_e64 v59, v34, v246, s[42:43]
	v_cndmask_b32_e64 v60, v35, v246, s[44:45]
	v_max3_f32 v58, v58, v59, v60
	v_add_u32_e32 v59, 16, v57
	v_add_u32_e32 v60, 17, v57
	v_cmp_gt_u32_e64 s[46:47], v59, v145
	v_cmp_gt_u32_e64 s[48:49], v60, v145
	s_nop 0
	v_cndmask_b32_e64 v59, v40, v246, s[46:47]
	v_cndmask_b32_e64 v60, v41, v246, s[48:49]
	v_max3_f32 v58, v58, v59, v60
	v_add_u32_e32 v59, 18, v57
	v_add_u32_e32 v57, 19, v57
	v_cmp_gt_u32_e64 s[50:51], v59, v145
	v_cmp_gt_u32_e64 s[52:53], v57, v145
	s_nop 0
	v_cndmask_b32_e64 v59, v42, v246, s[50:51]
	v_cndmask_b32_e64 v57, v43, v246, s[52:53]
	v_max3_f32 v57, v58, v59, v57
	v_mov_b32_e32 v58, v56
	v_mov_b32_e32 v59, v56
	s_nop 1
	v_permlane32_swap_b32_e32 v58, v59
	v_max3_f32 v56, v56, v58, v59
	v_mov_b32_e32 v58, v57
	v_mov_b32_e32 v59, v57
	s_nop 1
	v_permlane32_swap_b32_e32 v58, v59
	v_max3_f32 v57, v57, v58, v59
	v_mov_b32_e32 v58, v56
	v_mov_b32_e32 v59, v56
	s_nop 1
	v_permlane16_swap_b32_e32 v58, v59
	v_max_f32_e32 v56, v56, v58
	v_mov_b32_e32 v58, v57
	v_mov_b32_e32 v61, v57
	s_nop 1
	v_permlane16_swap_b32_e32 v58, v61
	v_max_f32_e32 v62, v57, v58
	v_max3_f32 v181, v175, v56, v59
	v_sub_f32_e32 v56, v175, v181
	v_max3_f32 v184, v177, v62, v61
	v_exp_f32_e32 v60, v56
	v_sub_f32_e32 v56, v64, v181
	v_sub_f32_e32 v32, v32, v184
	v_exp_f32_e32 v56, v56
	v_sub_f32_e32 v58, v65, v181
	v_exp_f32_e32 v32, v32
	v_sub_f32_e32 v33, v33, v184
	v_exp_f32_e32 v58, v58
	v_sub_f32_e32 v59, v66, v181
	v_exp_f32_e32 v33, v33
	v_sub_f32_e32 v34, v34, v184
	v_exp_f32_e32 v59, v59
	v_sub_f32_e32 v63, v67, v181
	v_exp_f32_e32 v34, v34
	v_sub_f32_e32 v35, v35, v184
	v_exp_f32_e32 v63, v63
	v_sub_f32_e32 v64, v88, v181
	v_exp_f32_e32 v35, v35
	v_sub_f32_e32 v40, v40, v184
	v_cndmask_b32_e64 v56, v56, 0, vcc
	v_exp_f32_e32 v64, v64
	v_sub_f32_e32 v65, v89, v181
	v_sub_f32_e32 v61, v177, v184
	v_cndmask_b32_e64 v32, v32, 0, s[38:39]
	v_exp_f32_e32 v40, v40
	v_sub_f32_e32 v41, v41, v184
	v_add_f32_e32 v57, 0, v56
	v_cndmask_b32_e64 v58, v58, 0, s[0:1]
	v_exp_f32_e32 v65, v65
	v_sub_f32_e32 v66, v90, v181
	v_exp_f32_e32 v62, v61
	v_add_f32_e32 v61, 0, v32
	v_cndmask_b32_e64 v33, v33, 0, s[40:41]
	v_exp_f32_e32 v41, v41
	v_sub_f32_e32 v42, v42, v184
	v_add_f32_e32 v57, v58, v57
	v_cndmask_b32_e64 v59, v59, 0, s[22:23]
	v_exp_f32_e32 v66, v66
	v_sub_f32_e32 v67, v91, v181
	v_add_f32_e32 v61, v33, v61
	v_cndmask_b32_e64 v34, v34, 0, s[42:43]
	v_exp_f32_e32 v42, v42
	v_sub_f32_e32 v43, v43, v184
	v_add_f32_e32 v57, v59, v57
	v_cndmask_b32_e64 v63, v63, 0, s[24:25]
	v_exp_f32_e32 v67, v67
	v_add_f32_e32 v61, v34, v61
	v_cndmask_b32_e64 v35, v35, 0, s[44:45]
	v_exp_f32_e32 v43, v43
	v_add_f32_e32 v57, v63, v57
	v_cndmask_b32_e64 v64, v64, 0, s[26:27]
	v_add_f32_e32 v61, v35, v61
	v_cndmask_b32_e64 v40, v40, 0, s[46:47]
	v_add_f32_e32 v57, v64, v57
	v_cndmask_b32_e64 v65, v65, 0, s[28:29]
	v_add_f32_e32 v61, v40, v61
	v_cndmask_b32_e64 v41, v41, 0, s[48:49]
	v_add_f32_e32 v57, v65, v57
	v_cndmask_b32_e64 v66, v66, 0, s[30:31]
	v_add_f32_e32 v61, v41, v61
	v_cndmask_b32_e64 v42, v42, 0, s[50:51]
	v_add_f32_e32 v57, v66, v57
	v_cndmask_b32_e64 v67, v67, 0, s[34:35]
	v_add_f32_e32 v61, v42, v61
	v_cndmask_b32_e64 v43, v43, 0, s[52:53]
	v_add_f32_e32 v183, v67, v57
	v_cvt_pk_bf16_f32 v56, v56, v58
	v_cvt_pk_bf16_f32 v57, v59, v63
	v_cvt_pk_bf16_f32 v58, v64, v65
	v_cvt_pk_bf16_f32 v59, v66, v67
	v_add_f32_e32 v185, v43, v61
	v_cvt_pk_bf16_f32 v32, v32, v33
	v_cvt_pk_bf16_f32 v33, v34, v35
	v_cvt_pk_bf16_f32 v34, v40, v41
	v_cvt_pk_bf16_f32 v35, v42, v43
	v_pk_mul_f32 v[42:43], v[78:79], v[60:61] op_sel_hi:[1,0]
	v_pk_mul_f32 v[40:41], v[76:77], v[60:61] op_sel_hi:[1,0]
	v_fmac_f32_e32 v185, v178, v62
	s_waitcnt lgkmcnt(10)
	v_mfma_f32_16x16x32_bf16 v[100:103], v[140:143], v[56:59], v[40:43]
	v_add_u32_e32 v178, 0x100, v151
	v_fmac_f32_e32 v183, v176, v60
	v_add_u32_e32 v177, 0x100, v252
	v_pk_mul_f32 v[42:43], v[94:95], v[62:63] op_sel_hi:[1,0]
	v_pk_mul_f32 v[40:41], v[92:93], v[62:63] op_sel_hi:[1,0]
	s_nop 1
	v_mfma_f32_16x16x32_bf16 v[92:95], v[140:143], v[32:35], v[40:43]
	s_nop 2
	v_mul_f32_e64 v42, v98, v60
	v_mul_f32_e64 v43, v99, v60
	v_pk_mul_f32 v[40:41], v[96:97], v[60:61] op_sel_hi:[1,0]
	s_waitcnt lgkmcnt(8)
	s_nop 0
	v_mfma_f32_16x16x32_bf16 v[104:107], v[136:139], v[56:59], v[40:43]
	s_nop 2
	v_mul_f32_e64 v42, v110, v62
	v_mul_f32_e64 v43, v111, v62
	v_pk_mul_f32 v[40:41], v[108:109], v[62:63] op_sel_hi:[1,0]
	s_nop 1
	v_mfma_f32_16x16x32_bf16 v[108:111], v[136:139], v[32:35], v[40:43]
	s_nop 2
	v_mul_f32_e64 v42, v114, v60
	v_mul_f32_e64 v43, v115, v60
	v_pk_mul_f32 v[40:41], v[112:113], v[60:61] op_sel_hi:[1,0]
	s_waitcnt lgkmcnt(6)
	s_nop 0
	v_mfma_f32_16x16x32_bf16 v[112:115], v[132:135], v[56:59], v[40:43]
	s_nop 2
	v_mul_f32_e64 v42, v118, v62
	v_mul_f32_e64 v43, v119, v62
	v_pk_mul_f32 v[40:41], v[116:117], v[62:63] op_sel_hi:[1,0]
	s_nop 1
	v_mfma_f32_16x16x32_bf16 v[116:119], v[132:135], v[32:35], v[40:43]
	s_nop 2
	v_mul_f32_e64 v42, v122, v60
	v_mul_f32_e64 v43, v123, v60
	v_pk_mul_f32 v[40:41], v[120:121], v[60:61] op_sel_hi:[1,0]
	s_waitcnt lgkmcnt(4)
	s_nop 0
	v_mfma_f32_16x16x32_bf16 v[120:123], v[128:131], v[56:59], v[40:43]
	s_nop 2
	v_mul_f32_e64 v42, v126, v62
	v_mul_f32_e64 v43, v127, v62
	v_pk_mul_f32 v[40:41], v[124:125], v[62:63] op_sel_hi:[1,0]
	s_nop 1
	v_mfma_f32_16x16x32_bf16 v[124:127], v[128:131], v[32:35], v[40:43]
	v_med3_i32 v32, v180, 0, s75
	v_add_u32_e32 v32, s74, v32
	v_ashrrev_i32_e32 v33, 31, v32
	v_lshlrev_b64 v[32:33], 9, v[32:33]
	v_lshl_add_u64 v[32:33], v[164:165], 0, v[32:33]
	global_load_dwordx4 v[56:59], v[32:33], off
	v_med3_i32 v32, v179, 0, s75
	v_add_u32_e32 v32, s74, v32
	v_ashrrev_i32_e32 v33, 31, v32
	v_lshlrev_b64 v[32:33], 9, v[32:33]
	v_lshl_add_u64 v[32:33], v[164:165], 0, v[32:33]
	global_load_dwordx4 v[60:63], v[32:33], off
	v_med3_i32 v32, v178, 0, s75
	v_add_u32_e32 v32, s74, v32
	v_ashrrev_i32_e32 v33, 31, v32
	v_lshlrev_b64 v[32:33], 9, v[32:33]
	v_lshl_add_u64 v[32:33], v[164:165], 0, v[32:33]
	global_load_dwordx4 v[88:91], v[32:33], off
	v_med3_i32 v32, v177, 0, s75
	v_add_u32_e32 v32, s74, v32
	v_ashrrev_i32_e32 v33, 31, v32
	v_lshlrev_b64 v[32:33], 9, v[32:33]
	v_lshl_add_u64 v[32:33], v[164:165], 0, v[32:33]
	global_load_dwordx4 v[96:99], v[32:33], off
	v_or_b32_e32 v32, 0x100, v166
	v_add_u32_e32 v32, s76, v32
	v_med3_i32 v32, v32, 0, s75
	v_add_u32_e32 v32, s74, v32
	v_ashrrev_i32_e32 v33, 31, v32
	v_lshlrev_b64 v[32:33], 9, v[32:33]
	v_lshl_add_u64 v[32:33], s[68:69], 0, v[32:33]
	v_lshl_add_u64 v[32:33], v[32:33], 0, v[158:159]
	global_load_dwordx4 v[76:79], v[32:33], off
	global_load_dwordx4 v[64:67], v[32:33], off offset:64
	v_or_b32_e32 v32, 0x110, v166
	v_add_u32_e32 v32, s76, v32
	v_med3_i32 v32, v32, 0, s75
	v_add_u32_e32 v32, s74, v32
	v_ashrrev_i32_e32 v33, 31, v32
	v_lshlrev_b64 v[32:33], 9, v[32:33]
	v_lshl_add_u64 v[32:33], s[68:69], 0, v[32:33]
	v_lshl_add_u64 v[32:33], v[32:33], 0, v[158:159]
	global_load_dwordx4 v[40:43], v[32:33], off
	s_nop 0
	global_load_dwordx4 v[32:35], v[32:33], off offset:64
	ds_read_b64_tr_b16 v[142:143], v169 offset:2304
	ds_read_b64_tr_b16 v[140:141], v169
	ds_read_b64_tr_b16 v[136:137], v169 offset:32
	ds_read_b64_tr_b16 v[138:139], v169 offset:2336
	ds_read_b64_tr_b16 v[132:133], v169 offset:64
	ds_read_b64_tr_b16 v[134:135], v169 offset:2368
	ds_read_b64_tr_b16 v[128:129], v169 offset:96
	ds_read_b64_tr_b16 v[130:131], v169 offset:2400
	s_waitcnt vmcnt(15)
	ds_write_b128 v241, v[68:71] offset:4608
	s_waitcnt vmcnt(14)
	ds_write_b128 v242, v[72:75] offset:4608
	s_waitcnt vmcnt(13)
	ds_write_b128 v243, v[80:83] offset:4608
	s_waitcnt vmcnt(12)
	ds_write_b128 v244, v[84:87] offset:4608
	v_mfma_f32_16x16x32_bf16 v[68:71], v[36:39], v[4:7], 0
	v_mfma_f32_16x16x32_bf16 v[72:75], v[24:27], v[4:7], 0
	v_mfma_f32_16x16x32_bf16 v[24:27], v[24:27], v[12:15], 0
	v_mfma_f32_16x16x32_bf16 v[68:71], v[44:47], v[8:11], v[68:71]
	v_mfma_f32_16x16x32_bf16 v[72:75], v[28:31], v[8:11], v[72:75]
	v_mfma_f32_16x16x32_bf16 v[24:27], v[28:31], v[0:3], v[24:27]
	v_add_u32_e32 v29, 0x100, v154
	v_sub_u32_e32 v28, v29, v147
	v_add_u32_e32 v31, 1, v28
	v_mfma_f32_16x16x32_bf16 v[36:39], v[36:39], v[12:15], 0
	s_nop 1
	v_max_f32_e32 v30, v68, v68
	v_cmp_gt_u32_e64 s[0:1], v31, v146
	v_cmp_gt_u32_e32 vcc, v28, v146
	v_max_f32_e32 v30, 0xf149f2ca, v30
	v_cndmask_b32_e64 v31, v69, v246, s[0:1]
	v_cndmask_b32_e32 v30, v30, v246, vcc
	v_mfma_f32_16x16x32_bf16 v[36:39], v[44:47], v[0:3], v[36:39]
	v_max_f32_e32 v30, v30, v31
	v_add_u32_e32 v31, 2, v28
	v_add_u32_e32 v44, 3, v28
	v_cmp_gt_u32_e64 s[22:23], v31, v146
	v_cmp_gt_u32_e64 s[24:25], v44, v146
	v_sub_u32_e32 v29, v29, v148
	v_cndmask_b32_e64 v31, v70, v246, s[22:23]
	v_cndmask_b32_e64 v44, v71, v246, s[24:25]
	v_max3_f32 v30, v30, v31, v44
	v_add_u32_e32 v31, 16, v28
	v_add_u32_e32 v44, 17, v28
	v_cmp_gt_u32_e64 s[26:27], v31, v146
	v_cmp_gt_u32_e64 s[28:29], v44, v146
	v_cmp_gt_u32_e64 s[38:39], v29, v145
	v_cndmask_b32_e64 v31, v72, v246, s[26:27]
	v_cndmask_b32_e64 v44, v73, v246, s[28:29]
	v_max3_f32 v30, v30, v31, v44
	v_add_u32_e32 v31, 18, v28
	v_add_u32_e32 v28, 19, v28
	v_cmp_gt_u32_e64 s[30:31], v31, v146
	v_cmp_gt_u32_e64 s[34:35], v28, v146
	v_add_u32_e32 v44, 3, v29
	v_cndmask_b32_e64 v31, v74, v246, s[30:31]
	v_cndmask_b32_e64 v28, v75, v246, s[34:35]
	v_max3_f32 v28, v30, v31, v28
	v_add_u32_e32 v31, 1, v29
	v_max_f32_e32 v30, v36, v36
	v_cmp_gt_u32_e64 s[40:41], v31, v145
	v_max_f32_e32 v30, 0xf149f2ca, v30
	v_cndmask_b32_e64 v30, v30, v246, s[38:39]
	v_cndmask_b32_e64 v31, v37, v246, s[40:41]
	v_max_f32_e32 v30, v30, v31
	v_add_u32_e32 v31, 2, v29
	v_cmp_gt_u32_e64 s[42:43], v31, v145
	v_cmp_gt_u32_e64 s[44:45], v44, v145
	s_nop 0
	v_cndmask_b32_e64 v31, v38, v246, s[42:43]
	v_cndmask_b32_e64 v44, v39, v246, s[44:45]
	v_max3_f32 v30, v30, v31, v44
	v_add_u32_e32 v31, 16, v29
	v_add_u32_e32 v44, 17, v29
	v_cmp_gt_u32_e64 s[46:47], v31, v145
	v_cmp_gt_u32_e64 s[48:49], v44, v145
	s_nop 0
	v_cndmask_b32_e64 v31, v24, v246, s[46:47]
	v_cndmask_b32_e64 v44, v25, v246, s[48:49]
	v_max3_f32 v30, v30, v31, v44
	v_add_u32_e32 v31, 18, v29
	v_add_u32_e32 v29, 19, v29
	v_cmp_gt_u32_e64 s[50:51], v31, v145
	v_cmp_gt_u32_e64 s[52:53], v29, v145
	s_nop 0
	v_cndmask_b32_e64 v31, v26, v246, s[50:51]
	v_cndmask_b32_e64 v29, v27, v246, s[52:53]
	v_max3_f32 v29, v30, v31, v29
	v_mov_b32_e32 v30, v28
	v_mov_b32_e32 v31, v28
	s_nop 1
	v_permlane32_swap_b32_e32 v30, v31
	v_max3_f32 v28, v28, v30, v31
	v_mov_b32_e32 v30, v29
	v_mov_b32_e32 v31, v29
	s_nop 1
	v_permlane32_swap_b32_e32 v30, v31
	v_max3_f32 v29, v29, v30, v31
	v_mov_b32_e32 v30, v28
	v_mov_b32_e32 v31, v28
	s_nop 1
	v_permlane16_swap_b32_e32 v30, v31
	v_max_f32_e32 v28, v28, v30
	v_mov_b32_e32 v30, v29
	v_mov_b32_e32 v45, v29
	v_max3_f32 v175, v181, v28, v31
	s_nop 0
	v_permlane16_swap_b32_e32 v30, v45
	v_sub_f32_e32 v28, v181, v175
	v_exp_f32_e32 v44, v28
	v_sub_f32_e32 v28, v68, v175
	v_max_f32_e32 v46, v29, v30
	v_exp_f32_e32 v28, v28
	v_sub_f32_e32 v30, v69, v175
	v_exp_f32_e32 v30, v30
	v_sub_f32_e32 v31, v70, v175
	v_exp_f32_e32 v31, v31
	v_sub_f32_e32 v47, v71, v175
	v_max3_f32 v181, v184, v46, v45
	v_exp_f32_e32 v47, v47
	v_sub_f32_e32 v68, v72, v175
	v_sub_f32_e32 v36, v36, v181
	v_cndmask_b32_e64 v28, v28, 0, vcc
	v_exp_f32_e32 v68, v68
	v_sub_f32_e32 v69, v73, v175
	v_exp_f32_e32 v36, v36
	v_sub_f32_e32 v37, v37, v181
	v_add_f32_e32 v29, 0, v28
	v_cndmask_b32_e64 v30, v30, 0, s[0:1]
	v_exp_f32_e32 v69, v69
	v_sub_f32_e32 v70, v74, v175
	v_exp_f32_e32 v37, v37
	v_sub_f32_e32 v38, v38, v181
	v_add_f32_e32 v29, v30, v29
	v_cndmask_b32_e64 v31, v31, 0, s[22:23]
	v_exp_f32_e32 v70, v70
	v_sub_f32_e32 v71, v75, v175
	v_exp_f32_e32 v38, v38
	v_sub_f32_e32 v39, v39, v181
	v_add_f32_e32 v29, v31, v29
	v_cndmask_b32_e64 v47, v47, 0, s[24:25]
	v_exp_f32_e32 v71, v71
	v_exp_f32_e32 v39, v39
	v_sub_f32_e32 v24, v24, v181
	v_add_f32_e32 v29, v47, v29
	v_cndmask_b32_e64 v68, v68, 0, s[26:27]
	v_sub_f32_e32 v45, v184, v181
	v_cndmask_b32_e64 v36, v36, 0, s[38:39]
	v_exp_f32_e32 v24, v24
	v_sub_f32_e32 v25, v25, v181
	v_add_f32_e32 v29, v68, v29
	v_cndmask_b32_e64 v69, v69, 0, s[28:29]
	v_exp_f32_e32 v46, v45
	v_add_f32_e32 v45, 0, v36
	v_cndmask_b32_e64 v37, v37, 0, s[40:41]
	v_exp_f32_e32 v25, v25
	v_add_f32_e32 v29, v69, v29
	v_cndmask_b32_e64 v70, v70, 0, s[30:31]
	v_add_f32_e32 v45, v37, v45
	v_cndmask_b32_e64 v38, v38, 0, s[42:43]
	v_add_f32_e32 v29, v70, v29
	v_cndmask_b32_e64 v71, v71, 0, s[34:35]
	v_add_f32_e32 v45, v38, v45
	v_cndmask_b32_e64 v39, v39, 0, s[44:45]
	v_add_f32_e32 v176, v71, v29
	v_cvt_pk_bf16_f32 v29, v31, v47
	v_add_f32_e32 v45, v39, v45
	v_cndmask_b32_e64 v47, v24, 0, s[46:47]
	v_add_f32_e32 v24, v47, v45
	v_cndmask_b32_e64 v45, v25, 0, s[48:49]
	v_sub_f32_e32 v25, v26, v181
	v_exp_f32_e32 v25, v25
	v_cvt_pk_bf16_f32 v28, v28, v30
	v_cvt_pk_bf16_f32 v30, v68, v69
	v_add_f32_e32 v24, v45, v24
	v_cndmask_b32_e64 v68, v25, 0, s[50:51]
	v_sub_f32_e32 v25, v27, v181
	v_exp_f32_e32 v25, v25
	v_add_f32_e32 v24, v68, v24
	v_fmac_f32_e32 v176, v183, v44
	v_cvt_pk_bf16_f32 v31, v70, v71
	v_cndmask_b32_e64 v27, v25, 0, s[52:53]
	v_add_f32_e32 v183, v27, v24
	v_cvt_pk_bf16_f32 v24, v36, v37
	v_cvt_pk_bf16_f32 v25, v38, v39
	v_pk_mul_f32 v[38:39], v[102:103], v[44:45] op_sel_hi:[1,0]
	v_pk_mul_f32 v[36:37], v[100:101], v[44:45] op_sel_hi:[1,0]
	v_cvt_pk_bf16_f32 v26, v47, v45
	v_cvt_pk_bf16_f32 v27, v68, v27
	s_waitcnt lgkmcnt(10)
	v_mfma_f32_16x16x32_bf16 v[80:83], v[140:143], v[28:31], v[36:39]
	v_fmac_f32_e32 v183, v185, v46
	v_add_u32_e32 v184, s76, v204
	v_add_u32_e32 v185, s76, v205
	v_pk_mul_f32 v[38:39], v[94:95], v[46:47] op_sel_hi:[1,0]
	v_pk_mul_f32 v[36:37], v[92:93], v[46:47] op_sel_hi:[1,0]
	s_nop 1
	v_mfma_f32_16x16x32_bf16 v[84:87], v[140:143], v[24:27], v[36:39]
	s_nop 2
	v_mul_f32_e64 v38, v106, v44
	v_mul_f32_e64 v39, v107, v44
	v_pk_mul_f32 v[36:37], v[104:105], v[44:45] op_sel_hi:[1,0]
	s_waitcnt lgkmcnt(8)
	s_nop 0
	v_mfma_f32_16x16x32_bf16 v[104:107], v[136:139], v[28:31], v[36:39]
	s_nop 2
	v_mul_f32_e64 v38, v110, v46
	v_mul_f32_e64 v39, v111, v46
	v_pk_mul_f32 v[36:37], v[108:109], v[46:47] op_sel_hi:[1,0]
	s_nop 1
	v_mfma_f32_16x16x32_bf16 v[108:111], v[136:139], v[24:27], v[36:39]
	s_nop 2
	v_mul_f32_e64 v38, v114, v44
	v_mul_f32_e64 v39, v115, v44
	v_pk_mul_f32 v[36:37], v[112:113], v[44:45] op_sel_hi:[1,0]
	s_waitcnt lgkmcnt(6)
	s_nop 0
	v_mfma_f32_16x16x32_bf16 v[112:115], v[132:135], v[28:31], v[36:39]
	s_nop 2
	v_mul_f32_e64 v38, v118, v46
	v_mul_f32_e64 v39, v119, v46
	v_pk_mul_f32 v[36:37], v[116:117], v[46:47] op_sel_hi:[1,0]
	s_nop 1
	v_mfma_f32_16x16x32_bf16 v[116:119], v[132:135], v[24:27], v[36:39]
	s_nop 2
	v_mul_f32_e64 v38, v122, v44
	v_mul_f32_e64 v39, v123, v44
	v_pk_mul_f32 v[36:37], v[120:121], v[44:45] op_sel_hi:[1,0]
	s_waitcnt lgkmcnt(4)
	s_nop 0
	v_mfma_f32_16x16x32_bf16 v[120:123], v[128:131], v[28:31], v[36:39]
	v_mul_f32_e64 v30, v126, v46
	v_mul_f32_e64 v31, v127, v46
	v_pk_mul_f32 v[28:29], v[124:125], v[46:47] op_sel_hi:[1,0]
	s_nop 1
	v_mfma_f32_16x16x32_bf16 v[124:127], v[128:131], v[24:27], v[28:31]
	v_add_u32_e32 v24, 0x120, v149
	v_med3_i32 v24, v24, 0, s75
	v_add_u32_e32 v24, s74, v24
	v_ashrrev_i32_e32 v25, 31, v24
	v_lshlrev_b64 v[24:25], 9, v[24:25]
	v_lshl_add_u64 v[24:25], v[164:165], 0, v[24:25]
	global_load_dwordx4 v[28:31], v[24:25], off
	v_add_u32_e32 v24, 0x120, v150
	v_med3_i32 v24, v24, 0, s75
	v_add_u32_e32 v24, s74, v24
	v_ashrrev_i32_e32 v25, 31, v24
	v_lshlrev_b64 v[24:25], 9, v[24:25]
	v_lshl_add_u64 v[24:25], v[164:165], 0, v[24:25]
	global_load_dwordx4 v[44:47], v[24:25], off
	v_add_u32_e32 v24, 0x120, v151
	v_med3_i32 v24, v24, 0, s75
	v_add_u32_e32 v24, s74, v24
	v_ashrrev_i32_e32 v25, 31, v24
	v_lshlrev_b64 v[24:25], 9, v[24:25]
	v_lshl_add_u64 v[24:25], v[164:165], 0, v[24:25]
	global_load_dwordx4 v[92:95], v[24:25], off
	v_add_u32_e32 v24, 0x120, v252
	v_med3_i32 v24, v24, 0, s75
	v_add_u32_e32 v24, s74, v24
	v_ashrrev_i32_e32 v25, 31, v24
	v_lshlrev_b64 v[24:25], 9, v[24:25]
	v_lshl_add_u64 v[24:25], v[164:165], 0, v[24:25]
	global_load_dwordx4 v[100:103], v[24:25], off
	v_or_b32_e32 v24, 0x120, v166
	v_add_u32_e32 v24, s76, v24
	v_med3_i32 v24, v24, 0, s75
	v_add_u32_e32 v24, s74, v24
	v_ashrrev_i32_e32 v25, 31, v24
	v_lshlrev_b64 v[24:25], 9, v[24:25]
	v_lshl_add_u64 v[24:25], s[68:69], 0, v[24:25]
	v_lshl_add_u64 v[24:25], v[24:25], 0, v[158:159]
	global_load_dwordx4 v[72:75], v[24:25], off
	global_load_dwordx4 v[68:71], v[24:25], off offset:64
	v_or_b32_e32 v24, 0x130, v166
	v_add_u32_e32 v24, s76, v24
	v_med3_i32 v24, v24, 0, s75
	v_add_u32_e32 v24, s74, v24
	v_ashrrev_i32_e32 v25, 31, v24
	v_lshlrev_b64 v[24:25], 9, v[24:25]
	v_lshl_add_u64 v[24:25], s[68:69], 0, v[24:25]
	v_lshl_add_u64 v[24:25], v[24:25], 0, v[158:159]
	global_load_dwordx4 v[36:39], v[24:25], off
	s_nop 0
	global_load_dwordx4 v[24:27], v[24:25], off offset:64
	ds_read_b64_tr_b16 v[142:143], v169 offset:6912
	ds_read_b64_tr_b16 v[140:141], v169 offset:4608
	ds_read_b64_tr_b16 v[136:137], v169 offset:4640
	ds_read_b64_tr_b16 v[138:139], v169 offset:6944
	ds_read_b64_tr_b16 v[132:133], v169 offset:4672
	ds_read_b64_tr_b16 v[134:135], v169 offset:6976
	ds_read_b64_tr_b16 v[128:129], v169 offset:4704
	ds_read_b64_tr_b16 v[130:131], v169 offset:7008
	s_waitcnt vmcnt(15)
	ds_write_b128 v241, v[56:59]
	s_waitcnt vmcnt(14)
	ds_write_b128 v242, v[60:63]
	s_waitcnt vmcnt(13)
	ds_write_b128 v243, v[88:91]
	s_waitcnt vmcnt(12)
	ds_write_b128 v244, v[96:99]
	v_mfma_f32_16x16x32_bf16 v[56:59], v[48:51], v[4:7], 0
	v_mfma_f32_16x16x32_bf16 v[60:63], v[16:19], v[4:7], 0
	v_mfma_f32_16x16x32_bf16 v[16:19], v[16:19], v[12:15], 0
	v_mfma_f32_16x16x32_bf16 v[56:59], v[52:55], v[8:11], v[56:59]
	v_mfma_f32_16x16x32_bf16 v[60:63], v[20:23], v[8:11], v[60:63]
	v_mfma_f32_16x16x32_bf16 v[16:19], v[20:23], v[0:3], v[16:19]
	v_sub_u32_e32 v20, v195, v147
	v_add_u32_e32 v23, 1, v20
	s_nop 3
	v_max_f32_e32 v22, v56, v56
	v_mfma_f32_16x16x32_bf16 v[48:51], v[48:51], v[12:15], 0
	v_cmp_gt_u32_e64 s[0:1], v23, v146
	v_cmp_gt_u32_e32 vcc, v20, v146
	v_max_f32_e32 v22, 0xf149f2ca, v22
	v_cndmask_b32_e64 v23, v57, v246, s[0:1]
	v_cndmask_b32_e32 v22, v22, v246, vcc
	v_mfma_f32_16x16x32_bf16 v[48:51], v[52:55], v[0:3], v[48:51]
	v_max_f32_e32 v22, v22, v23
	v_add_u32_e32 v23, 2, v20
	v_add_u32_e32 v52, 3, v20
	v_cmp_gt_u32_e64 s[22:23], v23, v146
	v_cmp_gt_u32_e64 s[24:25], v52, v146
	v_sub_u32_e32 v21, v195, v148
	v_cndmask_b32_e64 v23, v58, v246, s[22:23]
	v_cndmask_b32_e64 v52, v59, v246, s[24:25]
	v_max3_f32 v22, v22, v23, v52
	v_add_u32_e32 v23, 16, v20
	v_add_u32_e32 v52, 17, v20
	v_cmp_gt_u32_e64 s[26:27], v23, v146
	v_cmp_gt_u32_e64 s[28:29], v52, v146
	v_cmp_gt_u32_e64 s[38:39], v21, v145
	v_cndmask_b32_e64 v23, v60, v246, s[26:27]
	v_cndmask_b32_e64 v52, v61, v246, s[28:29]
	v_max3_f32 v22, v22, v23, v52
	v_add_u32_e32 v23, 18, v20
	v_add_u32_e32 v20, 19, v20
	v_cmp_gt_u32_e64 s[30:31], v23, v146
	v_cmp_gt_u32_e64 s[34:35], v20, v146
	v_add_u32_e32 v52, 3, v21
	v_cndmask_b32_e64 v23, v62, v246, s[30:31]
	v_cndmask_b32_e64 v20, v63, v246, s[34:35]
	v_max3_f32 v20, v22, v23, v20
	v_add_u32_e32 v23, 1, v21
	v_max_f32_e32 v22, v48, v48
	v_cmp_gt_u32_e64 s[40:41], v23, v145
	v_max_f32_e32 v22, 0xf149f2ca, v22
	v_cndmask_b32_e64 v22, v22, v246, s[38:39]
	v_cndmask_b32_e64 v23, v49, v246, s[40:41]
	v_max_f32_e32 v22, v22, v23
	v_add_u32_e32 v23, 2, v21
	v_cmp_gt_u32_e64 s[42:43], v23, v145
	v_cmp_gt_u32_e64 s[44:45], v52, v145
	s_nop 0
	v_cndmask_b32_e64 v23, v50, v246, s[42:43]
	v_cndmask_b32_e64 v52, v51, v246, s[44:45]
	v_max3_f32 v22, v22, v23, v52
	v_add_u32_e32 v23, 16, v21
	v_add_u32_e32 v52, 17, v21
	v_cmp_gt_u32_e64 s[46:47], v23, v145
	v_cmp_gt_u32_e64 s[48:49], v52, v145
	s_nop 0
	v_cndmask_b32_e64 v23, v16, v246, s[46:47]
	v_cndmask_b32_e64 v52, v17, v246, s[48:49]
	v_max3_f32 v22, v22, v23, v52
	v_add_u32_e32 v23, 18, v21
	v_add_u32_e32 v21, 19, v21
	v_cmp_gt_u32_e64 s[50:51], v23, v145
	v_cmp_gt_u32_e64 s[52:53], v21, v145
	s_nop 0
	v_cndmask_b32_e64 v23, v18, v246, s[50:51]
	v_cndmask_b32_e64 v21, v19, v246, s[52:53]
	v_max3_f32 v21, v22, v23, v21
	v_mov_b32_e32 v22, v20
	v_mov_b32_e32 v23, v20
	s_nop 1
	v_permlane32_swap_b32_e32 v22, v23
	v_max3_f32 v20, v20, v22, v23
	v_mov_b32_e32 v22, v21
	v_mov_b32_e32 v23, v21
	s_nop 1
	v_permlane32_swap_b32_e32 v22, v23
	v_max3_f32 v21, v21, v22, v23
	v_mov_b32_e32 v22, v20
	v_mov_b32_e32 v23, v20
	s_nop 1
	v_permlane16_swap_b32_e32 v22, v23
	v_max_f32_e32 v20, v20, v22
	v_max3_f32 v149, v175, v20, v23
	v_sub_f32_e32 v20, v175, v149
	v_exp_f32_e32 v88, v20
	v_sub_f32_e32 v20, v56, v149
	v_sub_f32_e32 v56, v61, v149
	v_exp_f32_e32 v56, v56
	v_exp_f32_e32 v20, v20
	v_sub_f32_e32 v23, v57, v149
	v_exp_f32_e32 v23, v23
	v_sub_f32_e32 v53, v58, v149
	v_cndmask_b32_e64 v58, v56, 0, s[28:29]
	v_sub_f32_e32 v56, v62, v149
	v_mov_b32_e32 v22, v21
	v_mov_b32_e32 v52, v21
	v_exp_f32_e32 v53, v53
	v_sub_f32_e32 v54, v59, v149
	v_exp_f32_e32 v56, v56
	v_permlane16_swap_b32_e32 v22, v52
	v_exp_f32_e32 v54, v54
	v_sub_f32_e32 v55, v60, v149
	v_cndmask_b32_e64 v20, v20, 0, vcc
	v_exp_f32_e32 v55, v55
	v_max_f32_e32 v21, v21, v22
	v_add_f32_e32 v22, 0, v20
	v_cndmask_b32_e64 v23, v23, 0, s[0:1]
	v_add_f32_e32 v22, v23, v22
	v_cndmask_b32_e64 v53, v53, 0, s[22:23]
	v_cndmask_b32_e64 v59, v56, 0, s[30:31]
	v_sub_f32_e32 v56, v63, v149
	v_add_f32_e32 v22, v53, v22
	v_cndmask_b32_e64 v54, v54, 0, s[24:25]
	v_exp_f32_e32 v56, v56
	v_add_f32_e32 v22, v54, v22
	v_cndmask_b32_e64 v55, v55, 0, s[26:27]
	v_add_f32_e32 v22, v55, v22
	v_add_f32_e32 v22, v58, v22
	v_max3_f32 v151, v181, v21, v52
	v_add_f32_e32 v22, v59, v22
	v_cndmask_b32_e64 v60, v56, 0, s[34:35]
	v_cvt_pk_bf16_f32 v56, v20, v23
	v_sub_f32_e32 v20, v181, v151
	v_add_f32_e32 v150, v60, v22
	v_cvt_pk_bf16_f32 v59, v59, v60
	v_exp_f32_e32 v60, v20
	v_sub_f32_e32 v20, v48, v151
	v_exp_f32_e32 v20, v20
	v_sub_f32_e32 v22, v49, v151
	v_exp_f32_e32 v22, v22
	v_sub_f32_e32 v23, v50, v151
	v_exp_f32_e32 v23, v23
	v_sub_f32_e32 v48, v51, v151
	v_exp_f32_e32 v48, v48
	v_sub_f32_e32 v16, v16, v151
	v_cndmask_b32_e64 v20, v20, 0, s[38:39]
	v_exp_f32_e32 v16, v16
	v_sub_f32_e32 v17, v17, v151
	v_add_f32_e32 v21, 0, v20
	v_cndmask_b32_e64 v22, v22, 0, s[40:41]
	v_exp_f32_e32 v17, v17
	v_add_f32_e32 v21, v22, v21
	v_cndmask_b32_e64 v23, v23, 0, s[42:43]
	v_add_f32_e32 v21, v23, v21
	v_cndmask_b32_e64 v48, v48, 0, s[44:45]
	v_add_f32_e32 v21, v48, v21
	v_cndmask_b32_e64 v49, v16, 0, s[46:47]
	v_add_f32_e32 v16, v49, v21
	v_cndmask_b32_e64 v21, v17, 0, s[48:49]
	v_sub_f32_e32 v17, v18, v151
	v_exp_f32_e32 v17, v17
	v_add_f32_e32 v16, v21, v16
	v_cvt_pk_bf16_f32 v18, v49, v21
	v_cvt_pk_bf16_f32 v57, v53, v54
	v_cndmask_b32_e64 v50, v17, 0, s[50:51]
	v_sub_f32_e32 v17, v19, v151
	v_exp_f32_e32 v17, v17
	v_add_f32_e32 v16, v50, v16
	v_cvt_pk_bf16_f32 v58, v55, v58
	v_fmac_f32_e32 v150, v176, v88
	v_cndmask_b32_e64 v19, v17, 0, s[52:53]
	v_add_f32_e32 v175, v19, v16
	v_cvt_pk_bf16_f32 v16, v20, v22
	v_cvt_pk_bf16_f32 v17, v23, v48
	v_cvt_pk_bf16_f32 v19, v50, v19
	v_pk_mul_f32 v[50:51], v[86:87], v[60:61] op_sel_hi:[1,0]
	v_pk_mul_f32 v[48:49], v[84:85], v[60:61] op_sel_hi:[1,0]
	v_pk_mul_f32 v[22:23], v[82:83], v[88:89] op_sel_hi:[1,0]
	v_pk_mul_f32 v[20:21], v[80:81], v[88:89] op_sel_hi:[1,0]
	s_waitcnt lgkmcnt(10)
	v_mfma_f32_16x16x32_bf16 v[52:55], v[140:143], v[16:19], v[48:51]
	v_fmac_f32_e32 v175, v183, v60
	s_nop 1
	v_pk_mul_f32 v[50:51], v[106:107], v[88:89] op_sel_hi:[1,0]
	v_pk_mul_f32 v[48:49], v[104:105], v[88:89] op_sel_hi:[1,0]
	v_mfma_f32_16x16x32_bf16 v[20:23], v[140:143], v[56:59], v[20:23]
	s_waitcnt lgkmcnt(8)
	v_mfma_f32_16x16x32_bf16 v[104:107], v[136:139], v[56:59], v[48:51]
	s_nop 2
	v_mul_f32_e64 v50, v110, v60
	v_mul_f32_e64 v51, v111, v60
	v_pk_mul_f32 v[48:49], v[108:109], v[60:61] op_sel_hi:[1,0]
	s_nop 1
	v_mfma_f32_16x16x32_bf16 v[108:111], v[136:139], v[16:19], v[48:51]
	s_nop 2
	v_mul_f32_e64 v50, v114, v88
	v_mul_f32_e64 v51, v115, v88
	v_pk_mul_f32 v[48:49], v[112:113], v[88:89] op_sel_hi:[1,0]
	s_waitcnt lgkmcnt(6)
	s_nop 0
	v_mfma_f32_16x16x32_bf16 v[112:115], v[132:135], v[56:59], v[48:51]
	s_nop 2
	v_mul_f32_e64 v50, v118, v60
	v_mul_f32_e64 v51, v119, v60
	v_pk_mul_f32 v[48:49], v[116:117], v[60:61] op_sel_hi:[1,0]
	s_nop 1
	v_mfma_f32_16x16x32_bf16 v[116:119], v[132:135], v[16:19], v[48:51]
	s_nop 2
	v_mul_f32_e64 v50, v122, v88
	v_mul_f32_e64 v51, v123, v88
	v_pk_mul_f32 v[48:49], v[120:121], v[88:89] op_sel_hi:[1,0]
	s_waitcnt lgkmcnt(4)
	s_nop 0
	v_mfma_f32_16x16x32_bf16 v[120:123], v[128:131], v[56:59], v[48:51]
	v_add_u32_e32 v56, 0xffffff00, v206
	v_add_u32_e32 v56, s76, v56
	s_nop 0
	v_pk_mul_f32 v[50:51], v[126:127], v[60:61] op_sel_hi:[1,0]
	v_pk_mul_f32 v[48:49], v[124:125], v[60:61] op_sel_hi:[1,0]
	s_nop 1
	v_mfma_f32_16x16x32_bf16 v[124:127], v[128:131], v[16:19], v[48:51]
	v_add_u32_e32 v16, 0xffffff00, v204
	v_add_u32_e32 v16, s76, v16
	s_nop 0
	v_add_u32_e32 v48, 0xffffff00, v205
	v_add_u32_e32 v48, s76, v48
	v_med3_i32 v16, v16, 0, s75
	v_add_u32_e32 v16, s74, v16
	v_ashrrev_i32_e32 v17, 31, v16
	v_med3_i32 v48, v48, 0, s75
	v_add_u32_e32 v48, s74, v48
	v_ashrrev_i32_e32 v49, 31, v48
	v_med3_i32 v56, v56, 0, s75
	v_add_u32_e32 v56, s74, v56
	v_ashrrev_i32_e32 v57, 31, v56
	v_lshlrev_b64 v[56:57], 9, v[56:57]
	v_lshl_add_u64 v[56:57], v[164:165], 0, v[56:57]
	global_load_dwordx4 v[88:91], v[56:57], off
	v_add_u32_e32 v56, 0xffffff00, v207
	v_add_u32_e32 v56, s76, v56
	v_lshlrev_b64 v[16:17], 9, v[16:17]
	v_lshlrev_b64 v[48:49], 9, v[48:49]
	v_med3_i32 v56, v56, 0, s75
	v_add_u32_e32 v56, s74, v56
	v_ashrrev_i32_e32 v57, 31, v56
	v_lshlrev_b64 v[56:57], 9, v[56:57]
	v_lshl_add_u64 v[56:57], v[164:165], 0, v[56:57]
	global_load_dwordx4 v[96:99], v[56:57], off
	v_add_u32_e32 v56, s76, v208
	v_lshl_add_u64 v[16:17], v[164:165], 0, v[16:17]
	v_lshl_add_u64 v[48:49], v[164:165], 0, v[48:49]
	v_med3_i32 v56, v56, 0, s75
	v_add_u32_e32 v56, s74, v56
	v_ashrrev_i32_e32 v57, 31, v56
	v_lshlrev_b64 v[56:57], 9, v[56:57]
	v_lshl_add_u64 v[56:57], s[68:69], 0, v[56:57]
	v_lshl_add_u64 v[56:57], v[56:57], 0, v[158:159]
	global_load_dwordx4 v[16:19], v[16:17], off
	s_nop 0
	global_load_dwordx4 v[48:51], v[48:49], off
	s_nop 0
	global_load_dwordx4 v[84:87], v[56:57], off
	global_load_dwordx4 v[80:83], v[56:57], off offset:64
	v_or_b32_e32 v56, 0xffffff40, v209
	v_add_u32_e32 v56, s76, v56
	v_med3_i32 v56, v56, 0, s75
	v_add_u32_e32 v56, s74, v56
	v_ashrrev_i32_e32 v57, 31, v56
	v_lshlrev_b64 v[56:57], 9, v[56:57]
	v_lshl_add_u64 v[56:57], s[68:69], 0, v[56:57]
	v_lshl_add_u64 v[56:57], v[56:57], 0, v[158:159]
	global_load_dwordx4 v[60:63], v[56:57], off
	s_nop 0
	global_load_dwordx4 v[56:59], v[56:57], off offset:64
	ds_read_b64_tr_b16 v[142:143], v169 offset:2304
	ds_read_b64_tr_b16 v[140:141], v169
	ds_read_b64_tr_b16 v[136:137], v169 offset:32
	ds_read_b64_tr_b16 v[138:139], v169 offset:2336
	ds_read_b64_tr_b16 v[132:133], v169 offset:64
	ds_read_b64_tr_b16 v[134:135], v169 offset:2368
	ds_read_b64_tr_b16 v[128:129], v169 offset:96
	ds_read_b64_tr_b16 v[130:131], v169 offset:2400
	s_waitcnt vmcnt(15)
	ds_write_b128 v241, v[28:31] offset:4608
	s_waitcnt vmcnt(14)
	ds_write_b128 v242, v[44:47] offset:4608
	s_waitcnt vmcnt(13)
	ds_write_b128 v243, v[92:95] offset:4608
	s_waitcnt vmcnt(12)
	ds_write_b128 v244, v[100:103] offset:4608
	v_mfma_f32_16x16x32_bf16 v[28:31], v[76:79], v[4:7], 0
	v_mfma_f32_16x16x32_bf16 v[44:47], v[40:43], v[4:7], 0
	v_mfma_f32_16x16x32_bf16 v[40:43], v[40:43], v[12:15], 0
	v_mfma_f32_16x16x32_bf16 v[28:31], v[64:67], v[8:11], v[28:31]
	v_mfma_f32_16x16x32_bf16 v[44:47], v[32:35], v[8:11], v[44:47]
	v_mfma_f32_16x16x32_bf16 v[32:35], v[32:35], v[0:3], v[40:43]
	s_nop 4
	v_sub_u32_e32 v40, v210, v147
	v_mfma_f32_16x16x32_bf16 v[76:79], v[76:79], v[12:15], 0
	v_add_u32_e32 v43, 1, v40
	v_max_f32_e32 v42, v28, v28
	v_cmp_gt_u32_e64 s[0:1], v43, v146
	v_cmp_gt_u32_e32 vcc, v40, v146
	v_max_f32_e32 v42, 0xf149f2ca, v42
	v_cndmask_b32_e64 v43, v29, v246, s[0:1]
	v_cndmask_b32_e32 v42, v42, v246, vcc
	v_mfma_f32_16x16x32_bf16 v[64:67], v[64:67], v[0:3], v[76:79]
	v_max_f32_e32 v42, v42, v43
	v_add_u32_e32 v43, 2, v40
	v_cmp_gt_u32_e64 s[22:23], v43, v146
	v_add_u32_e32 v76, 3, v40
	v_cmp_gt_u32_e64 s[24:25], v76, v146
	v_cndmask_b32_e64 v43, v30, v246, s[22:23]
	v_sub_u32_e32 v41, v210, v148
	v_cndmask_b32_e64 v76, v31, v246, s[24:25]
	v_max3_f32 v42, v42, v43, v76
	v_add_u32_e32 v43, 16, v40
	v_add_u32_e32 v76, 17, v40
	v_cmp_gt_u32_e64 s[26:27], v43, v146
	v_cmp_gt_u32_e64 s[28:29], v76, v146
	v_cmp_gt_u32_e64 s[38:39], v41, v145
	v_cndmask_b32_e64 v43, v44, v246, s[26:27]
	v_cndmask_b32_e64 v76, v45, v246, s[28:29]
	v_max3_f32 v42, v42, v43, v76
	v_add_u32_e32 v43, 18, v40
	v_add_u32_e32 v40, 19, v40
	v_cmp_gt_u32_e64 s[30:31], v43, v146
	v_cmp_gt_u32_e64 s[34:35], v40, v146
	v_add_u32_e32 v76, 3, v41
	v_cndmask_b32_e64 v43, v46, v246, s[30:31]
	v_cndmask_b32_e64 v40, v47, v246, s[34:35]
	v_max3_f32 v40, v42, v43, v40
	v_add_u32_e32 v43, 1, v41
	v_max_f32_e32 v42, v64, v64
	v_cmp_gt_u32_e64 s[40:41], v43, v145
	v_max_f32_e32 v42, 0xf149f2ca, v42
	v_cndmask_b32_e64 v42, v42, v246, s[38:39]
	v_cndmask_b32_e64 v43, v65, v246, s[40:41]
	v_max_f32_e32 v42, v42, v43
	v_add_u32_e32 v43, 2, v41
	v_cmp_gt_u32_e64 s[42:43], v43, v145
	v_cmp_gt_u32_e64 s[44:45], v76, v145
	s_nop 0
	v_cndmask_b32_e64 v43, v66, v246, s[42:43]
	v_cndmask_b32_e64 v76, v67, v246, s[44:45]
	v_max3_f32 v42, v42, v43, v76
	v_add_u32_e32 v43, 16, v41
	v_add_u32_e32 v76, 17, v41
	v_cmp_gt_u32_e64 s[46:47], v43, v145
	v_cmp_gt_u32_e64 s[48:49], v76, v145
	s_nop 0
	v_cndmask_b32_e64 v43, v32, v246, s[46:47]
	v_cndmask_b32_e64 v76, v33, v246, s[48:49]
	v_max3_f32 v42, v42, v43, v76
	v_add_u32_e32 v43, 18, v41
	v_add_u32_e32 v41, 19, v41
	v_cmp_gt_u32_e64 s[50:51], v43, v145
	v_cmp_gt_u32_e64 s[52:53], v41, v145
	s_nop 0
	v_cndmask_b32_e64 v43, v34, v246, s[50:51]
	v_cndmask_b32_e64 v41, v35, v246, s[52:53]
	v_max3_f32 v41, v42, v43, v41
	v_mov_b32_e32 v42, v40
	v_mov_b32_e32 v43, v40
	s_nop 1
	v_permlane32_swap_b32_e32 v42, v43
	v_max3_f32 v40, v40, v42, v43
	v_mov_b32_e32 v42, v41
	v_mov_b32_e32 v43, v41
	s_nop 1
	v_permlane32_swap_b32_e32 v42, v43
	v_max3_f32 v41, v41, v42, v43
	v_mov_b32_e32 v42, v40
	v_mov_b32_e32 v43, v40
	s_nop 1
	v_permlane16_swap_b32_e32 v42, v43
	v_max_f32_e32 v40, v40, v42
	v_max3_f32 v176, v149, v40, v43
	v_sub_f32_e32 v28, v28, v176
	v_mov_b32_e32 v42, v41
	v_mov_b32_e32 v77, v41
	v_exp_f32_e32 v28, v28
	v_sub_f32_e32 v29, v29, v176
	v_permlane16_swap_b32_e32 v42, v77
	v_exp_f32_e32 v29, v29
	v_sub_f32_e32 v30, v30, v176
	v_exp_f32_e32 v30, v30
	v_sub_f32_e32 v31, v31, v176
	v_max_f32_e32 v41, v41, v42
	v_exp_f32_e32 v31, v31
	v_sub_f32_e32 v42, v44, v176
	v_sub_f32_e32 v40, v149, v176
	v_cndmask_b32_e64 v28, v28, 0, vcc
	v_exp_f32_e32 v42, v42
	v_sub_f32_e32 v43, v45, v176
	v_exp_f32_e32 v76, v40
	v_add_f32_e32 v40, 0, v28
	v_cndmask_b32_e64 v29, v29, 0, s[0:1]
	v_exp_f32_e32 v43, v43
	v_sub_f32_e32 v44, v46, v176
	v_add_f32_e32 v40, v29, v40
	v_cndmask_b32_e64 v30, v30, 0, s[22:23]
	v_exp_f32_e32 v44, v44
	v_sub_f32_e32 v45, v47, v176
	v_add_f32_e32 v40, v30, v40
	v_cndmask_b32_e64 v31, v31, 0, s[24:25]
	v_exp_f32_e32 v45, v45
	v_add_f32_e32 v40, v31, v40
	v_cndmask_b32_e64 v42, v42, 0, s[26:27]
	v_add_f32_e32 v40, v42, v40
	v_cndmask_b32_e64 v43, v43, 0, s[28:29]
	v_add_f32_e32 v40, v43, v40
	v_cndmask_b32_e64 v44, v44, 0, s[30:31]
	v_add_f32_e32 v40, v44, v40
	v_cndmask_b32_e64 v45, v45, 0, s[34:35]
	v_add_f32_e32 v149, v45, v40
	v_fmac_f32_e32 v149, v150, v76
	v_max3_f32 v150, v151, v41, v77
	v_sub_f32_e32 v40, v151, v150
	v_cvt_pk_bf16_f32 v28, v28, v29
	v_cvt_pk_bf16_f32 v29, v30, v31
	v_cvt_pk_bf16_f32 v31, v44, v45
	v_exp_f32_e32 v44, v40
	v_sub_f32_e32 v40, v64, v150
	v_cvt_pk_bf16_f32 v30, v42, v43
	v_exp_f32_e32 v40, v40
	v_sub_f32_e32 v42, v65, v150
	v_exp_f32_e32 v42, v42
	v_sub_f32_e32 v43, v66, v150
	v_exp_f32_e32 v43, v43
	v_sub_f32_e32 v45, v67, v150
	v_exp_f32_e32 v45, v45
	v_sub_f32_e32 v32, v32, v150
	v_cndmask_b32_e64 v40, v40, 0, s[38:39]
	v_exp_f32_e32 v32, v32
	v_sub_f32_e32 v33, v33, v150
	v_add_f32_e32 v41, 0, v40
	v_cndmask_b32_e64 v42, v42, 0, s[40:41]
	v_exp_f32_e32 v33, v33
	v_add_f32_e32 v41, v42, v41
	v_cndmask_b32_e64 v43, v43, 0, s[42:43]
	v_add_f32_e32 v41, v43, v41
	v_cndmask_b32_e64 v45, v45, 0, s[44:45]
	v_add_f32_e32 v41, v45, v41
	v_cndmask_b32_e64 v46, v32, 0, s[46:47]
	v_add_f32_e32 v32, v46, v41
	v_cndmask_b32_e64 v41, v33, 0, s[48:49]
	v_sub_f32_e32 v33, v34, v150
	v_exp_f32_e32 v33, v33
	v_add_f32_e32 v32, v41, v32
	v_pk_mul_f32 v[22:23], v[22:23], v[76:77] op_sel_hi:[1,0]
	v_pk_mul_f32 v[20:21], v[20:21], v[76:77] op_sel_hi:[1,0]
	v_cndmask_b32_e64 v47, v33, 0, s[50:51]
	v_sub_f32_e32 v33, v35, v150
	v_exp_f32_e32 v33, v33
	v_add_f32_e32 v32, v47, v32
	v_cvt_pk_bf16_f32 v34, v46, v41
	v_cndmask_b32_e64 v35, v33, 0, s[52:53]
	v_add_f32_e32 v151, v35, v32
	v_cvt_pk_bf16_f32 v32, v40, v42
	v_cvt_pk_bf16_f32 v33, v43, v45
	v_cvt_pk_bf16_f32 v35, v47, v35
	s_waitcnt lgkmcnt(10)
	v_mfma_f32_16x16x32_bf16 v[40:43], v[140:143], v[28:31], v[20:23]
	v_fmac_f32_e32 v151, v175, v44
	s_nop 1
	v_pk_mul_f32 v[22:23], v[54:55], v[44:45] op_sel_hi:[1,0]
	v_pk_mul_f32 v[20:21], v[52:53], v[44:45] op_sel_hi:[1,0]
	s_nop 1
	v_mfma_f32_16x16x32_bf16 v[92:95], v[140:143], v[32:35], v[20:23]
	s_nop 2
	v_mul_f32_e64 v22, v106, v76
	v_mul_f32_e64 v23, v107, v76
	v_pk_mul_f32 v[20:21], v[104:105], v[76:77] op_sel_hi:[1,0]
	s_waitcnt lgkmcnt(8)
	s_nop 0
	v_mfma_f32_16x16x32_bf16 v[104:107], v[136:139], v[28:31], v[20:23]
	s_nop 2
	v_mul_f32_e64 v22, v110, v44
	v_mul_f32_e64 v23, v111, v44
	v_pk_mul_f32 v[20:21], v[108:109], v[44:45] op_sel_hi:[1,0]
	s_nop 1
	v_mfma_f32_16x16x32_bf16 v[108:111], v[136:139], v[32:35], v[20:23]
	s_nop 2
	v_mul_f32_e64 v22, v114, v76
	v_mul_f32_e64 v23, v115, v76
	v_pk_mul_f32 v[20:21], v[112:113], v[76:77] op_sel_hi:[1,0]
	s_waitcnt lgkmcnt(6)
	s_nop 0
	v_mfma_f32_16x16x32_bf16 v[112:115], v[132:135], v[28:31], v[20:23]
	s_nop 2
	v_mul_f32_e64 v22, v118, v44
	v_mul_f32_e64 v23, v119, v44
	v_pk_mul_f32 v[20:21], v[116:117], v[44:45] op_sel_hi:[1,0]
	s_nop 1
	v_mfma_f32_16x16x32_bf16 v[116:119], v[132:135], v[32:35], v[20:23]
	s_nop 2
	v_mul_f32_e64 v22, v122, v76
	v_mul_f32_e64 v23, v123, v76
	v_pk_mul_f32 v[20:21], v[120:121], v[76:77] op_sel_hi:[1,0]
	s_waitcnt lgkmcnt(4)
	s_nop 0
	v_mfma_f32_16x16x32_bf16 v[120:123], v[128:131], v[28:31], v[20:23]
	s_nop 2
	v_mul_f32_e64 v22, v126, v44
	v_mul_f32_e64 v23, v127, v44
	v_pk_mul_f32 v[20:21], v[124:125], v[44:45] op_sel_hi:[1,0]
	s_nop 1
	v_mfma_f32_16x16x32_bf16 v[124:127], v[128:131], v[32:35], v[20:23]
	s_nop 2
	v_add_u32_e32 v20, 0xffffff80, v204
	v_add_u32_e32 v20, s76, v20
	v_med3_i32 v20, v20, 0, s75
	v_add_u32_e32 v20, s74, v20
	v_ashrrev_i32_e32 v21, 31, v20
	v_lshlrev_b64 v[20:21], 9, v[20:21]
	v_lshl_add_u64 v[20:21], v[164:165], 0, v[20:21]
	global_load_dwordx4 v[32:35], v[20:21], off
	v_add_u32_e32 v20, 0xffffff80, v205
	v_add_u32_e32 v20, s76, v20
	v_med3_i32 v20, v20, 0, s75
	v_add_u32_e32 v20, s74, v20
	v_ashrrev_i32_e32 v21, 31, v20
	v_lshlrev_b64 v[20:21], 9, v[20:21]
	v_lshl_add_u64 v[20:21], v[164:165], 0, v[20:21]
	global_load_dwordx4 v[64:67], v[20:21], off
	v_add_u32_e32 v20, 0xffffff80, v206
	v_add_u32_e32 v20, s76, v20
	v_med3_i32 v20, v20, 0, s75
	v_add_u32_e32 v20, s74, v20
	v_ashrrev_i32_e32 v21, 31, v20
	v_lshlrev_b64 v[20:21], 9, v[20:21]
	v_lshl_add_u64 v[20:21], v[164:165], 0, v[20:21]
	global_load_dwordx4 v[76:79], v[20:21], off
	v_add_u32_e32 v20, 0xffffff80, v207
	v_add_u32_e32 v20, s76, v20
	v_med3_i32 v20, v20, 0, s75
	v_add_u32_e32 v20, s74, v20
	v_ashrrev_i32_e32 v21, 31, v20
	v_lshlrev_b64 v[20:21], 9, v[20:21]
	v_lshl_add_u64 v[20:21], v[164:165], 0, v[20:21]
	global_load_dwordx4 v[100:103], v[20:21], off
	v_or_b32_e32 v20, 0xffffff80, v209
	v_add_u32_e32 v20, s76, v20
	v_med3_i32 v20, v20, 0, s75
	v_add_u32_e32 v20, s74, v20
	v_ashrrev_i32_e32 v21, 31, v20
	v_lshlrev_b64 v[20:21], 9, v[20:21]
	v_lshl_add_u64 v[20:21], s[68:69], 0, v[20:21]
	v_lshl_add_u64 v[20:21], v[20:21], 0, v[158:159]
	global_load_dwordx4 v[52:55], v[20:21], off
	global_load_dwordx4 v[44:47], v[20:21], off offset:64
	v_add_u32_e32 v20, s76, v211
	v_med3_i32 v20, v20, 0, s75
	v_add_u32_e32 v20, s74, v20
	v_ashrrev_i32_e32 v21, 31, v20
	v_lshlrev_b64 v[20:21], 9, v[20:21]
	v_lshl_add_u64 v[20:21], s[68:69], 0, v[20:21]
	v_lshl_add_u64 v[20:21], v[20:21], 0, v[158:159]
	global_load_dwordx4 v[28:31], v[20:21], off
	s_nop 0
	global_load_dwordx4 v[20:23], v[20:21], off offset:64
	ds_read_b64_tr_b16 v[142:143], v169 offset:6912
	ds_read_b64_tr_b16 v[140:141], v169 offset:4608
	ds_read_b64_tr_b16 v[136:137], v169 offset:4640
	ds_read_b64_tr_b16 v[138:139], v169 offset:6944
	ds_read_b64_tr_b16 v[132:133], v169 offset:4672
	ds_read_b64_tr_b16 v[134:135], v169 offset:6976
	ds_read_b64_tr_b16 v[128:129], v169 offset:4704
	ds_read_b64_tr_b16 v[130:131], v169 offset:7008
	s_waitcnt vmcnt(13)
	ds_write_b128 v241, v[16:19]
	s_waitcnt vmcnt(12)
	ds_write_b128 v242, v[48:51]
	ds_write_b128 v243, v[88:91]
	ds_write_b128 v244, v[96:99]
	v_mfma_f32_16x16x32_bf16 v[16:19], v[72:75], v[4:7], 0
	v_mfma_f32_16x16x32_bf16 v[48:51], v[36:39], v[4:7], 0
	v_mfma_f32_16x16x32_bf16 v[36:39], v[36:39], v[12:15], 0
	v_mfma_f32_16x16x32_bf16 v[16:19], v[68:71], v[8:11], v[16:19]
	v_mfma_f32_16x16x32_bf16 v[48:51], v[24:27], v[8:11], v[48:51]
	v_mfma_f32_16x16x32_bf16 v[24:27], v[24:27], v[0:3], v[36:39]
	s_nop 4
	v_sub_u32_e32 v36, v212, v147
	v_mfma_f32_16x16x32_bf16 v[72:75], v[72:75], v[12:15], 0
	v_add_u32_e32 v39, 1, v36
	v_max_f32_e32 v38, v16, v16
	v_cmp_gt_u32_e64 s[0:1], v39, v146
	v_cmp_gt_u32_e32 vcc, v36, v146
	v_max_f32_e32 v38, 0xf149f2ca, v38
	v_cndmask_b32_e64 v39, v17, v246, s[0:1]
	v_cndmask_b32_e32 v38, v38, v246, vcc
	v_mfma_f32_16x16x32_bf16 v[68:71], v[68:71], v[0:3], v[72:75]
	v_max_f32_e32 v38, v38, v39
	v_add_u32_e32 v39, 2, v36
	v_cmp_gt_u32_e64 s[22:23], v39, v146
	v_add_u32_e32 v72, 3, v36
	v_cmp_gt_u32_e64 s[24:25], v72, v146
	v_cndmask_b32_e64 v39, v18, v246, s[22:23]
	v_sub_u32_e32 v37, v212, v148
	v_cndmask_b32_e64 v72, v19, v246, s[24:25]
	v_max3_f32 v38, v38, v39, v72
	v_add_u32_e32 v39, 16, v36
	v_add_u32_e32 v72, 17, v36
	v_cmp_gt_u32_e64 s[26:27], v39, v146
	v_cmp_gt_u32_e64 s[28:29], v72, v146
	v_cmp_gt_u32_e64 s[38:39], v37, v145
	v_cndmask_b32_e64 v39, v48, v246, s[26:27]
	v_cndmask_b32_e64 v72, v49, v246, s[28:29]
	v_max3_f32 v38, v38, v39, v72
	v_add_u32_e32 v39, 18, v36
	v_add_u32_e32 v36, 19, v36
	v_cmp_gt_u32_e64 s[30:31], v39, v146
	v_cmp_gt_u32_e64 s[34:35], v36, v146
	v_add_u32_e32 v72, 3, v37
	v_cndmask_b32_e64 v39, v50, v246, s[30:31]
	v_cndmask_b32_e64 v36, v51, v246, s[34:35]
	v_max3_f32 v36, v38, v39, v36
	v_add_u32_e32 v39, 1, v37
	v_max_f32_e32 v38, v68, v68
	v_cmp_gt_u32_e64 s[40:41], v39, v145
	v_max_f32_e32 v38, 0xf149f2ca, v38
	v_cndmask_b32_e64 v38, v38, v246, s[38:39]
	v_cndmask_b32_e64 v39, v69, v246, s[40:41]
	v_max_f32_e32 v38, v38, v39
	v_add_u32_e32 v39, 2, v37
	v_cmp_gt_u32_e64 s[42:43], v39, v145
	v_cmp_gt_u32_e64 s[44:45], v72, v145
	s_nop 0
	v_cndmask_b32_e64 v39, v70, v246, s[42:43]
	v_cndmask_b32_e64 v72, v71, v246, s[44:45]
	v_max3_f32 v38, v38, v39, v72
	v_add_u32_e32 v39, 16, v37
	v_add_u32_e32 v72, 17, v37
	v_cmp_gt_u32_e64 s[46:47], v39, v145
	v_cmp_gt_u32_e64 s[48:49], v72, v145
	s_nop 0
	v_cndmask_b32_e64 v39, v24, v246, s[46:47]
	v_cndmask_b32_e64 v72, v25, v246, s[48:49]
	v_max3_f32 v38, v38, v39, v72
	v_add_u32_e32 v39, 18, v37
	v_add_u32_e32 v37, 19, v37
	v_cmp_gt_u32_e64 s[50:51], v39, v145
	v_cmp_gt_u32_e64 s[52:53], v37, v145
	s_nop 0
	v_cndmask_b32_e64 v39, v26, v246, s[50:51]
	v_cndmask_b32_e64 v37, v27, v246, s[52:53]
	v_max3_f32 v37, v38, v39, v37
	v_mov_b32_e32 v38, v36
	v_mov_b32_e32 v39, v36
	s_nop 1
	v_permlane32_swap_b32_e32 v38, v39
	v_max3_f32 v36, v36, v38, v39
	v_mov_b32_e32 v38, v37
	v_mov_b32_e32 v39, v37
	s_nop 1
	v_permlane32_swap_b32_e32 v38, v39
	v_max3_f32 v37, v37, v38, v39
	v_mov_b32_e32 v38, v36
	v_mov_b32_e32 v39, v36
	s_nop 1
	v_permlane16_swap_b32_e32 v38, v39
	v_max_f32_e32 v36, v36, v38
	v_max3_f32 v145, v176, v36, v39
	v_sub_f32_e32 v16, v16, v145
	v_mov_b32_e32 v38, v37
	v_mov_b32_e32 v72, v37
	v_exp_f32_e32 v16, v16
	v_sub_f32_e32 v17, v17, v145
	v_permlane16_swap_b32_e32 v38, v72
	v_exp_f32_e32 v17, v17
	v_sub_f32_e32 v18, v18, v145
	v_exp_f32_e32 v18, v18
	v_sub_f32_e32 v19, v19, v145
	v_max_f32_e32 v37, v37, v38
	v_exp_f32_e32 v19, v19
	v_sub_f32_e32 v38, v48, v145
	v_sub_f32_e32 v36, v176, v145
	v_cndmask_b32_e64 v16, v16, 0, vcc
	v_exp_f32_e32 v38, v38
	v_sub_f32_e32 v39, v49, v145
	v_exp_f32_e32 v88, v36
	v_add_f32_e32 v36, 0, v16
	v_cndmask_b32_e64 v17, v17, 0, s[0:1]
	v_exp_f32_e32 v39, v39
	v_sub_f32_e32 v48, v50, v145
	v_add_f32_e32 v36, v17, v36
	v_cndmask_b32_e64 v18, v18, 0, s[22:23]
	v_exp_f32_e32 v48, v48
	v_sub_f32_e32 v49, v51, v145
	v_add_f32_e32 v36, v18, v36
	v_cndmask_b32_e64 v19, v19, 0, s[24:25]
	v_exp_f32_e32 v49, v49
	v_add_f32_e32 v36, v19, v36
	v_cndmask_b32_e64 v38, v38, 0, s[26:27]
	v_add_f32_e32 v36, v38, v36
	v_cndmask_b32_e64 v39, v39, 0, s[28:29]
	v_add_f32_e32 v36, v39, v36
	v_cndmask_b32_e64 v48, v48, 0, s[30:31]
	v_add_f32_e32 v36, v48, v36
	v_cndmask_b32_e64 v49, v49, 0, s[34:35]
	v_max3_f32 v147, v150, v37, v72
	v_add_f32_e32 v146, v49, v36
	v_sub_f32_e32 v36, v150, v147
	v_cvt_pk_bf16_f32 v16, v16, v17
	v_cvt_pk_bf16_f32 v17, v18, v19
	v_cvt_pk_bf16_f32 v19, v48, v49
	v_exp_f32_e32 v48, v36
	v_sub_f32_e32 v36, v68, v147
	v_cvt_pk_bf16_f32 v18, v38, v39
	v_exp_f32_e32 v36, v36
	v_sub_f32_e32 v38, v69, v147
	v_exp_f32_e32 v38, v38
	v_sub_f32_e32 v39, v70, v147
	v_exp_f32_e32 v39, v39
	v_sub_f32_e32 v49, v71, v147
	v_exp_f32_e32 v49, v49
	v_sub_f32_e32 v24, v24, v147
	v_cndmask_b32_e64 v36, v36, 0, s[38:39]
	v_exp_f32_e32 v24, v24
	v_sub_f32_e32 v25, v25, v147
	v_add_f32_e32 v37, 0, v36
	v_cndmask_b32_e64 v38, v38, 0, s[40:41]
	v_exp_f32_e32 v25, v25
	v_add_f32_e32 v37, v38, v37
	v_cndmask_b32_e64 v39, v39, 0, s[42:43]
	v_add_f32_e32 v37, v39, v37
	v_cndmask_b32_e64 v49, v49, 0, s[44:45]
	v_add_f32_e32 v37, v49, v37
	v_cndmask_b32_e64 v50, v24, 0, s[46:47]
	v_add_f32_e32 v24, v50, v37
	v_cndmask_b32_e64 v37, v25, 0, s[48:49]
	v_sub_f32_e32 v25, v26, v147
	v_exp_f32_e32 v25, v25
	v_add_f32_e32 v24, v37, v24
	v_cvt_pk_bf16_f32 v26, v50, v37
	v_cmp_lt_i32_e32 vcc, -1, v184
	v_cndmask_b32_e64 v51, v25, 0, s[50:51]
	v_sub_f32_e32 v25, v27, v147
	v_exp_f32_e32 v25, v25
	v_add_f32_e32 v24, v51, v24
	v_fmac_f32_e32 v146, v149, v88
	s_add_i32 s0, s76, 0xffffff00
	v_cndmask_b32_e64 v27, v25, 0, s[52:53]
	v_add_f32_e32 v183, v27, v24
	v_cvt_pk_bf16_f32 v24, v36, v38
	v_cvt_pk_bf16_f32 v25, v39, v49
	v_cvt_pk_bf16_f32 v27, v51, v27
	v_pk_mul_f32 v[38:39], v[42:43], v[88:89] op_sel_hi:[1,0]
	v_pk_mul_f32 v[36:37], v[40:41], v[88:89] op_sel_hi:[1,0]
	v_pk_mul_f32 v[42:43], v[94:95], v[48:49] op_sel_hi:[1,0]
	v_pk_mul_f32 v[40:41], v[92:93], v[48:49] op_sel_hi:[1,0]
	s_waitcnt lgkmcnt(10)
	v_mfma_f32_16x16x32_bf16 v[36:39], v[140:143], v[16:19], v[36:39]
	v_fmac_f32_e32 v183, v151, v48
	s_min_i32 s1, s0, 0
	s_sub_i32 s1, 3, s1
	v_mfma_f32_16x16x32_bf16 v[68:71], v[140:143], v[24:27], v[40:43]
	s_ashr_i32 s1, s1, 2
	s_sub_i32 s22, 0x200, s76
	s_sub_i32 s0, s75, s0
	v_pk_mul_f32 v[42:43], v[106:107], v[88:89] op_sel_hi:[1,0]
	v_pk_mul_f32 v[40:41], v[104:105], v[88:89] op_sel_hi:[1,0]
	s_ashr_i32 s0, s0, 2
	s_cmp_lt_i32 s76, 0
	s_waitcnt lgkmcnt(8)
	v_mfma_f32_16x16x32_bf16 v[72:75], v[136:139], v[16:19], v[40:43]
	s_nop 2
	v_mul_f32_e64 v42, v110, v48
	v_mul_f32_e64 v43, v111, v48
	v_pk_mul_f32 v[40:41], v[108:109], v[48:49] op_sel_hi:[1,0]
	s_nop 1
	v_mfma_f32_16x16x32_bf16 v[104:107], v[136:139], v[24:27], v[40:43]
	s_nop 2
	v_mul_f32_e64 v42, v114, v88
	v_mul_f32_e64 v43, v115, v88
	v_pk_mul_f32 v[40:41], v[112:113], v[88:89] op_sel_hi:[1,0]
	s_waitcnt lgkmcnt(6)
	s_nop 0
	v_mfma_f32_16x16x32_bf16 v[108:111], v[132:135], v[16:19], v[40:43]
	s_nop 2
	v_mul_f32_e64 v42, v118, v48
	v_mul_f32_e64 v43, v119, v48
	v_pk_mul_f32 v[40:41], v[116:117], v[48:49] op_sel_hi:[1,0]
	s_nop 1
	v_mfma_f32_16x16x32_bf16 v[112:115], v[132:135], v[24:27], v[40:43]
	s_nop 2
	v_mul_f32_e64 v42, v122, v88
	v_mul_f32_e64 v43, v123, v88
	v_pk_mul_f32 v[40:41], v[120:121], v[88:89] op_sel_hi:[1,0]
	s_waitcnt lgkmcnt(4)
	s_nop 0
	v_mfma_f32_16x16x32_bf16 v[116:119], v[128:131], v[16:19], v[40:43]
	v_mul_f32_e64 v18, v126, v48
	v_mul_f32_e64 v19, v127, v48
	v_pk_mul_f32 v[16:17], v[124:125], v[48:49] op_sel_hi:[1,0]
	s_nop 1
	v_mfma_f32_16x16x32_bf16 v[128:131], v[128:131], v[24:27], v[16:19]
	s_nop 2
	v_min_i32_e32 v16, s75, v184
	v_cndmask_b32_e32 v16, 0, v16, vcc
	v_add_u32_e32 v16, s74, v16
	v_ashrrev_i32_e32 v17, 31, v16
	v_lshlrev_b64 v[16:17], 9, v[16:17]
	v_lshl_add_u64 v[16:17], v[164:165], 0, v[16:17]
	global_load_dwordx4 v[88:91], v[16:17], off
	v_med3_i32 v16, v185, 0, s75
	v_add_u32_e32 v16, s74, v16
	v_ashrrev_i32_e32 v17, 31, v16
	v_lshlrev_b64 v[16:17], 9, v[16:17]
	v_lshl_add_u64 v[16:17], v[164:165], 0, v[16:17]
	global_load_dwordx4 v[92:95], v[16:17], off
	v_med3_i32 v16, v186, 0, s75
	v_add_u32_e32 v16, s74, v16
	v_ashrrev_i32_e32 v17, 31, v16
	v_lshlrev_b64 v[16:17], 9, v[16:17]
	v_lshl_add_u64 v[16:17], v[164:165], 0, v[16:17]
	global_load_dwordx4 v[120:123], v[16:17], off
	v_med3_i32 v16, v188, 0, s75
	v_add_u32_e32 v16, s74, v16
	v_ashrrev_i32_e32 v17, 31, v16
	v_lshlrev_b64 v[16:17], 9, v[16:17]
	v_lshl_add_u64 v[16:17], v[164:165], 0, v[16:17]
	global_load_dwordx4 v[124:127], v[16:17], off
	v_add_u32_e32 v16, s76, v209
	v_med3_i32 v16, v16, 0, s75
	v_add_u32_e32 v16, s74, v16
	v_ashrrev_i32_e32 v17, 31, v16
	v_lshlrev_b64 v[16:17], 9, v[16:17]
	v_lshl_add_u64 v[16:17], s[68:69], 0, v[16:17]
	v_lshl_add_u64 v[16:17], v[16:17], 0, v[158:159]
	global_load_dwordx4 v[48:51], v[16:17], off
	global_load_dwordx4 v[40:43], v[16:17], off offset:64
	v_or_b32_e32 v16, 64, v209
	v_add_u32_e32 v16, s76, v16
	v_med3_i32 v16, v16, 0, s75
	v_add_u32_e32 v16, s74, v16
	v_ashrrev_i32_e32 v17, 31, v16
	v_lshlrev_b64 v[16:17], 9, v[16:17]
	v_lshl_add_u64 v[16:17], s[68:69], 0, v[16:17]
	v_lshl_add_u64 v[16:17], v[16:17], 0, v[158:159]
	global_load_dwordx4 v[24:27], v[16:17], off
	s_nop 0
	global_load_dwordx4 v[16:19], v[16:17], off offset:64
	ds_read_b64_tr_b16 v[98:99], v169 offset:2304
	ds_read_b64_tr_b16 v[96:97], v169
	ds_read_b64_tr_b16 v[140:141], v169 offset:32
	ds_read_b64_tr_b16 v[142:143], v169 offset:2336
	ds_read_b64_tr_b16 v[136:137], v169 offset:64
	ds_read_b64_tr_b16 v[138:139], v169 offset:2368
	ds_read_b64_tr_b16 v[132:133], v169 offset:96
	ds_read_b64_tr_b16 v[134:135], v169 offset:2400
	s_waitcnt vmcnt(15)
	ds_write_b128 v241, v[32:35] offset:4608
	s_waitcnt vmcnt(14)
	ds_write_b128 v242, v[64:67] offset:4608
	s_waitcnt vmcnt(13)
	ds_write_b128 v243, v[76:79] offset:4608
	s_waitcnt vmcnt(12)
	ds_write_b128 v244, v[100:103] offset:4608
	v_mfma_f32_16x16x32_bf16 v[64:67], v[60:63], v[4:7], 0
	v_mfma_f32_16x16x32_bf16 v[60:63], v[60:63], v[12:15], 0
	v_mfma_f32_16x16x32_bf16 v[32:35], v[84:87], v[4:7], 0
	v_mfma_f32_16x16x32_bf16 v[64:67], v[56:59], v[8:11], v[64:67]
	v_mfma_f32_16x16x32_bf16 v[56:59], v[56:59], v[0:3], v[60:63]
	s_nop 4
	v_ashrrev_i32_e32 v60, 2, v250
	v_max_i32_e32 v176, s1, v60
	v_add_u32_e32 v60, s22, v251
	v_ashrrev_i32_e32 v60, 2, v60
	v_min3_i32 v60, v60, s0, v247
	v_mfma_f32_16x16x32_bf16 v[32:35], v[80:83], v[8:11], v[32:35]
	v_sub_u32_e32 v175, v60, v176
	v_ashrrev_i32_e32 v60, 2, v249
	v_max_i32_e32 v181, s1, v60
	v_add_u32_e32 v60, s22, v144
	v_sub_u32_e32 v61, v154, v176
	v_ashrrev_i32_e32 v60, 2, v60
	v_mfma_f32_16x16x32_bf16 v[76:79], v[84:87], v[12:15], 0
	v_min3_i32 v60, v60, s0, v247
	v_add_u32_e32 v63, 1, v61
	v_sub_u32_e32 v252, v60, v181
	v_max_f32_e32 v60, v32, v32
	v_cmp_gt_u32_e64 s[0:1], v63, v175
	v_cmp_gt_u32_e32 vcc, v61, v175
	v_max_f32_e32 v60, 0xf149f2ca, v60
	v_cndmask_b32_e64 v63, v33, v246, s[0:1]
	v_cndmask_b32_e32 v60, v60, v246, vcc
	v_mfma_f32_16x16x32_bf16 v[76:79], v[80:83], v[0:3], v[76:79]
	v_max_f32_e32 v60, v60, v63
	v_add_u32_e32 v63, 2, v61
	v_add_u32_e32 v80, 3, v61
	v_cmp_gt_u32_e64 s[22:23], v63, v175
	v_cmp_gt_u32_e64 s[24:25], v80, v175
	v_sub_u32_e32 v62, v154, v181
	v_cndmask_b32_e64 v63, v34, v246, s[22:23]
	v_cndmask_b32_e64 v80, v35, v246, s[24:25]
	v_max3_f32 v60, v60, v63, v80
	v_add_u32_e32 v63, 16, v61
	v_add_u32_e32 v80, 17, v61
	v_cmp_gt_u32_e64 s[26:27], v63, v175
	v_cmp_gt_u32_e64 s[28:29], v80, v175
	v_cmp_gt_u32_e64 s[38:39], v62, v252
	v_cndmask_b32_e64 v63, v64, v246, s[26:27]
	v_cndmask_b32_e64 v80, v65, v246, s[28:29]
	v_max3_f32 v60, v60, v63, v80
	v_add_u32_e32 v63, 18, v61
	v_add_u32_e32 v61, 19, v61
	v_cmp_gt_u32_e64 s[30:31], v63, v175
	v_cmp_gt_u32_e64 s[34:35], v61, v175
	v_add_u32_e32 v80, 3, v62
	v_cndmask_b32_e64 v63, v66, v246, s[30:31]
	v_cndmask_b32_e64 v61, v67, v246, s[34:35]
	v_max3_f32 v60, v60, v63, v61
	v_add_u32_e32 v63, 1, v62
	v_max_f32_e32 v61, v76, v76
	v_cmp_gt_u32_e64 s[40:41], v63, v252
	v_max_f32_e32 v61, 0xf149f2ca, v61
	v_cndmask_b32_e64 v61, v61, v246, s[38:39]
	v_cndmask_b32_e64 v63, v77, v246, s[40:41]
	v_max_f32_e32 v61, v61, v63
	v_add_u32_e32 v63, 2, v62
	v_cmp_gt_u32_e64 s[42:43], v63, v252
	v_cmp_gt_u32_e64 s[44:45], v80, v252
	s_nop 0
	v_cndmask_b32_e64 v63, v78, v246, s[42:43]
	v_cndmask_b32_e64 v80, v79, v246, s[44:45]
	v_max3_f32 v61, v61, v63, v80
	v_add_u32_e32 v63, 16, v62
	v_add_u32_e32 v80, 17, v62
	v_cmp_gt_u32_e64 s[46:47], v63, v252
	v_cmp_gt_u32_e64 s[48:49], v80, v252
	s_nop 0
	v_cndmask_b32_e64 v63, v56, v246, s[46:47]
	v_cndmask_b32_e64 v80, v57, v246, s[48:49]
	v_max3_f32 v61, v61, v63, v80
	v_add_u32_e32 v63, 18, v62
	v_add_u32_e32 v62, 19, v62
	v_cmp_gt_u32_e64 s[50:51], v63, v252
	v_cmp_gt_u32_e64 s[52:53], v62, v252
	s_nop 0
	v_cndmask_b32_e64 v63, v58, v246, s[50:51]
	v_cndmask_b32_e64 v62, v59, v246, s[52:53]
	v_max3_f32 v61, v61, v63, v62
	v_mov_b32_e32 v62, v60
	v_mov_b32_e32 v63, v60
	s_nop 1
	v_permlane32_swap_b32_e32 v62, v63
	v_max3_f32 v60, v60, v62, v63
	v_mov_b32_e32 v62, v61
	v_mov_b32_e32 v63, v61
	s_nop 1
	v_permlane32_swap_b32_e32 v62, v63
	v_max3_f32 v61, v61, v62, v63
	v_mov_b32_e32 v62, v60
	v_mov_b32_e32 v63, v60
	s_nop 1
	v_permlane16_swap_b32_e32 v62, v63
	v_max_f32_e32 v60, v60, v62
	v_max3_f32 v148, v145, v60, v63
	v_sub_f32_e32 v32, v32, v148
	v_exp_f32_e32 v32, v32
	v_sub_f32_e32 v33, v33, v148
	v_exp_f32_e32 v33, v33
	v_sub_f32_e32 v34, v34, v148
	v_mov_b32_e32 v62, v61
	v_mov_b32_e32 v80, v61
	v_exp_f32_e32 v34, v34
	v_sub_f32_e32 v35, v35, v148
	v_permlane16_swap_b32_e32 v62, v80
	v_exp_f32_e32 v35, v35
	v_sub_f32_e32 v63, v64, v148
	v_cndmask_b32_e64 v32, v32, 0, vcc
	v_exp_f32_e32 v63, v63
	v_sub_f32_e32 v64, v65, v148
	v_max_f32_e32 v61, v61, v62
	v_add_f32_e32 v62, 0, v32
	v_cndmask_b32_e64 v33, v33, 0, s[0:1]
	v_exp_f32_e32 v64, v64
	v_sub_f32_e32 v65, v66, v148
	v_add_f32_e32 v62, v33, v62
	v_cndmask_b32_e64 v34, v34, 0, s[22:23]
	v_exp_f32_e32 v65, v65
	v_sub_f32_e32 v66, v67, v148
	v_add_f32_e32 v62, v34, v62
	v_cndmask_b32_e64 v35, v35, 0, s[24:25]
	v_exp_f32_e32 v66, v66
	v_add_f32_e32 v62, v35, v62
	v_cndmask_b32_e64 v63, v63, 0, s[26:27]
	v_add_f32_e32 v62, v63, v62
	v_cndmask_b32_e64 v64, v64, 0, s[28:29]
	v_add_f32_e32 v62, v64, v62
	v_cndmask_b32_e64 v65, v65, 0, s[30:31]
	v_max3_f32 v150, v147, v61, v80
	v_add_f32_e32 v62, v65, v62
	v_cndmask_b32_e64 v66, v66, 0, s[34:35]
	v_sub_f32_e32 v61, v147, v150
	v_add_f32_e32 v149, v66, v62
	v_exp_f32_e32 v62, v61
	v_sub_f32_e32 v61, v76, v150
	v_cvt_pk_bf16_f32 v32, v32, v33
	v_cvt_pk_bf16_f32 v33, v34, v35
	v_cvt_pk_bf16_f32 v34, v63, v64
	v_exp_f32_e32 v61, v61
	v_sub_f32_e32 v64, v77, v150
	v_cvt_pk_bf16_f32 v35, v65, v66
	v_exp_f32_e32 v64, v64
	v_sub_f32_e32 v65, v78, v150
	v_exp_f32_e32 v65, v65
	v_sub_f32_e32 v66, v79, v150
	v_exp_f32_e32 v66, v66
	v_sub_f32_e32 v56, v56, v150
	v_cndmask_b32_e64 v61, v61, 0, s[38:39]
	v_exp_f32_e32 v56, v56
	v_sub_f32_e32 v57, v57, v150
	v_add_f32_e32 v63, 0, v61
	v_cndmask_b32_e64 v64, v64, 0, s[40:41]
	v_exp_f32_e32 v57, v57
	v_add_f32_e32 v63, v64, v63
	v_cndmask_b32_e64 v65, v65, 0, s[42:43]
	v_add_f32_e32 v63, v65, v63
	v_cndmask_b32_e64 v66, v66, 0, s[44:45]
	v_add_f32_e32 v63, v66, v63
	v_cndmask_b32_e64 v67, v56, 0, s[46:47]
	v_add_f32_e32 v56, v67, v63
	v_cndmask_b32_e64 v63, v57, 0, s[48:49]
	v_sub_f32_e32 v57, v58, v150
	v_exp_f32_e32 v57, v57
	v_sub_f32_e32 v60, v145, v148
	v_exp_f32_e32 v60, v60
	v_add_f32_e32 v56, v63, v56
	v_cndmask_b32_e64 v76, v57, 0, s[50:51]
	v_sub_f32_e32 v57, v59, v150
	v_exp_f32_e32 v57, v57
	v_add_f32_e32 v56, v76, v56
	v_pk_mul_f32 v[38:39], v[38:39], v[60:61] op_sel_hi:[1,0]
	v_pk_mul_f32 v[36:37], v[36:37], v[60:61] op_sel_hi:[1,0]
	v_cndmask_b32_e64 v59, v57, 0, s[52:53]
	v_add_f32_e32 v151, v59, v56
	v_cvt_pk_bf16_f32 v56, v61, v64
	v_cvt_pk_bf16_f32 v57, v65, v66
	v_cvt_pk_bf16_f32 v58, v67, v63
	v_cvt_pk_bf16_f32 v59, v76, v59
	s_waitcnt lgkmcnt(10)
	v_mfma_f32_16x16x32_bf16 v[80:83], v[96:99], v[32:35], v[36:39]
	v_fmac_f32_e32 v149, v146, v60
	v_fmac_f32_e32 v151, v183, v62
	s_nop 0
	v_pk_mul_f32 v[38:39], v[70:71], v[62:63] op_sel_hi:[1,0]
	v_pk_mul_f32 v[36:37], v[68:69], v[62:63] op_sel_hi:[1,0]
	s_nop 1
	v_mfma_f32_16x16x32_bf16 v[84:87], v[96:99], v[56:59], v[36:39]
	s_nop 2
	v_mul_f32_e64 v38, v74, v60
	v_mul_f32_e64 v39, v75, v60
	v_pk_mul_f32 v[36:37], v[72:73], v[60:61] op_sel_hi:[1,0]
	s_waitcnt lgkmcnt(8)
	s_nop 0
	v_mfma_f32_16x16x32_bf16 v[96:99], v[140:143], v[32:35], v[36:39]
	s_nop 2
	v_mul_f32_e64 v38, v106, v62
	v_mul_f32_e64 v39, v107, v62
	v_pk_mul_f32 v[36:37], v[104:105], v[62:63] op_sel_hi:[1,0]
	s_nop 1
	v_mfma_f32_16x16x32_bf16 v[100:103], v[140:143], v[56:59], v[36:39]
	s_nop 2
	v_mul_f32_e64 v38, v110, v60
	v_mul_f32_e64 v39, v111, v60
	v_pk_mul_f32 v[36:37], v[108:109], v[60:61] op_sel_hi:[1,0]
	s_waitcnt lgkmcnt(6)
	s_nop 0
	v_mfma_f32_16x16x32_bf16 v[104:107], v[136:139], v[32:35], v[36:39]
	s_nop 2
	v_mul_f32_e64 v38, v114, v62
	v_mul_f32_e64 v39, v115, v62
	v_pk_mul_f32 v[36:37], v[112:113], v[62:63] op_sel_hi:[1,0]
	s_nop 1
	v_mfma_f32_16x16x32_bf16 v[108:111], v[136:139], v[56:59], v[36:39]
	s_nop 2
	v_mul_f32_e64 v38, v118, v60
	v_mul_f32_e64 v39, v119, v60
	v_pk_mul_f32 v[36:37], v[116:117], v[60:61] op_sel_hi:[1,0]
	s_waitcnt lgkmcnt(4)
	s_nop 0
	v_mfma_f32_16x16x32_bf16 v[112:115], v[132:135], v[32:35], v[36:39]
	v_mul_f32_e64 v34, v130, v62
	v_mul_f32_e64 v35, v131, v62
	v_pk_mul_f32 v[32:33], v[128:129], v[62:63] op_sel_hi:[1,0]
	s_nop 1
	v_mfma_f32_16x16x32_bf16 v[116:119], v[132:135], v[56:59], v[32:35]
	s_nop 2
	v_add_u32_e32 v32, 0x80, v184
	v_med3_i32 v32, v32, 0, s75
	v_add_u32_e32 v32, s74, v32
	v_ashrrev_i32_e32 v33, 31, v32
	v_lshlrev_b64 v[32:33], 9, v[32:33]
	v_lshl_add_u64 v[32:33], v[164:165], 0, v[32:33]
	global_load_dwordx4 v[64:67], v[32:33], off
	v_add_u32_e32 v32, 0x80, v185
	v_med3_i32 v32, v32, 0, s75
	v_add_u32_e32 v32, s74, v32
	v_ashrrev_i32_e32 v33, 31, v32
	v_lshlrev_b64 v[32:33], 9, v[32:33]
	v_lshl_add_u64 v[32:33], v[164:165], 0, v[32:33]
	global_load_dwordx4 v[68:71], v[32:33], off
	v_add_u32_e32 v32, 0x80, v186
	v_med3_i32 v32, v32, 0, s75
	v_add_u32_e32 v32, s74, v32
	v_ashrrev_i32_e32 v33, 31, v32
	v_lshlrev_b64 v[32:33], 9, v[32:33]
	v_lshl_add_u64 v[32:33], v[164:165], 0, v[32:33]
	global_load_dwordx4 v[72:75], v[32:33], off
	v_add_u32_e32 v32, 0x80, v188
	v_med3_i32 v32, v32, 0, s75
	v_add_u32_e32 v32, s74, v32
	v_ashrrev_i32_e32 v33, 31, v32
	v_lshlrev_b64 v[32:33], 9, v[32:33]
	v_lshl_add_u64 v[32:33], v[164:165], 0, v[32:33]
	global_load_dwordx4 v[76:79], v[32:33], off
	v_or_b32_e32 v32, 0x80, v209
	v_add_u32_e32 v32, s76, v32
	v_med3_i32 v32, v32, 0, s75
	v_add_u32_e32 v32, s74, v32
	v_ashrrev_i32_e32 v33, 31, v32
	v_lshlrev_b64 v[32:33], 9, v[32:33]
	v_lshl_add_u64 v[32:33], s[68:69], 0, v[32:33]
	v_lshl_add_u64 v[32:33], v[32:33], 0, v[158:159]
	global_load_dwordx4 v[60:63], v[32:33], off
	global_load_dwordx4 v[56:59], v[32:33], off offset:64
	v_or_b32_e32 v32, 0xc0, v209
	v_add_u32_e32 v32, s76, v32
	v_med3_i32 v32, v32, 0, s75
	v_add_u32_e32 v32, s74, v32
	v_ashrrev_i32_e32 v33, 31, v32
	v_lshlrev_b64 v[32:33], 9, v[32:33]
	v_lshl_add_u64 v[32:33], s[68:69], 0, v[32:33]
	v_lshl_add_u64 v[32:33], v[32:33], 0, v[158:159]
	global_load_dwordx4 v[36:39], v[32:33], off
	s_nop 0
	global_load_dwordx4 v[32:35], v[32:33], off offset:64
	ds_read_b64_tr_b16 v[134:135], v169 offset:6912
	ds_read_b64_tr_b16 v[132:133], v169 offset:4608
	ds_read_b64_tr_b16 v[128:129], v169 offset:4640
	ds_read_b64_tr_b16 v[130:131], v169 offset:6944
	ds_read_b64_tr_b16 v[136:137], v169 offset:4672
	ds_read_b64_tr_b16 v[138:139], v169 offset:6976
	ds_read_b64_tr_b16 v[144:145], v169 offset:4704
	ds_read_b64_tr_b16 v[146:147], v169 offset:7008
	s_waitcnt vmcnt(15)
	ds_write_b128 v241, v[88:91]
	s_waitcnt vmcnt(14)
	ds_write_b128 v242, v[92:95]
	s_waitcnt vmcnt(13)
	ds_write_b128 v243, v[120:123]
	s_waitcnt vmcnt(12)
	ds_write_b128 v244, v[124:127]
	v_mfma_f32_16x16x32_bf16 v[88:91], v[52:55], v[4:7], 0
	v_mfma_f32_16x16x32_bf16 v[92:95], v[28:31], v[4:7], 0
	v_mfma_f32_16x16x32_bf16 v[28:31], v[28:31], v[12:15], 0
	v_mfma_f32_16x16x32_bf16 v[88:91], v[44:47], v[8:11], v[88:91]
	v_mfma_f32_16x16x32_bf16 v[92:95], v[20:23], v[8:11], v[92:95]
	v_mfma_f32_16x16x32_bf16 v[20:23], v[20:23], v[0:3], v[28:31]
	s_nop 4
	v_sub_u32_e32 v28, v187, v176
	v_mfma_f32_16x16x32_bf16 v[52:55], v[52:55], v[12:15], 0
	v_add_u32_e32 v31, 1, v28
	v_max_f32_e32 v30, v88, v88
	v_cmp_gt_u32_e64 s[0:1], v31, v175
	v_cmp_gt_u32_e32 vcc, v28, v175
	v_max_f32_e32 v30, 0xf149f2ca, v30
	v_cndmask_b32_e64 v31, v89, v246, s[0:1]
	v_cndmask_b32_e32 v30, v30, v246, vcc
	v_mfma_f32_16x16x32_bf16 v[44:47], v[44:47], v[0:3], v[52:55]
	v_max_f32_e32 v30, v30, v31
	v_add_u32_e32 v31, 2, v28
	v_cmp_gt_u32_e64 s[22:23], v31, v175
	v_add_u32_e32 v52, 3, v28
	v_cmp_gt_u32_e64 s[24:25], v52, v175
	v_cndmask_b32_e64 v31, v90, v246, s[22:23]
	v_sub_u32_e32 v29, v187, v181
	v_cndmask_b32_e64 v52, v91, v246, s[24:25]
	v_max3_f32 v30, v30, v31, v52
	v_add_u32_e32 v31, 16, v28
	v_add_u32_e32 v52, 17, v28
	v_cmp_gt_u32_e64 s[26:27], v31, v175
	v_cmp_gt_u32_e64 s[28:29], v52, v175
	v_cmp_gt_u32_e64 s[38:39], v29, v252
	v_cndmask_b32_e64 v31, v92, v246, s[26:27]
	v_cndmask_b32_e64 v52, v93, v246, s[28:29]
	v_max3_f32 v30, v30, v31, v52
	v_add_u32_e32 v31, 18, v28
	v_add_u32_e32 v28, 19, v28
	v_cmp_gt_u32_e64 s[30:31], v31, v175
	v_cmp_gt_u32_e64 s[34:35], v28, v175
	v_add_u32_e32 v52, 3, v29
	v_cndmask_b32_e64 v31, v94, v246, s[30:31]
	v_cndmask_b32_e64 v28, v95, v246, s[34:35]
	v_max3_f32 v28, v30, v31, v28
	v_add_u32_e32 v31, 1, v29
	v_max_f32_e32 v30, v44, v44
	v_cmp_gt_u32_e64 s[40:41], v31, v252
	v_max_f32_e32 v30, 0xf149f2ca, v30
	v_cndmask_b32_e64 v30, v30, v246, s[38:39]
	v_cndmask_b32_e64 v31, v45, v246, s[40:41]
	v_max_f32_e32 v30, v30, v31
	v_add_u32_e32 v31, 2, v29
	v_cmp_gt_u32_e64 s[42:43], v31, v252
	v_cmp_gt_u32_e64 s[44:45], v52, v252
	s_nop 0
	v_cndmask_b32_e64 v31, v46, v246, s[42:43]
	v_cndmask_b32_e64 v52, v47, v246, s[44:45]
	v_max3_f32 v30, v30, v31, v52
	v_add_u32_e32 v31, 16, v29
	v_add_u32_e32 v52, 17, v29
	v_cmp_gt_u32_e64 s[46:47], v31, v252
	v_cmp_gt_u32_e64 s[48:49], v52, v252
	s_nop 0
	v_cndmask_b32_e64 v31, v20, v246, s[46:47]
	v_cndmask_b32_e64 v52, v21, v246, s[48:49]
	v_max3_f32 v30, v30, v31, v52
	v_add_u32_e32 v31, 18, v29
	v_add_u32_e32 v29, 19, v29
	v_cmp_gt_u32_e64 s[50:51], v31, v252
	v_cmp_gt_u32_e64 s[52:53], v29, v252
	s_nop 0
	v_cndmask_b32_e64 v31, v22, v246, s[50:51]
	v_cndmask_b32_e64 v29, v23, v246, s[52:53]
	v_max3_f32 v29, v30, v31, v29
	v_mov_b32_e32 v30, v28
	v_mov_b32_e32 v31, v28
	s_nop 1
	v_permlane32_swap_b32_e32 v30, v31
	v_max3_f32 v28, v28, v30, v31
	v_mov_b32_e32 v30, v29
	v_mov_b32_e32 v31, v29
	s_nop 1
	v_permlane32_swap_b32_e32 v30, v31
	v_max3_f32 v29, v29, v30, v31
	v_mov_b32_e32 v30, v28
	v_mov_b32_e32 v31, v28
	s_nop 1
	v_permlane16_swap_b32_e32 v30, v31
	v_max_f32_e32 v28, v28, v30
	v_mov_b32_e32 v30, v29
	v_mov_b32_e32 v53, v29
	v_max3_f32 v183, v148, v28, v31
	s_nop 0
	v_permlane16_swap_b32_e32 v30, v53
	v_sub_f32_e32 v28, v148, v183
	v_exp_f32_e32 v52, v28
	v_sub_f32_e32 v28, v88, v183
	v_max_f32_e32 v54, v29, v30
	v_exp_f32_e32 v28, v28
	v_sub_f32_e32 v30, v89, v183
	v_exp_f32_e32 v30, v30
	v_sub_f32_e32 v31, v90, v183
	v_exp_f32_e32 v31, v31
	v_sub_f32_e32 v55, v91, v183
	v_max3_f32 v185, v150, v54, v53
	v_exp_f32_e32 v55, v55
	v_sub_f32_e32 v88, v92, v183
	v_sub_f32_e32 v44, v44, v185
	v_cndmask_b32_e64 v28, v28, 0, vcc
	v_exp_f32_e32 v88, v88
	v_sub_f32_e32 v89, v93, v183
	v_exp_f32_e32 v44, v44
	v_sub_f32_e32 v45, v45, v185
	v_add_f32_e32 v29, 0, v28
	v_cndmask_b32_e64 v30, v30, 0, s[0:1]
	v_exp_f32_e32 v89, v89
	v_sub_f32_e32 v90, v94, v183
	v_exp_f32_e32 v45, v45
	v_sub_f32_e32 v46, v46, v185
	v_add_f32_e32 v29, v30, v29
	v_cndmask_b32_e64 v31, v31, 0, s[22:23]
	v_exp_f32_e32 v90, v90
	v_sub_f32_e32 v91, v95, v183
	v_exp_f32_e32 v46, v46
	v_sub_f32_e32 v47, v47, v185
	v_add_f32_e32 v29, v31, v29
	v_cndmask_b32_e64 v55, v55, 0, s[24:25]
	v_exp_f32_e32 v91, v91
	v_exp_f32_e32 v47, v47
	v_sub_f32_e32 v20, v20, v185
	v_add_f32_e32 v29, v55, v29
	v_cndmask_b32_e64 v88, v88, 0, s[26:27]
	v_sub_f32_e32 v53, v150, v185
	v_cndmask_b32_e64 v44, v44, 0, s[38:39]
	v_exp_f32_e32 v20, v20
	v_sub_f32_e32 v21, v21, v185
	v_add_f32_e32 v29, v88, v29
	v_cndmask_b32_e64 v89, v89, 0, s[28:29]
	v_exp_f32_e32 v54, v53
	v_add_f32_e32 v53, 0, v44
	v_cndmask_b32_e64 v45, v45, 0, s[40:41]
	v_exp_f32_e32 v21, v21
	v_add_f32_e32 v29, v89, v29
	v_cndmask_b32_e64 v90, v90, 0, s[30:31]
	v_add_f32_e32 v53, v45, v53
	v_cndmask_b32_e64 v46, v46, 0, s[42:43]
	v_add_f32_e32 v29, v90, v29
	v_cndmask_b32_e64 v91, v91, 0, s[34:35]
	v_add_f32_e32 v53, v46, v53
	v_cndmask_b32_e64 v47, v47, 0, s[44:45]
	v_add_f32_e32 v184, v91, v29
	v_cvt_pk_bf16_f32 v29, v31, v55
	v_add_f32_e32 v53, v47, v53
	v_cndmask_b32_e64 v55, v20, 0, s[46:47]
	v_add_f32_e32 v20, v55, v53
	v_cndmask_b32_e64 v53, v21, 0, s[48:49]
	v_sub_f32_e32 v21, v22, v185
	v_exp_f32_e32 v21, v21
	v_cvt_pk_bf16_f32 v28, v28, v30
	v_cvt_pk_bf16_f32 v30, v88, v89
	v_add_f32_e32 v20, v53, v20
	v_cndmask_b32_e64 v88, v21, 0, s[50:51]
	v_sub_f32_e32 v21, v23, v185
	v_exp_f32_e32 v21, v21
	v_add_f32_e32 v20, v88, v20
	v_cvt_pk_bf16_f32 v31, v90, v91
	v_cvt_pk_bf16_f32 v22, v55, v53
	v_cndmask_b32_e64 v23, v21, 0, s[52:53]
	v_add_f32_e32 v186, v23, v20
	v_cvt_pk_bf16_f32 v20, v44, v45
	v_cvt_pk_bf16_f32 v21, v46, v47
	v_pk_mul_f32 v[46:47], v[82:83], v[52:53] op_sel_hi:[1,0]
	v_pk_mul_f32 v[44:45], v[80:81], v[52:53] op_sel_hi:[1,0]
	v_cvt_pk_bf16_f32 v23, v88, v23
	v_fmac_f32_e32 v184, v149, v52
	s_waitcnt lgkmcnt(10)
	v_mfma_f32_16x16x32_bf16 v[120:123], v[132:135], v[28:31], v[44:47]
	v_fmac_f32_e32 v186, v151, v54
	s_nop 1
	v_pk_mul_f32 v[46:47], v[86:87], v[54:55] op_sel_hi:[1,0]
	v_pk_mul_f32 v[44:45], v[84:85], v[54:55] op_sel_hi:[1,0]
	s_nop 1
	v_mfma_f32_16x16x32_bf16 v[124:127], v[132:135], v[20:23], v[44:47]
	s_nop 2
	v_mul_f32_e64 v46, v98, v52
	v_mul_f32_e64 v47, v99, v52
	v_pk_mul_f32 v[44:45], v[96:97], v[52:53] op_sel_hi:[1,0]
	s_waitcnt lgkmcnt(8)
	s_nop 0
	v_mfma_f32_16x16x32_bf16 v[96:99], v[128:131], v[28:31], v[44:47]
	s_nop 2
	v_mul_f32_e64 v46, v102, v54
	v_mul_f32_e64 v47, v103, v54
	v_pk_mul_f32 v[44:45], v[100:101], v[54:55] op_sel_hi:[1,0]
	s_nop 1
	v_mfma_f32_16x16x32_bf16 v[128:131], v[128:131], v[20:23], v[44:47]
	s_nop 2
	v_mul_f32_e64 v46, v106, v52
	v_mul_f32_e64 v47, v107, v52
	v_pk_mul_f32 v[44:45], v[104:105], v[52:53] op_sel_hi:[1,0]
	s_waitcnt lgkmcnt(6)
	s_nop 0
	v_mfma_f32_16x16x32_bf16 v[132:135], v[136:139], v[28:31], v[44:47]
	s_nop 2
	v_mul_f32_e64 v46, v110, v54
	v_mul_f32_e64 v47, v111, v54
	v_pk_mul_f32 v[44:45], v[108:109], v[54:55] op_sel_hi:[1,0]
	s_nop 1
	v_mfma_f32_16x16x32_bf16 v[136:139], v[136:139], v[20:23], v[44:47]
	s_nop 2
	v_mul_f32_e64 v46, v114, v52
	v_mul_f32_e64 v47, v115, v52
	v_pk_mul_f32 v[44:45], v[112:113], v[52:53] op_sel_hi:[1,0]
	s_waitcnt lgkmcnt(4)
	s_nop 0
	v_mfma_f32_16x16x32_bf16 v[140:143], v[144:147], v[28:31], v[44:47]
	v_mul_f32_e64 v30, v118, v54
	v_mul_f32_e64 v31, v119, v54
	v_pk_mul_f32 v[28:29], v[116:117], v[54:55] op_sel_hi:[1,0]
	s_nop 1
	v_mfma_f32_16x16x32_bf16 v[144:147], v[144:147], v[20:23], v[28:31]
	v_lshl_add_u32 v20, v155, 1, v155
	v_add_u32_e32 v20, v180, v20
	v_med3_i32 v20, v20, 0, s75
	v_add_u32_e32 v20, s74, v20
	v_ashrrev_i32_e32 v21, 31, v20
	v_lshlrev_b64 v[20:21], 9, v[20:21]
	v_lshl_add_u64 v[20:21], v[164:165], 0, v[20:21]
	global_load_dwordx4 v[80:83], v[20:21], off
	v_lshl_add_u32 v20, v172, 1, v172
	v_add_u32_e32 v20, v179, v20
	v_med3_i32 v20, v20, 0, s75
	v_add_u32_e32 v20, s74, v20
	v_ashrrev_i32_e32 v21, 31, v20
	v_lshlrev_b64 v[20:21], 9, v[20:21]
	v_lshl_add_u64 v[20:21], v[164:165], 0, v[20:21]
	global_load_dwordx4 v[84:87], v[20:21], off
	v_lshl_add_u32 v20, v173, 1, v173
	v_add_u32_e32 v20, v178, v20
	v_med3_i32 v20, v20, 0, s75
	v_add_u32_e32 v20, s74, v20
	v_ashrrev_i32_e32 v21, 31, v20
	v_lshlrev_b64 v[20:21], 9, v[20:21]
	v_lshl_add_u64 v[20:21], v[164:165], 0, v[20:21]
	global_load_dwordx4 v[88:91], v[20:21], off
	v_lshl_add_u32 v20, v182, 1, v182
	v_add_u32_e32 v20, v177, v20
	v_med3_i32 v20, v20, 0, s75
	v_add_u32_e32 v20, s74, v20
	v_ashrrev_i32_e32 v21, 31, v20
	v_lshlrev_b64 v[20:21], 9, v[20:21]
	v_lshl_add_u64 v[20:21], v[164:165], 0, v[20:21]
	global_load_dwordx4 v[92:95], v[20:21], off
	v_or_b32_e32 v20, 0x100, v209
	v_add_u32_e32 v20, s76, v20
	v_med3_i32 v20, v20, 0, s75
	v_add_u32_e32 v20, s74, v20
	v_ashrrev_i32_e32 v21, 31, v20
	v_lshlrev_b64 v[20:21], 9, v[20:21]
	v_lshl_add_u64 v[20:21], s[68:69], 0, v[20:21]
	v_lshl_add_u64 v[20:21], v[20:21], 0, v[158:159]
	global_load_dwordx4 v[52:55], v[20:21], off
	global_load_dwordx4 v[44:47], v[20:21], off offset:64
	v_or_b32_e32 v20, 0x140, v209
	v_add_u32_e32 v20, s76, v20
	v_med3_i32 v20, v20, 0, s75
	v_add_u32_e32 v20, s74, v20
	v_ashrrev_i32_e32 v21, 31, v20
	v_lshlrev_b64 v[20:21], 9, v[20:21]
	v_lshl_add_u64 v[20:21], s[68:69], 0, v[20:21]
	v_lshl_add_u64 v[20:21], v[20:21], 0, v[158:159]
	global_load_dwordx4 v[28:31], v[20:21], off
	s_nop 0
	global_load_dwordx4 v[20:23], v[20:21], off offset:64
	ds_read_b64_tr_b16 v[102:103], v169 offset:2304
	ds_read_b64_tr_b16 v[100:101], v169
	ds_read_b64_tr_b16 v[108:109], v169 offset:32
	ds_read_b64_tr_b16 v[110:111], v169 offset:2336
	ds_read_b64_tr_b16 v[116:117], v169 offset:64
	ds_read_b64_tr_b16 v[118:119], v169 offset:2368
	ds_read_b64_tr_b16 v[148:149], v169 offset:96
	ds_read_b64_tr_b16 v[150:151], v169 offset:2400
	s_waitcnt vmcnt(15)
	ds_write_b128 v241, v[64:67] offset:4608
	s_waitcnt vmcnt(14)
	ds_write_b128 v242, v[68:71] offset:4608
	s_waitcnt vmcnt(13)
	ds_write_b128 v243, v[72:75] offset:4608
	s_waitcnt vmcnt(12)
	ds_write_b128 v244, v[76:79] offset:4608
	v_mfma_f32_16x16x32_bf16 v[64:67], v[48:51], v[4:7], 0
	v_mfma_f32_16x16x32_bf16 v[68:71], v[24:27], v[4:7], 0
	v_mfma_f32_16x16x32_bf16 v[24:27], v[24:27], v[12:15], 0
	v_mfma_f32_16x16x32_bf16 v[64:67], v[40:43], v[8:11], v[64:67]
	v_mfma_f32_16x16x32_bf16 v[68:71], v[16:19], v[8:11], v[68:71]
	v_mfma_f32_16x16x32_bf16 v[16:19], v[16:19], v[0:3], v[24:27]
	s_nop 4
	v_sub_u32_e32 v24, v192, v176
	v_mfma_f32_16x16x32_bf16 v[48:51], v[48:51], v[12:15], 0
	v_add_u32_e32 v27, 1, v24
	v_max_f32_e32 v26, v64, v64
	v_cmp_gt_u32_e64 s[0:1], v27, v175
	v_cmp_gt_u32_e32 vcc, v24, v175
	v_max_f32_e32 v26, 0xf149f2ca, v26
	v_cndmask_b32_e64 v27, v65, v246, s[0:1]
	v_cndmask_b32_e32 v26, v26, v246, vcc
	v_mfma_f32_16x16x32_bf16 v[40:43], v[40:43], v[0:3], v[48:51]
	v_max_f32_e32 v26, v26, v27
	v_add_u32_e32 v27, 2, v24
	v_cmp_gt_u32_e64 s[22:23], v27, v175
	v_add_u32_e32 v48, 3, v24
	v_cmp_gt_u32_e64 s[24:25], v48, v175
	v_cndmask_b32_e64 v27, v66, v246, s[22:23]
	v_sub_u32_e32 v25, v192, v181
	v_cndmask_b32_e64 v48, v67, v246, s[24:25]
	v_max3_f32 v26, v26, v27, v48
	v_add_u32_e32 v27, 16, v24
	v_add_u32_e32 v48, 17, v24
	v_cmp_gt_u32_e64 s[26:27], v27, v175
	v_cmp_gt_u32_e64 s[28:29], v48, v175
	v_cmp_gt_u32_e64 s[38:39], v25, v252
	v_cndmask_b32_e64 v27, v68, v246, s[26:27]
	v_cndmask_b32_e64 v48, v69, v246, s[28:29]
	v_max3_f32 v26, v26, v27, v48
	v_add_u32_e32 v27, 18, v24
	v_add_u32_e32 v24, 19, v24
	v_cmp_gt_u32_e64 s[30:31], v27, v175
	v_cmp_gt_u32_e64 s[34:35], v24, v175
	v_add_u32_e32 v48, 3, v25
	v_cndmask_b32_e64 v27, v70, v246, s[30:31]
	v_cndmask_b32_e64 v24, v71, v246, s[34:35]
	v_max3_f32 v24, v26, v27, v24
	v_add_u32_e32 v27, 1, v25
	v_max_f32_e32 v26, v40, v40
	v_cmp_gt_u32_e64 s[40:41], v27, v252
	v_max_f32_e32 v26, 0xf149f2ca, v26
	v_cndmask_b32_e64 v26, v26, v246, s[38:39]
	v_cndmask_b32_e64 v27, v41, v246, s[40:41]
	v_max_f32_e32 v26, v26, v27
	v_add_u32_e32 v27, 2, v25
	v_cmp_gt_u32_e64 s[42:43], v27, v252
	v_cmp_gt_u32_e64 s[44:45], v48, v252
	s_nop 0
	v_cndmask_b32_e64 v27, v42, v246, s[42:43]
	v_cndmask_b32_e64 v48, v43, v246, s[44:45]
	v_max3_f32 v26, v26, v27, v48
	v_add_u32_e32 v27, 16, v25
	v_add_u32_e32 v48, 17, v25
	v_cmp_gt_u32_e64 s[46:47], v27, v252
	v_cmp_gt_u32_e64 s[48:49], v48, v252
	s_nop 0
	v_cndmask_b32_e64 v27, v16, v246, s[46:47]
	v_cndmask_b32_e64 v48, v17, v246, s[48:49]
	v_max3_f32 v26, v26, v27, v48
	v_add_u32_e32 v27, 18, v25
	v_add_u32_e32 v25, 19, v25
	v_cmp_gt_u32_e64 s[50:51], v27, v252
	v_cmp_gt_u32_e64 s[52:53], v25, v252
	s_nop 0
	v_cndmask_b32_e64 v27, v18, v246, s[50:51]
	v_cndmask_b32_e64 v25, v19, v246, s[52:53]
	v_max3_f32 v25, v26, v27, v25
	v_mov_b32_e32 v26, v24
	v_mov_b32_e32 v27, v24
	s_nop 1
	v_permlane32_swap_b32_e32 v26, v27
	v_max3_f32 v24, v24, v26, v27
	v_mov_b32_e32 v26, v25
	v_mov_b32_e32 v27, v25
	s_nop 1
	v_permlane32_swap_b32_e32 v26, v27
	v_max3_f32 v25, v25, v26, v27
	v_mov_b32_e32 v26, v24
	v_mov_b32_e32 v27, v24
	s_nop 1
	v_permlane16_swap_b32_e32 v26, v27
	v_max_f32_e32 v24, v24, v26
	v_max3_f32 v177, v183, v24, v27
	v_sub_f32_e32 v48, v66, v177
	v_exp_f32_e32 v48, v48
	v_sub_f32_e32 v24, v183, v177
	v_exp_f32_e32 v72, v24
	v_sub_f32_e32 v24, v64, v177
	v_cndmask_b32_e64 v49, v48, 0, s[22:23]
	v_sub_f32_e32 v48, v67, v177
	v_exp_f32_e32 v48, v48
	v_exp_f32_e32 v24, v24
	v_sub_f32_e32 v27, v65, v177
	v_exp_f32_e32 v27, v27
	v_cndmask_b32_e64 v50, v48, 0, s[24:25]
	v_sub_f32_e32 v48, v68, v177
	v_exp_f32_e32 v48, v48
	v_mov_b32_e32 v26, v25
	v_mov_b32_e32 v73, v25
	s_nop 1
	v_permlane16_swap_b32_e32 v26, v73
	v_cndmask_b32_e64 v51, v48, 0, s[26:27]
	v_sub_f32_e32 v48, v69, v177
	v_exp_f32_e32 v48, v48
	v_cndmask_b32_e64 v24, v24, 0, vcc
	v_max_f32_e32 v25, v25, v26
	v_cndmask_b32_e64 v64, v48, 0, s[28:29]
	v_sub_f32_e32 v48, v70, v177
	v_exp_f32_e32 v48, v48
	v_add_f32_e32 v26, 0, v24
	v_cndmask_b32_e64 v27, v27, 0, s[0:1]
	v_add_f32_e32 v26, v27, v26
	v_cndmask_b32_e64 v65, v48, 0, s[30:31]
	v_sub_f32_e32 v48, v71, v177
	v_exp_f32_e32 v48, v48
	v_add_f32_e32 v26, v49, v26
	v_add_f32_e32 v26, v50, v26
	v_add_f32_e32 v26, v51, v26
	v_max3_f32 v179, v185, v25, v73
	v_add_f32_e32 v26, v64, v26
	v_cndmask_b32_e64 v66, v48, 0, s[34:35]
	v_cvt_pk_bf16_f32 v48, v24, v27
	v_sub_f32_e32 v24, v185, v179
	v_add_f32_e32 v26, v65, v26
	v_cvt_pk_bf16_f32 v49, v49, v50
	v_cvt_pk_bf16_f32 v50, v51, v64
	v_exp_f32_e32 v64, v24
	v_sub_f32_e32 v24, v40, v179
	v_add_f32_e32 v178, v66, v26
	v_exp_f32_e32 v24, v24
	v_sub_f32_e32 v26, v41, v179
	v_exp_f32_e32 v26, v26
	v_sub_f32_e32 v27, v42, v179
	v_exp_f32_e32 v27, v27
	v_sub_f32_e32 v40, v43, v179
	v_exp_f32_e32 v40, v40
	v_sub_f32_e32 v16, v16, v179
	v_cndmask_b32_e64 v24, v24, 0, s[38:39]
	v_exp_f32_e32 v16, v16
	v_sub_f32_e32 v17, v17, v179
	v_add_f32_e32 v25, 0, v24
	v_cndmask_b32_e64 v26, v26, 0, s[40:41]
	v_exp_f32_e32 v17, v17
	v_add_f32_e32 v25, v26, v25
	v_cndmask_b32_e64 v27, v27, 0, s[42:43]
	v_add_f32_e32 v25, v27, v25
	v_cndmask_b32_e64 v40, v40, 0, s[44:45]
	v_add_f32_e32 v25, v40, v25
	v_cndmask_b32_e64 v41, v16, 0, s[46:47]
	v_add_f32_e32 v16, v41, v25
	v_cndmask_b32_e64 v25, v17, 0, s[48:49]
	v_sub_f32_e32 v17, v18, v179
	v_exp_f32_e32 v17, v17
	v_add_f32_e32 v16, v25, v16
	v_cvt_pk_bf16_f32 v51, v65, v66
	v_cvt_pk_bf16_f32 v18, v41, v25
	v_cndmask_b32_e64 v42, v17, 0, s[50:51]
	v_sub_f32_e32 v17, v19, v179
	v_exp_f32_e32 v17, v17
	v_add_f32_e32 v16, v42, v16
	v_fmac_f32_e32 v178, v184, v72
	v_cndmask_b32_e64 v19, v17, 0, s[52:53]
	v_add_f32_e32 v180, v19, v16
	v_cvt_pk_bf16_f32 v16, v24, v26
	v_cvt_pk_bf16_f32 v17, v27, v40
	v_cvt_pk_bf16_f32 v19, v42, v19
	v_pk_mul_f32 v[26:27], v[122:123], v[72:73] op_sel_hi:[1,0]
	v_pk_mul_f32 v[24:25], v[120:121], v[72:73] op_sel_hi:[1,0]
	v_pk_mul_f32 v[42:43], v[126:127], v[64:65] op_sel_hi:[1,0]
	v_pk_mul_f32 v[40:41], v[124:125], v[64:65] op_sel_hi:[1,0]
	s_waitcnt lgkmcnt(10)
	v_mfma_f32_16x16x32_bf16 v[24:27], v[100:103], v[48:51], v[24:27]
	v_fmac_f32_e32 v180, v186, v64
	v_mfma_f32_16x16x32_bf16 v[100:103], v[100:103], v[16:19], v[40:43]
	s_nop 2
	v_mul_f32_e64 v42, v98, v72
	v_mul_f32_e64 v43, v99, v72
	v_pk_mul_f32 v[40:41], v[96:97], v[72:73] op_sel_hi:[1,0]
	s_waitcnt lgkmcnt(8)
	s_nop 0
	v_mfma_f32_16x16x32_bf16 v[104:107], v[108:111], v[48:51], v[40:43]
	s_nop 2
	v_mul_f32_e64 v42, v130, v64
	v_mul_f32_e64 v43, v131, v64
	v_pk_mul_f32 v[40:41], v[128:129], v[64:65] op_sel_hi:[1,0]
	s_nop 1
	v_mfma_f32_16x16x32_bf16 v[108:111], v[108:111], v[16:19], v[40:43]
	s_nop 2
	v_mul_f32_e64 v42, v134, v72
	v_mul_f32_e64 v43, v135, v72
	v_pk_mul_f32 v[40:41], v[132:133], v[72:73] op_sel_hi:[1,0]
	s_waitcnt lgkmcnt(6)
	s_nop 0
	v_mfma_f32_16x16x32_bf16 v[112:115], v[116:119], v[48:51], v[40:43]
	s_nop 2
	v_mul_f32_e64 v42, v138, v64
	v_mul_f32_e64 v43, v139, v64
	v_pk_mul_f32 v[40:41], v[136:137], v[64:65] op_sel_hi:[1,0]
	s_nop 1
	v_mfma_f32_16x16x32_bf16 v[116:119], v[116:119], v[16:19], v[40:43]
	s_nop 2
	v_mul_f32_e64 v42, v142, v72
	v_mul_f32_e64 v43, v143, v72
	v_pk_mul_f32 v[40:41], v[140:141], v[72:73] op_sel_hi:[1,0]
	s_waitcnt lgkmcnt(4)
	s_nop 0
	v_mfma_f32_16x16x32_bf16 v[120:123], v[148:151], v[48:51], v[40:43]
	s_nop 2
	v_mul_f32_e64 v42, v146, v64
	v_mul_f32_e64 v43, v147, v64
	v_pk_mul_f32 v[40:41], v[144:145], v[64:65] op_sel_hi:[1,0]
	s_nop 1
	v_mfma_f32_16x16x32_bf16 v[124:127], v[148:151], v[16:19], v[40:43]
	v_lshlrev_b32_e32 v16, 2, v196
	v_add_u32_e32 v16, s76, v16
	v_med3_i32 v16, v16, 0, s75
	v_add_u32_e32 v16, s74, v16
	v_ashrrev_i32_e32 v17, 31, v16
	v_lshlrev_b64 v[16:17], 9, v[16:17]
	v_lshl_add_u64 v[16:17], v[164:165], 0, v[16:17]
	global_load_dwordx4 v[68:71], v[16:17], off
	v_lshlrev_b32_e32 v16, 2, v168
	v_add_u32_e32 v16, s76, v16
	v_med3_i32 v16, v16, 0, s75
	v_add_u32_e32 v16, s74, v16
	v_ashrrev_i32_e32 v17, 31, v16
	v_lshlrev_b64 v[16:17], 9, v[16:17]
	v_lshl_add_u64 v[16:17], v[164:165], 0, v[16:17]
	global_load_dwordx4 v[72:75], v[16:17], off
	v_lshlrev_b32_e32 v16, 2, v193
	v_add_u32_e32 v16, s76, v16
	v_med3_i32 v16, v16, 0, s75
	v_add_u32_e32 v16, s74, v16
	v_ashrrev_i32_e32 v17, 31, v16
	v_lshlrev_b64 v[16:17], 9, v[16:17]
	v_lshl_add_u64 v[16:17], v[164:165], 0, v[16:17]
	global_load_dwordx4 v[76:79], v[16:17], off
	v_lshlrev_b32_e32 v16, 2, v194
	v_add_u32_e32 v16, s76, v16
	v_med3_i32 v16, v16, 0, s75
	v_add_u32_e32 v16, s74, v16
	v_ashrrev_i32_e32 v17, 31, v16
	v_lshlrev_b64 v[16:17], 9, v[16:17]
	v_lshl_add_u64 v[16:17], v[164:165], 0, v[16:17]
	global_load_dwordx4 v[96:99], v[16:17], off
	v_or_b32_e32 v16, 0x180, v209
	v_add_u32_e32 v16, s76, v16
	v_med3_i32 v16, v16, 0, s75
	v_add_u32_e32 v16, s74, v16
	v_ashrrev_i32_e32 v17, 31, v16
	v_lshlrev_b64 v[16:17], 9, v[16:17]
	v_lshl_add_u64 v[16:17], s[68:69], 0, v[16:17]
	v_lshl_add_u64 v[16:17], v[16:17], 0, v[158:159]
	global_load_dwordx4 v[64:67], v[16:17], off
	global_load_dwordx4 v[48:51], v[16:17], off offset:64
	v_or_b32_e32 v16, 0x1c0, v209
	v_add_u32_e32 v16, s76, v16
	v_med3_i32 v16, v16, 0, s75
	v_add_u32_e32 v16, s74, v16
	v_ashrrev_i32_e32 v17, 31, v16
	v_lshlrev_b64 v[16:17], 9, v[16:17]
	v_lshl_add_u64 v[16:17], s[68:69], 0, v[16:17]
	v_lshl_add_u64 v[16:17], v[16:17], 0, v[158:159]
	global_load_dwordx4 v[40:43], v[16:17], off
	s_nop 0
	global_load_dwordx4 v[16:19], v[16:17], off offset:64
	ds_read_b64_tr_b16 v[142:143], v169 offset:6912
	ds_read_b64_tr_b16 v[140:141], v169 offset:4608
	ds_read_b64_tr_b16 v[136:137], v169 offset:4640
	ds_read_b64_tr_b16 v[138:139], v169 offset:6944
	ds_read_b64_tr_b16 v[132:133], v169 offset:4672
	ds_read_b64_tr_b16 v[134:135], v169 offset:6976
	ds_read_b64_tr_b16 v[128:129], v169 offset:4704
	ds_read_b64_tr_b16 v[130:131], v169 offset:7008
	s_waitcnt vmcnt(15)
	ds_write_b128 v241, v[80:83]
	s_waitcnt vmcnt(14)
	ds_write_b128 v242, v[84:87]
	s_waitcnt vmcnt(13)
	ds_write_b128 v243, v[88:91]
	s_waitcnt vmcnt(12)
	ds_write_b128 v244, v[92:95]
	v_mfma_f32_16x16x32_bf16 v[80:83], v[60:63], v[4:7], 0
	v_mfma_f32_16x16x32_bf16 v[84:87], v[36:39], v[4:7], 0
	v_mfma_f32_16x16x32_bf16 v[36:39], v[36:39], v[12:15], 0
	v_mfma_f32_16x16x32_bf16 v[80:83], v[56:59], v[8:11], v[80:83]
	v_mfma_f32_16x16x32_bf16 v[84:87], v[32:35], v[8:11], v[84:87]
	v_mfma_f32_16x16x32_bf16 v[32:35], v[32:35], v[0:3], v[36:39]
	s_nop 4
	v_sub_u32_e32 v36, v197, v176
	v_mfma_f32_16x16x32_bf16 v[60:63], v[60:63], v[12:15], 0
	v_add_u32_e32 v39, 1, v36
	v_max_f32_e32 v38, v80, v80
	v_cmp_gt_u32_e64 s[0:1], v39, v175
	v_cmp_gt_u32_e32 vcc, v36, v175
	v_max_f32_e32 v38, 0xf149f2ca, v38
	v_cndmask_b32_e64 v39, v81, v246, s[0:1]
	v_cndmask_b32_e32 v38, v38, v246, vcc
	v_mfma_f32_16x16x32_bf16 v[56:59], v[56:59], v[0:3], v[60:63]
	v_max_f32_e32 v38, v38, v39
	v_add_u32_e32 v39, 2, v36
	v_cmp_gt_u32_e64 s[22:23], v39, v175
	v_add_u32_e32 v60, 3, v36
	v_cmp_gt_u32_e64 s[24:25], v60, v175
	v_cndmask_b32_e64 v39, v82, v246, s[22:23]
	v_sub_u32_e32 v37, v197, v181
	v_cndmask_b32_e64 v60, v83, v246, s[24:25]
	v_max3_f32 v38, v38, v39, v60
	v_add_u32_e32 v39, 16, v36
	v_add_u32_e32 v60, 17, v36
	v_cmp_gt_u32_e64 s[26:27], v39, v175
	v_cmp_gt_u32_e64 s[28:29], v60, v175
	v_cmp_gt_u32_e64 s[38:39], v37, v252
	v_cndmask_b32_e64 v39, v84, v246, s[26:27]
	v_cndmask_b32_e64 v60, v85, v246, s[28:29]
	v_max3_f32 v38, v38, v39, v60
	v_add_u32_e32 v39, 18, v36
	v_add_u32_e32 v36, 19, v36
	v_cmp_gt_u32_e64 s[30:31], v39, v175
	v_cmp_gt_u32_e64 s[34:35], v36, v175
	v_add_u32_e32 v60, 3, v37
	v_cndmask_b32_e64 v39, v86, v246, s[30:31]
	v_cndmask_b32_e64 v36, v87, v246, s[34:35]
	v_max3_f32 v36, v38, v39, v36
	v_add_u32_e32 v39, 1, v37
	v_max_f32_e32 v38, v56, v56
	v_cmp_gt_u32_e64 s[40:41], v39, v252
	v_max_f32_e32 v38, 0xf149f2ca, v38
	v_cndmask_b32_e64 v38, v38, v246, s[38:39]
	v_cndmask_b32_e64 v39, v57, v246, s[40:41]
	v_max_f32_e32 v38, v38, v39
	v_add_u32_e32 v39, 2, v37
	v_cmp_gt_u32_e64 s[42:43], v39, v252
	v_cmp_gt_u32_e64 s[44:45], v60, v252
	s_nop 0
	v_cndmask_b32_e64 v39, v58, v246, s[42:43]
	v_cndmask_b32_e64 v60, v59, v246, s[44:45]
	v_max3_f32 v38, v38, v39, v60
	v_add_u32_e32 v39, 16, v37
	v_add_u32_e32 v60, 17, v37
	v_cmp_gt_u32_e64 s[46:47], v39, v252
	v_cmp_gt_u32_e64 s[48:49], v60, v252
	s_nop 0
	v_cndmask_b32_e64 v39, v32, v246, s[46:47]
	v_cndmask_b32_e64 v60, v33, v246, s[48:49]
	v_max3_f32 v38, v38, v39, v60
	v_add_u32_e32 v39, 18, v37
	v_add_u32_e32 v37, 19, v37
	v_cmp_gt_u32_e64 s[50:51], v39, v252
	v_cmp_gt_u32_e64 s[52:53], v37, v252
	s_nop 0
	v_cndmask_b32_e64 v39, v34, v246, s[50:51]
	v_cndmask_b32_e64 v37, v35, v246, s[52:53]
	v_max3_f32 v37, v38, v39, v37
	v_mov_b32_e32 v38, v36
	v_mov_b32_e32 v39, v36
	s_nop 1
	v_permlane32_swap_b32_e32 v38, v39
	v_max3_f32 v36, v36, v38, v39
	v_mov_b32_e32 v38, v37
	v_mov_b32_e32 v39, v37
	s_nop 1
	v_permlane32_swap_b32_e32 v38, v39
	v_max3_f32 v37, v37, v38, v39
	v_mov_b32_e32 v38, v36
	v_mov_b32_e32 v39, v36
	s_nop 1
	v_permlane16_swap_b32_e32 v38, v39
	v_max_f32_e32 v36, v36, v38
	v_mov_b32_e32 v38, v37
	v_mov_b32_e32 v61, v37
	v_max3_f32 v144, v177, v36, v39
	s_nop 0
	v_permlane16_swap_b32_e32 v38, v61
	v_sub_f32_e32 v36, v177, v144
	v_exp_f32_e32 v60, v36
	v_sub_f32_e32 v36, v80, v144
	v_max_f32_e32 v62, v37, v38
	v_exp_f32_e32 v36, v36
	v_sub_f32_e32 v38, v81, v144
	v_exp_f32_e32 v38, v38
	v_sub_f32_e32 v39, v82, v144
	v_exp_f32_e32 v39, v39
	v_sub_f32_e32 v63, v83, v144
	v_max3_f32 v146, v179, v62, v61
	v_exp_f32_e32 v63, v63
	v_sub_f32_e32 v80, v84, v144
	v_sub_f32_e32 v56, v56, v146
	v_cndmask_b32_e64 v36, v36, 0, vcc
	v_exp_f32_e32 v80, v80
	v_sub_f32_e32 v81, v85, v144
	v_exp_f32_e32 v56, v56
	v_sub_f32_e32 v57, v57, v146
	v_add_f32_e32 v37, 0, v36
	v_cndmask_b32_e64 v38, v38, 0, s[0:1]
	v_exp_f32_e32 v81, v81
	v_sub_f32_e32 v82, v86, v144
	v_exp_f32_e32 v57, v57
	v_sub_f32_e32 v58, v58, v146
	v_add_f32_e32 v37, v38, v37
	v_cndmask_b32_e64 v39, v39, 0, s[22:23]
	v_exp_f32_e32 v82, v82
	v_sub_f32_e32 v83, v87, v144
	v_exp_f32_e32 v58, v58
	v_sub_f32_e32 v59, v59, v146
	v_add_f32_e32 v37, v39, v37
	v_cndmask_b32_e64 v63, v63, 0, s[24:25]
	v_exp_f32_e32 v83, v83
	v_exp_f32_e32 v59, v59
	v_sub_f32_e32 v32, v32, v146
	v_add_f32_e32 v37, v63, v37
	v_cndmask_b32_e64 v80, v80, 0, s[26:27]
	v_sub_f32_e32 v61, v179, v146
	v_cndmask_b32_e64 v56, v56, 0, s[38:39]
	v_exp_f32_e32 v32, v32
	v_sub_f32_e32 v33, v33, v146
	v_add_f32_e32 v37, v80, v37
	v_cndmask_b32_e64 v81, v81, 0, s[28:29]
	v_exp_f32_e32 v62, v61
	v_add_f32_e32 v61, 0, v56
	v_cndmask_b32_e64 v57, v57, 0, s[40:41]
	v_exp_f32_e32 v33, v33
	v_add_f32_e32 v37, v81, v37
	v_cndmask_b32_e64 v82, v82, 0, s[30:31]
	v_add_f32_e32 v61, v57, v61
	v_cndmask_b32_e64 v58, v58, 0, s[42:43]
	v_add_f32_e32 v37, v82, v37
	v_cndmask_b32_e64 v83, v83, 0, s[34:35]
	v_add_f32_e32 v61, v58, v61
	v_cndmask_b32_e64 v59, v59, 0, s[44:45]
	v_add_f32_e32 v145, v83, v37
	v_cvt_pk_bf16_f32 v37, v39, v63
	v_add_f32_e32 v61, v59, v61
	v_cndmask_b32_e64 v63, v32, 0, s[46:47]
	v_add_f32_e32 v32, v63, v61
	v_cndmask_b32_e64 v61, v33, 0, s[48:49]
	v_sub_f32_e32 v33, v34, v146
	v_exp_f32_e32 v33, v33
	v_cvt_pk_bf16_f32 v36, v36, v38
	v_cvt_pk_bf16_f32 v38, v80, v81
	v_add_f32_e32 v32, v61, v32
	v_cndmask_b32_e64 v80, v33, 0, s[50:51]
	v_sub_f32_e32 v33, v35, v146
	v_exp_f32_e32 v33, v33
	v_cvt_pk_bf16_f32 v39, v82, v83
	v_add_f32_e32 v32, v80, v32
	v_pk_mul_f32 v[26:27], v[26:27], v[60:61] op_sel_hi:[1,0]
	v_cndmask_b32_e64 v35, v33, 0, s[52:53]
	v_pk_mul_f32 v[24:25], v[24:25], v[60:61] op_sel_hi:[1,0]
	v_add_f32_e32 v147, v35, v32
	v_cvt_pk_bf16_f32 v32, v56, v57
	v_cvt_pk_bf16_f32 v33, v58, v59
	v_cvt_pk_bf16_f32 v34, v63, v61
	v_cvt_pk_bf16_f32 v35, v80, v35
	s_waitcnt lgkmcnt(10)
	v_mfma_f32_16x16x32_bf16 v[92:95], v[140:143], v[36:39], v[24:27]
	v_fmac_f32_e32 v145, v178, v60
	v_fmac_f32_e32 v147, v180, v62
	s_nop 0
	v_pk_mul_f32 v[26:27], v[102:103], v[62:63] op_sel_hi:[1,0]
	v_pk_mul_f32 v[24:25], v[100:101], v[62:63] op_sel_hi:[1,0]
	s_nop 1
	v_mfma_f32_16x16x32_bf16 v[100:103], v[140:143], v[32:35], v[24:27]
	s_nop 2
	v_mul_f32_e64 v26, v106, v60
	v_mul_f32_e64 v27, v107, v60
	v_pk_mul_f32 v[24:25], v[104:105], v[60:61] op_sel_hi:[1,0]
	s_waitcnt lgkmcnt(8)
	s_nop 0
	v_mfma_f32_16x16x32_bf16 v[104:107], v[136:139], v[36:39], v[24:27]
	s_nop 2
	v_mul_f32_e64 v26, v110, v62
	v_mul_f32_e64 v27, v111, v62
	v_pk_mul_f32 v[24:25], v[108:109], v[62:63] op_sel_hi:[1,0]
	s_nop 1
	v_mfma_f32_16x16x32_bf16 v[108:111], v[136:139], v[32:35], v[24:27]
	s_nop 2
	v_mul_f32_e64 v26, v114, v60
	v_mul_f32_e64 v27, v115, v60
	v_pk_mul_f32 v[24:25], v[112:113], v[60:61] op_sel_hi:[1,0]
	s_waitcnt lgkmcnt(6)
	s_nop 0
	v_mfma_f32_16x16x32_bf16 v[112:115], v[132:135], v[36:39], v[24:27]
	s_nop 2
	v_mul_f32_e64 v26, v118, v62
	v_mul_f32_e64 v27, v119, v62
	v_pk_mul_f32 v[24:25], v[116:117], v[62:63] op_sel_hi:[1,0]
	s_nop 1
	v_mfma_f32_16x16x32_bf16 v[116:119], v[132:135], v[32:35], v[24:27]
	s_nop 2
	v_mul_f32_e64 v26, v122, v60
	v_mul_f32_e64 v27, v123, v60
	v_pk_mul_f32 v[24:25], v[120:121], v[60:61] op_sel_hi:[1,0]
	s_waitcnt lgkmcnt(4)
	s_nop 0
	v_mfma_f32_16x16x32_bf16 v[120:123], v[128:131], v[36:39], v[24:27]
	s_nop 2
	v_mul_f32_e64 v26, v126, v62
	v_mul_f32_e64 v27, v127, v62
	v_pk_mul_f32 v[24:25], v[124:125], v[62:63] op_sel_hi:[1,0]
	s_nop 1
	v_mfma_f32_16x16x32_bf16 v[124:127], v[128:131], v[32:35], v[24:27]
	s_nop 2
	v_add_u32_e32 v24, s76, v214
	v_med3_i32 v24, v24, 0, s75
	v_add_u32_e32 v24, s74, v24
	v_ashrrev_i32_e32 v25, 31, v24
	v_lshlrev_b64 v[24:25], 9, v[24:25]
	v_lshl_add_u64 v[24:25], v[164:165], 0, v[24:25]
	global_load_dwordx4 v[60:63], v[24:25], off
	v_add_u32_e32 v24, s76, v216
	v_med3_i32 v24, v24, 0, s75
	v_add_u32_e32 v24, s74, v24
	v_ashrrev_i32_e32 v25, 31, v24
	v_lshlrev_b64 v[24:25], 9, v[24:25]
	v_lshl_add_u64 v[24:25], v[164:165], 0, v[24:25]
	global_load_dwordx4 v[80:83], v[24:25], off
	v_add_u32_e32 v24, s76, v218
	v_med3_i32 v24, v24, 0, s75
	v_add_u32_e32 v24, s74, v24
	v_ashrrev_i32_e32 v25, 31, v24
	v_lshlrev_b64 v[24:25], 9, v[24:25]
	v_lshl_add_u64 v[24:25], v[164:165], 0, v[24:25]
	global_load_dwordx4 v[84:87], v[24:25], off
	v_add_u32_e32 v24, s76, v220
	v_med3_i32 v24, v24, 0, s75
	v_add_u32_e32 v24, s74, v24
	v_ashrrev_i32_e32 v25, 31, v24
	v_lshlrev_b64 v[24:25], 9, v[24:25]
	v_lshl_add_u64 v[24:25], v[164:165], 0, v[24:25]
	global_load_dwordx4 v[88:91], v[24:25], off
	v_add_u32_e32 v24, s76, v221
	v_med3_i32 v24, v24, 0, s75
	v_add_u32_e32 v24, s74, v24
	v_ashrrev_i32_e32 v25, 31, v24
	v_lshlrev_b64 v[24:25], 9, v[24:25]
	v_lshl_add_u64 v[24:25], s[68:69], 0, v[24:25]
	v_lshl_add_u64 v[24:25], v[24:25], 0, v[158:159]
	global_load_dwordx4 v[56:59], v[24:25], off
	global_load_dwordx4 v[36:39], v[24:25], off offset:64
	v_or_b32_e32 v24, 0x100, v221
	v_add_u32_e32 v24, s76, v24
	v_med3_i32 v24, v24, 0, s75
	v_add_u32_e32 v24, s74, v24
	v_ashrrev_i32_e32 v25, 31, v24
	v_lshlrev_b64 v[24:25], 9, v[24:25]
	v_lshl_add_u64 v[24:25], s[68:69], 0, v[24:25]
	v_lshl_add_u64 v[24:25], v[24:25], 0, v[158:159]
	global_load_dwordx4 v[32:35], v[24:25], off
	s_nop 0
	global_load_dwordx4 v[24:27], v[24:25], off offset:64
	ds_read_b64_tr_b16 v[142:143], v169 offset:2304
	ds_read_b64_tr_b16 v[140:141], v169
	ds_read_b64_tr_b16 v[136:137], v169 offset:32
	ds_read_b64_tr_b16 v[138:139], v169 offset:2336
	ds_read_b64_tr_b16 v[132:133], v169 offset:64
	ds_read_b64_tr_b16 v[134:135], v169 offset:2368
	ds_read_b64_tr_b16 v[128:129], v169 offset:96
	ds_read_b64_tr_b16 v[130:131], v169 offset:2400
	s_waitcnt vmcnt(15)
	ds_write_b128 v241, v[68:71] offset:4608
	s_waitcnt vmcnt(14)
	ds_write_b128 v242, v[72:75] offset:4608
	s_waitcnt vmcnt(13)
	ds_write_b128 v243, v[76:79] offset:4608
	s_waitcnt vmcnt(12)
	ds_write_b128 v244, v[96:99] offset:4608
	v_mfma_f32_16x16x32_bf16 v[68:71], v[52:55], v[4:7], 0
	v_mfma_f32_16x16x32_bf16 v[72:75], v[28:31], v[4:7], 0
	v_mfma_f32_16x16x32_bf16 v[28:31], v[28:31], v[12:15], 0
	v_mfma_f32_16x16x32_bf16 v[68:71], v[44:47], v[8:11], v[68:71]
	v_mfma_f32_16x16x32_bf16 v[72:75], v[20:23], v[8:11], v[72:75]
	v_mfma_f32_16x16x32_bf16 v[20:23], v[20:23], v[0:3], v[28:31]
	s_nop 4
	v_sub_u32_e32 v28, v198, v176
	v_mfma_f32_16x16x32_bf16 v[52:55], v[52:55], v[12:15], 0
	v_add_u32_e32 v31, 1, v28
	v_max_f32_e32 v30, v68, v68
	v_cmp_gt_u32_e64 s[0:1], v31, v175
	v_cmp_gt_u32_e32 vcc, v28, v175
	v_max_f32_e32 v30, 0xf149f2ca, v30
	v_cndmask_b32_e64 v31, v69, v246, s[0:1]
	v_cndmask_b32_e32 v30, v30, v246, vcc
	v_mfma_f32_16x16x32_bf16 v[44:47], v[44:47], v[0:3], v[52:55]
	v_max_f32_e32 v30, v30, v31
	v_add_u32_e32 v31, 2, v28
	v_cmp_gt_u32_e64 s[22:23], v31, v175
	v_add_u32_e32 v52, 3, v28
	v_cmp_gt_u32_e64 s[24:25], v52, v175
	v_cndmask_b32_e64 v31, v70, v246, s[22:23]
	v_sub_u32_e32 v29, v198, v181
	v_cndmask_b32_e64 v52, v71, v246, s[24:25]
	v_max3_f32 v30, v30, v31, v52
	v_add_u32_e32 v31, 16, v28
	v_add_u32_e32 v52, 17, v28
	v_cmp_gt_u32_e64 s[26:27], v31, v175
	v_cmp_gt_u32_e64 s[28:29], v52, v175
	v_cmp_gt_u32_e64 s[38:39], v29, v252
	v_cndmask_b32_e64 v31, v72, v246, s[26:27]
	v_cndmask_b32_e64 v52, v73, v246, s[28:29]
	v_max3_f32 v30, v30, v31, v52
	v_add_u32_e32 v31, 18, v28
	v_add_u32_e32 v28, 19, v28
	v_cmp_gt_u32_e64 s[30:31], v31, v175
	v_cmp_gt_u32_e64 s[34:35], v28, v175
	v_add_u32_e32 v52, 3, v29
	v_cndmask_b32_e64 v31, v74, v246, s[30:31]
	v_cndmask_b32_e64 v28, v75, v246, s[34:35]
	v_max3_f32 v28, v30, v31, v28
	v_add_u32_e32 v31, 1, v29
	v_max_f32_e32 v30, v44, v44
	v_cmp_gt_u32_e64 s[40:41], v31, v252
	v_max_f32_e32 v30, 0xf149f2ca, v30
	v_cndmask_b32_e64 v30, v30, v246, s[38:39]
	v_cndmask_b32_e64 v31, v45, v246, s[40:41]
	v_max_f32_e32 v30, v30, v31
	v_add_u32_e32 v31, 2, v29
	v_cmp_gt_u32_e64 s[42:43], v31, v252
	v_cmp_gt_u32_e64 s[44:45], v52, v252
	s_nop 0
	v_cndmask_b32_e64 v31, v46, v246, s[42:43]
	v_cndmask_b32_e64 v52, v47, v246, s[44:45]
	v_max3_f32 v30, v30, v31, v52
	v_add_u32_e32 v31, 16, v29
	v_add_u32_e32 v52, 17, v29
	v_cmp_gt_u32_e64 s[46:47], v31, v252
	v_cmp_gt_u32_e64 s[48:49], v52, v252
	s_nop 0
	v_cndmask_b32_e64 v31, v20, v246, s[46:47]
	v_cndmask_b32_e64 v52, v21, v246, s[48:49]
	v_max3_f32 v30, v30, v31, v52
	v_add_u32_e32 v31, 18, v29
	v_add_u32_e32 v29, 19, v29
	v_cmp_gt_u32_e64 s[50:51], v31, v252
	v_cmp_gt_u32_e64 s[52:53], v29, v252
	s_nop 0
	v_cndmask_b32_e64 v31, v22, v246, s[50:51]
	v_cndmask_b32_e64 v29, v23, v246, s[52:53]
	v_max3_f32 v29, v30, v31, v29
	v_mov_b32_e32 v30, v28
	v_mov_b32_e32 v31, v28
	s_nop 1
	v_permlane32_swap_b32_e32 v30, v31
	v_max3_f32 v28, v28, v30, v31
	v_mov_b32_e32 v30, v29
	v_mov_b32_e32 v31, v29
	s_nop 1
	v_permlane32_swap_b32_e32 v30, v31
	v_max3_f32 v29, v29, v30, v31
	v_mov_b32_e32 v30, v28
	v_mov_b32_e32 v31, v28
	s_nop 1
	v_permlane16_swap_b32_e32 v30, v31
	v_max_f32_e32 v28, v28, v30
	v_mov_b32_e32 v30, v29
	v_mov_b32_e32 v53, v29
	v_max3_f32 v148, v144, v28, v31
	s_nop 0
	v_permlane16_swap_b32_e32 v30, v53
	v_sub_f32_e32 v28, v144, v148
	v_exp_f32_e32 v52, v28
	v_sub_f32_e32 v28, v68, v148
	v_max_f32_e32 v54, v29, v30
	v_exp_f32_e32 v28, v28
	v_sub_f32_e32 v30, v69, v148
	v_exp_f32_e32 v30, v30
	v_sub_f32_e32 v31, v70, v148
	v_exp_f32_e32 v31, v31
	v_sub_f32_e32 v55, v71, v148
	v_max3_f32 v149, v146, v54, v53
	v_exp_f32_e32 v55, v55
	v_sub_f32_e32 v68, v72, v148
	v_sub_f32_e32 v44, v44, v149
	v_cndmask_b32_e64 v28, v28, 0, vcc
	v_exp_f32_e32 v68, v68
	v_sub_f32_e32 v69, v73, v148
	v_exp_f32_e32 v44, v44
	v_sub_f32_e32 v45, v45, v149
	v_add_f32_e32 v29, 0, v28
	v_cndmask_b32_e64 v30, v30, 0, s[0:1]
	v_exp_f32_e32 v69, v69
	v_sub_f32_e32 v70, v74, v148
	v_exp_f32_e32 v45, v45
	v_sub_f32_e32 v46, v46, v149
	v_add_f32_e32 v29, v30, v29
	v_cndmask_b32_e64 v31, v31, 0, s[22:23]
	v_exp_f32_e32 v70, v70
	v_sub_f32_e32 v71, v75, v148
	v_exp_f32_e32 v46, v46
	v_sub_f32_e32 v47, v47, v149
	v_add_f32_e32 v29, v31, v29
	v_cndmask_b32_e64 v55, v55, 0, s[24:25]
	v_exp_f32_e32 v71, v71
	v_exp_f32_e32 v47, v47
	v_sub_f32_e32 v20, v20, v149
	v_add_f32_e32 v29, v55, v29
	v_cndmask_b32_e64 v68, v68, 0, s[26:27]
	v_sub_f32_e32 v53, v146, v149
	v_cndmask_b32_e64 v44, v44, 0, s[38:39]
	v_exp_f32_e32 v20, v20
	v_sub_f32_e32 v21, v21, v149
	v_add_f32_e32 v29, v68, v29
	v_cndmask_b32_e64 v69, v69, 0, s[28:29]
	v_exp_f32_e32 v54, v53
	v_add_f32_e32 v53, 0, v44
	v_cndmask_b32_e64 v45, v45, 0, s[40:41]
	v_exp_f32_e32 v21, v21
	v_add_f32_e32 v29, v69, v29
	v_cndmask_b32_e64 v70, v70, 0, s[30:31]
	v_add_f32_e32 v53, v45, v53
	v_cndmask_b32_e64 v46, v46, 0, s[42:43]
	v_add_f32_e32 v29, v70, v29
	v_cndmask_b32_e64 v71, v71, 0, s[34:35]
	v_add_f32_e32 v53, v46, v53
	v_cndmask_b32_e64 v47, v47, 0, s[44:45]
	v_add_f32_e32 v144, v71, v29
	v_cvt_pk_bf16_f32 v29, v31, v55
	v_add_f32_e32 v53, v47, v53
	v_cndmask_b32_e64 v55, v20, 0, s[46:47]
	v_add_f32_e32 v20, v55, v53
	v_cndmask_b32_e64 v53, v21, 0, s[48:49]
	v_sub_f32_e32 v21, v22, v149
	v_exp_f32_e32 v21, v21
	v_cvt_pk_bf16_f32 v28, v28, v30
	v_cvt_pk_bf16_f32 v30, v68, v69
	v_add_f32_e32 v20, v53, v20
	v_cndmask_b32_e64 v68, v21, 0, s[50:51]
	v_sub_f32_e32 v21, v23, v149
	v_exp_f32_e32 v21, v21
	v_add_f32_e32 v20, v68, v20
	v_fmac_f32_e32 v144, v145, v52
	v_cvt_pk_bf16_f32 v31, v70, v71
	v_cndmask_b32_e64 v23, v21, 0, s[52:53]
	v_add_f32_e32 v145, v23, v20
	v_cvt_pk_bf16_f32 v20, v44, v45
	v_cvt_pk_bf16_f32 v21, v46, v47
	v_pk_mul_f32 v[46:47], v[94:95], v[52:53] op_sel_hi:[1,0]
	v_pk_mul_f32 v[44:45], v[92:93], v[52:53] op_sel_hi:[1,0]
	v_cvt_pk_bf16_f32 v22, v55, v53
	v_cvt_pk_bf16_f32 v23, v68, v23
	s_waitcnt lgkmcnt(10)
	v_mfma_f32_16x16x32_bf16 v[96:99], v[140:143], v[28:31], v[44:47]
	v_fmac_f32_e32 v145, v147, v54
	s_nop 1
	v_pk_mul_f32 v[46:47], v[102:103], v[54:55] op_sel_hi:[1,0]
	v_pk_mul_f32 v[44:45], v[100:101], v[54:55] op_sel_hi:[1,0]
	s_nop 1
	v_mfma_f32_16x16x32_bf16 v[100:103], v[140:143], v[20:23], v[44:47]
	s_nop 2
	v_mul_f32_e64 v46, v106, v52
	v_mul_f32_e64 v47, v107, v52
	v_pk_mul_f32 v[44:45], v[104:105], v[52:53] op_sel_hi:[1,0]
	s_waitcnt lgkmcnt(8)
	s_nop 0
	v_mfma_f32_16x16x32_bf16 v[104:107], v[136:139], v[28:31], v[44:47]
	s_nop 2
	v_mul_f32_e64 v46, v110, v54
	v_mul_f32_e64 v47, v111, v54
	v_pk_mul_f32 v[44:45], v[108:109], v[54:55] op_sel_hi:[1,0]
	s_nop 1
	v_mfma_f32_16x16x32_bf16 v[108:111], v[136:139], v[20:23], v[44:47]
	s_nop 2
	v_mul_f32_e64 v46, v114, v52
	v_mul_f32_e64 v47, v115, v52
	v_pk_mul_f32 v[44:45], v[112:113], v[52:53] op_sel_hi:[1,0]
	s_waitcnt lgkmcnt(6)
	s_nop 0
	v_mfma_f32_16x16x32_bf16 v[112:115], v[132:135], v[28:31], v[44:47]
	s_nop 2
	v_mul_f32_e64 v46, v118, v54
	v_mul_f32_e64 v47, v119, v54
	v_pk_mul_f32 v[44:45], v[116:117], v[54:55] op_sel_hi:[1,0]
	s_nop 1
	v_mfma_f32_16x16x32_bf16 v[116:119], v[132:135], v[20:23], v[44:47]
	s_nop 2
	v_mul_f32_e64 v46, v122, v52
	v_mul_f32_e64 v47, v123, v52
	v_pk_mul_f32 v[44:45], v[120:121], v[52:53] op_sel_hi:[1,0]
	s_waitcnt lgkmcnt(4)
	s_nop 0
	v_mfma_f32_16x16x32_bf16 v[120:123], v[128:131], v[28:31], v[44:47]
	v_mul_f32_e64 v30, v126, v54
	v_mul_f32_e64 v31, v127, v54
	v_pk_mul_f32 v[28:29], v[124:125], v[54:55] op_sel_hi:[1,0]
	s_nop 1
	v_mfma_f32_16x16x32_bf16 v[124:127], v[128:131], v[20:23], v[28:31]
	v_add_u32_e32 v20, s76, v222
	v_med3_i32 v20, v20, 0, s75
	v_add_u32_e32 v20, s74, v20
	v_ashrrev_i32_e32 v21, 31, v20
	v_lshlrev_b64 v[20:21], 9, v[20:21]
	v_lshl_add_u64 v[20:21], v[164:165], 0, v[20:21]
	global_load_dwordx4 v[68:71], v[20:21], off
	v_add_u32_e32 v20, s76, v223
	v_med3_i32 v20, v20, 0, s75
	v_add_u32_e32 v20, s74, v20
	v_ashrrev_i32_e32 v21, 31, v20
	v_lshlrev_b64 v[20:21], 9, v[20:21]
	v_lshl_add_u64 v[20:21], v[164:165], 0, v[20:21]
	global_load_dwordx4 v[72:75], v[20:21], off
	v_add_u32_e32 v20, s76, v224
	v_med3_i32 v20, v20, 0, s75
	v_add_u32_e32 v20, s74, v20
	v_ashrrev_i32_e32 v21, 31, v20
	v_lshlrev_b64 v[20:21], 9, v[20:21]
	v_lshl_add_u64 v[20:21], v[164:165], 0, v[20:21]
	global_load_dwordx4 v[76:79], v[20:21], off
	v_add_u32_e32 v20, s76, v225
	v_med3_i32 v20, v20, 0, s75
	v_add_u32_e32 v20, s74, v20
	v_ashrrev_i32_e32 v21, 31, v20
	v_lshlrev_b64 v[20:21], 9, v[20:21]
	v_lshl_add_u64 v[20:21], v[164:165], 0, v[20:21]
	global_load_dwordx4 v[92:95], v[20:21], off
	v_add_u32_e32 v20, s76, v226
	v_med3_i32 v20, v20, 0, s75
	v_add_u32_e32 v20, s74, v20
	v_ashrrev_i32_e32 v21, 31, v20
	v_lshlrev_b64 v[20:21], 9, v[20:21]
	v_lshl_add_u64 v[20:21], s[68:69], 0, v[20:21]
	v_lshl_add_u64 v[20:21], v[20:21], 0, v[158:159]
	global_load_dwordx4 v[52:55], v[20:21], off
	global_load_dwordx4 v[44:47], v[20:21], off offset:64
	v_add_u32_e32 v20, s76, v227
	v_med3_i32 v20, v20, 0, s75
	v_add_u32_e32 v20, s74, v20
	v_ashrrev_i32_e32 v21, 31, v20
	v_lshlrev_b64 v[20:21], 9, v[20:21]
	v_lshl_add_u64 v[20:21], s[68:69], 0, v[20:21]
	v_lshl_add_u64 v[20:21], v[20:21], 0, v[158:159]
	global_load_dwordx4 v[28:31], v[20:21], off
	s_nop 0
	global_load_dwordx4 v[20:23], v[20:21], off offset:64
	ds_read_b64_tr_b16 v[142:143], v169 offset:6912
	ds_read_b64_tr_b16 v[140:141], v169 offset:4608
	ds_read_b64_tr_b16 v[136:137], v169 offset:4640
	ds_read_b64_tr_b16 v[138:139], v169 offset:6944
	ds_read_b64_tr_b16 v[132:133], v169 offset:4672
	ds_read_b64_tr_b16 v[134:135], v169 offset:6976
	ds_read_b64_tr_b16 v[128:129], v169 offset:4704
	ds_read_b64_tr_b16 v[130:131], v169 offset:7008
	s_waitcnt vmcnt(15)
	ds_write_b128 v241, v[60:63]
	s_waitcnt vmcnt(14)
	ds_write_b128 v242, v[80:83]
	s_waitcnt vmcnt(13)
	ds_write_b128 v243, v[84:87]
	s_waitcnt vmcnt(12)
	ds_write_b128 v244, v[88:91]
	v_mfma_f32_16x16x32_bf16 v[60:63], v[64:67], v[4:7], 0
	v_mfma_f32_16x16x32_bf16 v[80:83], v[40:43], v[4:7], 0
	v_mfma_f32_16x16x32_bf16 v[40:43], v[40:43], v[12:15], 0
	v_mfma_f32_16x16x32_bf16 v[60:63], v[48:51], v[8:11], v[60:63]
	v_mfma_f32_16x16x32_bf16 v[80:83], v[16:19], v[8:11], v[80:83]
	v_mfma_f32_16x16x32_bf16 v[16:19], v[16:19], v[0:3], v[40:43]
	s_nop 4
	v_sub_u32_e32 v40, v199, v176
	v_mfma_f32_16x16x32_bf16 v[64:67], v[64:67], v[12:15], 0
	v_add_u32_e32 v43, 1, v40
	v_max_f32_e32 v42, v60, v60
	v_cmp_gt_u32_e64 s[0:1], v43, v175
	v_cmp_gt_u32_e32 vcc, v40, v175
	v_max_f32_e32 v42, 0xf149f2ca, v42
	v_cndmask_b32_e64 v43, v61, v246, s[0:1]
	v_cndmask_b32_e32 v42, v42, v246, vcc
	v_mfma_f32_16x16x32_bf16 v[48:51], v[48:51], v[0:3], v[64:67]
	v_max_f32_e32 v42, v42, v43
	v_add_u32_e32 v43, 2, v40
	v_cmp_gt_u32_e64 s[22:23], v43, v175
	v_add_u32_e32 v64, 3, v40
	v_cmp_gt_u32_e64 s[24:25], v64, v175
	v_cndmask_b32_e64 v43, v62, v246, s[22:23]
	v_sub_u32_e32 v41, v199, v181
	v_cndmask_b32_e64 v64, v63, v246, s[24:25]
	v_max3_f32 v42, v42, v43, v64
	v_add_u32_e32 v43, 16, v40
	v_add_u32_e32 v64, 17, v40
	v_cmp_gt_u32_e64 s[26:27], v43, v175
	v_cmp_gt_u32_e64 s[28:29], v64, v175
	v_cmp_gt_u32_e64 s[38:39], v41, v252
	v_cndmask_b32_e64 v43, v80, v246, s[26:27]
	v_cndmask_b32_e64 v64, v81, v246, s[28:29]
	v_max3_f32 v42, v42, v43, v64
	v_add_u32_e32 v43, 18, v40
	v_add_u32_e32 v40, 19, v40
	v_cmp_gt_u32_e64 s[30:31], v43, v175
	v_cmp_gt_u32_e64 s[34:35], v40, v175
	v_add_u32_e32 v64, 3, v41
	v_cndmask_b32_e64 v43, v82, v246, s[30:31]
	v_cndmask_b32_e64 v40, v83, v246, s[34:35]
	v_max3_f32 v40, v42, v43, v40
	v_add_u32_e32 v43, 1, v41
	v_max_f32_e32 v42, v48, v48
	v_cmp_gt_u32_e64 s[40:41], v43, v252
	v_max_f32_e32 v42, 0xf149f2ca, v42
	v_cndmask_b32_e64 v42, v42, v246, s[38:39]
	v_cndmask_b32_e64 v43, v49, v246, s[40:41]
	v_max_f32_e32 v42, v42, v43
	v_add_u32_e32 v43, 2, v41
	v_cmp_gt_u32_e64 s[42:43], v43, v252
	v_cmp_gt_u32_e64 s[44:45], v64, v252
	s_nop 0
	v_cndmask_b32_e64 v43, v50, v246, s[42:43]
	v_cndmask_b32_e64 v64, v51, v246, s[44:45]
	v_max3_f32 v42, v42, v43, v64
	v_add_u32_e32 v43, 16, v41
	v_add_u32_e32 v64, 17, v41
	v_cmp_gt_u32_e64 s[46:47], v43, v252
	v_cmp_gt_u32_e64 s[48:49], v64, v252
	s_nop 0
	v_cndmask_b32_e64 v43, v16, v246, s[46:47]
	v_cndmask_b32_e64 v64, v17, v246, s[48:49]
	v_max3_f32 v42, v42, v43, v64
	v_add_u32_e32 v43, 18, v41
	v_add_u32_e32 v41, 19, v41
	v_cmp_gt_u32_e64 s[50:51], v43, v252
	v_cmp_gt_u32_e64 s[52:53], v41, v252
	s_nop 0
	v_cndmask_b32_e64 v43, v18, v246, s[50:51]
	v_cndmask_b32_e64 v41, v19, v246, s[52:53]
	v_max3_f32 v41, v42, v43, v41
	v_mov_b32_e32 v42, v40
	v_mov_b32_e32 v43, v40
	s_nop 1
	v_permlane32_swap_b32_e32 v42, v43
	v_max3_f32 v40, v40, v42, v43
	v_mov_b32_e32 v42, v41
	v_mov_b32_e32 v43, v41
	s_nop 1
	v_permlane32_swap_b32_e32 v42, v43
	v_max3_f32 v41, v41, v42, v43
	v_mov_b32_e32 v42, v40
	v_mov_b32_e32 v43, v40
	s_nop 1
	v_permlane16_swap_b32_e32 v42, v43
	v_max_f32_e32 v40, v40, v42
	v_max3_f32 v147, v148, v40, v43
	v_sub_f32_e32 v40, v148, v147
	v_exp_f32_e32 v84, v40
	v_sub_f32_e32 v40, v60, v147
	v_exp_f32_e32 v40, v40
	v_mov_b32_e32 v42, v41
	v_mov_b32_e32 v64, v41
	s_nop 1
	v_permlane16_swap_b32_e32 v42, v64
	v_cndmask_b32_e64 v85, v40, 0, vcc
	v_sub_f32_e32 v40, v61, v147
	v_exp_f32_e32 v40, v40
	v_max_f32_e32 v65, v41, v42
	v_max3_f32 v146, v149, v65, v64
	v_cndmask_b32_e64 v61, v40, 0, s[0:1]
	v_sub_f32_e32 v40, v62, v147
	v_exp_f32_e32 v40, v40
	v_sub_f32_e32 v48, v48, v146
	v_sub_f32_e32 v16, v16, v146
	v_exp_f32_e32 v48, v48
	v_cndmask_b32_e64 v62, v40, 0, s[22:23]
	v_sub_f32_e32 v40, v63, v147
	v_exp_f32_e32 v40, v40
	v_exp_f32_e32 v16, v16
	v_cndmask_b32_e64 v86, v48, 0, s[38:39]
	v_sub_f32_e32 v48, v49, v146
	v_cndmask_b32_e64 v63, v40, 0, s[24:25]
	v_sub_f32_e32 v40, v80, v147
	v_exp_f32_e32 v40, v40
	v_cndmask_b32_e64 v90, v16, 0, s[46:47]
	v_sub_f32_e32 v16, v17, v146
	v_exp_f32_e32 v48, v48
	v_cndmask_b32_e64 v80, v40, 0, s[26:27]
	v_sub_f32_e32 v40, v81, v147
	v_exp_f32_e32 v40, v40
	v_exp_f32_e32 v16, v16
	v_cndmask_b32_e64 v87, v48, 0, s[40:41]
	v_sub_f32_e32 v48, v50, v146
	v_cndmask_b32_e64 v81, v40, 0, s[28:29]
	v_sub_f32_e32 v40, v82, v147
	v_exp_f32_e32 v40, v40
	v_cndmask_b32_e64 v91, v16, 0, s[48:49]
	v_sub_f32_e32 v16, v18, v146
	v_exp_f32_e32 v48, v48
	v_exp_f32_e32 v16, v16
	v_cndmask_b32_e64 v82, v40, 0, s[30:31]
	v_sub_f32_e32 v40, v83, v147
	v_exp_f32_e32 v40, v40
	v_cndmask_b32_e64 v88, v48, 0, s[42:43]
	v_sub_f32_e32 v48, v51, v146
	v_cndmask_b32_e64 v148, v16, 0, s[50:51]
	v_sub_f32_e32 v16, v19, v146
	v_sub_f32_e32 v60, v149, v146
	v_exp_f32_e32 v48, v48
	v_exp_f32_e32 v16, v16
	v_exp_f32_e32 v60, v60
	v_cndmask_b32_e64 v83, v40, 0, s[34:35]
	v_cvt_pk_bf16_f32 v40, v85, v61
	v_cvt_pk_bf16_f32 v41, v62, v63
	v_cvt_pk_bf16_f32 v42, v80, v81
	v_cvt_pk_bf16_f32 v43, v82, v83
	v_cndmask_b32_e64 v89, v48, 0, s[44:45]
	v_cndmask_b32_e64 v149, v16, 0, s[52:53]
	v_pk_mul_f32 v[50:51], v[98:99], v[84:85] op_sel_hi:[1,0]
	v_pk_mul_f32 v[48:49], v[96:97], v[84:85] op_sel_hi:[1,0]
	v_cvt_pk_bf16_f32 v16, v86, v87
	v_cvt_pk_bf16_f32 v17, v88, v89
	v_cvt_pk_bf16_f32 v18, v90, v91
	v_cvt_pk_bf16_f32 v19, v148, v149
	s_waitcnt lgkmcnt(10)
	v_mfma_f32_16x16x32_bf16 v[64:67], v[140:143], v[40:43], v[48:51]
	s_cselect_b64 s[38:39], -1, 0
	s_add_i32 s0, s76, 0xfffffc00
	s_min_i32 s1, s0, 0
	v_pk_mul_f32 v[50:51], v[102:103], v[60:61] op_sel_hi:[1,0]
	v_pk_mul_f32 v[48:49], v[100:101], v[60:61] op_sel_hi:[1,0]
	s_sub_i32 s1, 15, s1
	s_ashr_i32 s1, s1, 4
	v_mfma_f32_16x16x32_bf16 v[100:103], v[140:143], v[16:19], v[48:51]
	s_sub_i32 s0, s75, s0
	s_ashr_i32 s0, s0, 4
	s_or_b32 s40, s76, 8
	v_pk_mul_f32 v[50:51], v[106:107], v[84:85] op_sel_hi:[1,0]
	v_pk_mul_f32 v[48:49], v[104:105], v[84:85] op_sel_hi:[1,0]
	s_lshl_b32 s56, s56, 7
	s_add_i32 s71, s71, s78
	s_waitcnt lgkmcnt(8)
	v_mfma_f32_16x16x32_bf16 v[104:107], v[136:139], v[40:43], v[48:51]
	s_nop 2
	v_mul_f32_e64 v50, v110, v60
	v_mul_f32_e64 v51, v111, v60
	v_pk_mul_f32 v[48:49], v[108:109], v[60:61] op_sel_hi:[1,0]
	s_nop 1
	v_mfma_f32_16x16x32_bf16 v[108:111], v[136:139], v[16:19], v[48:51]
	s_nop 2
	v_mul_f32_e64 v50, v114, v84
	v_mul_f32_e64 v51, v115, v84
	v_pk_mul_f32 v[48:49], v[112:113], v[84:85] op_sel_hi:[1,0]
	s_waitcnt lgkmcnt(6)
	s_nop 0
	v_mfma_f32_16x16x32_bf16 v[112:115], v[132:135], v[40:43], v[48:51]
	s_nop 2
	v_mul_f32_e64 v50, v118, v60
	v_mul_f32_e64 v51, v119, v60
	v_pk_mul_f32 v[48:49], v[116:117], v[60:61] op_sel_hi:[1,0]
	s_nop 1
	v_mfma_f32_16x16x32_bf16 v[116:119], v[132:135], v[16:19], v[48:51]
	s_nop 2
	v_mul_f32_e64 v50, v122, v84
	v_mul_f32_e64 v51, v123, v84
	v_pk_mul_f32 v[48:49], v[120:121], v[84:85] op_sel_hi:[1,0]
	s_waitcnt lgkmcnt(4)
	s_nop 0
	v_mfma_f32_16x16x32_bf16 v[120:123], v[128:131], v[40:43], v[48:51]
	v_mul_f32_e64 v42, v126, v60
	v_mul_f32_e64 v43, v127, v60
	v_pk_mul_f32 v[40:41], v[124:125], v[60:61] op_sel_hi:[1,0]
	s_nop 1
	v_mfma_f32_16x16x32_bf16 v[124:127], v[128:131], v[16:19], v[40:43]
	v_add_f32_e32 v16, 0, v86
	v_add_f32_e32 v16, v87, v16
	v_add_f32_e32 v16, v88, v16
	v_add_f32_e32 v16, v89, v16
	v_add_f32_e32 v16, v90, v16
	v_add_f32_e32 v16, v91, v16
	v_add_f32_e32 v16, v148, v16
	v_add_f32_e32 v151, v149, v16
	v_add_f32_e32 v16, 0, v85
	v_add_f32_e32 v16, v61, v16
	v_add_f32_e32 v16, v62, v16
	v_add_f32_e32 v16, v63, v16
	v_add_f32_e32 v16, v80, v16
	v_add_f32_e32 v16, v81, v16
	v_add_f32_e32 v16, v82, v16
	v_fmac_f32_e32 v151, v145, v60
	v_add_f32_e32 v145, v83, v16
	v_add_u32_e32 v16, s76, v213
	v_fmac_f32_e32 v145, v144, v84
	v_ashrrev_i32_e32 v148, 4, v250
	v_med3_i32 v16, v16, 0, s75
	v_add_u32_e32 v16, s74, v16
	v_ashrrev_i32_e32 v17, 31, v16
	v_lshlrev_b64 v[16:17], 9, v[16:17]
	v_lshl_add_u64 v[16:17], v[164:165], 0, v[16:17]
	global_load_dwordx4 v[80:83], v[16:17], off
	v_add_u32_e32 v16, s76, v215
	v_max_i32_e32 v150, s1, v148
	s_nop 0
	v_med3_i32 v16, v16, 0, s75
	v_add_u32_e32 v16, s74, v16
	v_ashrrev_i32_e32 v17, 31, v16
	v_lshlrev_b64 v[16:17], 9, v[16:17]
	v_lshl_add_u64 v[16:17], v[164:165], 0, v[16:17]
	global_load_dwordx4 v[84:87], v[16:17], off
	v_add_u32_e32 v16, s76, v217
	v_med3_i32 v16, v16, 0, s75
	v_add_u32_e32 v16, s74, v16
	v_ashrrev_i32_e32 v17, 31, v16
	v_lshlrev_b64 v[16:17], 9, v[16:17]
	v_lshl_add_u64 v[16:17], v[164:165], 0, v[16:17]
	global_load_dwordx4 v[88:91], v[16:17], off
	v_add_u32_e32 v16, s76, v219
	v_med3_i32 v16, v16, 0, s75
	v_add_u32_e32 v16, s74, v16
	v_ashrrev_i32_e32 v17, 31, v16
	v_lshlrev_b64 v[16:17], 9, v[16:17]
	v_lshl_add_u64 v[16:17], v[164:165], 0, v[16:17]
	global_load_dwordx4 v[96:99], v[16:17], off
	v_min_i32_e32 v16, s75, v251
	v_cndmask_b32_e64 v16, v16, 0, s[38:39]
	v_add_u32_e32 v16, s74, v16
	v_ashrrev_i32_e32 v17, 31, v16
	v_lshlrev_b64 v[16:17], 9, v[16:17]
	v_lshl_add_u64 v[16:17], s[68:69], 0, v[16:17]
	v_lshl_add_u64 v[16:17], v[16:17], 0, v[158:159]
	global_load_dwordx4 v[48:51], v[16:17], off
	global_load_dwordx4 v[60:63], v[16:17], off offset:64
	v_add_u32_e32 v16, s76, v228
	v_med3_i32 v16, v16, 0, s75
	v_add_u32_e32 v16, s74, v16
	v_ashrrev_i32_e32 v17, 31, v16
	v_lshlrev_b64 v[16:17], 9, v[16:17]
	v_lshl_add_u64 v[16:17], s[68:69], 0, v[16:17]
	v_lshl_add_u64 v[16:17], v[16:17], 0, v[158:159]
	global_load_dwordx4 v[40:43], v[16:17], off
	s_nop 0
	global_load_dwordx4 v[16:19], v[16:17], off offset:64
	ds_read_b64_tr_b16 v[142:143], v169 offset:2304
	ds_read_b64_tr_b16 v[140:141], v169
	ds_read_b64_tr_b16 v[136:137], v169 offset:32
	ds_read_b64_tr_b16 v[138:139], v169 offset:2336
	ds_read_b64_tr_b16 v[132:133], v169 offset:64
	ds_read_b64_tr_b16 v[134:135], v169 offset:2368
	ds_read_b64_tr_b16 v[128:129], v169 offset:96
	ds_read_b64_tr_b16 v[130:131], v169 offset:2400
	s_waitcnt vmcnt(15)
	ds_write_b128 v241, v[68:71] offset:4608
	s_waitcnt vmcnt(14)
	ds_write_b128 v242, v[72:75] offset:4608
	s_waitcnt vmcnt(13)
	ds_write_b128 v243, v[76:79] offset:4608
	s_waitcnt vmcnt(12)
	ds_write_b128 v244, v[92:95] offset:4608
	v_mfma_f32_16x16x32_bf16 v[72:75], v[32:35], v[4:7], 0
	v_mfma_f32_16x16x32_bf16 v[32:35], v[32:35], v[12:15], 0
	v_mfma_f32_16x16x32_bf16 v[68:71], v[56:59], v[4:7], 0
	v_mfma_f32_16x16x32_bf16 v[72:75], v[24:27], v[8:11], v[72:75]
	v_mfma_f32_16x16x32_bf16 v[24:27], v[24:27], v[0:3], v[32:35]
	v_mfma_f32_16x16x32_bf16 v[68:71], v[36:39], v[8:11], v[68:71]
	v_mfma_f32_16x16x32_bf16 v[56:59], v[56:59], v[12:15], 0
	s_nop 5
	v_add_u32_e32 v25, 0x800, v250
	v_ashrrev_i32_e32 v25, 4, v25
	v_min3_i32 v25, v25, s0, v248
	v_sub_u32_e32 v26, v154, v150
	v_sub_u32_e32 v149, v25, v150
	v_add_u32_e32 v27, 1, v26
	v_max_f32_e32 v25, v68, v68
	v_cmp_gt_u32_e64 s[0:1], v27, v149
	v_cmp_gt_u32_e32 vcc, v26, v149
	v_max_f32_e32 v25, 0xf149f2ca, v25
	v_cndmask_b32_e64 v27, v69, v246, s[0:1]
	v_cndmask_b32_e32 v25, v25, v246, vcc
	v_max_f32_e32 v25, v25, v27
	v_add_u32_e32 v27, 2, v26
	v_add_u32_e32 v32, 3, v26
	v_cmp_gt_u32_e64 s[22:23], v27, v149
	v_cmp_gt_u32_e64 s[24:25], v32, v149
	v_mfma_f32_16x16x32_bf16 v[36:39], v[36:39], v[0:3], v[56:59]
	v_cndmask_b32_e64 v27, v70, v246, s[22:23]
	v_cndmask_b32_e64 v32, v71, v246, s[24:25]
	v_max3_f32 v25, v25, v27, v32
	v_add_u32_e32 v27, 16, v26
	v_add_u32_e32 v32, 17, v26
	v_cmp_gt_u32_e64 s[26:27], v27, v149
	v_cmp_gt_u32_e64 s[28:29], v32, v149
	s_nop 0
	v_cndmask_b32_e64 v27, v72, v246, s[26:27]
	v_cndmask_b32_e64 v32, v73, v246, s[28:29]
	v_max3_f32 v25, v25, v27, v32
	v_add_u32_e32 v27, 18, v26
	v_add_u32_e32 v26, 19, v26
	v_cmp_gt_u32_e64 s[30:31], v27, v149
	v_cmp_gt_u32_e64 s[34:35], v26, v149
	s_nop 0
	v_cndmask_b32_e64 v27, v74, v246, s[30:31]
	v_cndmask_b32_e64 v26, v75, v246, s[34:35]
	v_max3_f32 v25, v25, v27, v26
	v_max_f32_e32 v26, v36, v36
	v_max_f32_e32 v26, 0xf149f2ca, v26
	v_cndmask_b32_e64 v26, v246, v26, s[36:37]
	v_cndmask_b32_e64 v27, v246, v24, s[4:5]
	v_max3_f32 v26, v26, v27, s73
	v_mov_b32_e32 v27, v25
	v_mov_b32_e32 v32, v25
	s_nop 1
	v_permlane32_swap_b32_e32 v27, v32
	v_max3_f32 v25, v25, v27, v32
	v_mov_b32_e32 v27, v26
	v_mov_b32_e32 v32, v26
	s_nop 1
	v_permlane32_swap_b32_e32 v27, v32
	v_max3_f32 v26, v26, v27, v32
	v_mov_b32_e32 v27, v25
	v_mov_b32_e32 v32, v25
	s_nop 1
	v_permlane16_swap_b32_e32 v27, v32
	v_max_f32_e32 v25, v25, v27
	v_max3_f32 v144, v147, v25, v32
	v_sub_f32_e32 v25, v147, v144
	v_exp_f32_e32 v56, v25
	v_sub_f32_e32 v25, v68, v144
	v_exp_f32_e32 v25, v25
	v_sub_f32_e32 v32, v69, v144
	v_exp_f32_e32 v32, v32
	v_sub_f32_e32 v33, v70, v144
	v_mov_b32_e32 v27, v26
	v_mov_b32_e32 v37, v26
	v_exp_f32_e32 v33, v33
	v_sub_f32_e32 v34, v71, v144
	v_permlane16_swap_b32_e32 v27, v37
	v_exp_f32_e32 v34, v34
	v_sub_f32_e32 v35, v72, v144
	v_cndmask_b32_e64 v25, v25, 0, vcc
	v_exp_f32_e32 v35, v35
	v_sub_f32_e32 v38, v73, v144
	v_max_f32_e32 v26, v26, v27
	v_add_f32_e32 v27, 0, v25
	v_cndmask_b32_e64 v32, v32, 0, s[0:1]
	v_exp_f32_e32 v38, v38
	v_sub_f32_e32 v39, v74, v144
	v_add_f32_e32 v27, v32, v27
	v_cndmask_b32_e64 v33, v33, 0, s[22:23]
	v_exp_f32_e32 v39, v39
	v_sub_f32_e32 v57, v75, v144
	v_add_f32_e32 v27, v33, v27
	v_cndmask_b32_e64 v34, v34, 0, s[24:25]
	v_exp_f32_e32 v57, v57
	v_add_f32_e32 v27, v34, v27
	v_cndmask_b32_e64 v35, v35, 0, s[26:27]
	v_add_f32_e32 v27, v35, v27
	v_cndmask_b32_e64 v38, v38, 0, s[28:29]
	v_add_f32_e32 v27, v38, v27
	v_cndmask_b32_e64 v39, v39, 0, s[30:31]
	v_add_f32_e32 v27, v39, v27
	v_cndmask_b32_e64 v57, v57, 0, s[34:35]
	v_add_f32_e32 v147, v57, v27
	v_fmac_f32_e32 v147, v145, v56
	v_max3_f32 v145, v146, v26, v37
	v_cvt_pk_bf16_f32 v32, v25, v32
	v_sub_f32_e32 v25, v146, v145
	v_exp_f32_e32 v58, v25
	v_sub_f32_e32 v25, v36, v145
	v_exp_f32_e32 v25, v25
	v_sub_f32_e32 v24, v24, v145
	v_exp_f32_e32 v24, v24
	v_cvt_pk_bf16_f32 v33, v33, v34
	v_cndmask_b32_e64 v25, 0, v25, s[36:37]
	v_cvt_pk_bf16_f32 v34, v35, v38
	v_cvt_pk_bf16_f32 v35, v39, v57
	v_add_f32_e32 v26, 0, v25
	v_cndmask_b32_e64 v27, 0, v24, s[4:5]
	v_pk_mul_f32 v[38:39], v[66:67], v[56:57] op_sel_hi:[1,0]
	v_pk_mul_f32 v[36:37], v[64:65], v[56:57] op_sel_hi:[1,0]
	v_add_f32_e32 v146, v27, v26
	v_cvt_pk_bf16_f32 v24, v25, 0
	v_cvt_pk_bf16_f32 v26, v27, 0
	v_mov_b32_e32 v25, v153
	v_mov_b32_e32 v27, v153
	s_waitcnt lgkmcnt(10)
	v_mfma_f32_16x16x32_bf16 v[76:79], v[140:143], v[32:35], v[36:39]
	v_fmac_f32_e32 v146, v151, v58
	s_nop 1
	v_pk_mul_f32 v[38:39], v[102:103], v[58:59] op_sel_hi:[1,0]
	v_pk_mul_f32 v[36:37], v[100:101], v[58:59] op_sel_hi:[1,0]
	s_nop 1
	v_mfma_f32_16x16x32_bf16 v[100:103], v[140:143], v[24:27], v[36:39]
	s_nop 2
	v_mul_f32_e64 v38, v106, v56
	v_mul_f32_e64 v39, v107, v56
	v_pk_mul_f32 v[36:37], v[104:105], v[56:57] op_sel_hi:[1,0]
	s_waitcnt lgkmcnt(8)
	s_nop 0
	v_mfma_f32_16x16x32_bf16 v[104:107], v[136:139], v[32:35], v[36:39]
	s_nop 2
	v_mul_f32_e64 v38, v110, v58
	v_mul_f32_e64 v39, v111, v58
	v_pk_mul_f32 v[36:37], v[108:109], v[58:59] op_sel_hi:[1,0]
	s_nop 1
	v_mfma_f32_16x16x32_bf16 v[108:111], v[136:139], v[24:27], v[36:39]
	s_nop 2
	v_mul_f32_e64 v38, v114, v56
	v_mul_f32_e64 v39, v115, v56
	v_pk_mul_f32 v[36:37], v[112:113], v[56:57] op_sel_hi:[1,0]
	s_waitcnt lgkmcnt(6)
	s_nop 0
	v_mfma_f32_16x16x32_bf16 v[112:115], v[132:135], v[32:35], v[36:39]
	s_nop 2
	v_mul_f32_e64 v38, v118, v58
	v_mul_f32_e64 v39, v119, v58
	v_pk_mul_f32 v[36:37], v[116:117], v[58:59] op_sel_hi:[1,0]
	s_nop 1
	v_mfma_f32_16x16x32_bf16 v[116:119], v[132:135], v[24:27], v[36:39]
	s_nop 2
	v_mul_f32_e64 v38, v122, v56
	v_mul_f32_e64 v39, v123, v56
	v_pk_mul_f32 v[36:37], v[120:121], v[56:57] op_sel_hi:[1,0]
	v_add_u32_e32 v56, s76, v232
	s_waitcnt lgkmcnt(4)
	v_mfma_f32_16x16x32_bf16 v[120:123], v[128:131], v[32:35], v[36:39]
	v_mul_f32_e64 v34, v126, v58
	v_mul_f32_e64 v35, v127, v58
	v_pk_mul_f32 v[32:33], v[124:125], v[58:59] op_sel_hi:[1,0]
	v_add_u32_e32 v36, s76, v231
	s_nop 0
	v_mfma_f32_16x16x32_bf16 v[124:127], v[128:131], v[24:27], v[32:35]
	v_add_u32_e32 v24, s76, v229
	s_nop 1
	v_add_u32_e32 v32, s76, v230
	v_med3_i32 v24, v24, 0, s75
	v_add_u32_e32 v24, s74, v24
	v_med3_i32 v32, v32, 0, s75
	v_add_u32_e32 v32, s74, v32
	v_ashrrev_i32_e32 v25, 31, v24
	v_med3_i32 v36, v36, 0, s75
	v_add_u32_e32 v36, s74, v36
	v_ashrrev_i32_e32 v37, 31, v36
	v_med3_i32 v56, v56, 0, s75
	v_add_u32_e32 v56, s74, v56
	v_ashrrev_i32_e32 v57, 31, v56
	v_lshlrev_b64 v[36:37], 9, v[36:37]
	v_lshlrev_b64 v[56:57], 9, v[56:57]
	v_lshl_add_u64 v[36:37], v[164:165], 0, v[36:37]
	v_lshl_add_u64 v[56:57], v[164:165], 0, v[56:57]
	global_load_dwordx4 v[36:39], v[36:37], off
	v_ashrrev_i32_e32 v33, 31, v32
	global_load_dwordx4 v[92:95], v[56:57], off
	v_add_u32_e32 v56, s76, v233
	v_lshlrev_b64 v[24:25], 9, v[24:25]
	v_lshlrev_b64 v[32:33], 9, v[32:33]
	v_med3_i32 v56, v56, 0, s75
	v_add_u32_e32 v56, s74, v56
	v_ashrrev_i32_e32 v57, 31, v56
	v_lshlrev_b64 v[56:57], 9, v[56:57]
	v_lshl_add_u64 v[56:57], s[68:69], 0, v[56:57]
	v_lshl_add_u64 v[24:25], v[164:165], 0, v[24:25]
	v_lshl_add_u64 v[32:33], v[164:165], 0, v[32:33]
	v_lshl_add_u64 v[56:57], v[56:57], 0, v[158:159]
	global_load_dwordx4 v[24:27], v[24:25], off
	s_nop 0
	global_load_dwordx4 v[32:35], v[32:33], off
	s_nop 0
	global_load_dwordx4 v[72:75], v[56:57], off
	global_load_dwordx4 v[68:71], v[56:57], off offset:64
	v_add_u32_e32 v56, s76, v234
	v_med3_i32 v56, v56, 0, s75
	v_add_u32_e32 v56, s74, v56
	v_ashrrev_i32_e32 v57, 31, v56
	v_lshlrev_b64 v[56:57], 9, v[56:57]
	v_lshl_add_u64 v[56:57], s[68:69], 0, v[56:57]
	v_lshl_add_u64 v[56:57], v[56:57], 0, v[158:159]
	global_load_dwordx4 v[64:67], v[56:57], off
	s_nop 0
	global_load_dwordx4 v[56:59], v[56:57], off offset:64
	ds_read_b64_tr_b16 v[142:143], v169 offset:6912
	ds_read_b64_tr_b16 v[140:141], v169 offset:4608
	ds_read_b64_tr_b16 v[136:137], v169 offset:4640
	ds_read_b64_tr_b16 v[138:139], v169 offset:6944
	ds_read_b64_tr_b16 v[132:133], v169 offset:4672
	ds_read_b64_tr_b16 v[134:135], v169 offset:6976
	ds_read_b64_tr_b16 v[128:129], v169 offset:4704
	ds_read_b64_tr_b16 v[130:131], v169 offset:7008
	s_waitcnt vmcnt(15)
	ds_write_b128 v241, v[80:83]
	s_waitcnt vmcnt(14)
	ds_write_b128 v242, v[84:87]
	s_waitcnt vmcnt(13)
	ds_write_b128 v243, v[88:91]
	s_waitcnt vmcnt(12)
	ds_write_b128 v244, v[96:99]
	v_mfma_f32_16x16x32_bf16 v[80:83], v[52:55], v[4:7], 0
	v_mfma_f32_16x16x32_bf16 v[84:87], v[28:31], v[4:7], 0
	v_mfma_f32_16x16x32_bf16 v[28:31], v[28:31], v[12:15], 0
	v_mfma_f32_16x16x32_bf16 v[80:83], v[44:47], v[8:11], v[80:83]
	v_mfma_f32_16x16x32_bf16 v[84:87], v[20:23], v[8:11], v[84:87]
	v_mfma_f32_16x16x32_bf16 v[20:23], v[20:23], v[0:3], v[28:31]
	v_mfma_f32_16x16x32_bf16 v[52:55], v[52:55], v[12:15], 0
	v_mfma_f32_16x16x32_bf16 v[44:47], v[44:47], v[0:3], v[52:55]
	s_nop 5
	v_sub_u32_e32 v21, v187, v150
	v_add_u32_e32 v23, 1, v21
	v_max_f32_e32 v22, v80, v80
	v_cmp_gt_u32_e64 s[0:1], v23, v149
	v_cmp_gt_u32_e32 vcc, v21, v149
	v_max_f32_e32 v22, 0xf149f2ca, v22
	v_cndmask_b32_e64 v23, v81, v246, s[0:1]
	v_cndmask_b32_e32 v22, v22, v246, vcc
	v_max_f32_e32 v22, v22, v23
	v_add_u32_e32 v23, 2, v21
	v_add_u32_e32 v28, 3, v21
	v_cmp_gt_u32_e64 s[22:23], v23, v149
	v_cmp_gt_u32_e64 s[24:25], v28, v149
	s_nop 0
	v_cndmask_b32_e64 v23, v82, v246, s[22:23]
	v_cndmask_b32_e64 v28, v83, v246, s[24:25]
	v_max3_f32 v22, v22, v23, v28
	v_add_u32_e32 v23, 16, v21
	v_add_u32_e32 v28, 17, v21
	v_cmp_gt_u32_e64 s[26:27], v23, v149
	v_cmp_gt_u32_e64 s[28:29], v28, v149
	s_nop 0
	v_cndmask_b32_e64 v23, v84, v246, s[26:27]
	v_cndmask_b32_e64 v28, v85, v246, s[28:29]
	v_max3_f32 v22, v22, v23, v28
	v_add_u32_e32 v23, 18, v21
	v_add_u32_e32 v21, 19, v21
	v_cmp_gt_u32_e64 s[30:31], v23, v149
	v_cmp_gt_u32_e64 s[34:35], v21, v149
	s_nop 0
	v_cndmask_b32_e64 v23, v86, v246, s[30:31]
	v_cndmask_b32_e64 v21, v87, v246, s[34:35]
	v_max3_f32 v21, v22, v23, v21
	v_max_f32_e32 v22, v44, v44
	v_max_f32_e32 v22, 0xf149f2ca, v22
	v_cndmask_b32_e64 v22, v246, v22, s[6:7]
	v_cndmask_b32_e64 v23, v246, v20, s[8:9]
	v_max3_f32 v22, v22, v23, s73
	v_mov_b32_e32 v23, v21
	v_mov_b32_e32 v28, v21
	s_nop 1
	v_permlane32_swap_b32_e32 v23, v28
	v_max3_f32 v21, v21, v23, v28
	v_mov_b32_e32 v23, v22
	v_mov_b32_e32 v28, v22
	s_nop 1
	v_permlane32_swap_b32_e32 v23, v28
	v_max3_f32 v22, v22, v23, v28
	v_mov_b32_e32 v23, v21
	v_mov_b32_e32 v28, v21
	s_nop 1
	v_permlane16_swap_b32_e32 v23, v28
	v_max_f32_e32 v21, v21, v23
	v_max3_f32 v175, v144, v21, v28
	v_sub_f32_e32 v21, v144, v175
	v_exp_f32_e32 v144, v21
	v_sub_f32_e32 v21, v80, v175
	v_sub_f32_e32 v28, v81, v175
	v_mov_b32_e32 v23, v22
	v_mov_b32_e32 v29, v22
	v_exp_f32_e32 v21, v21
	v_exp_f32_e32 v28, v28
	v_permlane16_swap_b32_e32 v23, v29
	v_sub_f32_e32 v30, v82, v175
	v_exp_f32_e32 v30, v30
	v_sub_f32_e32 v31, v83, v175
	v_max_f32_e32 v22, v22, v23
	v_exp_f32_e32 v31, v31
	v_sub_f32_e32 v45, v84, v175
	v_cndmask_b32_e64 v21, v21, 0, vcc
	v_cndmask_b32_e64 v28, v28, 0, s[0:1]
	v_exp_f32_e32 v45, v45
	v_sub_f32_e32 v46, v85, v175
	v_max3_f32 v176, v145, v22, v29
	v_add_f32_e32 v23, 0, v21
	v_exp_f32_e32 v46, v46
	v_sub_f32_e32 v47, v86, v175
	v_cvt_pk_bf16_f32 v80, v21, v28
	v_sub_f32_e32 v21, v145, v176
	v_add_f32_e32 v23, v28, v23
	v_cndmask_b32_e64 v30, v30, 0, s[22:23]
	v_exp_f32_e32 v47, v47
	v_sub_f32_e32 v52, v87, v175
	v_exp_f32_e32 v84, v21
	v_sub_f32_e32 v21, v44, v176
	v_add_f32_e32 v23, v30, v23
	v_cndmask_b32_e64 v31, v31, 0, s[24:25]
	v_exp_f32_e32 v52, v52
	v_exp_f32_e32 v21, v21
	v_sub_f32_e32 v20, v20, v176
	v_add_f32_e32 v23, v31, v23
	v_cndmask_b32_e64 v45, v45, 0, s[26:27]
	v_exp_f32_e32 v20, v20
	v_add_f32_e32 v23, v45, v23
	v_cndmask_b32_e64 v46, v46, 0, s[28:29]
	v_add_f32_e32 v23, v46, v23
	v_cndmask_b32_e64 v47, v47, 0, s[30:31]
	v_add_f32_e32 v23, v47, v23
	v_cndmask_b32_e64 v52, v52, 0, s[34:35]
	v_cndmask_b32_e64 v21, 0, v21, s[6:7]
	v_add_f32_e32 v151, v52, v23
	v_add_f32_e32 v22, 0, v21
	v_cndmask_b32_e64 v23, 0, v20, s[8:9]
	v_fmac_f32_e32 v151, v147, v144
	v_cvt_pk_bf16_f32 v81, v30, v31
	v_add_f32_e32 v147, v23, v22
	v_cvt_pk_bf16_f32 v20, v21, 0
	v_cvt_pk_bf16_f32 v22, v23, 0
	v_mov_b32_e32 v21, v153
	v_mov_b32_e32 v23, v153
	v_pk_mul_f32 v[30:31], v[78:79], v[144:145] op_sel_hi:[1,0]
	v_pk_mul_f32 v[28:29], v[76:77], v[144:145] op_sel_hi:[1,0]
	v_pk_mul_f32 v[78:79], v[110:111], v[84:85] op_sel_hi:[1,0]
	v_pk_mul_f32 v[76:77], v[108:109], v[84:85] op_sel_hi:[1,0]
	v_cvt_pk_bf16_f32 v82, v45, v46
	v_cvt_pk_bf16_f32 v83, v47, v52
	s_waitcnt lgkmcnt(8)
	v_mfma_f32_16x16x32_bf16 v[88:91], v[136:139], v[20:23], v[76:79]
	v_mul_f32_e64 v46, v102, v84
	v_mul_f32_e64 v47, v103, v84
	v_pk_mul_f32 v[44:45], v[100:101], v[84:85] op_sel_hi:[1,0]
	v_pk_mul_f32 v[54:55], v[106:107], v[144:145] op_sel_hi:[1,0]
	v_pk_mul_f32 v[78:79], v[114:115], v[144:145] op_sel_hi:[1,0]
	v_pk_mul_f32 v[76:77], v[112:113], v[144:145] op_sel_hi:[1,0]
	v_pk_mul_f32 v[52:53], v[104:105], v[144:145] op_sel_hi:[1,0]
	v_mfma_f32_16x16x32_bf16 v[44:47], v[140:143], v[20:23], v[44:47]
	v_fmac_f32_e32 v147, v146, v84
	s_waitcnt lgkmcnt(6)
	v_mfma_f32_16x16x32_bf16 v[96:99], v[132:135], v[80:83], v[76:79]
	s_nop 2
	v_mul_f32_e64 v78, v118, v84
	v_mul_f32_e64 v79, v119, v84
	v_pk_mul_f32 v[76:77], v[116:117], v[84:85] op_sel_hi:[1,0]
	v_mfma_f32_16x16x32_bf16 v[28:31], v[140:143], v[80:83], v[28:31]
	s_nop 0
	v_mfma_f32_16x16x32_bf16 v[100:103], v[132:135], v[20:23], v[76:79]
	s_nop 2
	v_mul_f32_e64 v78, v122, v144
	v_mul_f32_e64 v79, v123, v144
	v_pk_mul_f32 v[76:77], v[120:121], v[144:145] op_sel_hi:[1,0]
	v_mfma_f32_16x16x32_bf16 v[52:55], v[136:139], v[80:83], v[52:55]
	s_waitcnt lgkmcnt(4)
	v_mfma_f32_16x16x32_bf16 v[104:107], v[128:131], v[80:83], v[76:79]
	s_nop 2
	v_mul_f32_e64 v78, v126, v84
	v_mul_f32_e64 v79, v127, v84
	v_pk_mul_f32 v[76:77], v[124:125], v[84:85] op_sel_hi:[1,0]
	s_nop 1
	v_mfma_f32_16x16x32_bf16 v[108:111], v[128:131], v[20:23], v[76:79]
	v_add_u32_e32 v20, s76, v235
	v_med3_i32 v20, v20, 0, s75
	v_add_u32_e32 v20, s74, v20
	v_ashrrev_i32_e32 v21, 31, v20
	v_lshlrev_b64 v[20:21], 9, v[20:21]
	v_lshl_add_u64 v[20:21], v[164:165], 0, v[20:21]
	global_load_dwordx4 v[112:115], v[20:21], off
	v_add_u32_e32 v20, s76, v236
	v_med3_i32 v20, v20, 0, s75
	v_add_u32_e32 v20, s74, v20
	v_ashrrev_i32_e32 v21, 31, v20
	v_lshlrev_b64 v[20:21], 9, v[20:21]
	v_lshl_add_u64 v[20:21], v[164:165], 0, v[20:21]
	global_load_dwordx4 v[116:119], v[20:21], off
	v_add_u32_e32 v20, s76, v237
	v_med3_i32 v20, v20, 0, s75
	v_add_u32_e32 v20, s74, v20
	v_ashrrev_i32_e32 v21, 31, v20
	v_lshlrev_b64 v[20:21], 9, v[20:21]
	v_lshl_add_u64 v[20:21], v[164:165], 0, v[20:21]
	global_load_dwordx4 v[120:123], v[20:21], off
	v_add_u32_e32 v20, s76, v238
	v_med3_i32 v20, v20, 0, s75
	v_add_u32_e32 v20, s74, v20
	v_ashrrev_i32_e32 v21, 31, v20
	v_lshlrev_b64 v[20:21], 9, v[20:21]
	v_lshl_add_u64 v[20:21], v[164:165], 0, v[20:21]
	global_load_dwordx4 v[124:127], v[20:21], off
	v_add_u32_e32 v20, s76, v239
	v_med3_i32 v20, v20, 0, s75
	v_add_u32_e32 v20, s74, v20
	v_ashrrev_i32_e32 v21, 31, v20
	v_lshlrev_b64 v[20:21], 9, v[20:21]
	v_lshl_add_u64 v[20:21], s[68:69], 0, v[20:21]
	v_lshl_add_u64 v[20:21], v[20:21], 0, v[158:159]
	global_load_dwordx4 v[84:87], v[20:21], off
	global_load_dwordx4 v[80:83], v[20:21], off offset:64
	v_add_u32_e32 v20, s76, v240
	s_addk_i32 s76, 0xfc08
	s_nop 0
	v_med3_i32 v20, v20, 0, s75
	v_add_u32_e32 v20, s74, v20
	v_ashrrev_i32_e32 v21, 31, v20
	v_lshlrev_b64 v[20:21], 9, v[20:21]
	v_lshl_add_u64 v[20:21], s[68:69], 0, v[20:21]
	v_lshl_add_u64 v[20:21], v[20:21], 0, v[158:159]
	global_load_dwordx4 v[76:79], v[20:21], off
	s_nop 0
	global_load_dwordx4 v[20:23], v[20:21], off offset:64
	ds_read_b64_tr_b16 v[142:143], v169 offset:2304
	ds_read_b64_tr_b16 v[140:141], v169
	ds_read_b64_tr_b16 v[136:137], v169 offset:32
	ds_read_b64_tr_b16 v[138:139], v169 offset:2336
	ds_read_b64_tr_b16 v[132:133], v169 offset:64
	ds_read_b64_tr_b16 v[134:135], v169 offset:2368
	ds_read_b64_tr_b16 v[128:129], v169 offset:96
	ds_read_b64_tr_b16 v[130:131], v169 offset:2400
	s_waitcnt vmcnt(13)
	ds_write_b128 v241, v[24:27] offset:4608
	s_waitcnt vmcnt(12)
	ds_write_b128 v242, v[32:35] offset:4608
	ds_write_b128 v243, v[36:39] offset:4608
	ds_write_b128 v244, v[92:95] offset:4608
	v_mfma_f32_16x16x32_bf16 v[36:39], v[48:51], v[12:15], 0
	v_mfma_f32_16x16x32_bf16 v[24:27], v[48:51], v[4:7], 0
	v_mfma_f32_16x16x32_bf16 v[36:39], v[60:63], v[0:3], v[36:39]
	v_mfma_f32_16x16x32_bf16 v[32:35], v[40:43], v[4:7], 0
	v_mfma_f32_16x16x32_bf16 v[38:41], v[40:43], v[12:15], 0
	v_mfma_f32_16x16x32_bf16 v[24:27], v[60:63], v[8:11], v[24:27]
	v_mfma_f32_16x16x32_bf16 v[32:35], v[16:19], v[8:11], v[32:35]
	v_mfma_f32_16x16x32_bf16 v[16:19], v[16:19], v[0:3], v[38:41]
	s_nop 7
	v_sub_u32_e32 v17, v192, v150
	v_add_u32_e32 v19, 1, v17
	v_max_f32_e32 v18, v24, v24
	v_cmp_gt_u32_e64 s[0:1], v19, v149
	v_cmp_gt_u32_e32 vcc, v17, v149
	v_max_f32_e32 v18, 0xf149f2ca, v18
	v_cndmask_b32_e64 v19, v25, v246, s[0:1]
	v_cndmask_b32_e32 v18, v18, v246, vcc
	v_max_f32_e32 v18, v18, v19
	v_add_u32_e32 v19, 2, v17
	v_add_u32_e32 v37, 3, v17
	v_cmp_gt_u32_e64 s[22:23], v19, v149
	v_cmp_gt_u32_e64 s[24:25], v37, v149
	s_nop 0
	v_cndmask_b32_e64 v19, v26, v246, s[22:23]
	v_cndmask_b32_e64 v37, v27, v246, s[24:25]
	v_max3_f32 v18, v18, v19, v37
	v_add_u32_e32 v19, 16, v17
	v_add_u32_e32 v37, 17, v17
	v_cmp_gt_u32_e64 s[26:27], v19, v149
	v_cmp_gt_u32_e64 s[28:29], v37, v149
	s_nop 0
	v_cndmask_b32_e64 v19, v32, v246, s[26:27]
	v_cndmask_b32_e64 v37, v33, v246, s[28:29]
	v_max3_f32 v18, v18, v19, v37
	v_add_u32_e32 v19, 18, v17
	v_add_u32_e32 v17, 19, v17
	v_cmp_gt_u32_e64 s[30:31], v19, v149
	v_cmp_gt_u32_e64 s[34:35], v17, v149
	s_nop 0
	v_cndmask_b32_e64 v19, v34, v246, s[30:31]
	v_cndmask_b32_e64 v17, v35, v246, s[34:35]
	v_max3_f32 v17, v18, v19, v17
	v_max_f32_e32 v18, v36, v36
	v_max_f32_e32 v18, 0xf149f2ca, v18
	v_cndmask_b32_e64 v18, v246, v18, s[10:11]
	v_cndmask_b32_e64 v19, v246, v16, s[12:13]
	v_max3_f32 v18, v18, v19, s73
	v_mov_b32_e32 v19, v17
	v_mov_b32_e32 v37, v17
	s_nop 1
	v_permlane32_swap_b32_e32 v19, v37
	v_max3_f32 v17, v17, v19, v37
	v_mov_b32_e32 v19, v18
	v_mov_b32_e32 v37, v18
	s_nop 1
	v_permlane32_swap_b32_e32 v19, v37
	v_max3_f32 v18, v18, v19, v37
	v_mov_b32_e32 v19, v17
	v_mov_b32_e32 v37, v17
	s_nop 1
	v_permlane16_swap_b32_e32 v19, v37
	v_max_f32_e32 v17, v17, v19
	v_max3_f32 v145, v175, v17, v37
	v_sub_f32_e32 v17, v175, v145
	v_exp_f32_e32 v38, v17
	v_sub_f32_e32 v17, v24, v145
	v_exp_f32_e32 v17, v17
	v_mov_b32_e32 v19, v18
	v_mov_b32_e32 v39, v18
	s_nop 1
	v_permlane16_swap_b32_e32 v19, v39
	v_cndmask_b32_e64 v37, v17, 0, vcc
	v_sub_f32_e32 v17, v25, v145
	v_exp_f32_e32 v17, v17
	v_max_f32_e32 v18, v18, v19
	v_max3_f32 v144, v176, v18, v39
	v_cndmask_b32_e64 v60, v17, 0, s[0:1]
	v_sub_f32_e32 v17, v26, v145
	v_exp_f32_e32 v17, v17
	v_sub_f32_e32 v16, v16, v144
	v_exp_f32_e32 v16, v16
	v_cvt_pk_bf16_f32 v24, v37, v60
	v_cndmask_b32_e64 v61, v17, 0, s[22:23]
	v_sub_f32_e32 v17, v27, v145
	v_exp_f32_e32 v17, v17
	v_cndmask_b32_e64 v39, 0, v16, s[12:13]
	v_pk_mul_f32 v[30:31], v[30:31], v[38:39] op_sel_hi:[1,0]
	v_pk_mul_f32 v[28:29], v[28:29], v[38:39] op_sel_hi:[1,0]
	v_cndmask_b32_e64 v62, v17, 0, s[24:25]
	v_sub_f32_e32 v17, v32, v145
	v_exp_f32_e32 v17, v17
	v_cvt_pk_bf16_f32 v25, v61, v62
	v_cvt_pk_bf16_f32 v18, v39, 0
	v_mov_b32_e32 v19, v153
	v_cndmask_b32_e64 v63, v17, 0, s[26:27]
	v_sub_f32_e32 v17, v33, v145
	v_exp_f32_e32 v17, v17
	s_nop 0
	v_cndmask_b32_e64 v33, v17, 0, s[28:29]
	v_sub_f32_e32 v17, v34, v145
	v_exp_f32_e32 v17, v17
	v_cvt_pk_bf16_f32 v26, v63, v33
	v_cndmask_b32_e64 v34, v17, 0, s[30:31]
	v_sub_f32_e32 v17, v35, v145
	v_exp_f32_e32 v17, v17
	s_nop 0
	v_cndmask_b32_e64 v35, v17, 0, s[34:35]
	v_sub_f32_e32 v17, v176, v144
	v_exp_f32_e32 v32, v17
	v_sub_f32_e32 v17, v36, v144
	v_exp_f32_e32 v17, v17
	v_cvt_pk_bf16_f32 v27, v34, v35
	v_cndmask_b32_e64 v36, 0, v17, s[10:11]
	v_cvt_pk_bf16_f32 v16, v36, 0
	v_mov_b32_e32 v17, v153
	s_waitcnt lgkmcnt(10)
	v_mfma_f32_16x16x32_bf16 v[40:43], v[140:143], v[24:27], v[28:31]
	s_nop 2
	v_mul_f32_e64 v30, v46, v32
	v_mul_f32_e64 v31, v47, v32
	v_pk_mul_f32 v[28:29], v[44:45], v[32:33] op_sel_hi:[1,0]
	s_nop 1
	v_mfma_f32_16x16x32_bf16 v[44:47], v[140:143], v[16:19], v[28:31]
	s_nop 2
	v_mul_f32_e64 v30, v54, v38
	v_mul_f32_e64 v31, v55, v38
	v_pk_mul_f32 v[28:29], v[52:53], v[38:39] op_sel_hi:[1,0]
	s_waitcnt lgkmcnt(8)
	s_nop 0
	v_mfma_f32_16x16x32_bf16 v[48:51], v[136:139], v[24:27], v[28:31]
	s_nop 2
	v_mul_f32_e64 v30, v90, v32
	v_mul_f32_e64 v31, v91, v32
	v_pk_mul_f32 v[28:29], v[88:89], v[32:33] op_sel_hi:[1,0]
	s_nop 1
	v_mfma_f32_16x16x32_bf16 v[52:55], v[136:139], v[16:19], v[28:31]
	s_nop 2
	v_mul_f32_e64 v30, v98, v38
	v_mul_f32_e64 v31, v99, v38
	v_pk_mul_f32 v[28:29], v[96:97], v[38:39] op_sel_hi:[1,0]
	s_waitcnt lgkmcnt(6)
	s_nop 0
	v_mfma_f32_16x16x32_bf16 v[88:91], v[132:135], v[24:27], v[28:31]
	s_nop 2
	v_mul_f32_e64 v30, v102, v32
	v_mul_f32_e64 v31, v103, v32
	v_pk_mul_f32 v[28:29], v[100:101], v[32:33] op_sel_hi:[1,0]
	s_nop 1
	v_mfma_f32_16x16x32_bf16 v[100:103], v[132:135], v[16:19], v[28:31]
	s_nop 2
	v_mul_f32_e64 v30, v106, v38
	v_mul_f32_e64 v31, v107, v38
	v_pk_mul_f32 v[28:29], v[104:105], v[38:39] op_sel_hi:[1,0]
	s_waitcnt lgkmcnt(4)
	s_nop 0
	v_mfma_f32_16x16x32_bf16 v[104:107], v[128:131], v[24:27], v[28:31]
	v_mul_f32_e64 v26, v110, v32
	v_mul_f32_e64 v27, v111, v32
	v_pk_mul_f32 v[24:25], v[108:109], v[32:33] op_sel_hi:[1,0]
	s_nop 1
	v_mfma_f32_16x16x32_bf16 v[108:111], v[128:131], v[16:19], v[24:27]
	v_add_f32_e32 v16, 0, v36
	v_add_f32_e32 v146, v39, v16
	v_add_f32_e32 v16, 0, v37
	v_add_f32_e32 v16, v60, v16
	v_add_f32_e32 v16, v61, v16
	v_add_f32_e32 v16, v62, v16
	v_add_f32_e32 v16, v63, v16
	v_add_f32_e32 v16, v33, v16
	v_add_f32_e32 v16, v34, v16
	v_fmac_f32_e32 v146, v147, v32
	v_add_f32_e32 v147, v35, v16
	v_add_u32_e32 v16, s40, v214
	v_add_u32_e32 v24, s40, v216
	v_med3_i32 v16, v16, 0, s75
	v_add_u32_e32 v16, s74, v16
	v_ashrrev_i32_e32 v17, 31, v16
	v_med3_i32 v24, v24, 0, s75
	v_add_u32_e32 v24, s74, v24
	v_ashrrev_i32_e32 v25, 31, v24
	v_lshlrev_b64 v[16:17], 9, v[16:17]
	v_lshlrev_b64 v[24:25], 9, v[24:25]
	v_lshl_add_u64 v[16:17], v[164:165], 0, v[16:17]
	v_lshl_add_u64 v[24:25], v[164:165], 0, v[24:25]
	global_load_dwordx4 v[16:19], v[16:17], off
	v_or_b32_e32 v32, 0xfffffd00, v167
	global_load_dwordx4 v[60:63], v[24:25], off
	v_add_u32_e32 v24, s40, v218
	v_add_u32_e32 v32, s40, v32
	v_med3_i32 v24, v24, 0, s75
	v_add_u32_e32 v24, s74, v24
	v_ashrrev_i32_e32 v25, 31, v24
	v_lshlrev_b64 v[24:25], 9, v[24:25]
	v_lshl_add_u64 v[24:25], v[164:165], 0, v[24:25]
	global_load_dwordx4 v[92:95], v[24:25], off
	v_add_u32_e32 v24, s40, v220
	v_fmac_f32_e32 v147, v151, v38
	s_nop 0
	v_med3_i32 v24, v24, 0, s75
	v_add_u32_e32 v24, s74, v24
	v_ashrrev_i32_e32 v25, 31, v24
	v_lshlrev_b64 v[24:25], 9, v[24:25]
	v_lshl_add_u64 v[24:25], v[164:165], 0, v[24:25]
	global_load_dwordx4 v[96:99], v[24:25], off
	v_add_u32_e32 v24, s40, v221
	v_med3_i32 v24, v24, 0, s75
	v_add_u32_e32 v24, s74, v24
	v_ashrrev_i32_e32 v25, 31, v24
	v_med3_i32 v32, v32, 0, s75
	v_add_u32_e32 v32, s74, v32
	v_ashrrev_i32_e32 v33, 31, v32
	v_lshlrev_b64 v[24:25], 9, v[24:25]
	v_lshlrev_b64 v[32:33], 9, v[32:33]
	v_lshl_add_u64 v[24:25], s[68:69], 0, v[24:25]
	v_lshl_add_u64 v[32:33], s[68:69], 0, v[32:33]
	v_lshl_add_u64 v[28:29], v[24:25], 0, v[158:159]
	v_lshl_add_u64 v[36:37], v[32:33], 0, v[158:159]
	global_load_dwordx4 v[24:27], v[28:29], off
	s_nop 0
	global_load_dwordx4 v[28:31], v[28:29], off offset:64
	s_nop 0
	global_load_dwordx4 v[32:35], v[36:37], off
	s_nop 0
	global_load_dwordx4 v[36:39], v[36:37], off offset:64
	ds_read_b64_tr_b16 v[142:143], v169 offset:6912
	ds_read_b64_tr_b16 v[140:141], v169 offset:4608
	ds_read_b64_tr_b16 v[132:133], v169 offset:4640
	ds_read_b64_tr_b16 v[134:135], v169 offset:6944
	ds_read_b64_tr_b16 v[128:129], v169 offset:4672
	ds_read_b64_tr_b16 v[130:131], v169 offset:6976
	ds_read_b64_tr_b16 v[136:137], v169 offset:4704
	ds_read_b64_tr_b16 v[138:139], v169 offset:7008
	s_waitcnt vmcnt(15)
	ds_write_b128 v241, v[112:115]
	s_waitcnt vmcnt(14)
	ds_write_b128 v242, v[116:119]
	s_waitcnt vmcnt(13)
	ds_write_b128 v243, v[120:123]
	s_waitcnt vmcnt(12)
	ds_write_b128 v244, v[124:127]
	v_mfma_f32_16x16x32_bf16 v[112:115], v[72:75], v[4:7], 0
	v_mfma_f32_16x16x32_bf16 v[116:119], v[64:67], v[4:7], 0
	v_mfma_f32_16x16x32_bf16 v[64:67], v[64:67], v[12:15], 0
	v_mfma_f32_16x16x32_bf16 v[112:115], v[68:71], v[8:11], v[112:115]
	v_mfma_f32_16x16x32_bf16 v[116:119], v[56:59], v[8:11], v[116:119]
	v_mfma_f32_16x16x32_bf16 v[56:59], v[56:59], v[0:3], v[64:67]
	v_mfma_f32_16x16x32_bf16 v[72:75], v[72:75], v[12:15], 0
	v_mfma_f32_16x16x32_bf16 v[68:71], v[68:71], v[0:3], v[72:75]
	s_nop 5
	v_sub_u32_e32 v57, v197, v150
	v_add_u32_e32 v59, 1, v57
	v_max_f32_e32 v58, v112, v112
	v_cmp_gt_u32_e64 s[0:1], v59, v149
	v_cmp_gt_u32_e32 vcc, v57, v149
	v_max_f32_e32 v58, 0xf149f2ca, v58
	v_cndmask_b32_e64 v59, v113, v246, s[0:1]
	v_cndmask_b32_e32 v58, v58, v246, vcc
	v_max_f32_e32 v58, v58, v59
	v_add_u32_e32 v59, 2, v57
	v_add_u32_e32 v64, 3, v57
	v_cmp_gt_u32_e64 s[22:23], v59, v149
	v_cmp_gt_u32_e64 s[24:25], v64, v149
	s_nop 0
	v_cndmask_b32_e64 v59, v114, v246, s[22:23]
	v_cndmask_b32_e64 v64, v115, v246, s[24:25]
	v_max3_f32 v58, v58, v59, v64
	v_add_u32_e32 v59, 16, v57
	v_add_u32_e32 v64, 17, v57
	v_cmp_gt_u32_e64 s[26:27], v59, v149
	v_cmp_gt_u32_e64 s[28:29], v64, v149
	s_nop 0
	v_cndmask_b32_e64 v59, v116, v246, s[26:27]
	v_cndmask_b32_e64 v64, v117, v246, s[28:29]
	v_max3_f32 v58, v58, v59, v64
	v_add_u32_e32 v59, 18, v57
	v_add_u32_e32 v57, 19, v57
	v_cmp_gt_u32_e64 s[30:31], v59, v149
	v_cmp_gt_u32_e64 s[34:35], v57, v149
	s_nop 0
	v_cndmask_b32_e64 v59, v118, v246, s[30:31]
	v_cndmask_b32_e64 v57, v119, v246, s[34:35]
	v_max3_f32 v57, v58, v59, v57
	v_max_f32_e32 v58, v68, v68
	v_max_f32_e32 v58, 0xf149f2ca, v58
	v_cndmask_b32_e64 v58, v246, v58, s[14:15]
	v_cndmask_b32_e64 v59, v246, v56, s[16:17]
	v_max3_f32 v58, v58, v59, s73
	v_mov_b32_e32 v59, v57
	v_mov_b32_e32 v64, v57
	s_nop 1
	v_permlane32_swap_b32_e32 v59, v64
	v_max3_f32 v57, v57, v59, v64
	v_mov_b32_e32 v59, v58
	v_mov_b32_e32 v64, v58
	s_nop 1
	v_permlane32_swap_b32_e32 v59, v64
	v_max3_f32 v58, v58, v59, v64
	v_mov_b32_e32 v59, v57
	v_mov_b32_e32 v64, v57
	s_nop 1
	v_permlane16_swap_b32_e32 v59, v64
	v_max_f32_e32 v57, v57, v59
	v_max3_f32 v175, v145, v57, v64
	v_sub_f32_e32 v57, v145, v175
	v_exp_f32_e32 v72, v57
	v_sub_f32_e32 v57, v112, v175
	v_exp_f32_e32 v57, v57
	v_sub_f32_e32 v64, v113, v175
	v_mov_b32_e32 v59, v58
	v_mov_b32_e32 v69, v58
	v_exp_f32_e32 v64, v64
	s_nop 0
	v_permlane16_swap_b32_e32 v59, v69
	v_sub_f32_e32 v65, v114, v175
	v_max_f32_e32 v58, v58, v59
	v_cndmask_b32_e64 v57, v57, 0, vcc
	v_exp_f32_e32 v65, v65
	v_sub_f32_e32 v66, v115, v175
	v_add_f32_e32 v59, 0, v57
	v_cndmask_b32_e64 v64, v64, 0, s[0:1]
	v_exp_f32_e32 v66, v66
	v_sub_f32_e32 v67, v116, v175
	v_max3_f32 v177, v144, v58, v69
	v_add_f32_e32 v59, v64, v59
	v_exp_f32_e32 v67, v67
	v_sub_f32_e32 v70, v117, v175
	v_cvt_pk_bf16_f32 v64, v57, v64
	v_sub_f32_e32 v57, v144, v177
	v_exp_f32_e32 v70, v70
	v_sub_f32_e32 v71, v118, v175
	v_sub_f32_e32 v73, v119, v175
	v_exp_f32_e32 v74, v57
	v_sub_f32_e32 v57, v68, v177
	v_cndmask_b32_e64 v65, v65, 0, s[22:23]
	v_exp_f32_e32 v71, v71
	v_exp_f32_e32 v73, v73
	v_exp_f32_e32 v57, v57
	v_sub_f32_e32 v56, v56, v177
	v_add_f32_e32 v59, v65, v59
	v_cndmask_b32_e64 v66, v66, 0, s[24:25]
	v_exp_f32_e32 v56, v56
	v_add_f32_e32 v59, v66, v59
	v_cndmask_b32_e64 v67, v67, 0, s[26:27]
	v_add_f32_e32 v59, v67, v59
	v_cndmask_b32_e64 v70, v70, 0, s[28:29]
	v_add_f32_e32 v59, v70, v59
	v_cndmask_b32_e64 v71, v71, 0, s[30:31]
	v_cndmask_b32_e64 v73, v73, 0, s[34:35]
	v_cndmask_b32_e64 v57, 0, v57, s[14:15]
	v_add_f32_e32 v59, v71, v59
	v_cvt_pk_bf16_f32 v65, v65, v66
	v_cvt_pk_bf16_f32 v66, v67, v70
	v_cvt_pk_bf16_f32 v67, v71, v73
	v_add_f32_e32 v58, 0, v57
	v_cndmask_b32_e64 v56, 0, v56, s[16:17]
	v_pk_mul_f32 v[42:43], v[42:43], v[72:73] op_sel_hi:[1,0]
	v_pk_mul_f32 v[40:41], v[40:41], v[72:73] op_sel_hi:[1,0]
	v_add_f32_e32 v176, v73, v59
	v_add_f32_e32 v178, v56, v58
	v_cvt_pk_bf16_f32 v68, v57, 0
	v_cvt_pk_bf16_f32 v70, v56, 0
	v_mov_b32_e32 v69, v153
	v_mov_b32_e32 v71, v153
	s_waitcnt lgkmcnt(10)
	v_mfma_f32_16x16x32_bf16 v[56:59], v[140:143], v[64:67], v[40:43]
	v_fmac_f32_e32 v176, v147, v72
	v_fmac_f32_e32 v178, v146, v74
	s_nop 0
	v_pk_mul_f32 v[42:43], v[46:47], v[74:75] op_sel_hi:[1,0]
	v_pk_mul_f32 v[40:41], v[44:45], v[74:75] op_sel_hi:[1,0]
	s_nop 1
	v_mfma_f32_16x16x32_bf16 v[112:115], v[140:143], v[68:71], v[40:43]
	s_nop 2
	v_mul_f32_e64 v42, v50, v72
	v_mul_f32_e64 v43, v51, v72
	v_pk_mul_f32 v[40:41], v[48:49], v[72:73] op_sel_hi:[1,0]
	v_add_u32_e32 v48, s40, v227
	v_min_i32_e32 v49, s75, v48
	s_waitcnt lgkmcnt(8)
	v_mfma_f32_16x16x32_bf16 v[116:119], v[132:135], v[64:67], v[40:43]
	s_nop 2
	v_mul_f32_e64 v42, v54, v74
	v_mul_f32_e64 v43, v55, v74
	v_pk_mul_f32 v[40:41], v[52:53], v[74:75] op_sel_hi:[1,0]
	s_nop 1
	v_mfma_f32_16x16x32_bf16 v[120:123], v[132:135], v[68:71], v[40:43]
	s_nop 2
	v_mul_f32_e64 v42, v90, v72
	v_mul_f32_e64 v43, v91, v72
	v_pk_mul_f32 v[40:41], v[88:89], v[72:73] op_sel_hi:[1,0]
	s_waitcnt lgkmcnt(6)
	s_nop 0
	v_mfma_f32_16x16x32_bf16 v[124:127], v[128:131], v[64:67], v[40:43]
	s_nop 2
	v_mul_f32_e64 v42, v102, v74
	v_mul_f32_e64 v43, v103, v74
	v_pk_mul_f32 v[40:41], v[100:101], v[74:75] op_sel_hi:[1,0]
	s_nop 1
	v_mfma_f32_16x16x32_bf16 v[128:131], v[128:131], v[68:71], v[40:43]
	s_nop 2
	v_mul_f32_e64 v42, v106, v72
	v_mul_f32_e64 v43, v107, v72
	v_pk_mul_f32 v[40:41], v[104:105], v[72:73] op_sel_hi:[1,0]
	s_waitcnt lgkmcnt(4)
	s_nop 0
	v_mfma_f32_16x16x32_bf16 v[132:135], v[136:139], v[64:67], v[40:43]
	s_nop 2
	v_mul_f32_e64 v42, v110, v74
	v_mul_f32_e64 v43, v111, v74
	v_pk_mul_f32 v[40:41], v[108:109], v[74:75] op_sel_hi:[1,0]
	s_nop 1
	v_mfma_f32_16x16x32_bf16 v[136:139], v[136:139], v[68:71], v[40:43]
	s_nop 2
	v_add_u32_e32 v40, s40, v222
	v_med3_i32 v40, v40, 0, s75
	v_add_u32_e32 v40, s74, v40
	v_ashrrev_i32_e32 v41, 31, v40
	v_lshlrev_b64 v[40:41], 9, v[40:41]
	v_lshl_add_u64 v[40:41], v[164:165], 0, v[40:41]
	global_load_dwordx4 v[64:67], v[40:41], off
	v_add_u32_e32 v40, s40, v223
	v_med3_i32 v40, v40, 0, s75
	v_add_u32_e32 v40, s74, v40
	v_ashrrev_i32_e32 v41, 31, v40
	v_lshlrev_b64 v[40:41], 9, v[40:41]
	v_lshl_add_u64 v[40:41], v[164:165], 0, v[40:41]
	global_load_dwordx4 v[68:71], v[40:41], off
	v_add_u32_e32 v40, s40, v224
	v_med3_i32 v40, v40, 0, s75
	v_add_u32_e32 v40, s74, v40
	v_ashrrev_i32_e32 v41, 31, v40
	v_lshlrev_b64 v[40:41], 9, v[40:41]
	v_lshl_add_u64 v[40:41], v[164:165], 0, v[40:41]
	global_load_dwordx4 v[72:75], v[40:41], off
	v_add_u32_e32 v40, s40, v225
	v_med3_i32 v40, v40, 0, s75
	v_add_u32_e32 v40, s74, v40
	v_ashrrev_i32_e32 v41, 31, v40
	v_lshlrev_b64 v[40:41], 9, v[40:41]
	v_lshl_add_u64 v[40:41], v[164:165], 0, v[40:41]
	global_load_dwordx4 v[88:91], v[40:41], off
	v_add_u32_e32 v40, s40, v226
	v_med3_i32 v40, v40, 0, s75
	v_cmp_lt_i32_e32 vcc, -1, v48
	v_add_u32_e32 v40, s74, v40
	v_ashrrev_i32_e32 v41, 31, v40
	v_cndmask_b32_e32 v48, 0, v49, vcc
	v_add_u32_e32 v48, s74, v48
	v_ashrrev_i32_e32 v49, 31, v48
	v_lshlrev_b64 v[40:41], 9, v[40:41]
	v_lshlrev_b64 v[48:49], 9, v[48:49]
	v_lshl_add_u64 v[40:41], s[68:69], 0, v[40:41]
	v_lshl_add_u64 v[48:49], s[68:69], 0, v[48:49]
	v_lshl_add_u64 v[44:45], v[40:41], 0, v[158:159]
	v_lshl_add_u64 v[52:53], v[48:49], 0, v[158:159]
	global_load_dwordx4 v[40:43], v[44:45], off
	s_nop 0
	global_load_dwordx4 v[44:47], v[44:45], off offset:64
	s_nop 0
	global_load_dwordx4 v[48:51], v[52:53], off
	s_nop 0
	global_load_dwordx4 v[52:55], v[52:53], off offset:64
	ds_read_b64_tr_b16 v[102:103], v169 offset:2304
	ds_read_b64_tr_b16 v[100:101], v169
	ds_read_b64_tr_b16 v[108:109], v169 offset:32
	ds_read_b64_tr_b16 v[110:111], v169 offset:2336
	ds_read_b64_tr_b16 v[144:145], v169 offset:64
	ds_read_b64_tr_b16 v[146:147], v169 offset:2368
	ds_read_b64_tr_b16 v[140:141], v169 offset:96
	ds_read_b64_tr_b16 v[142:143], v169 offset:2400
	s_waitcnt vmcnt(15)
	ds_write_b128 v241, v[16:19] offset:4608
	s_waitcnt vmcnt(14)
	ds_write_b128 v242, v[60:63] offset:4608
	s_waitcnt vmcnt(13)
	ds_write_b128 v243, v[92:95] offset:4608
	s_waitcnt vmcnt(12)
	ds_write_b128 v244, v[96:99] offset:4608
	v_mfma_f32_16x16x32_bf16 v[16:19], v[84:87], v[4:7], 0
	v_mfma_f32_16x16x32_bf16 v[60:63], v[76:79], v[4:7], 0
	v_mfma_f32_16x16x32_bf16 v[76:79], v[76:79], v[12:15], 0
	v_mfma_f32_16x16x32_bf16 v[16:19], v[80:83], v[8:11], v[16:19]
	v_mfma_f32_16x16x32_bf16 v[60:63], v[20:23], v[8:11], v[60:63]
	v_mfma_f32_16x16x32_bf16 v[20:23], v[20:23], v[0:3], v[76:79]
	v_mfma_f32_16x16x32_bf16 v[84:87], v[84:87], v[12:15], 0
	v_mfma_f32_16x16x32_bf16 v[80:83], v[80:83], v[0:3], v[84:87]
	s_nop 5
	v_sub_u32_e32 v21, v198, v150
	v_add_u32_e32 v23, 1, v21
	v_max_f32_e32 v22, v16, v16
	v_cmp_gt_u32_e64 s[0:1], v23, v149
	v_cmp_gt_u32_e32 vcc, v21, v149
	v_max_f32_e32 v22, 0xf149f2ca, v22
	v_cndmask_b32_e64 v23, v17, v246, s[0:1]
	v_cndmask_b32_e32 v22, v22, v246, vcc
	v_max_f32_e32 v22, v22, v23
	v_add_u32_e32 v23, 2, v21
	v_add_u32_e32 v76, 3, v21
	v_cmp_gt_u32_e64 s[22:23], v23, v149
	v_cmp_gt_u32_e64 s[24:25], v76, v149
	s_nop 0
	v_cndmask_b32_e64 v23, v18, v246, s[22:23]
	v_cndmask_b32_e64 v76, v19, v246, s[24:25]
	v_max3_f32 v22, v22, v23, v76
	v_add_u32_e32 v23, 16, v21
	v_add_u32_e32 v76, 17, v21
	v_cmp_gt_u32_e64 s[26:27], v23, v149
	v_cmp_gt_u32_e64 s[28:29], v76, v149
	s_nop 0
	v_cndmask_b32_e64 v23, v60, v246, s[26:27]
	v_cndmask_b32_e64 v76, v61, v246, s[28:29]
	v_max3_f32 v22, v22, v23, v76
	v_add_u32_e32 v23, 18, v21
	v_add_u32_e32 v21, 19, v21
	v_cmp_gt_u32_e64 s[30:31], v23, v149
	v_cmp_gt_u32_e64 s[34:35], v21, v149
	s_nop 0
	v_cndmask_b32_e64 v23, v62, v246, s[30:31]
	v_cndmask_b32_e64 v21, v63, v246, s[34:35]
	v_max3_f32 v21, v22, v23, v21
	v_max_f32_e32 v22, v80, v80
	v_max_f32_e32 v22, 0xf149f2ca, v22
	v_cndmask_b32_e64 v22, v246, v22, s[18:19]
	v_cndmask_b32_e64 v23, v246, v20, s[20:21]
	v_max3_f32 v22, v22, v23, s73
	v_mov_b32_e32 v23, v21
	v_mov_b32_e32 v76, v21
	s_nop 1
	v_permlane32_swap_b32_e32 v23, v76
	v_max3_f32 v21, v21, v23, v76
	v_mov_b32_e32 v23, v22
	v_mov_b32_e32 v76, v22
	s_nop 1
	v_permlane32_swap_b32_e32 v23, v76
	v_max3_f32 v22, v22, v23, v76
	v_mov_b32_e32 v23, v21
	v_mov_b32_e32 v76, v21
	s_nop 1
	v_permlane16_swap_b32_e32 v23, v76
	v_max_f32_e32 v21, v21, v23
	v_max3_f32 v151, v175, v21, v76
	v_sub_f32_e32 v16, v16, v151
	v_mov_b32_e32 v23, v22
	v_mov_b32_e32 v77, v22
	v_exp_f32_e32 v16, v16
	v_sub_f32_e32 v17, v17, v151
	v_permlane16_swap_b32_e32 v23, v77
	v_exp_f32_e32 v17, v17
	v_sub_f32_e32 v18, v18, v151
	v_exp_f32_e32 v18, v18
	v_sub_f32_e32 v19, v19, v151
	v_max_f32_e32 v22, v22, v23
	v_exp_f32_e32 v19, v19
	v_sub_f32_e32 v23, v60, v151
	v_sub_f32_e32 v21, v175, v151
	v_cndmask_b32_e64 v16, v16, 0, vcc
	v_exp_f32_e32 v23, v23
	v_sub_f32_e32 v60, v61, v151
	v_exp_f32_e32 v76, v21
	v_add_f32_e32 v21, 0, v16
	v_cndmask_b32_e64 v17, v17, 0, s[0:1]
	v_exp_f32_e32 v60, v60
	v_sub_f32_e32 v61, v62, v151
	v_add_f32_e32 v21, v17, v21
	v_cndmask_b32_e64 v18, v18, 0, s[22:23]
	v_exp_f32_e32 v61, v61
	v_sub_f32_e32 v62, v63, v151
	v_add_f32_e32 v21, v18, v21
	v_cndmask_b32_e64 v19, v19, 0, s[24:25]
	v_exp_f32_e32 v62, v62
	v_add_f32_e32 v21, v19, v21
	v_cndmask_b32_e64 v23, v23, 0, s[26:27]
	v_add_f32_e32 v21, v23, v21
	v_cndmask_b32_e64 v60, v60, 0, s[28:29]
	v_add_f32_e32 v21, v60, v21
	v_cndmask_b32_e64 v61, v61, 0, s[30:31]
	v_add_f32_e32 v21, v61, v21
	v_cndmask_b32_e64 v62, v62, 0, s[34:35]
	v_max3_f32 v175, v177, v22, v77
	v_add_f32_e32 v149, v62, v21
	v_sub_f32_e32 v21, v177, v175
	v_cvt_pk_bf16_f32 v16, v16, v17
	v_cvt_pk_bf16_f32 v17, v18, v19
	v_cvt_pk_bf16_f32 v18, v23, v60
	v_exp_f32_e32 v60, v21
	v_sub_f32_e32 v21, v80, v175
	v_exp_f32_e32 v21, v21
	v_sub_f32_e32 v20, v20, v175
	v_exp_f32_e32 v20, v20
	v_cvt_pk_bf16_f32 v19, v61, v62
	v_cndmask_b32_e64 v21, 0, v21, s[18:19]
	v_add_f32_e32 v22, 0, v21
	v_cndmask_b32_e64 v23, 0, v20, s[20:21]
	v_pk_mul_f32 v[58:59], v[58:59], v[76:77] op_sel_hi:[1,0]
	v_pk_mul_f32 v[56:57], v[56:57], v[76:77] op_sel_hi:[1,0]
	v_add_f32_e32 v150, v23, v22
	v_cvt_pk_bf16_f32 v20, v21, 0
	v_cvt_pk_bf16_f32 v22, v23, 0
	v_mov_b32_e32 v21, v153
	v_mov_b32_e32 v23, v153
	s_waitcnt lgkmcnt(10)
	v_mfma_f32_16x16x32_bf16 v[96:99], v[100:103], v[16:19], v[56:59]
	v_fmac_f32_e32 v149, v176, v76
	v_fmac_f32_e32 v150, v178, v60
	s_min_i32 s0, s76, 0
	v_pk_mul_f32 v[58:59], v[114:115], v[60:61] op_sel_hi:[1,0]
	v_pk_mul_f32 v[56:57], v[112:113], v[60:61] op_sel_hi:[1,0]
	s_sub_i32 s0, 15, s0
	s_sub_i32 s1, s75, s76
	v_mfma_f32_16x16x32_bf16 v[100:103], v[100:103], v[20:23], v[56:59]
	s_ashr_i32 s0, s0, 4
	s_ashr_i32 s1, s1, 4
	s_cmpk_lt_i32 s71, 0x3000
	v_pk_mul_f32 v[58:59], v[118:119], v[76:77] op_sel_hi:[1,0]
	v_pk_mul_f32 v[56:57], v[116:117], v[76:77] op_sel_hi:[1,0]
	s_waitcnt lgkmcnt(8)
	s_nop 0
	v_mfma_f32_16x16x32_bf16 v[104:107], v[108:111], v[16:19], v[56:59]
	s_nop 2
	v_mul_f32_e64 v58, v122, v60
	v_mul_f32_e64 v59, v123, v60
	v_pk_mul_f32 v[56:57], v[120:121], v[60:61] op_sel_hi:[1,0]
	s_nop 1
	v_mfma_f32_16x16x32_bf16 v[108:111], v[108:111], v[20:23], v[56:59]
	s_nop 2
	v_mul_f32_e64 v58, v126, v76
	v_mul_f32_e64 v59, v127, v76
	v_pk_mul_f32 v[56:57], v[124:125], v[76:77] op_sel_hi:[1,0]
	s_waitcnt lgkmcnt(6)
	s_nop 0
	v_mfma_f32_16x16x32_bf16 v[112:115], v[144:147], v[16:19], v[56:59]
	s_nop 2
	v_mul_f32_e64 v58, v130, v60
	v_mul_f32_e64 v59, v131, v60
	v_pk_mul_f32 v[56:57], v[128:129], v[60:61] op_sel_hi:[1,0]
	s_nop 1
	v_mfma_f32_16x16x32_bf16 v[116:119], v[144:147], v[20:23], v[56:59]
	v_max_i32_e32 v145, s0, v148
	s_nop 1
	v_pk_mul_f32 v[58:59], v[134:135], v[76:77] op_sel_hi:[1,0]
	v_pk_mul_f32 v[56:57], v[132:133], v[76:77] op_sel_hi:[1,0]
	s_waitcnt lgkmcnt(4)
	s_nop 0
	v_mfma_f32_16x16x32_bf16 v[120:123], v[140:143], v[16:19], v[56:59]
	v_mul_f32_e64 v18, v138, v60
	v_mul_f32_e64 v19, v139, v60
	v_pk_mul_f32 v[16:17], v[136:137], v[60:61] op_sel_hi:[1,0]
	v_add_u32_e32 v56, s40, v228
	s_nop 0
	v_mfma_f32_16x16x32_bf16 v[124:127], v[140:143], v[20:23], v[16:19]
	s_nop 1
	s_nop 0
	v_add_u32_e32 v16, s40, v213
	v_med3_i32 v16, v16, 0, s75
	v_add_u32_e32 v16, s74, v16
	v_ashrrev_i32_e32 v17, 31, v16
	v_lshlrev_b64 v[16:17], 9, v[16:17]
	v_lshl_add_u64 v[16:17], v[164:165], 0, v[16:17]
	global_load_dwordx4 v[76:79], v[16:17], off
	v_add_u32_e32 v16, s40, v215
	v_med3_i32 v16, v16, 0, s75
	v_add_u32_e32 v16, s74, v16
	v_ashrrev_i32_e32 v17, 31, v16
	v_lshlrev_b64 v[16:17], 9, v[16:17]
	v_lshl_add_u64 v[16:17], v[164:165], 0, v[16:17]
	global_load_dwordx4 v[80:83], v[16:17], off
	v_add_u32_e32 v16, s40, v217
	v_med3_i32 v16, v16, 0, s75
	v_add_u32_e32 v16, s74, v16
	v_ashrrev_i32_e32 v17, 31, v16
	v_lshlrev_b64 v[16:17], 9, v[16:17]
	v_lshl_add_u64 v[16:17], v[164:165], 0, v[16:17]
	global_load_dwordx4 v[84:87], v[16:17], off
	v_add_u32_e32 v16, s40, v219
	v_med3_i32 v16, v16, 0, s75
	v_add_u32_e32 v16, s74, v16
	v_ashrrev_i32_e32 v17, 31, v16
	v_lshlrev_b64 v[16:17], 9, v[16:17]
	v_lshl_add_u64 v[16:17], v[164:165], 0, v[16:17]
	global_load_dwordx4 v[92:95], v[16:17], off
	v_or_b32_e32 v16, s40, v167
	v_min_i32_e32 v16, s75, v16
	v_cndmask_b32_e64 v16, v16, 0, s[38:39]
	v_add_u32_e32 v16, s74, v16
	v_med3_i32 v56, v56, 0, s75
	v_add_u32_e32 v56, s74, v56
	v_ashrrev_i32_e32 v17, 31, v16
	v_ashrrev_i32_e32 v57, 31, v56
	v_lshlrev_b64 v[16:17], 9, v[16:17]
	v_lshlrev_b64 v[56:57], 9, v[56:57]
	v_lshl_add_u64 v[16:17], s[68:69], 0, v[16:17]
	v_lshl_add_u64 v[56:57], s[68:69], 0, v[56:57]
	v_lshl_add_u64 v[20:21], v[16:17], 0, v[158:159]
	v_lshl_add_u64 v[60:61], v[56:57], 0, v[158:159]
	global_load_dwordx4 v[16:19], v[20:21], off
	s_nop 0
	global_load_dwordx4 v[20:23], v[20:21], off offset:64
	s_nop 0
	global_load_dwordx4 v[56:59], v[60:61], off
	s_nop 0
	global_load_dwordx4 v[60:63], v[60:61], off offset:64
	ds_read_b64_tr_b16 v[132:133], v169 offset:6912
	ds_read_b64_tr_b16 v[130:131], v169 offset:4608
	ds_read_b64_tr_b16 v[134:135], v169 offset:4640
	ds_read_b64_tr_b16 v[136:137], v169 offset:6944
	ds_read_b64_tr_b16 v[138:139], v169 offset:4672
	ds_read_b64_tr_b16 v[140:141], v169 offset:6976
	ds_read_b64_tr_b16 v[176:177], v169 offset:4704
	ds_read_b64_tr_b16 v[178:179], v169 offset:7008
	s_waitcnt vmcnt(15)
	ds_write_b128 v241, v[64:67]
	s_waitcnt vmcnt(14)
	ds_write_b128 v242, v[68:71]
	s_waitcnt vmcnt(13)
	ds_write_b128 v243, v[72:75]
	s_waitcnt vmcnt(12)
	ds_write_b128 v244, v[88:91]
	v_mfma_f32_16x16x32_bf16 v[64:67], v[24:27], v[4:7], 0
	v_mfma_f32_16x16x32_bf16 v[64:67], v[28:31], v[8:11], v[64:67]
	v_mfma_f32_16x16x32_bf16 v[24:27], v[24:27], v[12:15], 0
	v_mfma_f32_16x16x32_bf16 v[66:69], v[32:35], v[4:7], 0
	v_mfma_f32_16x16x32_bf16 v[24:27], v[28:31], v[0:3], v[24:27]
	v_mfma_f32_16x16x32_bf16 v[28:31], v[32:35], v[12:15], 0
	v_add_u32_e32 v32, 0x7f8, v249
	v_ashrrev_i32_e32 v32, 4, v32
	v_min3_i32 v32, v32, s1, v248
	v_mfma_f32_16x16x32_bf16 v[66:69], v[36:39], v[8:11], v[66:69]
	v_sub_u32_e32 v144, v32, v145
	v_max_f32_e32 v32, v64, v64
	v_sub_u32_e32 v33, v154, v145
	v_max_f32_e32 v32, 0xf149f2ca, v32
	v_cndmask_b32_e64 v32, v246, v32, s[36:37]
	s_nop 2
	v_cndmask_b32_e64 v34, v246, v66, s[4:5]
	v_add_u32_e32 v35, 1, v33
	v_max3_f32 v32, v32, v34, s73
	v_max_f32_e32 v34, v24, v24
	v_cmp_gt_u32_e64 s[0:1], v35, v144
	v_cmp_gt_u32_e32 vcc, v33, v144
	v_max_f32_e32 v34, 0xf149f2ca, v34
	v_cndmask_b32_e64 v35, v25, v246, s[0:1]
	v_cndmask_b32_e32 v34, v34, v246, vcc
	v_mfma_f32_16x16x32_bf16 v[28:31], v[36:39], v[0:3], v[28:31]
	v_max_f32_e32 v34, v34, v35
	v_add_u32_e32 v35, 2, v33
	v_add_u32_e32 v36, 3, v33
	v_cmp_gt_u32_e64 s[22:23], v35, v144
	v_cmp_gt_u32_e64 s[24:25], v36, v144
	s_nop 0
	v_cndmask_b32_e64 v35, v26, v246, s[22:23]
	v_cndmask_b32_e64 v36, v27, v246, s[24:25]
	v_max3_f32 v34, v34, v35, v36
	v_add_u32_e32 v35, 16, v33
	v_add_u32_e32 v36, 17, v33
	v_cmp_gt_u32_e64 s[26:27], v35, v144
	v_cmp_gt_u32_e64 s[28:29], v36, v144
	s_nop 0
	v_cndmask_b32_e64 v35, v28, v246, s[26:27]
	v_cndmask_b32_e64 v36, v29, v246, s[28:29]
	v_max3_f32 v34, v34, v35, v36
	v_add_u32_e32 v35, 18, v33
	v_add_u32_e32 v33, 19, v33
	v_cmp_gt_u32_e64 s[30:31], v35, v144
	v_cmp_gt_u32_e64 s[34:35], v33, v144
	s_nop 0
	v_cndmask_b32_e64 v35, v30, v246, s[30:31]
	v_cndmask_b32_e64 v33, v31, v246, s[34:35]
	v_max3_f32 v33, v34, v35, v33
	v_mov_b32_e32 v34, v32
	v_mov_b32_e32 v35, v32
	s_nop 1
	v_permlane32_swap_b32_e32 v34, v35
	v_max3_f32 v32, v32, v34, v35
	v_mov_b32_e32 v34, v33
	v_mov_b32_e32 v35, v33
	s_nop 1
	v_permlane32_swap_b32_e32 v34, v35
	v_max3_f32 v33, v33, v34, v35
	v_mov_b32_e32 v34, v32
	v_mov_b32_e32 v35, v32
	s_nop 1
	v_permlane16_swap_b32_e32 v34, v35
	v_max_f32_e32 v32, v32, v34
	v_mov_b32_e32 v34, v33
	v_mov_b32_e32 v37, v33
	s_nop 1
	v_permlane16_swap_b32_e32 v34, v37
	v_max_f32_e32 v38, v33, v34
	v_max3_f32 v128, v175, v38, v37
	v_sub_f32_e32 v24, v24, v128
	v_exp_f32_e32 v24, v24
	v_sub_f32_e32 v37, v175, v128
	v_exp_f32_e32 v38, v37
	v_max3_f32 v129, v151, v32, v35
	v_cndmask_b32_e64 v37, v24, 0, vcc
	v_sub_f32_e32 v24, v25, v128
	v_exp_f32_e32 v24, v24
	v_sub_f32_e32 v32, v151, v129
	v_exp_f32_e32 v36, v32
	v_sub_f32_e32 v32, v64, v129
	v_cndmask_b32_e64 v65, v24, 0, s[0:1]
	v_sub_f32_e32 v24, v26, v128
	v_exp_f32_e32 v32, v32
	v_exp_f32_e32 v24, v24
	v_mov_b32_e32 v33, v153
	v_mov_b32_e32 v35, v153
	v_cndmask_b32_e64 v39, 0, v32, s[36:37]
	v_sub_f32_e32 v32, v66, v129
	v_cndmask_b32_e64 v66, v24, 0, s[22:23]
	v_sub_f32_e32 v24, v27, v128
	v_exp_f32_e32 v24, v24
	v_exp_f32_e32 v32, v32
	v_cndmask_b32_e64 v67, v24, 0, s[24:25]
	v_sub_f32_e32 v24, v28, v128
	v_exp_f32_e32 v24, v24
	v_cndmask_b32_e64 v64, 0, v32, s[4:5]
	v_cvt_pk_bf16_f32 v32, v39, 0
	v_cvt_pk_bf16_f32 v34, v64, 0
	v_cndmask_b32_e64 v68, v24, 0, s[26:27]
	v_sub_f32_e32 v24, v29, v128
	v_exp_f32_e32 v24, v24
	v_pk_mul_f32 v[28:29], v[96:97], v[36:37] op_sel_hi:[1,0]
	v_cvt_pk_bf16_f32 v25, v66, v67
	v_cndmask_b32_e64 v69, v24, 0, s[28:29]
	v_sub_f32_e32 v24, v30, v128
	v_exp_f32_e32 v24, v24
	v_cvt_pk_bf16_f32 v26, v68, v69
	v_cndmask_b32_e64 v70, v24, 0, s[30:31]
	v_sub_f32_e32 v24, v31, v128
	v_exp_f32_e32 v24, v24
	v_pk_mul_f32 v[30:31], v[98:99], v[36:37] op_sel_hi:[1,0]
	v_cndmask_b32_e64 v71, v24, 0, s[34:35]
	v_cvt_pk_bf16_f32 v24, v37, v65
	v_cvt_pk_bf16_f32 v27, v70, v71
	s_waitcnt lgkmcnt(10)
	v_mfma_f32_16x16x32_bf16 v[96:99], v[130:133], v[32:35], v[28:31]
	s_nop 2
	v_mul_f32_e64 v30, v102, v38
	v_mul_f32_e64 v31, v103, v38
	v_pk_mul_f32 v[28:29], v[100:101], v[38:39] op_sel_hi:[1,0]
	s_nop 1
	v_mfma_f32_16x16x32_bf16 v[100:103], v[130:133], v[24:27], v[28:31]
	s_nop 2
	v_mul_f32_e64 v30, v106, v36
	v_mul_f32_e64 v31, v107, v36
	v_pk_mul_f32 v[28:29], v[104:105], v[36:37] op_sel_hi:[1,0]
	s_waitcnt lgkmcnt(8)
	s_nop 0
	v_mfma_f32_16x16x32_bf16 v[104:107], v[134:137], v[32:35], v[28:31]
	s_nop 2
	v_mul_f32_e64 v30, v110, v38
	v_mul_f32_e64 v31, v111, v38
	v_pk_mul_f32 v[28:29], v[108:109], v[38:39] op_sel_hi:[1,0]
	s_nop 1
	v_mfma_f32_16x16x32_bf16 v[108:111], v[134:137], v[24:27], v[28:31]
	s_nop 2
	v_mul_f32_e64 v30, v114, v36
	v_mul_f32_e64 v31, v115, v36
	v_pk_mul_f32 v[28:29], v[112:113], v[36:37] op_sel_hi:[1,0]
	s_waitcnt lgkmcnt(6)
	s_nop 0
	v_mfma_f32_16x16x32_bf16 v[112:115], v[138:141], v[32:35], v[28:31]
	s_nop 2
	v_mul_f32_e64 v30, v118, v38
	v_mul_f32_e64 v31, v119, v38
	v_pk_mul_f32 v[28:29], v[116:117], v[38:39] op_sel_hi:[1,0]
	s_nop 1
	v_mfma_f32_16x16x32_bf16 v[116:119], v[138:141], v[24:27], v[28:31]
	s_nop 2
	v_mul_f32_e64 v30, v122, v36
	v_mul_f32_e64 v31, v123, v36
	v_pk_mul_f32 v[28:29], v[120:121], v[36:37] op_sel_hi:[1,0]
	s_waitcnt lgkmcnt(4)
	s_nop 0
	v_mfma_f32_16x16x32_bf16 v[120:123], v[176:179], v[32:35], v[28:31]
	v_add_u32_e32 v32, s40, v234
	s_nop 0
	s_nop 0
	v_pk_mul_f32 v[30:31], v[126:127], v[38:39] op_sel_hi:[1,0]
	v_pk_mul_f32 v[28:29], v[124:125], v[38:39] op_sel_hi:[1,0]
	s_nop 1
	v_mfma_f32_16x16x32_bf16 v[124:127], v[176:179], v[24:27], v[28:31]
	v_add_f32_e32 v24, 0, v37
	v_add_f32_e32 v24, v65, v24
	v_add_f32_e32 v24, v66, v24
	v_add_f32_e32 v24, v67, v24
	v_add_f32_e32 v24, v68, v24
	v_add_f32_e32 v24, v69, v24
	v_add_f32_e32 v24, v70, v24
	v_add_f32_e32 v130, v71, v24
	v_add_f32_e32 v24, 0, v39
	v_add_f32_e32 v131, v64, v24
	v_add_u32_e32 v24, s40, v229
	v_fmac_f32_e32 v131, v149, v36
	v_fmac_f32_e32 v130, v150, v38
	v_med3_i32 v24, v24, 0, s75
	v_add_u32_e32 v24, s74, v24
	v_ashrrev_i32_e32 v25, 31, v24
	v_lshlrev_b64 v[24:25], 9, v[24:25]
	v_lshl_add_u64 v[24:25], v[164:165], 0, v[24:25]
	global_load_dwordx4 v[64:67], v[24:25], off
	v_add_u32_e32 v24, s40, v230
	v_med3_i32 v24, v24, 0, s75
	v_add_u32_e32 v24, s74, v24
	v_ashrrev_i32_e32 v25, 31, v24
	v_lshlrev_b64 v[24:25], 9, v[24:25]
	v_lshl_add_u64 v[24:25], v[164:165], 0, v[24:25]
	global_load_dwordx4 v[68:71], v[24:25], off
	v_add_u32_e32 v24, s40, v231
	v_med3_i32 v24, v24, 0, s75
	v_add_u32_e32 v24, s74, v24
	v_ashrrev_i32_e32 v25, 31, v24
	v_lshlrev_b64 v[24:25], 9, v[24:25]
	v_lshl_add_u64 v[24:25], v[164:165], 0, v[24:25]
	global_load_dwordx4 v[72:75], v[24:25], off
	v_add_u32_e32 v24, s40, v232
	v_med3_i32 v24, v24, 0, s75
	v_add_u32_e32 v24, s74, v24
	v_ashrrev_i32_e32 v25, 31, v24
	v_lshlrev_b64 v[24:25], 9, v[24:25]
	v_lshl_add_u64 v[24:25], v[164:165], 0, v[24:25]
	global_load_dwordx4 v[88:91], v[24:25], off
	v_add_u32_e32 v24, s40, v233
	v_med3_i32 v24, v24, 0, s75
	v_add_u32_e32 v24, s74, v24
	v_ashrrev_i32_e32 v25, 31, v24
	v_med3_i32 v32, v32, 0, s75
	v_add_u32_e32 v32, s74, v32
	v_ashrrev_i32_e32 v33, 31, v32
	v_lshlrev_b64 v[24:25], 9, v[24:25]
	v_lshlrev_b64 v[32:33], 9, v[32:33]
	v_lshl_add_u64 v[24:25], s[68:69], 0, v[24:25]
	v_lshl_add_u64 v[32:33], s[68:69], 0, v[32:33]
	v_lshl_add_u64 v[28:29], v[24:25], 0, v[158:159]
	v_lshl_add_u64 v[36:37], v[32:33], 0, v[158:159]
	global_load_dwordx4 v[24:27], v[28:29], off
	s_nop 0
	global_load_dwordx4 v[28:31], v[28:29], off offset:64
	s_nop 0
	global_load_dwordx4 v[32:35], v[36:37], off
	s_nop 0
	global_load_dwordx4 v[36:39], v[36:37], off offset:64
	ds_read_b64_tr_b16 v[134:135], v169 offset:2304
	ds_read_b64_tr_b16 v[132:133], v169
	ds_read_b64_tr_b16 v[136:137], v169 offset:32
	ds_read_b64_tr_b16 v[138:139], v169 offset:2336
	ds_read_b64_tr_b16 v[140:141], v169 offset:64
	ds_read_b64_tr_b16 v[142:143], v169 offset:2368
	ds_read_b64_tr_b16 v[176:177], v169 offset:96
	ds_read_b64_tr_b16 v[178:179], v169 offset:2400
	s_waitcnt vmcnt(15)
	ds_write_b128 v241, v[76:79] offset:4608
	s_waitcnt vmcnt(14)
	ds_write_b128 v242, v[80:83] offset:4608
	s_waitcnt vmcnt(13)
	ds_write_b128 v243, v[84:87] offset:4608
	s_waitcnt vmcnt(12)
	ds_write_b128 v244, v[92:95] offset:4608
	v_mfma_f32_16x16x32_bf16 v[76:79], v[40:43], v[4:7], 0
	v_mfma_f32_16x16x32_bf16 v[76:79], v[44:47], v[8:11], v[76:79]
	v_mfma_f32_16x16x32_bf16 v[78:81], v[48:51], v[4:7], 0
	v_mfma_f32_16x16x32_bf16 v[40:43], v[40:43], v[12:15], 0
	s_nop 5
	v_mov_b32_e32 v77, v153
	v_mfma_f32_16x16x32_bf16 v[78:81], v[52:55], v[8:11], v[78:81]
	v_mfma_f32_16x16x32_bf16 v[40:43], v[44:47], v[0:3], v[40:43]
	v_mfma_f32_16x16x32_bf16 v[44:47], v[48:51], v[12:15], 0
	v_max_f32_e32 v49, v76, v76
	v_sub_u32_e32 v48, v187, v145
	v_max_f32_e32 v49, 0xf149f2ca, v49
	v_cndmask_b32_e64 v49, v246, v49, s[6:7]
	s_nop 1
	v_cndmask_b32_e64 v50, v246, v78, s[8:9]
	v_add_u32_e32 v51, 1, v48
	v_max3_f32 v49, v49, v50, s73
	v_max_f32_e32 v50, v40, v40
	v_cmp_gt_u32_e64 s[0:1], v51, v144
	v_cmp_gt_u32_e32 vcc, v48, v144
	v_max_f32_e32 v50, 0xf149f2ca, v50
	v_cndmask_b32_e64 v51, v41, v246, s[0:1]
	v_cndmask_b32_e32 v50, v50, v246, vcc
	v_mfma_f32_16x16x32_bf16 v[44:47], v[52:55], v[0:3], v[44:47]
	v_max_f32_e32 v50, v50, v51
	v_add_u32_e32 v51, 2, v48
	v_add_u32_e32 v52, 3, v48
	v_cmp_gt_u32_e64 s[22:23], v51, v144
	v_cmp_gt_u32_e64 s[24:25], v52, v144
	v_mov_b32_e32 v79, v153
	v_cndmask_b32_e64 v51, v42, v246, s[22:23]
	v_cndmask_b32_e64 v52, v43, v246, s[24:25]
	v_max3_f32 v50, v50, v51, v52
	v_add_u32_e32 v51, 16, v48
	v_add_u32_e32 v52, 17, v48
	v_cmp_gt_u32_e64 s[26:27], v51, v144
	v_cmp_gt_u32_e64 s[28:29], v52, v144
	s_nop 0
	v_cndmask_b32_e64 v51, v44, v246, s[26:27]
	v_cndmask_b32_e64 v52, v45, v246, s[28:29]
	v_max3_f32 v50, v50, v51, v52
	v_add_u32_e32 v51, 18, v48
	v_add_u32_e32 v48, 19, v48
	v_cmp_gt_u32_e64 s[30:31], v51, v144
	v_cmp_gt_u32_e64 s[34:35], v48, v144
	s_nop 0
	v_cndmask_b32_e64 v51, v46, v246, s[30:31]
	v_cndmask_b32_e64 v48, v47, v246, s[34:35]
	v_max3_f32 v48, v50, v51, v48
	v_mov_b32_e32 v50, v49
	v_mov_b32_e32 v51, v49
	s_nop 1
	v_permlane32_swap_b32_e32 v50, v51
	v_max3_f32 v49, v49, v50, v51
	v_mov_b32_e32 v50, v48
	v_mov_b32_e32 v51, v48
	s_nop 1
	v_permlane32_swap_b32_e32 v50, v51
	v_max3_f32 v48, v48, v50, v51
	v_mov_b32_e32 v50, v49
	v_mov_b32_e32 v51, v49
	s_nop 1
	v_permlane16_swap_b32_e32 v50, v51
	v_max_f32_e32 v49, v49, v50
	v_mov_b32_e32 v50, v48
	v_mov_b32_e32 v52, v48
	s_nop 1
	v_permlane16_swap_b32_e32 v50, v52
	v_max_f32_e32 v48, v48, v50
	v_max3_f32 v148, v128, v48, v52
	v_sub_f32_e32 v40, v40, v148
	v_exp_f32_e32 v40, v40
	v_sub_f32_e32 v41, v41, v148
	v_exp_f32_e32 v41, v41
	v_sub_f32_e32 v42, v42, v148
	v_exp_f32_e32 v42, v42
	v_sub_f32_e32 v43, v43, v148
	v_exp_f32_e32 v43, v43
	v_sub_f32_e32 v44, v44, v148
	v_max3_f32 v146, v129, v49, v51
	v_sub_f32_e32 v48, v128, v148
	v_cndmask_b32_e64 v40, v40, 0, vcc
	v_exp_f32_e32 v44, v44
	v_sub_f32_e32 v45, v45, v148
	v_sub_f32_e32 v49, v129, v146
	v_exp_f32_e32 v86, v48
	v_add_f32_e32 v48, 0, v40
	v_cndmask_b32_e64 v41, v41, 0, s[0:1]
	v_exp_f32_e32 v45, v45
	v_sub_f32_e32 v46, v46, v148
	v_sub_f32_e32 v47, v47, v148
	v_exp_f32_e32 v84, v49
	v_sub_f32_e32 v49, v76, v146
	v_sub_f32_e32 v51, v78, v146
	v_add_f32_e32 v48, v41, v48
	v_cndmask_b32_e64 v42, v42, 0, s[22:23]
	v_exp_f32_e32 v46, v46
	v_exp_f32_e32 v47, v47
	v_exp_f32_e32 v49, v49
	v_exp_f32_e32 v51, v51
	v_add_f32_e32 v48, v42, v48
	v_cndmask_b32_e64 v43, v43, 0, s[24:25]
	v_add_f32_e32 v48, v43, v48
	v_cndmask_b32_e64 v44, v44, 0, s[26:27]
	v_add_f32_e32 v48, v44, v48
	v_cndmask_b32_e64 v45, v45, 0, s[28:29]
	v_add_f32_e32 v48, v45, v48
	v_cndmask_b32_e64 v46, v46, 0, s[30:31]
	v_cndmask_b32_e64 v47, v47, 0, s[34:35]
	v_cndmask_b32_e64 v49, 0, v49, s[6:7]
	v_cndmask_b32_e64 v51, 0, v51, s[8:9]
	v_add_f32_e32 v48, v46, v48
	v_cvt_pk_bf16_f32 v40, v40, v41
	v_cvt_pk_bf16_f32 v41, v42, v43
	v_cvt_pk_bf16_f32 v42, v44, v45
	v_cvt_pk_bf16_f32 v43, v46, v47
	v_pk_mul_f32 v[82:83], v[110:111], v[86:87] op_sel_hi:[1,0]
	v_pk_mul_f32 v[80:81], v[108:109], v[86:87] op_sel_hi:[1,0]
	v_add_f32_e32 v50, 0, v49
	v_cvt_pk_bf16_f32 v76, v49, 0
	v_cvt_pk_bf16_f32 v78, v51, 0
	v_add_f32_e32 v149, v47, v48
	v_pk_mul_f32 v[46:47], v[98:99], v[84:85] op_sel_hi:[1,0]
	v_pk_mul_f32 v[44:45], v[96:97], v[84:85] op_sel_hi:[1,0]
	s_waitcnt lgkmcnt(8)
	v_mfma_f32_16x16x32_bf16 v[96:99], v[136:139], v[40:43], v[80:83]
	v_add_f32_e32 v147, v51, v50
	v_pk_mul_f32 v[50:51], v[102:103], v[86:87] op_sel_hi:[1,0]
	v_pk_mul_f32 v[48:49], v[100:101], v[86:87] op_sel_hi:[1,0]
	v_pk_mul_f32 v[82:83], v[114:115], v[84:85] op_sel_hi:[1,0]
	v_pk_mul_f32 v[80:81], v[112:113], v[84:85] op_sel_hi:[1,0]
	v_pk_mul_f32 v[54:55], v[106:107], v[84:85] op_sel_hi:[1,0]
	v_pk_mul_f32 v[52:53], v[104:105], v[84:85] op_sel_hi:[1,0]
	s_waitcnt lgkmcnt(6)
	v_mfma_f32_16x16x32_bf16 v[100:103], v[140:143], v[76:79], v[80:83]
	v_fmac_f32_e32 v147, v131, v84
	v_fmac_f32_e32 v149, v130, v86
	s_nop 0
	v_pk_mul_f32 v[82:83], v[118:119], v[86:87] op_sel_hi:[1,0]
	v_pk_mul_f32 v[80:81], v[116:117], v[86:87] op_sel_hi:[1,0]
	v_mfma_f32_16x16x32_bf16 v[44:47], v[132:135], v[76:79], v[44:47]
	s_nop 0
	v_mfma_f32_16x16x32_bf16 v[104:107], v[140:143], v[40:43], v[80:83]
	s_nop 2
	v_mul_f32_e64 v82, v122, v84
	v_mul_f32_e64 v83, v123, v84
	v_pk_mul_f32 v[80:81], v[120:121], v[84:85] op_sel_hi:[1,0]
	v_mfma_f32_16x16x32_bf16 v[52:55], v[136:139], v[76:79], v[52:55]
	v_add_u32_e32 v84, s40, v240
	s_waitcnt lgkmcnt(4)
	v_mfma_f32_16x16x32_bf16 v[108:111], v[176:179], v[76:79], v[80:83]
	v_mul_f32_e64 v78, v126, v86
	v_mul_f32_e64 v79, v127, v86
	v_pk_mul_f32 v[76:77], v[124:125], v[86:87] op_sel_hi:[1,0]
	v_mfma_f32_16x16x32_bf16 v[48:51], v[132:135], v[40:43], v[48:51]
	s_nop 0
	v_mfma_f32_16x16x32_bf16 v[112:115], v[176:179], v[40:43], v[76:79]
	v_add_u32_e32 v40, s40, v235
	s_nop 1
	v_add_u32_e32 v76, s40, v236
	v_med3_i32 v40, v40, 0, s75
	v_add_u32_e32 v40, s74, v40
	v_ashrrev_i32_e32 v41, 31, v40
	v_med3_i32 v76, v76, 0, s75
	v_add_u32_e32 v76, s74, v76
	v_ashrrev_i32_e32 v77, 31, v76
	v_lshlrev_b64 v[40:41], 9, v[40:41]
	v_lshlrev_b64 v[76:77], 9, v[76:77]
	v_lshl_add_u64 v[40:41], v[164:165], 0, v[40:41]
	v_lshl_add_u64 v[76:77], v[164:165], 0, v[76:77]
	global_load_dwordx4 v[40:43], v[40:41], off
	s_nop 0
	global_load_dwordx4 v[116:119], v[76:77], off
	v_add_u32_e32 v76, s40, v237
	v_med3_i32 v76, v76, 0, s75
	v_add_u32_e32 v76, s74, v76
	v_ashrrev_i32_e32 v77, 31, v76
	v_lshlrev_b64 v[76:77], 9, v[76:77]
	v_lshl_add_u64 v[76:77], v[164:165], 0, v[76:77]
	global_load_dwordx4 v[120:123], v[76:77], off
	v_add_u32_e32 v76, s40, v238
	v_med3_i32 v76, v76, 0, s75
	v_add_u32_e32 v76, s74, v76
	v_ashrrev_i32_e32 v77, 31, v76
	v_lshlrev_b64 v[76:77], 9, v[76:77]
	v_lshl_add_u64 v[76:77], v[164:165], 0, v[76:77]
	global_load_dwordx4 v[124:127], v[76:77], off
	v_add_u32_e32 v76, s40, v239
	v_med3_i32 v76, v76, 0, s75
	v_add_u32_e32 v76, s74, v76
	v_ashrrev_i32_e32 v77, 31, v76
	v_med3_i32 v84, v84, 0, s75
	v_add_u32_e32 v84, s74, v84
	v_ashrrev_i32_e32 v85, 31, v84
	v_lshlrev_b64 v[76:77], 9, v[76:77]
	v_lshlrev_b64 v[84:85], 9, v[84:85]
	v_lshl_add_u64 v[76:77], s[68:69], 0, v[76:77]
	v_lshl_add_u64 v[84:85], s[68:69], 0, v[84:85]
	v_lshl_add_u64 v[80:81], v[76:77], 0, v[158:159]
	v_lshl_add_u64 v[84:85], v[84:85], 0, v[158:159]
	global_load_dwordx4 v[76:79], v[80:81], off
	s_nop 0
	global_load_dwordx4 v[80:83], v[80:81], off offset:64
	s_nop 0
	global_load_dwordx4 v[92:95], v[84:85], off
	s_nop 0
	global_load_dwordx4 v[84:87], v[84:85], off offset:64
	ds_read_b64_tr_b16 v[142:143], v169 offset:6912
	ds_read_b64_tr_b16 v[140:141], v169 offset:4608
	ds_read_b64_tr_b16 v[136:137], v169 offset:4640
	ds_read_b64_tr_b16 v[138:139], v169 offset:6944
	ds_read_b64_tr_b16 v[132:133], v169 offset:4672
	ds_read_b64_tr_b16 v[134:135], v169 offset:6976
	ds_read_b64_tr_b16 v[128:129], v169 offset:4704
	ds_read_b64_tr_b16 v[130:131], v169 offset:7008
	s_waitcnt vmcnt(15)
	ds_write_b128 v241, v[64:67]
	s_waitcnt vmcnt(14)
	ds_write_b128 v242, v[68:71]
	s_waitcnt vmcnt(13)
	ds_write_b128 v243, v[72:75]
	s_waitcnt vmcnt(12)
	ds_write_b128 v244, v[88:91]
	v_mfma_f32_16x16x32_bf16 v[64:67], v[16:19], v[4:7], 0
	v_mfma_f32_16x16x32_bf16 v[64:67], v[20:23], v[8:11], v[64:67]
	v_mfma_f32_16x16x32_bf16 v[66:69], v[56:59], v[4:7], 0
	v_mfma_f32_16x16x32_bf16 v[16:19], v[16:19], v[12:15], 0
	v_mfma_f32_16x16x32_bf16 v[66:69], v[60:63], v[8:11], v[66:69]
	v_mfma_f32_16x16x32_bf16 v[16:19], v[20:23], v[0:3], v[16:19]
	v_mfma_f32_16x16x32_bf16 v[20:23], v[56:59], v[12:15], 0
	s_nop 2
	v_max_f32_e32 v57, v64, v64
	v_sub_u32_e32 v56, v192, v145
	v_max_f32_e32 v57, 0xf149f2ca, v57
	v_cndmask_b32_e64 v57, v246, v57, s[10:11]
	v_cndmask_b32_e64 v58, v246, v66, s[12:13]
	v_add_u32_e32 v59, 1, v56
	v_max3_f32 v57, v57, v58, s73
	v_max_f32_e32 v58, v16, v16
	v_cmp_gt_u32_e64 s[0:1], v59, v144
	v_cmp_gt_u32_e32 vcc, v56, v144
	v_max_f32_e32 v58, 0xf149f2ca, v58
	v_cndmask_b32_e64 v59, v17, v246, s[0:1]
	v_cndmask_b32_e32 v58, v58, v246, vcc
	v_mfma_f32_16x16x32_bf16 v[20:23], v[60:63], v[0:3], v[20:23]
	v_max_f32_e32 v58, v58, v59
	v_add_u32_e32 v59, 2, v56
	v_add_u32_e32 v60, 3, v56
	v_cmp_gt_u32_e64 s[22:23], v59, v144
	v_cmp_gt_u32_e64 s[24:25], v60, v144
	v_mov_b32_e32 v61, v153
	v_cndmask_b32_e64 v59, v18, v246, s[22:23]
	v_cndmask_b32_e64 v60, v19, v246, s[24:25]
	v_max3_f32 v58, v58, v59, v60
	v_add_u32_e32 v59, 16, v56
	v_add_u32_e32 v60, 17, v56
	v_cmp_gt_u32_e64 s[26:27], v59, v144
	v_cmp_gt_u32_e64 s[28:29], v60, v144
	v_mov_b32_e32 v63, v153
	v_cndmask_b32_e64 v59, v20, v246, s[26:27]
	v_cndmask_b32_e64 v60, v21, v246, s[28:29]
	v_max3_f32 v58, v58, v59, v60
	v_add_u32_e32 v59, 18, v56
	v_add_u32_e32 v56, 19, v56
	v_cmp_gt_u32_e64 s[30:31], v59, v144
	v_cmp_gt_u32_e64 s[34:35], v56, v144
	s_nop 0
	v_cndmask_b32_e64 v59, v22, v246, s[30:31]
	v_cndmask_b32_e64 v56, v23, v246, s[34:35]
	v_max3_f32 v56, v58, v59, v56
	v_mov_b32_e32 v58, v57
	v_mov_b32_e32 v59, v57
	s_nop 1
	v_permlane32_swap_b32_e32 v58, v59
	v_max3_f32 v57, v57, v58, v59
	v_mov_b32_e32 v58, v56
	v_mov_b32_e32 v59, v56
	s_nop 1
	v_permlane32_swap_b32_e32 v58, v59
	v_max3_f32 v56, v56, v58, v59
	v_mov_b32_e32 v58, v57
	v_mov_b32_e32 v59, v57
	s_nop 1
	v_permlane16_swap_b32_e32 v58, v59
	v_max_f32_e32 v57, v57, v58
	v_mov_b32_e32 v58, v56
	v_mov_b32_e32 v65, v56
	s_nop 1
	v_permlane16_swap_b32_e32 v58, v65
	v_max_f32_e32 v56, v56, v58
	v_max3_f32 v151, v148, v56, v65
	v_sub_f32_e32 v16, v16, v151
	v_exp_f32_e32 v16, v16
	v_sub_f32_e32 v17, v17, v151
	v_max3_f32 v150, v146, v57, v59
	v_exp_f32_e32 v17, v17
	v_sub_f32_e32 v18, v18, v151
	v_sub_f32_e32 v57, v146, v150
	v_exp_f32_e32 v18, v18
	v_sub_f32_e32 v19, v19, v151
	v_exp_f32_e32 v68, v57
	v_sub_f32_e32 v57, v64, v150
	v_exp_f32_e32 v19, v19
	v_sub_f32_e32 v20, v20, v151
	v_exp_f32_e32 v57, v57
	v_sub_f32_e32 v59, v66, v150
	v_sub_f32_e32 v56, v148, v151
	v_cndmask_b32_e64 v16, v16, 0, vcc
	v_exp_f32_e32 v20, v20
	v_sub_f32_e32 v21, v21, v151
	v_exp_f32_e32 v59, v59
	v_exp_f32_e32 v72, v56
	v_add_f32_e32 v56, 0, v16
	v_cndmask_b32_e64 v17, v17, 0, s[0:1]
	v_exp_f32_e32 v21, v21
	v_sub_f32_e32 v22, v22, v151
	v_add_f32_e32 v56, v17, v56
	v_cndmask_b32_e64 v18, v18, 0, s[22:23]
	v_exp_f32_e32 v22, v22
	v_sub_f32_e32 v23, v23, v151
	v_add_f32_e32 v56, v18, v56
	v_cndmask_b32_e64 v19, v19, 0, s[24:25]
	v_exp_f32_e32 v23, v23
	v_cndmask_b32_e64 v57, 0, v57, s[10:11]
	v_add_f32_e32 v56, v19, v56
	v_cndmask_b32_e64 v20, v20, 0, s[26:27]
	v_add_f32_e32 v58, 0, v57
	v_cndmask_b32_e64 v59, 0, v59, s[12:13]
	v_add_f32_e32 v56, v20, v56
	v_cndmask_b32_e64 v21, v21, 0, s[28:29]
	v_add_f32_e32 v146, v59, v58
	v_add_f32_e32 v56, v21, v56
	v_cndmask_b32_e64 v22, v22, 0, s[30:31]
	v_fmac_f32_e32 v146, v147, v68
	v_cvt_pk_bf16_f32 v60, v57, 0
	v_cvt_pk_bf16_f32 v62, v59, 0
	v_add_f32_e32 v56, v22, v56
	v_cndmask_b32_e64 v23, v23, 0, s[34:35]
	v_cvt_pk_bf16_f32 v64, v16, v17
	v_cvt_pk_bf16_f32 v65, v18, v19
	v_pk_mul_f32 v[18:19], v[46:47], v[68:69] op_sel_hi:[1,0]
	v_pk_mul_f32 v[16:17], v[44:45], v[68:69] op_sel_hi:[1,0]
	v_pk_mul_f32 v[46:47], v[54:55], v[68:69] op_sel_hi:[1,0]
	v_pk_mul_f32 v[44:45], v[52:53], v[68:69] op_sel_hi:[1,0]
	v_pk_mul_f32 v[54:55], v[102:103], v[68:69] op_sel_hi:[1,0]
	v_pk_mul_f32 v[52:53], v[100:101], v[68:69] op_sel_hi:[1,0]
	v_pk_mul_f32 v[70:71], v[110:111], v[68:69] op_sel_hi:[1,0]
	v_pk_mul_f32 v[68:69], v[108:109], v[68:69] op_sel_hi:[1,0]
	v_add_f32_e32 v147, v23, v56
	v_cvt_pk_bf16_f32 v66, v20, v21
	v_cvt_pk_bf16_f32 v67, v22, v23
	s_waitcnt lgkmcnt(10)
	v_mfma_f32_16x16x32_bf16 v[16:19], v[140:143], v[60:63], v[16:19]
	v_mul_f32_e64 v22, v50, v72
	v_mul_f32_e64 v23, v51, v72
	v_pk_mul_f32 v[20:21], v[48:49], v[72:73] op_sel_hi:[1,0]
	v_pk_mul_f32 v[50:51], v[98:99], v[72:73] op_sel_hi:[1,0]
	s_waitcnt lgkmcnt(8)
	v_mfma_f32_16x16x32_bf16 v[44:47], v[136:139], v[60:63], v[44:47]
	v_mul_f32_e64 v48, v96, v72
	v_mul_f32_e64 v49, v97, v72
	v_pk_mul_f32 v[58:59], v[106:107], v[72:73] op_sel_hi:[1,0]
	v_pk_mul_f32 v[56:57], v[104:105], v[72:73] op_sel_hi:[1,0]
	s_waitcnt lgkmcnt(6)
	v_mfma_f32_16x16x32_bf16 v[52:55], v[132:135], v[60:63], v[52:55]
	v_fmac_f32_e32 v147, v149, v72
	s_waitcnt lgkmcnt(4)
	v_mfma_f32_16x16x32_bf16 v[60:63], v[128:131], v[60:63], v[68:71]
	s_nop 2
	v_mul_f32_e64 v70, v114, v72
	v_mul_f32_e64 v71, v115, v72
	v_pk_mul_f32 v[68:69], v[112:113], v[72:73] op_sel_hi:[1,0]
	v_mfma_f32_16x16x32_bf16 v[20:23], v[140:143], v[64:67], v[20:23]
	v_mfma_f32_16x16x32_bf16 v[48:51], v[136:139], v[64:67], v[48:51]
	v_mfma_f32_16x16x32_bf16 v[56:59], v[132:135], v[64:67], v[56:59]
	v_mfma_f32_16x16x32_bf16 v[64:67], v[128:131], v[64:67], v[68:71]
	ds_read_b64_tr_b16 v[98:99], v169 offset:2304
	ds_read_b64_tr_b16 v[96:97], v169
	ds_read_b64_tr_b16 v[88:89], v169 offset:32
	ds_read_b64_tr_b16 v[90:91], v169 offset:2336
	ds_read_b64_tr_b16 v[72:73], v169 offset:64
	ds_read_b64_tr_b16 v[74:75], v169 offset:2368
	ds_read_b64_tr_b16 v[68:69], v169 offset:96
	ds_read_b64_tr_b16 v[70:71], v169 offset:2400
	s_waitcnt vmcnt(7)
	ds_write_b128 v241, v[40:43] offset:4608
	s_waitcnt vmcnt(6)
	ds_write_b128 v242, v[116:119] offset:4608
	s_waitcnt vmcnt(5)
	ds_write_b128 v243, v[120:123] offset:4608
	s_waitcnt vmcnt(4)
	ds_write_b128 v244, v[124:127] offset:4608
	v_mfma_f32_16x16x32_bf16 v[40:43], v[24:27], v[4:7], 0
	v_mfma_f32_16x16x32_bf16 v[100:103], v[32:35], v[4:7], 0
	v_mfma_f32_16x16x32_bf16 v[24:27], v[24:27], v[12:15], 0
	v_mfma_f32_16x16x32_bf16 v[40:43], v[28:31], v[8:11], v[40:43]
	v_mfma_f32_16x16x32_bf16 v[100:103], v[36:39], v[8:11], v[100:103]
	v_mfma_f32_16x16x32_bf16 v[24:27], v[28:31], v[0:3], v[24:27]
	s_nop 5
	v_mov_b32_e32 v41, v153
	v_mov_b32_e32 v43, v153
	v_mfma_f32_16x16x32_bf16 v[28:31], v[32:35], v[12:15], 0
	v_max_f32_e32 v33, v40, v40
	v_sub_u32_e32 v32, v197, v145
	v_max_f32_e32 v33, 0xf149f2ca, v33
	v_cndmask_b32_e64 v33, v246, v33, s[14:15]
	v_cndmask_b32_e64 v34, v246, v100, s[16:17]
	v_add_u32_e32 v35, 1, v32
	v_max3_f32 v33, v33, v34, s73
	v_max_f32_e32 v34, v24, v24
	v_cmp_gt_u32_e64 s[0:1], v35, v144
	v_cmp_gt_u32_e32 vcc, v32, v144
	v_max_f32_e32 v34, 0xf149f2ca, v34
	v_cndmask_b32_e64 v35, v25, v246, s[0:1]
	v_cndmask_b32_e32 v34, v34, v246, vcc
	v_mfma_f32_16x16x32_bf16 v[28:31], v[36:39], v[0:3], v[28:31]
	v_max_f32_e32 v34, v34, v35
	v_add_u32_e32 v35, 2, v32
	v_add_u32_e32 v36, 3, v32
	v_cmp_gt_u32_e64 s[22:23], v35, v144
	v_cmp_gt_u32_e64 s[24:25], v36, v144
	s_nop 0
	v_cndmask_b32_e64 v35, v26, v246, s[22:23]
	v_cndmask_b32_e64 v36, v27, v246, s[24:25]
	v_max3_f32 v34, v34, v35, v36
	v_add_u32_e32 v35, 16, v32
	v_add_u32_e32 v36, 17, v32
	v_cmp_gt_u32_e64 s[26:27], v35, v144
	v_cmp_gt_u32_e64 s[28:29], v36, v144
	s_nop 0
	v_cndmask_b32_e64 v35, v28, v246, s[26:27]
	v_cndmask_b32_e64 v36, v29, v246, s[28:29]
	v_max3_f32 v34, v34, v35, v36
	v_add_u32_e32 v35, 18, v32
	v_add_u32_e32 v32, 19, v32
	v_cmp_gt_u32_e64 s[30:31], v35, v144
	v_cmp_gt_u32_e64 s[34:35], v32, v144
	s_nop 0
	v_cndmask_b32_e64 v35, v30, v246, s[30:31]
	v_cndmask_b32_e64 v32, v31, v246, s[34:35]
	v_max3_f32 v32, v34, v35, v32
	v_mov_b32_e32 v34, v33
	v_mov_b32_e32 v35, v33
	s_nop 1
	v_permlane32_swap_b32_e32 v34, v35
	v_max3_f32 v33, v33, v34, v35
	v_mov_b32_e32 v34, v32
	v_mov_b32_e32 v35, v32
	s_nop 1
	v_permlane32_swap_b32_e32 v34, v35
	v_max3_f32 v32, v32, v34, v35
	v_mov_b32_e32 v34, v33
	v_mov_b32_e32 v35, v33
	s_nop 1
	v_permlane16_swap_b32_e32 v34, v35
	v_max_f32_e32 v33, v33, v34
	v_max3_f32 v101, v150, v33, v35
	v_sub_f32_e32 v33, v150, v101
	v_exp_f32_e32 v106, v33
	v_sub_f32_e32 v33, v40, v101
	v_mov_b32_e32 v34, v32
	v_mov_b32_e32 v36, v32
	v_exp_f32_e32 v33, v33
	s_nop 0
	v_permlane16_swap_b32_e32 v34, v36
	v_max_f32_e32 v32, v32, v34
	v_cndmask_b32_e64 v107, 0, v33, s[14:15]
	v_sub_f32_e32 v33, v100, v101
	v_max3_f32 v100, v151, v32, v36
	v_sub_f32_e32 v24, v24, v100
	v_exp_f32_e32 v24, v24
	v_exp_f32_e32 v33, v33
	v_sub_f32_e32 v32, v151, v100
	v_exp_f32_e32 v108, v32
	v_cndmask_b32_e64 v110, v24, 0, vcc
	v_sub_f32_e32 v24, v25, v100
	v_exp_f32_e32 v24, v24
	v_cndmask_b32_e64 v109, 0, v33, s[16:17]
	v_cvt_pk_bf16_f32 v40, v107, 0
	v_cvt_pk_bf16_f32 v42, v109, 0
	v_cndmask_b32_e64 v111, v24, 0, s[0:1]
	v_sub_f32_e32 v24, v26, v100
	v_exp_f32_e32 v24, v24
	v_pk_mul_f32 v[18:19], v[18:19], v[106:107] op_sel_hi:[1,0]
	v_pk_mul_f32 v[16:17], v[16:17], v[106:107] op_sel_hi:[1,0]
	v_pk_mul_f32 v[34:35], v[54:55], v[106:107] op_sel_hi:[1,0]
	v_cndmask_b32_e64 v112, v24, 0, s[22:23]
	v_sub_f32_e32 v24, v27, v100
	v_exp_f32_e32 v24, v24
	v_pk_mul_f32 v[26:27], v[46:47], v[106:107] op_sel_hi:[1,0]
	v_pk_mul_f32 v[32:33], v[52:53], v[106:107] op_sel_hi:[1,0]
	v_pk_mul_f32 v[46:47], v[62:63], v[106:107] op_sel_hi:[1,0]
	v_cndmask_b32_e64 v113, v24, 0, s[24:25]
	v_sub_f32_e32 v24, v28, v100
	v_exp_f32_e32 v24, v24
	s_waitcnt lgkmcnt(10)
	v_mfma_f32_16x16x32_bf16 v[16:19], v[96:99], v[40:43], v[16:19]
	v_cvt_pk_bf16_f32 v102, v110, v111
	v_cvt_pk_bf16_f32 v103, v112, v113
	v_cndmask_b32_e64 v114, v24, 0, s[26:27]
	v_sub_f32_e32 v24, v29, v100
	v_exp_f32_e32 v24, v24
	s_waitcnt lgkmcnt(6)
	v_mfma_f32_16x16x32_bf16 v[32:35], v[72:75], v[40:43], v[32:35]
	v_mul_f32_e64 v28, v48, v108
	v_mul_f32_e64 v29, v49, v108
	v_add_f32_e32 v48, 0, v110
	v_cndmask_b32_e64 v115, v24, 0, s[28:29]
	v_sub_f32_e32 v24, v30, v100
	v_exp_f32_e32 v24, v24
	v_add_f32_e32 v48, v111, v48
	v_add_f32_e32 v48, v112, v48
	v_add_f32_e32 v48, v113, v48
	v_cndmask_b32_e64 v116, v24, 0, s[30:31]
	v_sub_f32_e32 v24, v31, v100
	v_exp_f32_e32 v24, v24
	v_add_f32_e32 v48, v114, v48
	v_add_f32_e32 v48, v115, v48
	v_cvt_pk_bf16_f32 v104, v114, v115
	v_cndmask_b32_e64 v117, v24, 0, s[34:35]
	v_pk_mul_f32 v[24:25], v[44:45], v[106:107] op_sel_hi:[1,0]
	v_pk_mul_f32 v[44:45], v[60:61], v[106:107] op_sel_hi:[1,0]
	v_cvt_pk_bf16_f32 v105, v116, v117
	v_mfma_f32_16x16x32_bf16 v[24:27], v[88:91], v[40:43], v[24:27]
	v_add_f32_e32 v48, v116, v48
	v_pk_mul_f32 v[38:39], v[58:59], v[108:109] op_sel_hi:[1,0]
	v_pk_mul_f32 v[36:37], v[56:57], v[108:109] op_sel_hi:[1,0]
	s_waitcnt lgkmcnt(4)
	v_mfma_f32_16x16x32_bf16 v[40:43], v[68:71], v[40:43], v[44:47]
	v_mul_f32_e64 v30, v50, v108
	v_mul_f32_e64 v31, v51, v108
	v_pk_mul_f32 v[22:23], v[22:23], v[108:109] op_sel_hi:[1,0]
	v_pk_mul_f32 v[20:21], v[20:21], v[108:109] op_sel_hi:[1,0]
	v_pk_mul_f32 v[46:47], v[66:67], v[108:109] op_sel_hi:[1,0]
	v_pk_mul_f32 v[44:45], v[64:65], v[108:109] op_sel_hi:[1,0]
	s_waitcnt vmcnt(3)
	v_mfma_f32_16x16x32_bf16 v[64:67], v[76:79], v[4:7], 0
	s_waitcnt vmcnt(1)
	v_mfma_f32_16x16x32_bf16 v[4:7], v[92:95], v[4:7], 0
	v_mfma_f32_16x16x32_bf16 v[64:67], v[80:83], v[8:11], v[64:67]
	s_waitcnt vmcnt(0)
	v_mfma_f32_16x16x32_bf16 v[8:11], v[84:87], v[8:11], v[4:7]
	v_mfma_f32_16x16x32_bf16 v[4:7], v[76:79], v[12:15], 0
	v_mfma_f32_16x16x32_bf16 v[10:13], v[92:95], v[12:15], 0
	s_nop 5
	v_sub_u32_e32 v9, v198, v145
	v_cmp_gt_u32_e64 s[34:35], v9, v144
	v_mov_b32_e32 v15, v153
	v_mfma_f32_16x16x32_bf16 v[4:7], v[80:83], v[0:3], v[4:7]
	v_mfma_f32_16x16x32_bf16 v[0:3], v[84:87], v[0:3], v[10:13]
	s_nop 2
	v_max_f32_e32 v10, v64, v64
	v_max_f32_e32 v10, 0xf149f2ca, v10
	v_cndmask_b32_e64 v10, v246, v10, s[18:19]
	v_cndmask_b32_e64 v11, v246, v8, s[20:21]
	v_add_u32_e32 v12, 1, v9
	v_max3_f32 v10, v10, v11, s73
	v_max_f32_e32 v11, v4, v4
	v_cmp_gt_u32_e64 s[30:31], v12, v144
	v_max_f32_e32 v11, 0xf149f2ca, v11
	v_cndmask_b32_e64 v11, v11, v246, s[34:35]
	v_cndmask_b32_e64 v12, v5, v246, s[30:31]
	v_max_f32_e32 v11, v11, v12
	v_add_u32_e32 v12, 2, v9
	v_add_u32_e32 v13, 3, v9
	v_cmp_gt_u32_e64 s[28:29], v12, v144
	v_cmp_gt_u32_e64 s[26:27], v13, v144
	v_mfma_f32_16x16x32_bf16 v[44:47], v[68:71], v[102:105], v[44:47]
	v_cndmask_b32_e64 v12, v6, v246, s[28:29]
	v_cndmask_b32_e64 v13, v7, v246, s[26:27]
	v_max3_f32 v11, v11, v12, v13
	v_add_u32_e32 v12, 16, v9
	v_add_u32_e32 v13, 17, v9
	v_cmp_gt_u32_e64 s[24:25], v12, v144
	v_cmp_gt_u32_e64 s[22:23], v13, v144
	v_add_f32_e32 v68, v117, v48
	v_cndmask_b32_e64 v12, v0, v246, s[24:25]
	v_cndmask_b32_e64 v13, v1, v246, s[22:23]
	v_max3_f32 v11, v11, v12, v13
	v_add_u32_e32 v12, 18, v9
	v_add_u32_e32 v9, 19, v9
	v_cmp_gt_u32_e64 s[0:1], v12, v144
	v_cmp_gt_u32_e32 vcc, v9, v144
	v_add_f32_e32 v48, 0, v107
	v_cndmask_b32_e64 v12, v2, v246, s[0:1]
	v_cndmask_b32_e32 v9, v3, v246, vcc
	v_max3_f32 v9, v11, v12, v9
	v_mov_b32_e32 v11, v10
	v_mov_b32_e32 v12, v10
	s_nop 1
	v_permlane32_swap_b32_e32 v11, v12
	v_max3_f32 v10, v10, v11, v12
	v_mov_b32_e32 v11, v9
	v_mov_b32_e32 v12, v9
	s_nop 1
	v_permlane32_swap_b32_e32 v11, v12
	v_max3_f32 v9, v9, v11, v12
	v_mov_b32_e32 v11, v10
	v_mov_b32_e32 v12, v10
	s_nop 1
	v_permlane16_swap_b32_e32 v11, v12
	v_max_f32_e32 v10, v10, v11
	v_mov_b32_e32 v11, v9
	v_mov_b32_e32 v67, v9
	s_nop 1
	v_permlane16_swap_b32_e32 v11, v67
	v_max3_f32 v10, v101, v10, v12
	v_max_f32_e32 v9, v9, v11
	v_sub_f32_e32 v11, v101, v10
	v_exp_f32_e32 v66, v11
	v_sub_f32_e32 v11, v64, v10
	v_exp_f32_e32 v11, v11
	v_sub_f32_e32 v8, v8, v10
	v_exp_f32_e32 v8, v8
	v_add_f32_e32 v69, v109, v48
	v_cndmask_b32_e64 v11, 0, v11, s[18:19]
	v_add_f32_e32 v12, 0, v11
	v_cndmask_b32_e64 v8, 0, v8, s[20:21]
	v_fmac_f32_e32 v69, v146, v106
	v_add_f32_e32 v65, v8, v12
	v_cvt_pk_bf16_f32 v14, v8, 0
	v_max3_f32 v8, v100, v9, v67
	v_fmac_f32_e32 v65, v69, v66
	v_sub_f32_e32 v4, v4, v8
	v_cvt_pk_bf16_f32 v12, v11, 0
	v_exp_f32_e32 v4, v4
	v_sub_f32_e32 v5, v5, v8
	v_pk_mul_f32 v[10:11], v[34:35], v[66:67] op_sel_hi:[1,0]
	ds_bpermute_b32 v34, v170, v65
	v_exp_f32_e32 v5, v5
	v_sub_f32_e32 v6, v6, v8
	v_exp_f32_e32 v6, v6
	v_sub_f32_e32 v7, v7, v8
	v_exp_f32_e32 v7, v7
	v_sub_f32_e32 v0, v0, v8
	v_sub_f32_e32 v9, v100, v8
	v_cndmask_b32_e64 v4, v4, 0, s[34:35]
	v_exp_f32_e32 v0, v0
	v_sub_f32_e32 v1, v1, v8
	v_mfma_f32_16x16x32_bf16 v[36:39], v[72:75], v[102:105], v[36:39]
	v_exp_f32_e32 v72, v9
	v_add_f32_e32 v9, 0, v4
	v_cndmask_b32_e64 v5, v5, 0, s[30:31]
	v_exp_f32_e32 v1, v1
	v_sub_f32_e32 v2, v2, v8
	s_waitcnt lgkmcnt(0)
	v_add_f32_e32 v34, v65, v34
	v_add_f32_e32 v9, v5, v9
	v_cndmask_b32_e64 v6, v6, 0, s[28:29]
	v_exp_f32_e32 v2, v2
	v_sub_f32_e32 v3, v3, v8
	ds_bpermute_b32 v35, v171, v34
	v_add_f32_e32 v9, v6, v9
	v_cndmask_b32_e64 v7, v7, 0, s[26:27]
	v_exp_f32_e32 v3, v3
	v_add_f32_e32 v9, v7, v9
	v_cndmask_b32_e64 v0, v0, 0, s[24:25]
	v_add_f32_e32 v9, v0, v9
	v_cndmask_b32_e64 v1, v1, 0, s[22:23]
	ds_read_b64_tr_b16 v[62:63], v169 offset:6912
	ds_read_b64_tr_b16 v[60:61], v169 offset:4608
	ds_read_b64_tr_b16 v[56:57], v169 offset:4640
	ds_read_b64_tr_b16 v[58:59], v169 offset:6944
	ds_read_b64_tr_b16 v[52:53], v169 offset:4672
	ds_read_b64_tr_b16 v[54:55], v169 offset:6976
	ds_read_b64_tr_b16 v[48:49], v169 offset:4704
	ds_read_b64_tr_b16 v[50:51], v169 offset:7008
	v_add_f32_e32 v9, v1, v9
	v_cndmask_b32_e64 v2, v2, 0, s[0:1]
	v_add_f32_e32 v9, v2, v9
	v_cndmask_b32_e64 v3, v3, 0, vcc
	s_waitcnt lgkmcnt(8)
	v_add_f32_e32 v34, v34, v35
	v_fmac_f32_e32 v68, v147, v108
	v_mov_b32_e32 v13, v153
	v_add_f32_e32 v64, v3, v9
	v_pk_mul_f32 v[8:9], v[32:33], v[66:67] op_sel_hi:[1,0]
	v_div_scale_f32 v35, s[0:1], v34, v34, 1.0
	v_fmac_f32_e32 v64, v68, v72
	v_cvt_pk_bf16_f32 v68, v4, v5
	v_cvt_pk_bf16_f32 v69, v6, v7
	v_pk_mul_f32 v[6:7], v[26:27], v[66:67] op_sel_hi:[1,0]
	v_pk_mul_f32 v[4:5], v[24:25], v[66:67] op_sel_hi:[1,0]
	s_waitcnt lgkmcnt(2)
	v_mfma_f32_16x16x32_bf16 v[24:27], v[52:55], v[12:15], v[8:11]
	v_cvt_pk_bf16_f32 v70, v0, v1
	v_cvt_pk_bf16_f32 v71, v2, v3
	v_pk_mul_f32 v[2:3], v[18:19], v[66:67] op_sel_hi:[1,0]
	v_pk_mul_f32 v[8:9], v[36:37], v[72:73] op_sel_hi:[1,0]
	v_rcp_f32_e32 v36, v35
	v_mfma_f32_16x16x32_bf16 v[20:23], v[96:99], v[102:105], v[20:23]
	v_mul_f32_e64 v10, v38, v72
	v_mul_f32_e64 v11, v39, v72
	v_pk_mul_f32 v[0:1], v[16:17], v[66:67] op_sel_hi:[1,0]
	v_fma_f32 v37, -v35, v36, 1.0
	v_fmac_f32_e32 v36, v37, v36
	v_div_scale_f32 v37, vcc, 1.0, v34, 1.0
	v_mul_f32_e32 v38, v37, v36
	v_fma_f32 v39, -v35, v38, v37
	v_mfma_f32_16x16x32_bf16 v[16:19], v[60:63], v[12:15], v[0:3]
	v_fmac_f32_e32 v38, v39, v36
	v_fma_f32 v35, -v35, v38, v37
	v_div_fmas_f32 v35, v35, v36, v38
	v_mfma_f32_16x16x32_bf16 v[28:31], v[88:91], v[102:105], v[28:31]
	v_mul_f32_e64 v2, v22, v72
	v_mul_f32_e64 v3, v23, v72
	v_pk_mul_f32 v[0:1], v[20:21], v[72:73] op_sel_hi:[1,0]
	v_div_fixup_f32 v34, v35, v34, 1.0
	v_mfma_f32_16x16x32_bf16 v[20:23], v[56:59], v[12:15], v[4:7]
	v_lshl_add_u64 v[32:33], v[156:157], 0, s[56:57]
	v_lshlrev_b64 v[36:37], 11, v[162:163]
	v_pk_mul_f32 v[16:17], v[16:17], v[34:35] op_sel_hi:[1,0]
	v_pk_mul_f32 v[18:19], v[18:19], v[34:35] op_sel_hi:[1,0]
	v_pk_mul_f32 v[6:7], v[30:31], v[72:73] op_sel_hi:[1,0]
	v_pk_mul_f32 v[4:5], v[28:29], v[72:73] op_sel_hi:[1,0]
	v_pk_mul_f32 v[30:31], v[42:43], v[66:67] op_sel_hi:[1,0]
	v_pk_mul_f32 v[28:29], v[40:41], v[66:67] op_sel_hi:[1,0]
	v_lshl_add_u64 v[36:37], v[32:33], 0, v[36:37]
	v_cvt_pk_bf16_f32 v16, v16, v17
	v_cvt_pk_bf16_f32 v17, v18, v19
	s_waitcnt lgkmcnt(0)
	v_mfma_f32_16x16x32_bf16 v[28:31], v[48:51], v[12:15], v[28:31]
	global_store_dwordx2 v[36:37], v[16:17], off
	v_pk_mul_f32 v[16:17], v[20:21], v[34:35] op_sel_hi:[1,0]
	v_pk_mul_f32 v[18:19], v[22:23], v[34:35] op_sel_hi:[1,0]
	v_cvt_pk_bf16_f32 v16, v16, v17
	v_cvt_pk_bf16_f32 v17, v18, v19
	global_store_dwordx2 v[36:37], v[16:17], off offset:32
	v_pk_mul_f32 v[16:17], v[24:25], v[34:35] op_sel_hi:[1,0]
	v_pk_mul_f32 v[18:19], v[26:27], v[34:35] op_sel_hi:[1,0]
	v_cvt_pk_bf16_f32 v16, v16, v17
	v_cvt_pk_bf16_f32 v17, v18, v19
	global_store_dwordx2 v[36:37], v[16:17], off offset:64
	v_pk_mul_f32 v[16:17], v[28:29], v[34:35] op_sel_hi:[1,0]
	v_pk_mul_f32 v[18:19], v[30:31], v[34:35] op_sel_hi:[1,0]
	v_cvt_pk_bf16_f32 v16, v16, v17
	v_cvt_pk_bf16_f32 v17, v18, v19
	global_store_dwordx2 v[36:37], v[16:17], off offset:96
	ds_bpermute_b32 v16, v170, v64
	v_mfma_f32_16x16x32_bf16 v[0:3], v[60:63], v[68:71], v[0:3]
	v_mul_f32_e64 v14, v46, v72
	v_mul_f32_e64 v15, v47, v72
	v_pk_mul_f32 v[12:13], v[44:45], v[72:73] op_sel_hi:[1,0]
	s_waitcnt lgkmcnt(0)
	v_add_f32_e32 v16, v64, v16
	ds_bpermute_b32 v17, v171, v16
	v_mfma_f32_16x16x32_bf16 v[4:7], v[56:59], v[68:71], v[4:7]
	s_waitcnt lgkmcnt(0)
	v_add_f32_e32 v16, v16, v17
	v_div_scale_f32 v17, s[0:1], v16, v16, 1.0
	v_rcp_f32_e32 v18, v17
	v_mfma_f32_16x16x32_bf16 v[8:11], v[52:55], v[68:71], v[8:11]
	v_fma_f32 v19, -v17, v18, 1.0
	v_fmac_f32_e32 v18, v19, v18
	v_div_scale_f32 v19, vcc, 1.0, v16, 1.0
	v_mul_f32_e32 v20, v19, v18
	v_fma_f32 v21, -v17, v20, v19
	v_fmac_f32_e32 v20, v21, v18
	v_fma_f32 v17, -v17, v20, v19
	v_div_fmas_f32 v17, v17, v18, v20
	v_div_fixup_f32 v16, v17, v16, 1.0
	v_lshlrev_b64 v[18:19], 11, v[160:161]
	v_pk_mul_f32 v[0:1], v[0:1], v[16:17] op_sel_hi:[1,0]
	v_pk_mul_f32 v[2:3], v[2:3], v[16:17] op_sel_hi:[1,0]
	v_lshl_add_u64 v[18:19], v[32:33], 0, v[18:19]
	v_cvt_pk_bf16_f32 v0, v0, v1
	v_cvt_pk_bf16_f32 v1, v2, v3
	v_mfma_f32_16x16x32_bf16 v[12:15], v[48:51], v[68:71], v[12:15]
	global_store_dwordx2 v[18:19], v[0:1], off
	v_pk_mul_f32 v[0:1], v[4:5], v[16:17] op_sel_hi:[1,0]
	v_pk_mul_f32 v[2:3], v[6:7], v[16:17] op_sel_hi:[1,0]
	v_cvt_pk_bf16_f32 v0, v0, v1
	v_cvt_pk_bf16_f32 v1, v2, v3
	global_store_dwordx2 v[18:19], v[0:1], off offset:32
	v_pk_mul_f32 v[0:1], v[8:9], v[16:17] op_sel_hi:[1,0]
	v_pk_mul_f32 v[2:3], v[10:11], v[16:17] op_sel_hi:[1,0]
	v_cvt_pk_bf16_f32 v0, v0, v1
	v_cvt_pk_bf16_f32 v1, v2, v3
	global_store_dwordx2 v[18:19], v[0:1], off offset:64
	v_pk_mul_f32 v[0:1], v[12:13], v[16:17] op_sel_hi:[1,0]
	v_pk_mul_f32 v[2:3], v[14:15], v[16:17] op_sel_hi:[1,0]
	v_cvt_pk_bf16_f32 v0, v0, v1
	v_cvt_pk_bf16_f32 v1, v2, v3
	global_store_dwordx2 v[18:19], v[0:1], off offset:96
	s_cbranch_scc1 .LBB0_246
	s_mov_b32 s76, s79
	v_readlane_b32 s72, v253, 43
	v_xor_b32_e32 v240, 32, v174
	v_xor_b32_e32 v241, 16, v174
	v_xor_b32_e32 v242, 8, v174
	v_xor_b32_e32 v243, 4, v174
	v_xor_b32_e32 v244, 2, v174
	v_xor_b32_e32 v245, 1, v174
	v_and_b32_e32 v246, 64, v174
